# v19 + gates epilogue XRC loads hoisted + residual epilogues (phases 5, 8/20, 17) loads issued ahead with exact vmcnt
# speedup vs baseline: 1.0229x; 1.0009x over previous
; __device__ __forceinline__ void ss_add(ss_t* p, float v) { (void)__hip_atomic_fetch_add(p, (ss_t)(v * 1048576.0f), __ATOMIC_RELAXED, __HIP_MEMORY_SCOPE_AGENT); }
; __device__ __forceinline__ unsigned cvt_pk_bf16(float lo, float hi) { unsigned r; asm volatile("v_cvt_pk_bf16_f32 %0, %1, %2" : "=v"(r) : "v"(lo), "v"(hi)); return r; }
; __device__ __forceinline__ float bflo(unsigned w) { return __uint_as_float(w << 16); }
; __device__ __forceinline__ float bfhi(unsigned w) { return __uint_as_float(w & 0xffff0000u); }
;     __device__ __forceinline__ void operator()(const f32x4 (&acc)[2][2][4][2], const Unit& u, int wr, int wc, int fr, int fq) const {
;     ...
;             for (int m = 0; m < 4; ++m) { const int row = row0 + ai * 128 + m * 16; const size_t off = (size_t)row * D + col0; float sq = 0.f;
; #pragma unroll
;                 for (int bj = 0; bj < 2; ++bj) { const size_t o = off + bj * 128; f32x4 b0, b1;
;                     if (XF32) { b0 = *(const f32x4*)((const float*)base + o); b1 = *(const f32x4*)((const float*)base + o + 4); }
;                     else { const u32x4 hw = *(const u32x4*)((const bf16_t*)base + o); b0 = (f32x4){bflo(hw.x), bfhi(hw.x), bflo(hw.y), bfhi(hw.y)}; b1 = (f32x4){bflo(hw.z), bfhi(hw.z), bflo(hw.w), bfhi(hw.w)}; }
;                     const f32x4 r0 = b0 + acc[ai][bj][m][0], r1 = b1 + acc[ai][bj][m][1];
;                     u32x4 hb; hb.x = cvt_pk_bf16(r0[0], r0[1]); hb.y = cvt_pk_bf16(r0[2], r0[3]); hb.z = cvt_pk_bf16(r1[0], r1[1]); hb.w = cvt_pk_bf16(r1[2], r1[3]); *(u32x4*)(HB + o) = hb;
;                     sq += ((r0[0] * r0[0] + r0[1] * r0[1]) + (r0[2] * r0[2] + r0[3] * r0[3])) + ((r1[0] * r1[0] + r1[1] * r1[1]) + (r1[2] * r1[2] + r1[3] * r1[3])); }
;                 sq += __shfl_xor(sq, 16); sq += __shfl_xor(sq, 32);
;                 if (fq == 0) ss_add(SS + row, sq);
.LBB0_59:
	v_lshl_add_u32 v160, s26, 8, v1
	v_lshl_or_b32 v158, s28, 8, v157
	v_ashrrev_i32_e32 v161, 31, v160
	v_ashrrev_i32_e32 v159, 31, v158
	v_lshlrev_b64 v[148:149], 11, v[160:161]
	v_lshl_add_u64 v[148:149], v[148:149], 0, v[158:159]
	v_lshlrev_b64 v[162:163], 1, v[148:149]
	v_lshl_add_u64 v[148:149], s[0:1], 0, v[162:163]
	v_mov_b64_e32 v[204:205], v[148:149]
	global_load_dwordx4 v[170:173], v[204:205], off
	global_load_dwordx4 v[174:177], v[204:205], off offset:256
	s_mov_b64 s[26:27], 0x10000
	v_lshl_add_u64 v[204:205], v[204:205], 0, s[26:27]
	global_load_dwordx4 v[178:181], v[204:205], off
	global_load_dwordx4 v[182:185], v[204:205], off offset:256
	s_mov_b64 s[26:27], 0x10000
	v_lshl_add_u64 v[204:205], v[204:205], 0, s[26:27]
	global_load_dwordx4 v[186:189], v[204:205], off
	global_load_dwordx4 v[190:193], v[204:205], off offset:256
	s_mov_b64 s[26:27], 0x10000
	v_lshl_add_u64 v[204:205], v[204:205], 0, s[26:27]
	global_load_dwordx4 v[214:217], v[204:205], off
	global_load_dwordx4 v[218:221], v[204:205], off offset:256
	s_mov_b64 s[26:27], 0x50000
	v_lshl_add_u64 v[204:205], v[204:205], 0, s[26:27]
	global_load_dwordx4 v[222:225], v[204:205], off
	global_load_dwordx4 v[226:229], v[204:205], off offset:256
	s_mov_b64 s[26:27], 0x10000
	v_lshl_add_u64 v[204:205], v[204:205], 0, s[26:27]
	global_load_dwordx4 v[230:233], v[204:205], off
	global_load_dwordx4 v[234:237], v[204:205], off offset:256
	s_mov_b64 s[26:27], 0x10000
	v_lshl_add_u64 v[204:205], v[204:205], 0, s[26:27]
	global_load_dwordx4 v[238:241], v[204:205], off
	global_load_dwordx4 v[242:245], v[204:205], off offset:256
	s_mov_b64 s[26:27], 0x10000
	v_lshl_add_u64 v[204:205], v[204:205], 0, s[26:27]
	global_load_dwordx4 v[246:249], v[204:205], off
	global_load_dwordx4 v[250:253], v[204:205], off offset:256
	v_cmp_lt_i32_e32 vcc, v207, v202
	s_waitcnt vmcnt(15)
	s_nop 1
	v_mov_b64_e32 v[166:167], v[170:171]
	v_mov_b64_e32 v[168:169], v[172:173]
	v_lshlrev_b32_e32 v148, 16, v166
	v_and_b32_e32 v149, 0xffff0000, v166
	v_lshlrev_b32_e32 v150, 16, v167
	v_and_b32_e32 v151, 0xffff0000, v167
	v_lshlrev_b32_e32 v166, 16, v168
	v_and_b32_e32 v167, 0xffff0000, v168
	v_lshlrev_b32_e32 v168, 16, v169
	v_and_b32_e32 v169, 0xffff0000, v169
	v_pk_add_f32 v[150:151], v[124:125], v[150:151]
	v_pk_add_f32 v[148:149], v[122:123], v[148:149]
	v_pk_add_f32 v[126:127], v[126:127], v[166:167]
	v_cvt_pk_bf16_f32 v122, v148, v149
	v_cvt_pk_bf16_f32 v123, v150, v151
	v_lshl_add_u64 v[166:167], s[96:97], 0, v[162:163]
	v_pk_add_f32 v[128:129], v[128:129], v[168:169]
	v_cvt_pk_bf16_f32 v124, v126, v127
	v_or_b32_e32 v162, 0x100, v162
	v_cvt_pk_bf16_f32 v125, v128, v129
	global_store_dwordx4 v[166:167], v[122:125], off
	s_nop 1
	v_mul_f32_e32 v122, v149, v149
	v_mul_f32_e32 v123, v151, v151
	v_fmac_f32_e32 v122, v148, v148
	v_fmac_f32_e32 v123, v150, v150
	v_add_f32_e32 v122, v122, v123
	v_mul_f32_e32 v123, v127, v127
	v_mul_f32_e32 v124, v129, v129
	v_fmac_f32_e32 v123, v126, v126
	v_fmac_f32_e32 v124, v128, v128
	v_add_f32_e32 v123, v123, v124
	v_add_f32_e32 v148, v122, v123
	v_lshl_add_u64 v[122:123], s[0:1], 0, v[162:163]
	s_waitcnt vmcnt(15)
	s_nop 1
	v_mov_b64_e32 v[122:123], v[174:175]
	v_mov_b64_e32 v[124:125], v[176:177]
	v_lshlrev_b32_e32 v126, 16, v122
	v_and_b32_e32 v127, 0xffff0000, v122
	v_lshlrev_b32_e32 v122, 16, v123
	v_and_b32_e32 v123, 0xffff0000, v123
	v_lshlrev_b32_e32 v128, 16, v124
	v_and_b32_e32 v129, 0xffff0000, v124
	v_lshlrev_b32_e32 v124, 16, v125
	v_and_b32_e32 v125, 0xffff0000, v125
	v_pk_add_f32 v[120:121], v[120:121], v[122:123]
	v_pk_add_f32 v[118:119], v[118:119], v[126:127]
	v_pk_add_f32 v[122:123], v[116:117], v[124:125]
	v_pk_add_f32 v[124:125], v[114:115], v[128:129]
	v_cvt_pk_bf16_f32 v114, v118, v119
	v_cvt_pk_bf16_f32 v115, v120, v121
	v_lshl_add_u64 v[126:127], s[96:97], 0, v[162:163]
	v_cvt_pk_bf16_f32 v116, v124, v125
	v_cvt_pk_bf16_f32 v117, v122, v123
	global_store_dwordx4 v[126:127], v[114:117], off
	s_nop 1
	v_mul_f32_e32 v114, v119, v119
	v_mul_f32_e32 v115, v121, v121
	v_fmac_f32_e32 v114, v118, v118
	v_fmac_f32_e32 v115, v120, v120
	v_add_f32_e32 v114, v114, v115
	v_mul_f32_e32 v115, v125, v125
	v_mul_f32_e32 v116, v123, v123
	v_fmac_f32_e32 v115, v124, v124
	v_fmac_f32_e32 v116, v122, v122
	v_add_f32_e32 v115, v115, v116
	v_add_f32_e32 v114, v114, v115
	v_cndmask_b32_e32 v115, v200, v207, vcc
	v_add_f32_e32 v114, v148, v114
	v_lshlrev_b32_e32 v118, 2, v115
	ds_bpermute_b32 v115, v118, v114
	v_cmp_lt_i32_e32 vcc, v208, v202
	s_waitcnt lgkmcnt(0)
	v_add_f32_e32 v114, v114, v115
	v_cndmask_b32_e32 v115, v200, v208, vcc
	v_lshlrev_b32_e32 v119, 2, v115
	ds_bpermute_b32 v115, v119, v114
	s_and_saveexec_b64 s[26:27], s[6:7]
	s_cbranch_execz .LBB0_61
	s_waitcnt lgkmcnt(0)
	v_add_f32_e32 v114, v114, v115
	v_mul_f32_e32 v114, 0x49800000, v114
	v_trunc_f32_e32 v114, v114
	v_mul_f32_e32 v115, 0x2f800000, v114
	v_floor_f32_e32 v115, v115
	v_fmac_f32_e32 v114, 0xcf800000, v115
	v_cvt_u32_f32_e32 v114, v114
	v_cvt_u32_f32_e32 v115, v115
	v_lshl_add_u64 v[116:117], v[160:161], 3, s[10:11]
	global_atomic_add_x2 v[116:117], v[114:115], off
; __device__ __forceinline__ void ss_add(ss_t* p, float v) { (void)__hip_atomic_fetch_add(p, (ss_t)(v * 1048576.0f), __ATOMIC_RELAXED, __HIP_MEMORY_SCOPE_AGENT); }
; __device__ __forceinline__ unsigned cvt_pk_bf16(float lo, float hi) { unsigned r; asm volatile("v_cvt_pk_bf16_f32 %0, %1, %2" : "=v"(r) : "v"(lo), "v"(hi)); return r; }
; __device__ __forceinline__ float bflo(unsigned w) { return __uint_as_float(w << 16); }
; __device__ __forceinline__ float bfhi(unsigned w) { return __uint_as_float(w & 0xffff0000u); }
;     __device__ __forceinline__ void operator()(const f32x4 (&acc)[2][2][4][2], const Unit& u, int wr, int wc, int fr, int fq) const {
;     ...
;             for (int m = 0; m < 4; ++m) { const int row = row0 + ai * 128 + m * 16; const size_t off = (size_t)row * D + col0; float sq = 0.f;
; #pragma unroll
;                 for (int bj = 0; bj < 2; ++bj) { const size_t o = off + bj * 128; f32x4 b0, b1;
;                     if (XF32) { b0 = *(const f32x4*)((const float*)base + o); b1 = *(const f32x4*)((const float*)base + o + 4); }
;                     else { const u32x4 hw = *(const u32x4*)((const bf16_t*)base + o); b0 = (f32x4){bflo(hw.x), bfhi(hw.x), bflo(hw.y), bfhi(hw.y)}; b1 = (f32x4){bflo(hw.z), bfhi(hw.z), bflo(hw.w), bfhi(hw.w)}; }
;                     const f32x4 r0 = b0 + acc[ai][bj][m][0], r1 = b1 + acc[ai][bj][m][1];
;                     u32x4 hb; hb.x = cvt_pk_bf16(r0[0], r0[1]); hb.y = cvt_pk_bf16(r0[2], r0[3]); hb.z = cvt_pk_bf16(r1[0], r1[1]); hb.w = cvt_pk_bf16(r1[2], r1[3]); *(u32x4*)(HB + o) = hb;
;                     sq += ((r0[0] * r0[0] + r0[1] * r0[1]) + (r0[2] * r0[2] + r0[3] * r0[3])) + ((r1[0] * r1[0] + r1[1] * r1[1]) + (r1[2] * r1[2] + r1[3] * r1[3])); }
;                 sq += __shfl_xor(sq, 16); sq += __shfl_xor(sq, 32);
;                 if (fq == 0) ss_add(SS + row, sq);
.LBB0_61:
	s_or_b64 exec, exec, s[26:27]
	v_or_b32_e32 v114, 16, v160
	s_waitcnt lgkmcnt(0)
	v_ashrrev_i32_e32 v115, 31, v114
	v_lshlrev_b64 v[116:117], 11, v[114:115]
	v_lshl_add_u64 v[116:117], v[116:117], 0, v[158:159]
	v_lshlrev_b64 v[116:117], 1, v[116:117]
	v_lshl_add_u64 v[120:121], s[0:1], 0, v[116:117]
	s_waitcnt vmcnt(16)
	s_nop 1
	v_mov_b64_e32 v[120:121], v[178:179]
	v_mov_b64_e32 v[122:123], v[180:181]
	v_lshlrev_b32_e32 v124, 16, v120
	v_and_b32_e32 v125, 0xffff0000, v120
	v_lshlrev_b32_e32 v120, 16, v121
	v_and_b32_e32 v121, 0xffff0000, v121
	v_lshlrev_b32_e32 v126, 16, v122
	v_and_b32_e32 v127, 0xffff0000, v122
	v_lshlrev_b32_e32 v122, 16, v123
	v_and_b32_e32 v123, 0xffff0000, v123
	v_pk_add_f32 v[112:113], v[112:113], v[120:121]
	v_pk_add_f32 v[110:111], v[110:111], v[124:125]
	v_pk_add_f32 v[120:121], v[108:109], v[122:123]
	v_pk_add_f32 v[122:123], v[106:107], v[126:127]
	v_cvt_pk_bf16_f32 v106, v110, v111
	v_cvt_pk_bf16_f32 v107, v112, v113
	v_lshl_add_u64 v[124:125], s[96:97], 0, v[116:117]
	v_cvt_pk_bf16_f32 v108, v122, v123
	v_cvt_pk_bf16_f32 v109, v120, v121
	global_store_dwordx4 v[124:125], v[106:109], off
	v_or_b32_e32 v116, 0x100, v116
	s_nop 0
	v_mul_f32_e32 v106, v111, v111
	v_mul_f32_e32 v107, v113, v113
	v_fmac_f32_e32 v106, v110, v110
	v_fmac_f32_e32 v107, v112, v112
	v_add_f32_e32 v106, v106, v107
	v_mul_f32_e32 v107, v123, v123
	v_mul_f32_e32 v108, v121, v121
	v_fmac_f32_e32 v107, v122, v122
	v_fmac_f32_e32 v108, v120, v120
	v_add_f32_e32 v107, v107, v108
	v_add_f32_e32 v120, v106, v107
	v_lshl_add_u64 v[106:107], s[0:1], 0, v[116:117]
	s_waitcnt vmcnt(16)
	s_nop 1
	v_mov_b64_e32 v[106:107], v[182:183]
	v_mov_b64_e32 v[108:109], v[184:185]
	v_lshlrev_b32_e32 v110, 16, v106
	v_and_b32_e32 v111, 0xffff0000, v106
	v_lshlrev_b32_e32 v106, 16, v107
	v_and_b32_e32 v107, 0xffff0000, v107
	v_lshlrev_b32_e32 v112, 16, v108
	v_and_b32_e32 v113, 0xffff0000, v108
	v_lshlrev_b32_e32 v108, 16, v109
	v_and_b32_e32 v109, 0xffff0000, v109
	v_pk_add_f32 v[104:105], v[104:105], v[106:107]
	v_pk_add_f32 v[102:103], v[102:103], v[110:111]
	v_pk_add_f32 v[106:107], v[100:101], v[108:109]
	v_pk_add_f32 v[108:109], v[98:99], v[112:113]
	v_cvt_pk_bf16_f32 v98, v102, v103
	v_cvt_pk_bf16_f32 v99, v104, v105
	v_lshl_add_u64 v[110:111], s[96:97], 0, v[116:117]
	v_cvt_pk_bf16_f32 v100, v108, v109
	v_cvt_pk_bf16_f32 v101, v106, v107
	global_store_dwordx4 v[110:111], v[98:101], off
	s_nop 1
	v_mul_f32_e32 v98, v103, v103
	v_mul_f32_e32 v99, v105, v105
	v_fmac_f32_e32 v98, v102, v102
	v_fmac_f32_e32 v99, v104, v104
	v_add_f32_e32 v98, v98, v99
	v_mul_f32_e32 v99, v109, v109
	v_mul_f32_e32 v100, v107, v107
	v_fmac_f32_e32 v99, v108, v108
	v_fmac_f32_e32 v100, v106, v106
	v_add_f32_e32 v99, v99, v100
	v_add_f32_e32 v98, v98, v99
	v_add_f32_e32 v98, v120, v98
	ds_bpermute_b32 v99, v118, v98
	s_waitcnt lgkmcnt(0)
	v_add_f32_e32 v98, v98, v99
	ds_bpermute_b32 v99, v119, v98
	s_and_saveexec_b64 s[26:27], s[6:7]
	s_cbranch_execz .LBB0_63
	s_waitcnt lgkmcnt(0)
	v_add_f32_e32 v98, v98, v99
	v_mul_f32_e32 v98, 0x49800000, v98
	v_trunc_f32_e32 v98, v98
	v_mul_f32_e32 v99, 0x2f800000, v98
	v_floor_f32_e32 v99, v99
	v_fmac_f32_e32 v98, 0xcf800000, v99
	v_cvt_u32_f32_e32 v98, v98
	v_cvt_u32_f32_e32 v99, v99
	v_lshl_add_u64 v[100:101], v[114:115], 3, s[10:11]
	global_atomic_add_x2 v[100:101], v[98:99], off
.LBB0_63:
	s_or_b64 exec, exec, s[26:27]
	v_or_b32_e32 v98, 32, v160
	s_waitcnt lgkmcnt(0)
	v_ashrrev_i32_e32 v99, 31, v98
	v_lshlrev_b64 v[100:101], 11, v[98:99]
	v_lshl_add_u64 v[100:101], v[100:101], 0, v[158:159]
	v_lshlrev_b64 v[100:101], 1, v[100:101]
	v_lshl_add_u64 v[102:103], s[0:1], 0, v[100:101]
	s_waitcnt vmcnt(17)
	s_nop 1
	v_mov_b64_e32 v[102:103], v[186:187]
	v_mov_b64_e32 v[104:105], v[188:189]
	v_lshlrev_b32_e32 v106, 16, v102
	v_and_b32_e32 v107, 0xffff0000, v102
	v_lshlrev_b32_e32 v102, 16, v103
	v_and_b32_e32 v103, 0xffff0000, v103
	v_lshlrev_b32_e32 v108, 16, v104
	v_and_b32_e32 v109, 0xffff0000, v104
	v_lshlrev_b32_e32 v104, 16, v105
	v_and_b32_e32 v105, 0xffff0000, v105
	v_pk_add_f32 v[96:97], v[96:97], v[102:103]
	v_pk_add_f32 v[94:95], v[94:95], v[106:107]
	v_pk_add_f32 v[102:103], v[92:93], v[104:105]
	v_pk_add_f32 v[104:105], v[90:91], v[108:109]
	v_cvt_pk_bf16_f32 v90, v94, v95
	v_cvt_pk_bf16_f32 v91, v96, v97
	v_lshl_add_u64 v[106:107], s[96:97], 0, v[100:101]
	v_cvt_pk_bf16_f32 v92, v104, v105
	v_cvt_pk_bf16_f32 v93, v102, v103
	global_store_dwordx4 v[106:107], v[90:93], off
	v_or_b32_e32 v100, 0x100, v100
	s_nop 0
	v_mul_f32_e32 v90, v95, v95
	v_mul_f32_e32 v91, v97, v97
	v_fmac_f32_e32 v90, v94, v94
	v_fmac_f32_e32 v91, v96, v96
	v_add_f32_e32 v90, v90, v91
	v_mul_f32_e32 v91, v105, v105
	v_mul_f32_e32 v92, v103, v103
	v_fmac_f32_e32 v91, v104, v104
	v_fmac_f32_e32 v92, v102, v102
	v_add_f32_e32 v91, v91, v92
	v_add_f32_e32 v102, v90, v91
	v_lshl_add_u64 v[90:91], s[0:1], 0, v[100:101]
	s_waitcnt vmcnt(17)
	s_nop 1
	v_mov_b64_e32 v[90:91], v[190:191]
	v_mov_b64_e32 v[92:93], v[192:193]
	v_lshlrev_b32_e32 v94, 16, v90
	v_and_b32_e32 v95, 0xffff0000, v90
	v_lshlrev_b32_e32 v90, 16, v91
	v_and_b32_e32 v91, 0xffff0000, v91
	v_lshlrev_b32_e32 v96, 16, v92
	v_and_b32_e32 v97, 0xffff0000, v92
	v_lshlrev_b32_e32 v92, 16, v93
	v_and_b32_e32 v93, 0xffff0000, v93
	v_pk_add_f32 v[88:89], v[88:89], v[90:91]
	v_pk_add_f32 v[86:87], v[86:87], v[94:95]
	v_pk_add_f32 v[90:91], v[84:85], v[92:93]
	v_pk_add_f32 v[92:93], v[82:83], v[96:97]
	v_cvt_pk_bf16_f32 v82, v86, v87
	v_cvt_pk_bf16_f32 v83, v88, v89
	v_lshl_add_u64 v[94:95], s[96:97], 0, v[100:101]
	v_cvt_pk_bf16_f32 v84, v92, v93
	v_cvt_pk_bf16_f32 v85, v90, v91
	global_store_dwordx4 v[94:95], v[82:85], off
	s_nop 1
	v_mul_f32_e32 v82, v87, v87
	v_mul_f32_e32 v83, v89, v89
	v_fmac_f32_e32 v82, v86, v86
	v_fmac_f32_e32 v83, v88, v88
	v_add_f32_e32 v82, v82, v83
	v_mul_f32_e32 v83, v93, v93
	v_mul_f32_e32 v84, v91, v91
	v_fmac_f32_e32 v83, v92, v92
	v_fmac_f32_e32 v84, v90, v90
	v_add_f32_e32 v83, v83, v84
	v_add_f32_e32 v82, v82, v83
	v_add_f32_e32 v82, v102, v82
	ds_bpermute_b32 v83, v118, v82
	s_waitcnt lgkmcnt(0)
	v_add_f32_e32 v82, v82, v83
	ds_bpermute_b32 v83, v119, v82
	s_and_saveexec_b64 s[26:27], s[6:7]
	s_cbranch_execz .LBB0_65
	s_waitcnt lgkmcnt(0)
	v_add_f32_e32 v82, v82, v83
	v_mul_f32_e32 v82, 0x49800000, v82
	v_trunc_f32_e32 v82, v82
	v_mul_f32_e32 v83, 0x2f800000, v82
	v_floor_f32_e32 v83, v83
	v_fmac_f32_e32 v82, 0xcf800000, v83
	v_cvt_u32_f32_e32 v82, v82
	v_cvt_u32_f32_e32 v83, v83
	v_lshl_add_u64 v[84:85], v[98:99], 3, s[10:11]
	global_atomic_add_x2 v[84:85], v[82:83], off
; __device__ __forceinline__ void ss_add(ss_t* p, float v) { (void)__hip_atomic_fetch_add(p, (ss_t)(v * 1048576.0f), __ATOMIC_RELAXED, __HIP_MEMORY_SCOPE_AGENT); }
; __device__ __forceinline__ unsigned cvt_pk_bf16(float lo, float hi) { unsigned r; asm volatile("v_cvt_pk_bf16_f32 %0, %1, %2" : "=v"(r) : "v"(lo), "v"(hi)); return r; }
; __device__ __forceinline__ float bflo(unsigned w) { return __uint_as_float(w << 16); }
; __device__ __forceinline__ float bfhi(unsigned w) { return __uint_as_float(w & 0xffff0000u); }
;     __device__ __forceinline__ void operator()(const f32x4 (&acc)[2][2][4][2], const Unit& u, int wr, int wc, int fr, int fq) const {
;     ...
;             for (int m = 0; m < 4; ++m) { const int row = row0 + ai * 128 + m * 16; const size_t off = (size_t)row * D + col0; float sq = 0.f;
; #pragma unroll
;                 for (int bj = 0; bj < 2; ++bj) { const size_t o = off + bj * 128; f32x4 b0, b1;
;                     if (XF32) { b0 = *(const f32x4*)((const float*)base + o); b1 = *(const f32x4*)((const float*)base + o + 4); }
;                     else { const u32x4 hw = *(const u32x4*)((const bf16_t*)base + o); b0 = (f32x4){bflo(hw.x), bfhi(hw.x), bflo(hw.y), bfhi(hw.y)}; b1 = (f32x4){bflo(hw.z), bfhi(hw.z), bflo(hw.w), bfhi(hw.w)}; }
;                     const f32x4 r0 = b0 + acc[ai][bj][m][0], r1 = b1 + acc[ai][bj][m][1];
;                     u32x4 hb; hb.x = cvt_pk_bf16(r0[0], r0[1]); hb.y = cvt_pk_bf16(r0[2], r0[3]); hb.z = cvt_pk_bf16(r1[0], r1[1]); hb.w = cvt_pk_bf16(r1[2], r1[3]); *(u32x4*)(HB + o) = hb;
;                     sq += ((r0[0] * r0[0] + r0[1] * r0[1]) + (r0[2] * r0[2] + r0[3] * r0[3])) + ((r1[0] * r1[0] + r1[1] * r1[1]) + (r1[2] * r1[2] + r1[3] * r1[3])); }
;                 sq += __shfl_xor(sq, 16); sq += __shfl_xor(sq, 32);
;                 if (fq == 0) ss_add(SS + row, sq);
.LBB0_65:
	s_or_b64 exec, exec, s[26:27]
	v_or_b32_e32 v82, 48, v160
	s_waitcnt lgkmcnt(0)
	v_ashrrev_i32_e32 v83, 31, v82
	v_lshlrev_b64 v[84:85], 11, v[82:83]
	v_lshl_add_u64 v[84:85], v[84:85], 0, v[158:159]
	v_lshlrev_b64 v[84:85], 1, v[84:85]
	v_lshl_add_u64 v[86:87], s[0:1], 0, v[84:85]
	s_waitcnt vmcnt(18)
	s_nop 1
	v_mov_b64_e32 v[86:87], v[214:215]
	v_mov_b64_e32 v[88:89], v[216:217]
	v_lshlrev_b32_e32 v90, 16, v86
	v_and_b32_e32 v91, 0xffff0000, v86
	v_lshlrev_b32_e32 v86, 16, v87
	v_and_b32_e32 v87, 0xffff0000, v87
	v_lshlrev_b32_e32 v92, 16, v88
	v_and_b32_e32 v93, 0xffff0000, v88
	v_lshlrev_b32_e32 v88, 16, v89
	v_and_b32_e32 v89, 0xffff0000, v89
	v_pk_add_f32 v[80:81], v[80:81], v[86:87]
	v_pk_add_f32 v[78:79], v[78:79], v[90:91]
	v_pk_add_f32 v[86:87], v[76:77], v[88:89]
	v_pk_add_f32 v[88:89], v[74:75], v[92:93]
	v_cvt_pk_bf16_f32 v74, v78, v79
	v_cvt_pk_bf16_f32 v75, v80, v81
	v_lshl_add_u64 v[90:91], s[96:97], 0, v[84:85]
	v_cvt_pk_bf16_f32 v76, v88, v89
	v_cvt_pk_bf16_f32 v77, v86, v87
	global_store_dwordx4 v[90:91], v[74:77], off
	v_or_b32_e32 v84, 0x100, v84
	s_nop 0
	v_mul_f32_e32 v74, v79, v79
	v_mul_f32_e32 v75, v81, v81
	v_fmac_f32_e32 v74, v78, v78
	v_fmac_f32_e32 v75, v80, v80
	v_add_f32_e32 v74, v74, v75
	v_mul_f32_e32 v75, v89, v89
	v_mul_f32_e32 v76, v87, v87
	v_fmac_f32_e32 v75, v88, v88
	v_fmac_f32_e32 v76, v86, v86
	v_add_f32_e32 v75, v75, v76
	v_add_f32_e32 v86, v74, v75
	v_lshl_add_u64 v[74:75], s[0:1], 0, v[84:85]
	s_waitcnt vmcnt(18)
	s_nop 1
	v_mov_b64_e32 v[74:75], v[218:219]
	v_mov_b64_e32 v[76:77], v[220:221]
	v_lshlrev_b32_e32 v78, 16, v74
	v_and_b32_e32 v79, 0xffff0000, v74
	v_lshlrev_b32_e32 v74, 16, v75
	v_and_b32_e32 v75, 0xffff0000, v75
	v_lshlrev_b32_e32 v80, 16, v76
	v_and_b32_e32 v81, 0xffff0000, v76
	v_lshlrev_b32_e32 v76, 16, v77
	v_and_b32_e32 v77, 0xffff0000, v77
	v_pk_add_f32 v[72:73], v[72:73], v[74:75]
	v_pk_add_f32 v[70:71], v[70:71], v[78:79]
	v_pk_add_f32 v[74:75], v[68:69], v[76:77]
	v_pk_add_f32 v[76:77], v[66:67], v[80:81]
	v_cvt_pk_bf16_f32 v66, v70, v71
	v_cvt_pk_bf16_f32 v67, v72, v73
	v_lshl_add_u64 v[78:79], s[96:97], 0, v[84:85]
	v_cvt_pk_bf16_f32 v68, v76, v77
	v_cvt_pk_bf16_f32 v69, v74, v75
	global_store_dwordx4 v[78:79], v[66:69], off
	s_nop 1
	v_mul_f32_e32 v66, v71, v71
	v_mul_f32_e32 v67, v73, v73
	v_fmac_f32_e32 v66, v70, v70
	v_fmac_f32_e32 v67, v72, v72
	v_add_f32_e32 v66, v66, v67
	v_mul_f32_e32 v67, v77, v77
	v_mul_f32_e32 v68, v75, v75
	v_fmac_f32_e32 v67, v76, v76
	v_fmac_f32_e32 v68, v74, v74
	v_add_f32_e32 v67, v67, v68
	v_add_f32_e32 v66, v66, v67
	v_add_f32_e32 v66, v86, v66
	ds_bpermute_b32 v67, v118, v66
	s_waitcnt lgkmcnt(0)
	v_add_f32_e32 v66, v66, v67
	ds_bpermute_b32 v67, v119, v66
	s_and_saveexec_b64 s[26:27], s[6:7]
	s_cbranch_execz .LBB0_67
	s_waitcnt lgkmcnt(0)
	v_add_f32_e32 v66, v66, v67
	v_mul_f32_e32 v66, 0x49800000, v66
	v_trunc_f32_e32 v66, v66
	v_mul_f32_e32 v67, 0x2f800000, v66
	v_floor_f32_e32 v67, v67
	v_fmac_f32_e32 v66, 0xcf800000, v67
	v_cvt_u32_f32_e32 v66, v66
	v_cvt_u32_f32_e32 v67, v67
	v_lshl_add_u64 v[68:69], v[82:83], 3, s[10:11]
	global_atomic_add_x2 v[68:69], v[66:67], off
.LBB0_67:
	s_or_b64 exec, exec, s[26:27]
	v_add_u32_e32 v66, 0x80, v160
	s_waitcnt lgkmcnt(0)
	v_ashrrev_i32_e32 v67, 31, v66
	v_lshlrev_b64 v[68:69], 11, v[66:67]
	v_lshl_add_u64 v[68:69], v[68:69], 0, v[158:159]
	v_lshlrev_b64 v[68:69], 1, v[68:69]
	v_lshl_add_u64 v[70:71], s[0:1], 0, v[68:69]
	s_waitcnt vmcnt(19)
	s_nop 1
	v_mov_b64_e32 v[70:71], v[222:223]
	v_mov_b64_e32 v[72:73], v[224:225]
	v_lshlrev_b32_e32 v74, 16, v70
	v_and_b32_e32 v75, 0xffff0000, v70
	v_lshlrev_b32_e32 v70, 16, v71
	v_and_b32_e32 v71, 0xffff0000, v71
	v_lshlrev_b32_e32 v76, 16, v72
	v_and_b32_e32 v77, 0xffff0000, v72
	v_lshlrev_b32_e32 v72, 16, v73
	v_and_b32_e32 v73, 0xffff0000, v73
	v_pk_add_f32 v[64:65], v[64:65], v[70:71]
	v_pk_add_f32 v[62:63], v[62:63], v[74:75]
	v_pk_add_f32 v[70:71], v[60:61], v[72:73]
	v_pk_add_f32 v[72:73], v[58:59], v[76:77]
	v_cvt_pk_bf16_f32 v58, v62, v63
	v_cvt_pk_bf16_f32 v59, v64, v65
	v_lshl_add_u64 v[74:75], s[96:97], 0, v[68:69]
	v_cvt_pk_bf16_f32 v60, v72, v73
	v_cvt_pk_bf16_f32 v61, v70, v71
	global_store_dwordx4 v[74:75], v[58:61], off
	v_or_b32_e32 v68, 0x100, v68
	s_nop 0
	v_mul_f32_e32 v58, v63, v63
	v_mul_f32_e32 v59, v65, v65
	v_fmac_f32_e32 v58, v62, v62
	v_fmac_f32_e32 v59, v64, v64
	v_add_f32_e32 v58, v58, v59
	v_mul_f32_e32 v59, v73, v73
	v_mul_f32_e32 v60, v71, v71
	v_fmac_f32_e32 v59, v72, v72
	v_fmac_f32_e32 v60, v70, v70
	v_add_f32_e32 v59, v59, v60
	v_add_f32_e32 v70, v58, v59
	v_lshl_add_u64 v[58:59], s[0:1], 0, v[68:69]
	s_waitcnt vmcnt(19)
	s_nop 1
	v_mov_b64_e32 v[58:59], v[226:227]
	v_mov_b64_e32 v[60:61], v[228:229]
	v_lshlrev_b32_e32 v62, 16, v58
	v_and_b32_e32 v63, 0xffff0000, v58
	v_lshlrev_b32_e32 v58, 16, v59
	v_and_b32_e32 v59, 0xffff0000, v59
	v_lshlrev_b32_e32 v64, 16, v60
	v_and_b32_e32 v65, 0xffff0000, v60
	v_lshlrev_b32_e32 v60, 16, v61
	v_and_b32_e32 v61, 0xffff0000, v61
	v_pk_add_f32 v[56:57], v[56:57], v[58:59]
	v_pk_add_f32 v[54:55], v[54:55], v[62:63]
	v_pk_add_f32 v[58:59], v[52:53], v[60:61]
	v_pk_add_f32 v[60:61], v[50:51], v[64:65]
	v_cvt_pk_bf16_f32 v50, v54, v55
	v_cvt_pk_bf16_f32 v51, v56, v57
	v_lshl_add_u64 v[62:63], s[96:97], 0, v[68:69]
	v_cvt_pk_bf16_f32 v52, v60, v61
	v_cvt_pk_bf16_f32 v53, v58, v59
	global_store_dwordx4 v[62:63], v[50:53], off
	s_nop 1
	v_mul_f32_e32 v50, v55, v55
	v_mul_f32_e32 v51, v57, v57
	v_fmac_f32_e32 v50, v54, v54
	v_fmac_f32_e32 v51, v56, v56
	v_add_f32_e32 v50, v50, v51
	v_mul_f32_e32 v51, v61, v61
	v_mul_f32_e32 v52, v59, v59
	v_fmac_f32_e32 v51, v60, v60
	v_fmac_f32_e32 v52, v58, v58
	v_add_f32_e32 v51, v51, v52
	v_add_f32_e32 v50, v50, v51
	v_add_f32_e32 v50, v70, v50
	ds_bpermute_b32 v51, v118, v50
	s_waitcnt lgkmcnt(0)
	v_add_f32_e32 v50, v50, v51
	ds_bpermute_b32 v51, v119, v50
	s_and_saveexec_b64 s[26:27], s[6:7]
	s_cbranch_execz .LBB0_69
	s_waitcnt lgkmcnt(0)
	v_add_f32_e32 v50, v50, v51
	v_mul_f32_e32 v50, 0x49800000, v50
	v_trunc_f32_e32 v50, v50
	v_mul_f32_e32 v51, 0x2f800000, v50
	v_floor_f32_e32 v51, v51
	v_fmac_f32_e32 v50, 0xcf800000, v51
	v_cvt_u32_f32_e32 v50, v50
	v_cvt_u32_f32_e32 v51, v51
	v_lshl_add_u64 v[52:53], v[66:67], 3, s[10:11]
	global_atomic_add_x2 v[52:53], v[50:51], off
; __device__ __forceinline__ void ss_add(ss_t* p, float v) { (void)__hip_atomic_fetch_add(p, (ss_t)(v * 1048576.0f), __ATOMIC_RELAXED, __HIP_MEMORY_SCOPE_AGENT); }
; __device__ __forceinline__ unsigned cvt_pk_bf16(float lo, float hi) { unsigned r; asm volatile("v_cvt_pk_bf16_f32 %0, %1, %2" : "=v"(r) : "v"(lo), "v"(hi)); return r; }
; __device__ __forceinline__ float bflo(unsigned w) { return __uint_as_float(w << 16); }
; __device__ __forceinline__ float bfhi(unsigned w) { return __uint_as_float(w & 0xffff0000u); }
;     __device__ __forceinline__ void operator()(const f32x4 (&acc)[2][2][4][2], const Unit& u, int wr, int wc, int fr, int fq) const {
;     ...
;             for (int m = 0; m < 4; ++m) { const int row = row0 + ai * 128 + m * 16; const size_t off = (size_t)row * D + col0; float sq = 0.f;
; #pragma unroll
;                 for (int bj = 0; bj < 2; ++bj) { const size_t o = off + bj * 128; f32x4 b0, b1;
;                     if (XF32) { b0 = *(const f32x4*)((const float*)base + o); b1 = *(const f32x4*)((const float*)base + o + 4); }
;                     else { const u32x4 hw = *(const u32x4*)((const bf16_t*)base + o); b0 = (f32x4){bflo(hw.x), bfhi(hw.x), bflo(hw.y), bfhi(hw.y)}; b1 = (f32x4){bflo(hw.z), bfhi(hw.z), bflo(hw.w), bfhi(hw.w)}; }
;                     const f32x4 r0 = b0 + acc[ai][bj][m][0], r1 = b1 + acc[ai][bj][m][1];
;                     u32x4 hb; hb.x = cvt_pk_bf16(r0[0], r0[1]); hb.y = cvt_pk_bf16(r0[2], r0[3]); hb.z = cvt_pk_bf16(r1[0], r1[1]); hb.w = cvt_pk_bf16(r1[2], r1[3]); *(u32x4*)(HB + o) = hb;
;                     sq += ((r0[0] * r0[0] + r0[1] * r0[1]) + (r0[2] * r0[2] + r0[3] * r0[3])) + ((r1[0] * r1[0] + r1[1] * r1[1]) + (r1[2] * r1[2] + r1[3] * r1[3])); }
;                 sq += __shfl_xor(sq, 16); sq += __shfl_xor(sq, 32);
;                 if (fq == 0) ss_add(SS + row, sq);
.LBB0_69:
	s_or_b64 exec, exec, s[26:27]
	v_add_u32_e32 v50, 0x90, v160
	s_waitcnt lgkmcnt(0)
	v_ashrrev_i32_e32 v51, 31, v50
	v_lshlrev_b64 v[52:53], 11, v[50:51]
	v_lshl_add_u64 v[52:53], v[52:53], 0, v[158:159]
	v_lshlrev_b64 v[52:53], 1, v[52:53]
	v_lshl_add_u64 v[54:55], s[0:1], 0, v[52:53]
	s_waitcnt vmcnt(20)
	s_nop 1
	v_mov_b64_e32 v[54:55], v[230:231]
	v_mov_b64_e32 v[56:57], v[232:233]
	v_lshlrev_b32_e32 v58, 16, v54
	v_and_b32_e32 v59, 0xffff0000, v54
	v_lshlrev_b32_e32 v54, 16, v55
	v_and_b32_e32 v55, 0xffff0000, v55
	v_lshlrev_b32_e32 v60, 16, v56
	v_and_b32_e32 v61, 0xffff0000, v56
	v_lshlrev_b32_e32 v56, 16, v57
	v_and_b32_e32 v57, 0xffff0000, v57
	v_pk_add_f32 v[48:49], v[48:49], v[54:55]
	v_pk_add_f32 v[46:47], v[46:47], v[58:59]
	v_pk_add_f32 v[54:55], v[44:45], v[56:57]
	v_pk_add_f32 v[56:57], v[42:43], v[60:61]
	v_cvt_pk_bf16_f32 v42, v46, v47
	v_cvt_pk_bf16_f32 v43, v48, v49
	v_lshl_add_u64 v[58:59], s[96:97], 0, v[52:53]
	v_cvt_pk_bf16_f32 v44, v56, v57
	v_cvt_pk_bf16_f32 v45, v54, v55
	global_store_dwordx4 v[58:59], v[42:45], off
	v_or_b32_e32 v52, 0x100, v52
	s_nop 0
	v_mul_f32_e32 v42, v47, v47
	v_mul_f32_e32 v43, v49, v49
	v_fmac_f32_e32 v42, v46, v46
	v_fmac_f32_e32 v43, v48, v48
	v_add_f32_e32 v42, v42, v43
	v_mul_f32_e32 v43, v57, v57
	v_mul_f32_e32 v44, v55, v55
	v_fmac_f32_e32 v43, v56, v56
	v_fmac_f32_e32 v44, v54, v54
	v_add_f32_e32 v43, v43, v44
	v_add_f32_e32 v54, v42, v43
	v_lshl_add_u64 v[42:43], s[0:1], 0, v[52:53]
	s_waitcnt vmcnt(20)
	s_nop 1
	v_mov_b64_e32 v[42:43], v[234:235]
	v_mov_b64_e32 v[44:45], v[236:237]
	v_lshlrev_b32_e32 v46, 16, v42
	v_and_b32_e32 v47, 0xffff0000, v42
	v_lshlrev_b32_e32 v42, 16, v43
	v_and_b32_e32 v43, 0xffff0000, v43
	v_lshlrev_b32_e32 v48, 16, v44
	v_and_b32_e32 v49, 0xffff0000, v44
	v_lshlrev_b32_e32 v44, 16, v45
	v_and_b32_e32 v45, 0xffff0000, v45
	v_pk_add_f32 v[40:41], v[40:41], v[42:43]
	v_pk_add_f32 v[38:39], v[38:39], v[46:47]
	v_pk_add_f32 v[42:43], v[36:37], v[44:45]
	v_pk_add_f32 v[44:45], v[34:35], v[48:49]
	v_cvt_pk_bf16_f32 v34, v38, v39
	v_cvt_pk_bf16_f32 v35, v40, v41
	v_lshl_add_u64 v[46:47], s[96:97], 0, v[52:53]
	v_cvt_pk_bf16_f32 v36, v44, v45
	v_cvt_pk_bf16_f32 v37, v42, v43
	global_store_dwordx4 v[46:47], v[34:37], off
	s_nop 1
	v_mul_f32_e32 v34, v39, v39
	v_mul_f32_e32 v35, v41, v41
	v_fmac_f32_e32 v34, v38, v38
	v_fmac_f32_e32 v35, v40, v40
	v_add_f32_e32 v34, v34, v35
	v_mul_f32_e32 v35, v45, v45
	v_mul_f32_e32 v36, v43, v43
	v_fmac_f32_e32 v35, v44, v44
	v_fmac_f32_e32 v36, v42, v42
	v_add_f32_e32 v35, v35, v36
	v_add_f32_e32 v34, v34, v35
	v_add_f32_e32 v34, v54, v34
	ds_bpermute_b32 v35, v118, v34
	s_waitcnt lgkmcnt(0)
	v_add_f32_e32 v34, v34, v35
	ds_bpermute_b32 v35, v119, v34
	s_and_saveexec_b64 s[26:27], s[6:7]
	s_cbranch_execz .LBB0_71
	s_waitcnt lgkmcnt(0)
	v_add_f32_e32 v34, v34, v35
	v_mul_f32_e32 v34, 0x49800000, v34
	v_trunc_f32_e32 v34, v34
	v_mul_f32_e32 v35, 0x2f800000, v34
	v_floor_f32_e32 v35, v35
	v_fmac_f32_e32 v34, 0xcf800000, v35
	v_cvt_u32_f32_e32 v34, v34
	v_cvt_u32_f32_e32 v35, v35
	v_lshl_add_u64 v[36:37], v[50:51], 3, s[10:11]
	global_atomic_add_x2 v[36:37], v[34:35], off
; __device__ __forceinline__ void ss_add(ss_t* p, float v) { (void)__hip_atomic_fetch_add(p, (ss_t)(v * 1048576.0f), __ATOMIC_RELAXED, __HIP_MEMORY_SCOPE_AGENT); }
; __device__ __forceinline__ unsigned cvt_pk_bf16(float lo, float hi) { unsigned r; asm volatile("v_cvt_pk_bf16_f32 %0, %1, %2" : "=v"(r) : "v"(lo), "v"(hi)); return r; }
; __device__ __forceinline__ float bflo(unsigned w) { return __uint_as_float(w << 16); }
; __device__ __forceinline__ float bfhi(unsigned w) { return __uint_as_float(w & 0xffff0000u); }
;     __device__ __forceinline__ void operator()(const f32x4 (&acc)[2][2][4][2], const Unit& u, int wr, int wc, int fr, int fq) const {
;     ...
;             for (int m = 0; m < 4; ++m) { const int row = row0 + ai * 128 + m * 16; const size_t off = (size_t)row * D + col0; float sq = 0.f;
; #pragma unroll
;                 for (int bj = 0; bj < 2; ++bj) { const size_t o = off + bj * 128; f32x4 b0, b1;
;                     if (XF32) { b0 = *(const f32x4*)((const float*)base + o); b1 = *(const f32x4*)((const float*)base + o + 4); }
;                     else { const u32x4 hw = *(const u32x4*)((const bf16_t*)base + o); b0 = (f32x4){bflo(hw.x), bfhi(hw.x), bflo(hw.y), bfhi(hw.y)}; b1 = (f32x4){bflo(hw.z), bfhi(hw.z), bflo(hw.w), bfhi(hw.w)}; }
;                     const f32x4 r0 = b0 + acc[ai][bj][m][0], r1 = b1 + acc[ai][bj][m][1];
;                     u32x4 hb; hb.x = cvt_pk_bf16(r0[0], r0[1]); hb.y = cvt_pk_bf16(r0[2], r0[3]); hb.z = cvt_pk_bf16(r1[0], r1[1]); hb.w = cvt_pk_bf16(r1[2], r1[3]); *(u32x4*)(HB + o) = hb;
;                     sq += ((r0[0] * r0[0] + r0[1] * r0[1]) + (r0[2] * r0[2] + r0[3] * r0[3])) + ((r1[0] * r1[0] + r1[1] * r1[1]) + (r1[2] * r1[2] + r1[3] * r1[3])); }
;                 sq += __shfl_xor(sq, 16); sq += __shfl_xor(sq, 32);
;                 if (fq == 0) ss_add(SS + row, sq);
.LBB0_71:
	s_or_b64 exec, exec, s[26:27]
	v_add_u32_e32 v34, 0xa0, v160
	s_waitcnt lgkmcnt(0)
	v_ashrrev_i32_e32 v35, 31, v34
	v_lshlrev_b64 v[36:37], 11, v[34:35]
	v_lshl_add_u64 v[36:37], v[36:37], 0, v[158:159]
	v_lshlrev_b64 v[36:37], 1, v[36:37]
	v_lshl_add_u64 v[38:39], s[0:1], 0, v[36:37]
	s_waitcnt vmcnt(21)
	s_nop 1
	v_mov_b64_e32 v[38:39], v[238:239]
	v_mov_b64_e32 v[40:41], v[240:241]
	v_lshlrev_b32_e32 v42, 16, v38
	v_and_b32_e32 v43, 0xffff0000, v38
	v_lshlrev_b32_e32 v38, 16, v39
	v_and_b32_e32 v39, 0xffff0000, v39
	v_lshlrev_b32_e32 v44, 16, v40
	v_and_b32_e32 v45, 0xffff0000, v40
	v_lshlrev_b32_e32 v40, 16, v41
	v_and_b32_e32 v41, 0xffff0000, v41
	v_pk_add_f32 v[32:33], v[32:33], v[38:39]
	v_pk_add_f32 v[30:31], v[30:31], v[42:43]
	v_pk_add_f32 v[38:39], v[28:29], v[40:41]
	v_pk_add_f32 v[40:41], v[26:27], v[44:45]
	v_cvt_pk_bf16_f32 v26, v30, v31
	v_cvt_pk_bf16_f32 v27, v32, v33
	v_lshl_add_u64 v[42:43], s[96:97], 0, v[36:37]
	v_cvt_pk_bf16_f32 v28, v40, v41
	v_cvt_pk_bf16_f32 v29, v38, v39
	global_store_dwordx4 v[42:43], v[26:29], off
	v_or_b32_e32 v36, 0x100, v36
	s_nop 0
	v_mul_f32_e32 v26, v31, v31
	v_mul_f32_e32 v27, v33, v33
	v_fmac_f32_e32 v26, v30, v30
	v_fmac_f32_e32 v27, v32, v32
	v_add_f32_e32 v26, v26, v27
	v_mul_f32_e32 v27, v41, v41
	v_mul_f32_e32 v28, v39, v39
	v_fmac_f32_e32 v27, v40, v40
	v_fmac_f32_e32 v28, v38, v38
	v_add_f32_e32 v27, v27, v28
	v_add_f32_e32 v38, v26, v27
	v_lshl_add_u64 v[26:27], s[0:1], 0, v[36:37]
	s_waitcnt vmcnt(21)
	s_nop 1
	v_mov_b64_e32 v[26:27], v[242:243]
	v_mov_b64_e32 v[28:29], v[244:245]
	v_lshlrev_b32_e32 v30, 16, v26
	v_and_b32_e32 v31, 0xffff0000, v26
	v_lshlrev_b32_e32 v26, 16, v27
	v_and_b32_e32 v27, 0xffff0000, v27
	v_lshlrev_b32_e32 v32, 16, v28
	v_and_b32_e32 v33, 0xffff0000, v28
	v_lshlrev_b32_e32 v28, 16, v29
	v_and_b32_e32 v29, 0xffff0000, v29
	v_pk_add_f32 v[24:25], v[24:25], v[26:27]
	v_pk_add_f32 v[22:23], v[22:23], v[30:31]
	v_pk_add_f32 v[26:27], v[20:21], v[28:29]
	v_pk_add_f32 v[28:29], v[18:19], v[32:33]
	v_cvt_pk_bf16_f32 v18, v22, v23
	v_cvt_pk_bf16_f32 v19, v24, v25
	v_lshl_add_u64 v[30:31], s[96:97], 0, v[36:37]
	v_cvt_pk_bf16_f32 v20, v28, v29
	v_cvt_pk_bf16_f32 v21, v26, v27
	global_store_dwordx4 v[30:31], v[18:21], off
	s_nop 1
	v_mul_f32_e32 v18, v23, v23
	v_mul_f32_e32 v19, v25, v25
	v_fmac_f32_e32 v18, v22, v22
	v_fmac_f32_e32 v19, v24, v24
	v_add_f32_e32 v18, v18, v19
	v_mul_f32_e32 v19, v29, v29
	v_mul_f32_e32 v20, v27, v27
	v_fmac_f32_e32 v19, v28, v28
	v_fmac_f32_e32 v20, v26, v26
	v_add_f32_e32 v19, v19, v20
	v_add_f32_e32 v18, v18, v19
	v_add_f32_e32 v18, v38, v18
	ds_bpermute_b32 v19, v118, v18
	s_waitcnt lgkmcnt(0)
	v_add_f32_e32 v18, v18, v19
	ds_bpermute_b32 v19, v119, v18
	s_and_saveexec_b64 s[26:27], s[6:7]
	s_cbranch_execz .LBB0_73
	s_waitcnt lgkmcnt(0)
	v_add_f32_e32 v18, v18, v19
	v_mul_f32_e32 v18, 0x49800000, v18
	v_trunc_f32_e32 v18, v18
	v_mul_f32_e32 v19, 0x2f800000, v18
	v_floor_f32_e32 v19, v19
	v_fmac_f32_e32 v18, 0xcf800000, v19
	v_cvt_u32_f32_e32 v18, v18
	v_cvt_u32_f32_e32 v19, v19
	v_lshl_add_u64 v[20:21], v[34:35], 3, s[10:11]
	global_atomic_add_x2 v[20:21], v[18:19], off
.LBB0_73:
	s_or_b64 exec, exec, s[26:27]
	v_add_u32_e32 v18, 0xb0, v160
	s_waitcnt lgkmcnt(0)
	v_ashrrev_i32_e32 v19, 31, v18
	v_lshlrev_b64 v[20:21], 11, v[18:19]
	v_lshl_add_u64 v[20:21], v[20:21], 0, v[158:159]
	v_lshlrev_b64 v[20:21], 1, v[20:21]
	v_lshl_add_u64 v[22:23], s[0:1], 0, v[20:21]
	s_waitcnt vmcnt(22)
	s_nop 1
	v_mov_b64_e32 v[22:23], v[246:247]
	v_mov_b64_e32 v[24:25], v[248:249]
	v_lshlrev_b32_e32 v26, 16, v22
	v_and_b32_e32 v27, 0xffff0000, v22
	v_lshlrev_b32_e32 v22, 16, v23
	v_and_b32_e32 v23, 0xffff0000, v23
	v_lshlrev_b32_e32 v28, 16, v24
	v_and_b32_e32 v29, 0xffff0000, v24
	v_lshlrev_b32_e32 v24, 16, v25
	v_and_b32_e32 v25, 0xffff0000, v25
	v_pk_add_f32 v[16:17], v[16:17], v[22:23]
	v_pk_add_f32 v[14:15], v[14:15], v[26:27]
	v_pk_add_f32 v[22:23], v[12:13], v[24:25]
	v_pk_add_f32 v[24:25], v[10:11], v[28:29]
	v_cvt_pk_bf16_f32 v10, v14, v15
	v_cvt_pk_bf16_f32 v11, v16, v17
	v_lshl_add_u64 v[26:27], s[96:97], 0, v[20:21]
	v_cvt_pk_bf16_f32 v12, v24, v25
	v_cvt_pk_bf16_f32 v13, v22, v23
	global_store_dwordx4 v[26:27], v[10:13], off
	v_or_b32_e32 v20, 0x100, v20
	s_nop 0
	v_mul_f32_e32 v10, v15, v15
	v_mul_f32_e32 v11, v17, v17
	v_fmac_f32_e32 v10, v14, v14
	v_fmac_f32_e32 v11, v16, v16
	v_add_f32_e32 v10, v10, v11
	v_mul_f32_e32 v11, v25, v25
	v_mul_f32_e32 v12, v23, v23
	v_fmac_f32_e32 v11, v24, v24
	v_fmac_f32_e32 v12, v22, v22
	v_add_f32_e32 v11, v11, v12
	v_add_f32_e32 v22, v10, v11
	v_lshl_add_u64 v[10:11], s[0:1], 0, v[20:21]
	s_waitcnt vmcnt(22)
	s_nop 1
	v_mov_b64_e32 v[10:11], v[250:251]
	v_mov_b64_e32 v[12:13], v[252:253]
	v_lshlrev_b32_e32 v14, 16, v10
	v_and_b32_e32 v15, 0xffff0000, v10
	v_lshlrev_b32_e32 v10, 16, v11
	v_and_b32_e32 v11, 0xffff0000, v11
	v_lshlrev_b32_e32 v16, 16, v12
	v_and_b32_e32 v17, 0xffff0000, v12
	v_lshlrev_b32_e32 v12, 16, v13
	v_and_b32_e32 v13, 0xffff0000, v13
	v_pk_add_f32 v[8:9], v[8:9], v[10:11]
	v_pk_add_f32 v[6:7], v[6:7], v[14:15]
	v_pk_add_f32 v[10:11], v[4:5], v[12:13]
	v_pk_add_f32 v[12:13], v[2:3], v[16:17]
	v_cvt_pk_bf16_f32 v2, v6, v7
	v_cvt_pk_bf16_f32 v3, v8, v9
	v_lshl_add_u64 v[14:15], s[96:97], 0, v[20:21]
	v_cvt_pk_bf16_f32 v4, v12, v13
	v_cvt_pk_bf16_f32 v5, v10, v11
	global_store_dwordx4 v[14:15], v[2:5], off
	s_nop 1
	v_mul_f32_e32 v2, v7, v7
	v_mul_f32_e32 v3, v9, v9
	v_fmac_f32_e32 v2, v6, v6
	v_fmac_f32_e32 v3, v8, v8
	v_add_f32_e32 v2, v2, v3
	v_mul_f32_e32 v3, v13, v13
	v_mul_f32_e32 v4, v11, v11
	v_fmac_f32_e32 v3, v12, v12
	v_fmac_f32_e32 v4, v10, v10
	v_add_f32_e32 v3, v3, v4
	v_add_f32_e32 v2, v2, v3
	v_add_f32_e32 v2, v22, v2
	ds_bpermute_b32 v3, v118, v2
	s_waitcnt lgkmcnt(0)
	v_add_f32_e32 v2, v2, v3
	ds_bpermute_b32 v3, v119, v2
	s_and_saveexec_b64 s[26:27], s[6:7]
	s_cbranch_execz .LBB0_75
	s_waitcnt lgkmcnt(0)
	v_add_f32_e32 v2, v2, v3
	v_mul_f32_e32 v2, 0x49800000, v2
	v_trunc_f32_e32 v2, v2
	v_mul_f32_e32 v3, 0x2f800000, v2
	v_floor_f32_e32 v3, v3
	v_fmac_f32_e32 v2, 0xcf800000, v3
	v_cvt_u32_f32_e32 v2, v2
	v_cvt_u32_f32_e32 v3, v3
	v_lshl_add_u64 v[4:5], v[18:19], 3, s[10:11]
	global_atomic_add_x2 v[4:5], v[2:3], off

; __device__ __forceinline__ void ss_add(ss_t* p, float v) { (void)__hip_atomic_fetch_add(p, (ss_t)(v * 1048576.0f), __ATOMIC_RELAXED, __HIP_MEMORY_SCOPE_AGENT); }
; __device__ __forceinline__ unsigned cvt_pk_bf16(float lo, float hi) { unsigned r; asm volatile("v_cvt_pk_bf16_f32 %0, %1, %2" : "=v"(r) : "v"(lo), "v"(hi)); return r; }
; __device__ __forceinline__ float bflo(unsigned w) { return __uint_as_float(w << 16); }
; __device__ __forceinline__ float bfhi(unsigned w) { return __uint_as_float(w & 0xffff0000u); }
;     __device__ __forceinline__ void operator()(const f32x4 (&acc)[2][2][4][2], const Unit& u, int wr, int wc, int fr, int fq) const {
;         const int row0 = u.pm * 256 + wr * 64 + fr, col0 = u.pn * 256 + wc * 32 + 8 * fq;
; #pragma unroll
;         for (int ai = 0; ai < 2; ++ai)
; #pragma unroll
;             for (int m = 0; m < 4; ++m) { const int row = row0 + ai * 128 + m * 16; const size_t off = (size_t)row * D + col0; float sq = 0.f;
; #pragma unroll
;                 for (int bj = 0; bj < 2; ++bj) { const size_t o = off + bj * 128; f32x4 b0, b1;
;                     if (XF32) { b0 = *(const f32x4*)((const float*)base + o); b1 = *(const f32x4*)((const float*)base + o + 4); }
;                     else { const u32x4 hw = *(const u32x4*)((const bf16_t*)base + o); b0 = (f32x4){bflo(hw.x), bfhi(hw.x), bflo(hw.y), bfhi(hw.y)}; b1 = (f32x4){bflo(hw.z), bfhi(hw.z), bflo(hw.w), bfhi(hw.w)}; }
;                     const f32x4 r0 = b0 + acc[ai][bj][m][0], r1 = b1 + acc[ai][bj][m][1];
;                     u32x4 hb; hb.x = cvt_pk_bf16(r0[0], r0[1]); hb.y = cvt_pk_bf16(r0[2], r0[3]); hb.z = cvt_pk_bf16(r1[0], r1[1]); hb.w = cvt_pk_bf16(r1[2], r1[3]); *(u32x4*)(HB + o) = hb;
;                     sq += ((r0[0] * r0[0] + r0[1] * r0[1]) + (r0[2] * r0[2] + r0[3] * r0[3])) + ((r1[0] * r1[0] + r1[1] * r1[1]) + (r1[2] * r1[2] + r1[3] * r1[3])); }
;                 sq += __shfl_xor(sq, 16); sq += __shfl_xor(sq, 32);
;                 if (fq == 0) ss_add(SS + row, sq);
.LBB0_381:
	v_lshl_add_u32 v158, s50, 8, v1
	v_ashrrev_i32_e32 v159, 31, v158
	v_lshl_or_b32 v162, s51, 8, v157
	v_lshlrev_b64 v[160:161], 12, v[158:159]
	v_ashrrev_i32_e32 v163, 31, v162
	v_lshl_add_u64 v[160:161], s[96:97], 0, v[160:161]
	v_lshl_add_u64 v[160:161], v[162:163], 1, v[160:161]
	v_mov_b64_e32 v[204:205], v[160:161]
	s_mov_b64 s[22:23], 0x0
	v_lshl_add_u64 v[198:199], v[204:205], 0, s[22:23]
	global_load_dwordx4 v[178:181], v[198:199], off
	global_load_dwordx4 v[182:185], v[198:199], off offset:256
	s_mov_b64 s[22:23], 0x10000
	v_lshl_add_u64 v[198:199], v[204:205], 0, s[22:23]
	global_load_dwordx4 v[186:189], v[198:199], off
	global_load_dwordx4 v[190:193], v[198:199], off offset:256
	s_mov_b64 s[22:23], 0x20000
	v_lshl_add_u64 v[198:199], v[204:205], 0, s[22:23]
	global_load_dwordx4 v[214:217], v[198:199], off
	global_load_dwordx4 v[218:221], v[198:199], off offset:256
	s_mov_b64 s[22:23], 0x30000
	v_lshl_add_u64 v[198:199], v[204:205], 0, s[22:23]
	global_load_dwordx4 v[222:225], v[198:199], off
	global_load_dwordx4 v[226:229], v[198:199], off offset:256
	s_mov_b64 s[22:23], 0x80000
	v_lshl_add_u64 v[198:199], v[204:205], 0, s[22:23]
	global_load_dwordx4 v[230:233], v[198:199], off
	global_load_dwordx4 v[234:237], v[198:199], off offset:256
	s_mov_b64 s[22:23], 0x90000
	v_lshl_add_u64 v[198:199], v[204:205], 0, s[22:23]
	global_load_dwordx4 v[238:241], v[198:199], off
	global_load_dwordx4 v[242:245], v[198:199], off offset:256
	v_cmp_lt_i32_e32 vcc, v207, v202
	s_waitcnt vmcnt(11)
	s_nop 1
	v_mov_b64_e32 v[166:167], v[178:179]
	v_mov_b64_e32 v[168:169], v[180:181]
	v_lshlrev_b32_e32 v170, 16, v166
	v_and_b32_e32 v171, 0xffff0000, v166
	v_lshlrev_b32_e32 v166, 16, v167
	v_and_b32_e32 v167, 0xffff0000, v167
	v_lshlrev_b32_e32 v172, 16, v168
	v_and_b32_e32 v173, 0xffff0000, v168
	v_lshlrev_b32_e32 v168, 16, v169
	v_and_b32_e32 v169, 0xffff0000, v169
	v_pk_add_f32 v[128:129], v[128:129], v[166:167]
	v_pk_add_f32 v[170:171], v[126:127], v[170:171]
	v_pk_add_f32 v[174:175], v[124:125], v[168:169]
	v_pk_add_f32 v[172:173], v[122:123], v[172:173]
	v_cvt_pk_bf16_f32 v124, v170, v171
	v_cvt_pk_bf16_f32 v125, v128, v129
	v_mul_f32_e32 v123, v171, v171
	v_cvt_pk_bf16_f32 v126, v172, v173
	v_cvt_pk_bf16_f32 v127, v174, v175
	v_mul_f32_e32 v129, v129, v129
	v_mul_f32_e32 v148, v173, v173
	v_mul_f32_e32 v149, v175, v175
	v_fmac_f32_e32 v123, v170, v170
	v_fmac_f32_e32 v129, v128, v128
	v_fmac_f32_e32 v148, v172, v172
	v_fmac_f32_e32 v149, v174, v174
	v_add_f32_e32 v123, v123, v129
	v_add_f32_e32 v128, v148, v149
	v_add_f32_e32 v123, v123, v128
	v_cndmask_b32_e32 v122, v200, v207, vcc
	v_lshlrev_b32_e32 v122, 2, v122
	v_cmp_lt_i32_e32 vcc, v208, v202
	global_store_dwordx4 v[160:161], v[124:127], off
	s_waitcnt vmcnt(11)
	s_nop 1
	v_mov_b64_e32 v[166:167], v[182:183]
	v_mov_b64_e32 v[168:169], v[184:185]
	v_lshlrev_b32_e32 v128, 16, v166
	v_and_b32_e32 v129, 0xffff0000, v166
	v_lshlrev_b32_e32 v166, 16, v167
	v_and_b32_e32 v167, 0xffff0000, v167
	v_lshlrev_b32_e32 v170, 16, v168
	v_and_b32_e32 v171, 0xffff0000, v168
	v_lshlrev_b32_e32 v168, 16, v169
	v_and_b32_e32 v169, 0xffff0000, v169
	v_pk_add_f32 v[120:121], v[120:121], v[166:167]
	v_pk_add_f32 v[118:119], v[118:119], v[128:129]
	v_pk_add_f32 v[128:129], v[116:117], v[168:169]
	v_pk_add_f32 v[166:167], v[114:115], v[170:171]
	v_mul_f32_e32 v114, v119, v119
	v_mul_f32_e32 v115, v121, v121
	v_mul_f32_e32 v116, v167, v167
	v_mul_f32_e32 v117, v129, v129
	v_fmac_f32_e32 v114, v118, v118
	v_fmac_f32_e32 v115, v120, v120
	v_fmac_f32_e32 v116, v166, v166
	v_fmac_f32_e32 v117, v128, v128
	v_add_f32_e32 v114, v114, v115
	v_add_f32_e32 v115, v116, v117
	v_add_f32_e32 v114, v114, v115
	v_add_f32_e32 v114, v123, v114
	ds_bpermute_b32 v115, v122, v114
	v_cndmask_b32_e32 v116, v200, v208, vcc
	v_cvt_pk_bf16_f32 v118, v118, v119
	v_cvt_pk_bf16_f32 v119, v120, v121
	v_cvt_pk_bf16_f32 v120, v166, v167
	s_waitcnt lgkmcnt(0)
	v_add_f32_e32 v115, v114, v115
	v_lshlrev_b32_e32 v114, 2, v116
	ds_bpermute_b32 v116, v114, v115
	v_cvt_pk_bf16_f32 v121, v128, v129
	global_store_dwordx4 v[160:161], v[118:121], off offset:256
	s_and_saveexec_b64 s[22:23], s[6:7]
	s_cbranch_execz .LBB0_383
	s_waitcnt lgkmcnt(0)
	v_add_f32_e32 v115, v115, v116
	v_mul_f32_e32 v115, 0x49800000, v115
	v_trunc_f32_e32 v115, v115
	v_mul_f32_e32 v116, 0x2f800000, v115
	v_floor_f32_e32 v117, v116
	v_fmac_f32_e32 v115, 0xcf800000, v117
	v_cvt_u32_f32_e32 v116, v115
	v_cvt_u32_f32_e32 v117, v117
	v_lshl_add_u64 v[118:119], v[158:159], 3, s[2:3]
	global_atomic_add_x2 v[118:119], v[116:117], off
; __device__ __forceinline__ void ss_add(ss_t* p, float v) { (void)__hip_atomic_fetch_add(p, (ss_t)(v * 1048576.0f), __ATOMIC_RELAXED, __HIP_MEMORY_SCOPE_AGENT); }
; __device__ __forceinline__ unsigned cvt_pk_bf16(float lo, float hi) { unsigned r; asm volatile("v_cvt_pk_bf16_f32 %0, %1, %2" : "=v"(r) : "v"(lo), "v"(hi)); return r; }
; __device__ __forceinline__ float bflo(unsigned w) { return __uint_as_float(w << 16); }
; __device__ __forceinline__ float bfhi(unsigned w) { return __uint_as_float(w & 0xffff0000u); }
;     __device__ __forceinline__ void operator()(const f32x4 (&acc)[2][2][4][2], const Unit& u, int wr, int wc, int fr, int fq) const {
;         const int row0 = u.pm * 256 + wr * 64 + fr, col0 = u.pn * 256 + wc * 32 + 8 * fq;
; #pragma unroll
;         for (int ai = 0; ai < 2; ++ai)
; #pragma unroll
;             for (int m = 0; m < 4; ++m) { const int row = row0 + ai * 128 + m * 16; const size_t off = (size_t)row * D + col0; float sq = 0.f;
; #pragma unroll
;                 for (int bj = 0; bj < 2; ++bj) { const size_t o = off + bj * 128; f32x4 b0, b1;
;                     if (XF32) { b0 = *(const f32x4*)((const float*)base + o); b1 = *(const f32x4*)((const float*)base + o + 4); }
;                     else { const u32x4 hw = *(const u32x4*)((const bf16_t*)base + o); b0 = (f32x4){bflo(hw.x), bfhi(hw.x), bflo(hw.y), bfhi(hw.y)}; b1 = (f32x4){bflo(hw.z), bfhi(hw.z), bflo(hw.w), bfhi(hw.w)}; }
;                     const f32x4 r0 = b0 + acc[ai][bj][m][0], r1 = b1 + acc[ai][bj][m][1];
;                     u32x4 hb; hb.x = cvt_pk_bf16(r0[0], r0[1]); hb.y = cvt_pk_bf16(r0[2], r0[3]); hb.z = cvt_pk_bf16(r1[0], r1[1]); hb.w = cvt_pk_bf16(r1[2], r1[3]); *(u32x4*)(HB + o) = hb;
;                     sq += ((r0[0] * r0[0] + r0[1] * r0[1]) + (r0[2] * r0[2] + r0[3] * r0[3])) + ((r1[0] * r1[0] + r1[1] * r1[1]) + (r1[2] * r1[2] + r1[3] * r1[3])); }
;                 sq += __shfl_xor(sq, 16); sq += __shfl_xor(sq, 32);
;                 if (fq == 0) ss_add(SS + row, sq);
.LBB0_383:
	s_or_b64 exec, exec, s[22:23]
	s_mov_b64 s[22:23], 0xa0000
	v_lshl_add_u64 v[198:199], v[204:205], 0, s[22:23]
	global_load_dwordx4 v[178:181], v[198:199], off
	global_load_dwordx4 v[182:185], v[198:199], off offset:256
	s_waitcnt lgkmcnt(0)
	v_or_b32_e32 v116, 16, v158
	v_ashrrev_i32_e32 v117, 31, v116
	v_lshlrev_b64 v[116:117], 12, v[116:117]
	v_lshl_add_u64 v[116:117], s[96:97], 0, v[116:117]
	v_lshl_add_u64 v[120:121], v[162:163], 1, v[116:117]
	s_waitcnt vmcnt(14)
	s_nop 1
	v_mov_b64_e32 v[116:117], v[186:187]
	v_mov_b64_e32 v[118:119], v[188:189]
	v_lshlrev_b32_e32 v124, 16, v116
	v_and_b32_e32 v125, 0xffff0000, v116
	v_lshlrev_b32_e32 v116, 16, v117
	v_and_b32_e32 v117, 0xffff0000, v117
	v_lshlrev_b32_e32 v126, 16, v118
	v_and_b32_e32 v127, 0xffff0000, v118
	v_lshlrev_b32_e32 v118, 16, v119
	v_and_b32_e32 v119, 0xffff0000, v119
	v_pk_add_f32 v[116:117], v[112:113], v[116:117]
	v_pk_add_f32 v[124:125], v[110:111], v[124:125]
	v_pk_add_f32 v[118:119], v[108:109], v[118:119]
	v_pk_add_f32 v[126:127], v[106:107], v[126:127]
	v_cvt_pk_bf16_f32 v106, v124, v125
	v_cvt_pk_bf16_f32 v107, v116, v117
	v_mul_f32_e32 v115, v125, v125
	v_cvt_pk_bf16_f32 v108, v126, v127
	v_cvt_pk_bf16_f32 v109, v118, v119
	v_mul_f32_e32 v117, v117, v117
	v_mul_f32_e32 v123, v127, v127
	v_mul_f32_e32 v119, v119, v119
	v_fmac_f32_e32 v115, v124, v124
	v_fmac_f32_e32 v117, v116, v116
	v_fmac_f32_e32 v123, v126, v126
	v_fmac_f32_e32 v119, v118, v118
	v_add_f32_e32 v115, v115, v117
	v_add_f32_e32 v116, v123, v119
	v_add_f32_e32 v115, v115, v116
	global_store_dwordx4 v[120:121], v[106:109], off
	s_waitcnt vmcnt(14)
	s_nop 1
	v_mov_b64_e32 v[110:111], v[190:191]
	v_mov_b64_e32 v[112:113], v[192:193]
	v_lshlrev_b32_e32 v116, 16, v110
	v_and_b32_e32 v117, 0xffff0000, v110
	v_lshlrev_b32_e32 v110, 16, v111
	v_and_b32_e32 v111, 0xffff0000, v111
	v_lshlrev_b32_e32 v118, 16, v112
	v_and_b32_e32 v119, 0xffff0000, v112
	v_lshlrev_b32_e32 v112, 16, v113
	v_and_b32_e32 v113, 0xffff0000, v113
	v_pk_add_f32 v[104:105], v[104:105], v[110:111]
	v_pk_add_f32 v[102:103], v[102:103], v[116:117]
	v_pk_add_f32 v[110:111], v[100:101], v[112:113]
	v_pk_add_f32 v[112:113], v[98:99], v[118:119]
	v_mul_f32_e32 v98, v103, v103
	v_mul_f32_e32 v99, v105, v105
	v_mul_f32_e32 v100, v113, v113
	v_mul_f32_e32 v101, v111, v111
	v_fmac_f32_e32 v98, v102, v102
	v_fmac_f32_e32 v99, v104, v104
	v_fmac_f32_e32 v100, v112, v112
	v_fmac_f32_e32 v101, v110, v110
	v_add_f32_e32 v98, v98, v99
	v_add_f32_e32 v99, v100, v101
	v_add_f32_e32 v98, v98, v99
	v_add_f32_e32 v98, v115, v98
	ds_bpermute_b32 v99, v122, v98
	v_cvt_pk_bf16_f32 v100, v102, v103
	v_cvt_pk_bf16_f32 v101, v104, v105
	v_cvt_pk_bf16_f32 v102, v112, v113
	v_cvt_pk_bf16_f32 v103, v110, v111
	s_waitcnt lgkmcnt(0)
	v_add_f32_e32 v98, v98, v99
	ds_bpermute_b32 v99, v114, v98
	global_store_dwordx4 v[120:121], v[100:103], off offset:256
	s_and_saveexec_b64 s[22:23], s[6:7]
	s_cbranch_execz .LBB0_385
	s_waitcnt lgkmcnt(0)
	v_add_f32_e32 v98, v98, v99
	v_mul_f32_e32 v98, 0x49800000, v98
	v_trunc_f32_e32 v98, v98
	v_mul_f32_e32 v99, 0x2f800000, v98
	v_floor_f32_e32 v99, v99
	v_fmac_f32_e32 v98, 0xcf800000, v99
	v_cvt_u32_f32_e32 v98, v98
	v_cvt_u32_f32_e32 v99, v99
	v_lshl_add_u64 v[100:101], v[158:159], 3, s[2:3]
	global_atomic_add_x2 v[100:101], v[98:99], off offset:128
.LBB0_385:
	s_or_b64 exec, exec, s[22:23]
	s_mov_b64 s[22:23], 0xb0000
	v_lshl_add_u64 v[198:199], v[204:205], 0, s[22:23]
	global_load_dwordx4 v[186:189], v[198:199], off
	global_load_dwordx4 v[190:193], v[198:199], off offset:256
	v_or_b32_e32 v98, 32, v158
	s_waitcnt lgkmcnt(0)
	v_ashrrev_i32_e32 v99, 31, v98
	v_lshlrev_b64 v[98:99], 12, v[98:99]
	v_lshl_add_u64 v[98:99], s[96:97], 0, v[98:99]
	v_lshl_add_u64 v[102:103], v[162:163], 1, v[98:99]
	s_waitcnt vmcnt(17)
	s_nop 1
	v_mov_b64_e32 v[98:99], v[214:215]
	v_mov_b64_e32 v[100:101], v[216:217]
	v_lshlrev_b32_e32 v104, 16, v98
	v_and_b32_e32 v105, 0xffff0000, v98
	v_lshlrev_b32_e32 v98, 16, v99
	v_and_b32_e32 v99, 0xffff0000, v99
	v_lshlrev_b32_e32 v106, 16, v100
	v_and_b32_e32 v107, 0xffff0000, v100
	v_lshlrev_b32_e32 v100, 16, v101
	v_and_b32_e32 v101, 0xffff0000, v101
	v_pk_add_f32 v[98:99], v[96:97], v[98:99]
	v_pk_add_f32 v[104:105], v[94:95], v[104:105]
	v_pk_add_f32 v[100:101], v[92:93], v[100:101]
	v_pk_add_f32 v[106:107], v[90:91], v[106:107]
	v_cvt_pk_bf16_f32 v90, v104, v105
	v_cvt_pk_bf16_f32 v91, v98, v99
	v_mul_f32_e32 v105, v105, v105
	v_cvt_pk_bf16_f32 v92, v106, v107
	v_cvt_pk_bf16_f32 v93, v100, v101
	v_mul_f32_e32 v99, v99, v99
	v_mul_f32_e32 v107, v107, v107
	v_mul_f32_e32 v101, v101, v101
	v_fmac_f32_e32 v105, v104, v104
	v_fmac_f32_e32 v99, v98, v98
	v_fmac_f32_e32 v107, v106, v106
	v_fmac_f32_e32 v101, v100, v100
	v_add_f32_e32 v98, v105, v99
	v_add_f32_e32 v99, v107, v101
	v_add_f32_e32 v104, v98, v99
	global_store_dwordx4 v[102:103], v[90:93], off
	s_waitcnt vmcnt(17)
	s_nop 1
	v_mov_b64_e32 v[94:95], v[218:219]
	v_mov_b64_e32 v[96:97], v[220:221]
	v_lshlrev_b32_e32 v98, 16, v94
	v_and_b32_e32 v99, 0xffff0000, v94
	v_lshlrev_b32_e32 v94, 16, v95
	v_and_b32_e32 v95, 0xffff0000, v95
	v_lshlrev_b32_e32 v100, 16, v96
	v_and_b32_e32 v101, 0xffff0000, v96
	v_lshlrev_b32_e32 v96, 16, v97
	v_and_b32_e32 v97, 0xffff0000, v97
	v_pk_add_f32 v[88:89], v[88:89], v[94:95]
	v_pk_add_f32 v[86:87], v[86:87], v[98:99]
	v_pk_add_f32 v[94:95], v[84:85], v[96:97]
	v_pk_add_f32 v[96:97], v[82:83], v[100:101]
	v_mul_f32_e32 v82, v87, v87
	v_mul_f32_e32 v83, v89, v89
	v_mul_f32_e32 v84, v97, v97
	v_mul_f32_e32 v85, v95, v95
	v_fmac_f32_e32 v82, v86, v86
	v_fmac_f32_e32 v83, v88, v88
	v_fmac_f32_e32 v84, v96, v96
	v_fmac_f32_e32 v85, v94, v94
	v_add_f32_e32 v82, v82, v83
	v_add_f32_e32 v83, v84, v85
	v_add_f32_e32 v82, v82, v83
	v_add_f32_e32 v82, v104, v82
	ds_bpermute_b32 v83, v122, v82
	v_cvt_pk_bf16_f32 v84, v86, v87
	v_cvt_pk_bf16_f32 v85, v88, v89
	v_cvt_pk_bf16_f32 v86, v96, v97
	v_cvt_pk_bf16_f32 v87, v94, v95
	s_waitcnt lgkmcnt(0)
	v_add_f32_e32 v82, v82, v83
	ds_bpermute_b32 v83, v114, v82
	global_store_dwordx4 v[102:103], v[84:87], off offset:256
	s_and_saveexec_b64 s[22:23], s[6:7]
	s_cbranch_execz .LBB0_387
	s_waitcnt lgkmcnt(0)
	v_add_f32_e32 v82, v82, v83
	v_mul_f32_e32 v82, 0x49800000, v82
	v_trunc_f32_e32 v82, v82
	v_mul_f32_e32 v83, 0x2f800000, v82
	v_floor_f32_e32 v83, v83
	v_fmac_f32_e32 v82, 0xcf800000, v83
	v_cvt_u32_f32_e32 v82, v82
	v_cvt_u32_f32_e32 v83, v83
	v_lshl_add_u64 v[84:85], v[158:159], 3, s[2:3]
	global_atomic_add_x2 v[84:85], v[82:83], off offset:256
; __device__ __forceinline__ void ss_add(ss_t* p, float v) { (void)__hip_atomic_fetch_add(p, (ss_t)(v * 1048576.0f), __ATOMIC_RELAXED, __HIP_MEMORY_SCOPE_AGENT); }
; __device__ __forceinline__ unsigned cvt_pk_bf16(float lo, float hi) { unsigned r; asm volatile("v_cvt_pk_bf16_f32 %0, %1, %2" : "=v"(r) : "v"(lo), "v"(hi)); return r; }
; __device__ __forceinline__ float bflo(unsigned w) { return __uint_as_float(w << 16); }
; __device__ __forceinline__ float bfhi(unsigned w) { return __uint_as_float(w & 0xffff0000u); }
;     __device__ __forceinline__ void operator()(const f32x4 (&acc)[2][2][4][2], const Unit& u, int wr, int wc, int fr, int fq) const {
;         const int row0 = u.pm * 256 + wr * 64 + fr, col0 = u.pn * 256 + wc * 32 + 8 * fq;
; #pragma unroll
;         for (int ai = 0; ai < 2; ++ai)
; #pragma unroll
;             for (int m = 0; m < 4; ++m) { const int row = row0 + ai * 128 + m * 16; const size_t off = (size_t)row * D + col0; float sq = 0.f;
; #pragma unroll
;                 for (int bj = 0; bj < 2; ++bj) { const size_t o = off + bj * 128; f32x4 b0, b1;
;                     if (XF32) { b0 = *(const f32x4*)((const float*)base + o); b1 = *(const f32x4*)((const float*)base + o + 4); }
;                     else { const u32x4 hw = *(const u32x4*)((const bf16_t*)base + o); b0 = (f32x4){bflo(hw.x), bfhi(hw.x), bflo(hw.y), bfhi(hw.y)}; b1 = (f32x4){bflo(hw.z), bfhi(hw.z), bflo(hw.w), bfhi(hw.w)}; }
;                     const f32x4 r0 = b0 + acc[ai][bj][m][0], r1 = b1 + acc[ai][bj][m][1];
;                     u32x4 hb; hb.x = cvt_pk_bf16(r0[0], r0[1]); hb.y = cvt_pk_bf16(r0[2], r0[3]); hb.z = cvt_pk_bf16(r1[0], r1[1]); hb.w = cvt_pk_bf16(r1[2], r1[3]); *(u32x4*)(HB + o) = hb;
;                     sq += ((r0[0] * r0[0] + r0[1] * r0[1]) + (r0[2] * r0[2] + r0[3] * r0[3])) + ((r1[0] * r1[0] + r1[1] * r1[1]) + (r1[2] * r1[2] + r1[3] * r1[3])); }
;                 sq += __shfl_xor(sq, 16); sq += __shfl_xor(sq, 32);
;                 if (fq == 0) ss_add(SS + row, sq);
.LBB0_387:
	s_or_b64 exec, exec, s[22:23]
	v_or_b32_e32 v82, 48, v158
	s_waitcnt lgkmcnt(0)
	v_ashrrev_i32_e32 v83, 31, v82
	v_lshlrev_b64 v[82:83], 12, v[82:83]
	v_lshl_add_u64 v[82:83], s[96:97], 0, v[82:83]
	v_lshl_add_u64 v[86:87], v[162:163], 1, v[82:83]
	s_waitcnt vmcnt(18)
	s_nop 1
	v_mov_b64_e32 v[82:83], v[222:223]
	v_mov_b64_e32 v[84:85], v[224:225]
	v_lshlrev_b32_e32 v88, 16, v82
	v_and_b32_e32 v89, 0xffff0000, v82
	v_lshlrev_b32_e32 v82, 16, v83
	v_and_b32_e32 v83, 0xffff0000, v83
	v_lshlrev_b32_e32 v90, 16, v84
	v_and_b32_e32 v91, 0xffff0000, v84
	v_lshlrev_b32_e32 v84, 16, v85
	v_and_b32_e32 v85, 0xffff0000, v85
	v_pk_add_f32 v[82:83], v[80:81], v[82:83]
	v_pk_add_f32 v[88:89], v[78:79], v[88:89]
	v_pk_add_f32 v[84:85], v[76:77], v[84:85]
	v_pk_add_f32 v[90:91], v[74:75], v[90:91]
	v_cvt_pk_bf16_f32 v74, v88, v89
	v_cvt_pk_bf16_f32 v75, v82, v83
	v_mul_f32_e32 v89, v89, v89
	v_cvt_pk_bf16_f32 v76, v90, v91
	v_cvt_pk_bf16_f32 v77, v84, v85
	v_mul_f32_e32 v83, v83, v83
	v_mul_f32_e32 v91, v91, v91
	v_mul_f32_e32 v85, v85, v85
	v_fmac_f32_e32 v89, v88, v88
	v_fmac_f32_e32 v83, v82, v82
	v_fmac_f32_e32 v91, v90, v90
	v_fmac_f32_e32 v85, v84, v84
	v_add_f32_e32 v82, v89, v83
	v_add_f32_e32 v83, v91, v85
	v_add_f32_e32 v88, v82, v83
	global_store_dwordx4 v[86:87], v[74:77], off
	s_waitcnt vmcnt(18)
	s_nop 1
	v_mov_b64_e32 v[78:79], v[226:227]
	v_mov_b64_e32 v[80:81], v[228:229]
	v_lshlrev_b32_e32 v82, 16, v78
	v_and_b32_e32 v83, 0xffff0000, v78
	v_lshlrev_b32_e32 v78, 16, v79
	v_and_b32_e32 v79, 0xffff0000, v79
	v_lshlrev_b32_e32 v84, 16, v80
	v_and_b32_e32 v85, 0xffff0000, v80
	v_lshlrev_b32_e32 v80, 16, v81
	v_and_b32_e32 v81, 0xffff0000, v81
	v_pk_add_f32 v[72:73], v[72:73], v[78:79]
	v_pk_add_f32 v[70:71], v[70:71], v[82:83]
	v_pk_add_f32 v[78:79], v[68:69], v[80:81]
	v_pk_add_f32 v[80:81], v[66:67], v[84:85]
	v_mul_f32_e32 v66, v71, v71
	v_mul_f32_e32 v67, v73, v73
	v_mul_f32_e32 v68, v81, v81
	v_mul_f32_e32 v69, v79, v79
	v_fmac_f32_e32 v66, v70, v70
	v_fmac_f32_e32 v67, v72, v72
	v_fmac_f32_e32 v68, v80, v80
	v_fmac_f32_e32 v69, v78, v78
	v_add_f32_e32 v66, v66, v67
	v_add_f32_e32 v67, v68, v69
	v_add_f32_e32 v66, v66, v67
	v_add_f32_e32 v66, v88, v66
	ds_bpermute_b32 v67, v122, v66
	v_cvt_pk_bf16_f32 v68, v70, v71
	v_cvt_pk_bf16_f32 v69, v72, v73
	v_cvt_pk_bf16_f32 v70, v80, v81
	v_cvt_pk_bf16_f32 v71, v78, v79
	s_waitcnt lgkmcnt(0)
	v_add_f32_e32 v66, v66, v67
	ds_bpermute_b32 v67, v114, v66
	global_store_dwordx4 v[86:87], v[68:71], off offset:256
	s_and_saveexec_b64 s[22:23], s[6:7]
	s_cbranch_execz .LBB0_389
	s_waitcnt lgkmcnt(0)
	v_add_f32_e32 v66, v66, v67
	v_mul_f32_e32 v66, 0x49800000, v66
	v_trunc_f32_e32 v66, v66
	v_mul_f32_e32 v67, 0x2f800000, v66
	v_floor_f32_e32 v67, v67
	v_fmac_f32_e32 v66, 0xcf800000, v67
	v_cvt_u32_f32_e32 v66, v66
	v_cvt_u32_f32_e32 v67, v67
	v_lshl_add_u64 v[68:69], v[158:159], 3, s[2:3]
	global_atomic_add_x2 v[68:69], v[66:67], off offset:384
.LBB0_389:
	s_or_b64 exec, exec, s[22:23]
	v_add_co_u32_e32 v70, vcc, 0x80000, v160
	s_mov_b64 s[22:23], 0x80000
	s_nop 0
	v_addc_co_u32_e32 v71, vcc, 0, v161, vcc
	s_waitcnt lgkmcnt(0)
	v_lshl_add_u64 v[72:73], v[160:161], 0, s[22:23]
	s_waitcnt vmcnt(19)
	s_nop 1
	v_mov_b64_e32 v[66:67], v[230:231]
	v_mov_b64_e32 v[68:69], v[232:233]
	v_lshlrev_b32_e32 v74, 16, v66
	v_and_b32_e32 v75, 0xffff0000, v66
	v_lshlrev_b32_e32 v66, 16, v67
	v_and_b32_e32 v67, 0xffff0000, v67
	v_lshlrev_b32_e32 v76, 16, v68
	v_and_b32_e32 v77, 0xffff0000, v68
	v_lshlrev_b32_e32 v68, 16, v69
	v_and_b32_e32 v69, 0xffff0000, v69
	v_pk_add_f32 v[66:67], v[64:65], v[66:67]
	v_pk_add_f32 v[74:75], v[62:63], v[74:75]
	v_pk_add_f32 v[68:69], v[60:61], v[68:69]
	v_pk_add_f32 v[76:77], v[58:59], v[76:77]
	v_cvt_pk_bf16_f32 v58, v74, v75
	v_cvt_pk_bf16_f32 v59, v66, v67
	v_mul_f32_e32 v75, v75, v75
	v_cvt_pk_bf16_f32 v60, v76, v77
	v_cvt_pk_bf16_f32 v61, v68, v69
	v_mul_f32_e32 v67, v67, v67
	v_mul_f32_e32 v77, v77, v77
	v_mul_f32_e32 v69, v69, v69
	v_fmac_f32_e32 v75, v74, v74
	v_fmac_f32_e32 v67, v66, v66
	v_fmac_f32_e32 v77, v76, v76
	v_fmac_f32_e32 v69, v68, v68
	v_add_f32_e32 v66, v75, v67
	v_add_f32_e32 v67, v77, v69
	v_add_f32_e32 v74, v66, v67
	global_store_dwordx4 v[70:71], v[58:61], off
	s_waitcnt vmcnt(19)
	s_nop 1
	v_mov_b64_e32 v[62:63], v[234:235]
	v_mov_b64_e32 v[64:65], v[236:237]
	v_lshlrev_b32_e32 v66, 16, v62
	v_and_b32_e32 v67, 0xffff0000, v62
	v_lshlrev_b32_e32 v62, 16, v63
	v_and_b32_e32 v63, 0xffff0000, v63
	v_lshlrev_b32_e32 v68, 16, v64
	v_and_b32_e32 v69, 0xffff0000, v64
	v_lshlrev_b32_e32 v64, 16, v65
	v_and_b32_e32 v65, 0xffff0000, v65
	v_pk_add_f32 v[56:57], v[56:57], v[62:63]
	v_pk_add_f32 v[54:55], v[54:55], v[66:67]
	v_pk_add_f32 v[62:63], v[52:53], v[64:65]
	v_pk_add_f32 v[64:65], v[50:51], v[68:69]
	v_mul_f32_e32 v50, v55, v55
	v_mul_f32_e32 v51, v57, v57
	v_mul_f32_e32 v52, v65, v65
	v_mul_f32_e32 v53, v63, v63
	v_fmac_f32_e32 v50, v54, v54
	v_fmac_f32_e32 v51, v56, v56
	v_fmac_f32_e32 v52, v64, v64
	v_fmac_f32_e32 v53, v62, v62
	v_add_f32_e32 v50, v50, v51
	v_add_f32_e32 v51, v52, v53
	v_add_f32_e32 v50, v50, v51
	v_add_f32_e32 v50, v74, v50
	ds_bpermute_b32 v51, v122, v50
	v_cvt_pk_bf16_f32 v52, v54, v55
	v_cvt_pk_bf16_f32 v53, v56, v57
	v_cvt_pk_bf16_f32 v54, v64, v65
	v_cvt_pk_bf16_f32 v55, v62, v63
	s_waitcnt lgkmcnt(0)
	v_add_f32_e32 v50, v50, v51
	ds_bpermute_b32 v51, v114, v50
	global_store_dwordx4 v[72:73], v[52:55], off offset:256
	s_and_saveexec_b64 s[22:23], s[6:7]
	s_cbranch_execz .LBB0_391
	s_waitcnt lgkmcnt(0)
	v_add_f32_e32 v50, v50, v51
	v_mul_f32_e32 v50, 0x49800000, v50
	v_trunc_f32_e32 v50, v50
	v_mul_f32_e32 v51, 0x2f800000, v50
	v_floor_f32_e32 v51, v51
	v_fmac_f32_e32 v50, 0xcf800000, v51
	v_cvt_u32_f32_e32 v50, v50
	v_cvt_u32_f32_e32 v51, v51
	v_lshl_add_u64 v[52:53], v[158:159], 3, s[2:3]
	global_atomic_add_x2 v[52:53], v[50:51], off offset:1024
; __device__ __forceinline__ void ss_add(ss_t* p, float v) { (void)__hip_atomic_fetch_add(p, (ss_t)(v * 1048576.0f), __ATOMIC_RELAXED, __HIP_MEMORY_SCOPE_AGENT); }
; __device__ __forceinline__ unsigned cvt_pk_bf16(float lo, float hi) { unsigned r; asm volatile("v_cvt_pk_bf16_f32 %0, %1, %2" : "=v"(r) : "v"(lo), "v"(hi)); return r; }
; __device__ __forceinline__ float bflo(unsigned w) { return __uint_as_float(w << 16); }
; __device__ __forceinline__ float bfhi(unsigned w) { return __uint_as_float(w & 0xffff0000u); }
;     __device__ __forceinline__ void operator()(const f32x4 (&acc)[2][2][4][2], const Unit& u, int wr, int wc, int fr, int fq) const {
;         const int row0 = u.pm * 256 + wr * 64 + fr, col0 = u.pn * 256 + wc * 32 + 8 * fq;
; #pragma unroll
;         for (int ai = 0; ai < 2; ++ai)
; #pragma unroll
;             for (int m = 0; m < 4; ++m) { const int row = row0 + ai * 128 + m * 16; const size_t off = (size_t)row * D + col0; float sq = 0.f;
; #pragma unroll
;                 for (int bj = 0; bj < 2; ++bj) { const size_t o = off + bj * 128; f32x4 b0, b1;
;                     if (XF32) { b0 = *(const f32x4*)((const float*)base + o); b1 = *(const f32x4*)((const float*)base + o + 4); }
;                     else { const u32x4 hw = *(const u32x4*)((const bf16_t*)base + o); b0 = (f32x4){bflo(hw.x), bfhi(hw.x), bflo(hw.y), bfhi(hw.y)}; b1 = (f32x4){bflo(hw.z), bfhi(hw.z), bflo(hw.w), bfhi(hw.w)}; }
;                     const f32x4 r0 = b0 + acc[ai][bj][m][0], r1 = b1 + acc[ai][bj][m][1];
;                     u32x4 hb; hb.x = cvt_pk_bf16(r0[0], r0[1]); hb.y = cvt_pk_bf16(r0[2], r0[3]); hb.z = cvt_pk_bf16(r1[0], r1[1]); hb.w = cvt_pk_bf16(r1[2], r1[3]); *(u32x4*)(HB + o) = hb;
;                     sq += ((r0[0] * r0[0] + r0[1] * r0[1]) + (r0[2] * r0[2] + r0[3] * r0[3])) + ((r1[0] * r1[0] + r1[1] * r1[1]) + (r1[2] * r1[2] + r1[3] * r1[3])); }
;                 sq += __shfl_xor(sq, 16); sq += __shfl_xor(sq, 32);
;                 if (fq == 0) ss_add(SS + row, sq);
.LBB0_391:
	s_or_b64 exec, exec, s[22:23]
	v_add_co_u32_e32 v54, vcc, 0x90000, v160
	s_mov_b64 s[22:23], 0x90000
	s_nop 0
	v_addc_co_u32_e32 v55, vcc, 0, v161, vcc
	s_waitcnt lgkmcnt(0)
	v_lshl_add_u64 v[56:57], v[160:161], 0, s[22:23]
	s_waitcnt vmcnt(20)
	s_nop 1
	v_mov_b64_e32 v[50:51], v[238:239]
	v_mov_b64_e32 v[52:53], v[240:241]
	v_lshlrev_b32_e32 v58, 16, v50
	v_and_b32_e32 v59, 0xffff0000, v50
	v_lshlrev_b32_e32 v50, 16, v51
	v_and_b32_e32 v51, 0xffff0000, v51
	v_lshlrev_b32_e32 v60, 16, v52
	v_and_b32_e32 v61, 0xffff0000, v52
	v_lshlrev_b32_e32 v52, 16, v53
	v_and_b32_e32 v53, 0xffff0000, v53
	v_pk_add_f32 v[50:51], v[48:49], v[50:51]
	v_pk_add_f32 v[58:59], v[46:47], v[58:59]
	v_pk_add_f32 v[52:53], v[44:45], v[52:53]
	v_pk_add_f32 v[60:61], v[42:43], v[60:61]
	v_cvt_pk_bf16_f32 v42, v58, v59
	v_cvt_pk_bf16_f32 v43, v50, v51
	v_mul_f32_e32 v59, v59, v59
	v_cvt_pk_bf16_f32 v44, v60, v61
	v_cvt_pk_bf16_f32 v45, v52, v53
	v_mul_f32_e32 v51, v51, v51
	v_mul_f32_e32 v61, v61, v61
	v_mul_f32_e32 v53, v53, v53
	v_fmac_f32_e32 v59, v58, v58
	v_fmac_f32_e32 v51, v50, v50
	v_fmac_f32_e32 v61, v60, v60
	v_fmac_f32_e32 v53, v52, v52
	v_add_f32_e32 v50, v59, v51
	v_add_f32_e32 v51, v61, v53
	v_add_f32_e32 v58, v50, v51
	global_store_dwordx4 v[54:55], v[42:45], off
	s_waitcnt vmcnt(20)
	s_nop 1
	v_mov_b64_e32 v[46:47], v[242:243]
	v_mov_b64_e32 v[48:49], v[244:245]
	v_lshlrev_b32_e32 v50, 16, v46
	v_and_b32_e32 v51, 0xffff0000, v46
	v_lshlrev_b32_e32 v46, 16, v47
	v_and_b32_e32 v47, 0xffff0000, v47
	v_lshlrev_b32_e32 v52, 16, v48
	v_and_b32_e32 v53, 0xffff0000, v48
	v_lshlrev_b32_e32 v48, 16, v49
	v_and_b32_e32 v49, 0xffff0000, v49
	v_pk_add_f32 v[40:41], v[40:41], v[46:47]
	v_pk_add_f32 v[38:39], v[38:39], v[50:51]
	v_pk_add_f32 v[46:47], v[36:37], v[48:49]
	v_pk_add_f32 v[48:49], v[34:35], v[52:53]
	v_mul_f32_e32 v34, v39, v39
	v_mul_f32_e32 v35, v41, v41
	v_mul_f32_e32 v36, v49, v49
	v_mul_f32_e32 v37, v47, v47
	v_fmac_f32_e32 v34, v38, v38
	v_fmac_f32_e32 v35, v40, v40
	v_fmac_f32_e32 v36, v48, v48
	v_fmac_f32_e32 v37, v46, v46
	v_add_f32_e32 v34, v34, v35
	v_add_f32_e32 v35, v36, v37
	v_add_f32_e32 v34, v34, v35
	v_add_f32_e32 v34, v58, v34
	ds_bpermute_b32 v35, v122, v34
	v_cvt_pk_bf16_f32 v36, v38, v39
	v_cvt_pk_bf16_f32 v37, v40, v41
	v_cvt_pk_bf16_f32 v38, v48, v49
	v_cvt_pk_bf16_f32 v39, v46, v47
	s_waitcnt lgkmcnt(0)
	v_add_f32_e32 v34, v34, v35
	ds_bpermute_b32 v35, v114, v34
	global_store_dwordx4 v[56:57], v[36:39], off offset:256
	s_and_saveexec_b64 s[22:23], s[6:7]
	s_cbranch_execz .LBB0_393
	s_waitcnt lgkmcnt(0)
	v_add_f32_e32 v34, v34, v35
	v_mul_f32_e32 v34, 0x49800000, v34
	v_trunc_f32_e32 v34, v34
	v_mul_f32_e32 v35, 0x2f800000, v34
	v_floor_f32_e32 v35, v35
	v_fmac_f32_e32 v34, 0xcf800000, v35
	v_cvt_u32_f32_e32 v34, v34
	v_cvt_u32_f32_e32 v35, v35
	v_lshl_add_u64 v[36:37], v[158:159], 3, s[2:3]
	global_atomic_add_x2 v[36:37], v[34:35], off offset:1152
; __device__ __forceinline__ void ss_add(ss_t* p, float v) { (void)__hip_atomic_fetch_add(p, (ss_t)(v * 1048576.0f), __ATOMIC_RELAXED, __HIP_MEMORY_SCOPE_AGENT); }
; __device__ __forceinline__ unsigned cvt_pk_bf16(float lo, float hi) { unsigned r; asm volatile("v_cvt_pk_bf16_f32 %0, %1, %2" : "=v"(r) : "v"(lo), "v"(hi)); return r; }
; __device__ __forceinline__ float bflo(unsigned w) { return __uint_as_float(w << 16); }
; __device__ __forceinline__ float bfhi(unsigned w) { return __uint_as_float(w & 0xffff0000u); }
;     __device__ __forceinline__ void operator()(const f32x4 (&acc)[2][2][4][2], const Unit& u, int wr, int wc, int fr, int fq) const {
;         const int row0 = u.pm * 256 + wr * 64 + fr, col0 = u.pn * 256 + wc * 32 + 8 * fq;
; #pragma unroll
;         for (int ai = 0; ai < 2; ++ai)
; #pragma unroll
;             for (int m = 0; m < 4; ++m) { const int row = row0 + ai * 128 + m * 16; const size_t off = (size_t)row * D + col0; float sq = 0.f;
; #pragma unroll
;                 for (int bj = 0; bj < 2; ++bj) { const size_t o = off + bj * 128; f32x4 b0, b1;
;                     if (XF32) { b0 = *(const f32x4*)((const float*)base + o); b1 = *(const f32x4*)((const float*)base + o + 4); }
;                     else { const u32x4 hw = *(const u32x4*)((const bf16_t*)base + o); b0 = (f32x4){bflo(hw.x), bfhi(hw.x), bflo(hw.y), bfhi(hw.y)}; b1 = (f32x4){bflo(hw.z), bfhi(hw.z), bflo(hw.w), bfhi(hw.w)}; }
;                     const f32x4 r0 = b0 + acc[ai][bj][m][0], r1 = b1 + acc[ai][bj][m][1];
;                     u32x4 hb; hb.x = cvt_pk_bf16(r0[0], r0[1]); hb.y = cvt_pk_bf16(r0[2], r0[3]); hb.z = cvt_pk_bf16(r1[0], r1[1]); hb.w = cvt_pk_bf16(r1[2], r1[3]); *(u32x4*)(HB + o) = hb;
;                     sq += ((r0[0] * r0[0] + r0[1] * r0[1]) + (r0[2] * r0[2] + r0[3] * r0[3])) + ((r1[0] * r1[0] + r1[1] * r1[1]) + (r1[2] * r1[2] + r1[3] * r1[3])); }
;                 sq += __shfl_xor(sq, 16); sq += __shfl_xor(sq, 32);
;                 if (fq == 0) ss_add(SS + row, sq);
.LBB0_393:
	s_or_b64 exec, exec, s[22:23]
	v_add_co_u32_e32 v38, vcc, 0xa0000, v160
	s_mov_b64 s[22:23], 0xa0000
	s_nop 0
	v_addc_co_u32_e32 v39, vcc, 0, v161, vcc
	s_waitcnt lgkmcnt(0)
	v_lshl_add_u64 v[40:41], v[160:161], 0, s[22:23]
	s_waitcnt vmcnt(18)
	s_nop 1
	v_mov_b64_e32 v[34:35], v[178:179]
	v_mov_b64_e32 v[36:37], v[180:181]
	v_lshlrev_b32_e32 v42, 16, v34
	v_and_b32_e32 v43, 0xffff0000, v34
	v_lshlrev_b32_e32 v34, 16, v35
	v_and_b32_e32 v35, 0xffff0000, v35
	v_lshlrev_b32_e32 v44, 16, v36
	v_and_b32_e32 v45, 0xffff0000, v36
	v_lshlrev_b32_e32 v36, 16, v37
	v_and_b32_e32 v37, 0xffff0000, v37
	v_pk_add_f32 v[34:35], v[32:33], v[34:35]
	v_pk_add_f32 v[42:43], v[30:31], v[42:43]
	v_pk_add_f32 v[36:37], v[28:29], v[36:37]
	v_pk_add_f32 v[44:45], v[26:27], v[44:45]
	v_cvt_pk_bf16_f32 v26, v42, v43
	v_cvt_pk_bf16_f32 v27, v34, v35
	v_mul_f32_e32 v43, v43, v43
	v_cvt_pk_bf16_f32 v28, v44, v45
	v_cvt_pk_bf16_f32 v29, v36, v37
	v_mul_f32_e32 v35, v35, v35
	v_mul_f32_e32 v45, v45, v45
	v_mul_f32_e32 v37, v37, v37
	v_fmac_f32_e32 v43, v42, v42
	v_fmac_f32_e32 v35, v34, v34
	v_fmac_f32_e32 v45, v44, v44
	v_fmac_f32_e32 v37, v36, v36
	v_add_f32_e32 v34, v43, v35
	v_add_f32_e32 v35, v45, v37
	v_add_f32_e32 v42, v34, v35
	global_store_dwordx4 v[38:39], v[26:29], off
	s_waitcnt vmcnt(18)
	s_nop 1
	v_mov_b64_e32 v[30:31], v[182:183]
	v_mov_b64_e32 v[32:33], v[184:185]
	v_lshlrev_b32_e32 v34, 16, v30
	v_and_b32_e32 v35, 0xffff0000, v30
	v_lshlrev_b32_e32 v30, 16, v31
	v_and_b32_e32 v31, 0xffff0000, v31
	v_lshlrev_b32_e32 v36, 16, v32
	v_and_b32_e32 v37, 0xffff0000, v32
	v_lshlrev_b32_e32 v32, 16, v33
	v_and_b32_e32 v33, 0xffff0000, v33
	v_pk_add_f32 v[24:25], v[24:25], v[30:31]
	v_pk_add_f32 v[22:23], v[22:23], v[34:35]
	v_pk_add_f32 v[30:31], v[20:21], v[32:33]
	v_pk_add_f32 v[32:33], v[18:19], v[36:37]
	v_mul_f32_e32 v18, v23, v23
	v_mul_f32_e32 v19, v25, v25
	v_mul_f32_e32 v20, v33, v33
	v_mul_f32_e32 v21, v31, v31
	v_fmac_f32_e32 v18, v22, v22
	v_fmac_f32_e32 v19, v24, v24
	v_fmac_f32_e32 v20, v32, v32
	v_fmac_f32_e32 v21, v30, v30
	v_add_f32_e32 v18, v18, v19
	v_add_f32_e32 v19, v20, v21
	v_add_f32_e32 v18, v18, v19
	v_add_f32_e32 v18, v42, v18
	ds_bpermute_b32 v19, v122, v18
	v_cvt_pk_bf16_f32 v20, v22, v23
	v_cvt_pk_bf16_f32 v21, v24, v25
	v_cvt_pk_bf16_f32 v22, v32, v33
	v_cvt_pk_bf16_f32 v23, v30, v31
	s_waitcnt lgkmcnt(0)
	v_add_f32_e32 v18, v18, v19
	ds_bpermute_b32 v19, v114, v18
	global_store_dwordx4 v[40:41], v[20:23], off offset:256
	s_and_saveexec_b64 s[22:23], s[6:7]
	s_cbranch_execz .LBB0_395
	s_waitcnt lgkmcnt(0)
	v_add_f32_e32 v18, v18, v19
	v_mul_f32_e32 v18, 0x49800000, v18
	v_trunc_f32_e32 v18, v18
	v_mul_f32_e32 v19, 0x2f800000, v18
	v_floor_f32_e32 v19, v19
	v_fmac_f32_e32 v18, 0xcf800000, v19
	v_cvt_u32_f32_e32 v18, v18
	v_cvt_u32_f32_e32 v19, v19
	v_lshl_add_u64 v[20:21], v[158:159], 3, s[2:3]
	global_atomic_add_x2 v[20:21], v[18:19], off offset:1280
.LBB0_395:
	s_or_b64 exec, exec, s[22:23]
	v_add_co_u32_e32 v22, vcc, 0xb0000, v160
	s_mov_b64 s[22:23], 0xb0000
	s_nop 0
	v_addc_co_u32_e32 v23, vcc, 0, v161, vcc
	s_waitcnt lgkmcnt(0)
	v_lshl_add_u64 v[24:25], v[160:161], 0, s[22:23]
	s_waitcnt vmcnt(16)
	s_nop 1
	v_mov_b64_e32 v[18:19], v[186:187]
	v_mov_b64_e32 v[20:21], v[188:189]
	v_lshlrev_b32_e32 v26, 16, v18
	v_and_b32_e32 v27, 0xffff0000, v18
	v_lshlrev_b32_e32 v18, 16, v19
	v_and_b32_e32 v19, 0xffff0000, v19
	v_lshlrev_b32_e32 v28, 16, v20
	v_and_b32_e32 v29, 0xffff0000, v20
	v_lshlrev_b32_e32 v20, 16, v21
	v_and_b32_e32 v21, 0xffff0000, v21
	v_pk_add_f32 v[18:19], v[16:17], v[18:19]
	v_pk_add_f32 v[26:27], v[14:15], v[26:27]
	v_pk_add_f32 v[20:21], v[12:13], v[20:21]
	v_pk_add_f32 v[28:29], v[10:11], v[28:29]
	v_cvt_pk_bf16_f32 v10, v26, v27
	v_cvt_pk_bf16_f32 v11, v18, v19
	v_mul_f32_e32 v27, v27, v27
	v_cvt_pk_bf16_f32 v12, v28, v29
	v_cvt_pk_bf16_f32 v13, v20, v21
	v_mul_f32_e32 v19, v19, v19
	v_mul_f32_e32 v29, v29, v29
	v_mul_f32_e32 v21, v21, v21
	v_fmac_f32_e32 v27, v26, v26
	v_fmac_f32_e32 v19, v18, v18
	v_fmac_f32_e32 v29, v28, v28
	v_fmac_f32_e32 v21, v20, v20
	v_add_f32_e32 v18, v27, v19
	v_add_f32_e32 v19, v29, v21
	v_add_f32_e32 v26, v18, v19
	global_store_dwordx4 v[22:23], v[10:13], off
	s_waitcnt vmcnt(16)
	s_nop 1
	v_mov_b64_e32 v[14:15], v[190:191]
	v_mov_b64_e32 v[16:17], v[192:193]
	v_lshlrev_b32_e32 v18, 16, v14
	v_and_b32_e32 v19, 0xffff0000, v14
	v_lshlrev_b32_e32 v14, 16, v15
	v_and_b32_e32 v15, 0xffff0000, v15
	v_lshlrev_b32_e32 v20, 16, v16
	v_and_b32_e32 v21, 0xffff0000, v16
	v_lshlrev_b32_e32 v16, 16, v17
	v_and_b32_e32 v17, 0xffff0000, v17
	v_pk_add_f32 v[8:9], v[8:9], v[14:15]
	v_pk_add_f32 v[6:7], v[6:7], v[18:19]
	v_pk_add_f32 v[14:15], v[4:5], v[16:17]
	v_pk_add_f32 v[16:17], v[2:3], v[20:21]
	v_mul_f32_e32 v2, v7, v7
	v_mul_f32_e32 v3, v9, v9
	v_mul_f32_e32 v4, v17, v17
	v_mul_f32_e32 v5, v15, v15
	v_fmac_f32_e32 v2, v6, v6
	v_fmac_f32_e32 v3, v8, v8
	v_fmac_f32_e32 v4, v16, v16
	v_fmac_f32_e32 v5, v14, v14
	v_add_f32_e32 v2, v2, v3
	v_add_f32_e32 v3, v4, v5
	v_add_f32_e32 v2, v2, v3
	v_add_f32_e32 v2, v26, v2
	ds_bpermute_b32 v3, v122, v2
	v_cvt_pk_bf16_f32 v4, v6, v7
	v_cvt_pk_bf16_f32 v5, v8, v9
	v_cvt_pk_bf16_f32 v6, v16, v17
	v_cvt_pk_bf16_f32 v7, v14, v15
	s_waitcnt lgkmcnt(0)
	v_add_f32_e32 v2, v2, v3
	ds_bpermute_b32 v3, v114, v2
	global_store_dwordx4 v[24:25], v[4:7], off offset:256
	s_and_saveexec_b64 s[22:23], s[6:7]
	s_cbranch_execz .LBB0_397
	s_waitcnt lgkmcnt(0)
	v_add_f32_e32 v2, v2, v3
	v_mul_f32_e32 v2, 0x49800000, v2
	v_trunc_f32_e32 v2, v2
	v_mul_f32_e32 v3, 0x2f800000, v2
	v_floor_f32_e32 v3, v3
	v_fmac_f32_e32 v2, 0xcf800000, v3
	v_cvt_u32_f32_e32 v2, v2
	v_cvt_u32_f32_e32 v3, v3
	v_lshl_add_u64 v[4:5], v[158:159], 3, s[2:3]
	global_atomic_add_x2 v[4:5], v[2:3], off offset:1408

; __device__ __forceinline__ void ss_add(ss_t* p, float v) { (void)__hip_atomic_fetch_add(p, (ss_t)(v * 1048576.0f), __ATOMIC_RELAXED, __HIP_MEMORY_SCOPE_AGENT); }
; __device__ __forceinline__ unsigned cvt_pk_bf16(float lo, float hi) { unsigned r; asm volatile("v_cvt_pk_bf16_f32 %0, %1, %2" : "=v"(r) : "v"(lo), "v"(hi)); return r; }
; __device__ __forceinline__ float bflo(unsigned w) { return __uint_as_float(w << 16); }
; __device__ __forceinline__ float bfhi(unsigned w) { return __uint_as_float(w & 0xffff0000u); }
;     __device__ __forceinline__ void operator()(const f32x4 (&acc)[2][2][4][2], const Unit& u, int wr, int wc, int fr, int fq) const {
;         const int row0 = u.pm * 256 + wr * 64 + fr, col0 = u.pn * 256 + wc * 32 + 8 * fq;
; #pragma unroll
;         for (int ai = 0; ai < 2; ++ai)
; #pragma unroll
;             for (int m = 0; m < 4; ++m) { const int row = row0 + ai * 128 + m * 16; const size_t off = (size_t)row * D + col0; float sq = 0.f;
; #pragma unroll
;                 for (int bj = 0; bj < 2; ++bj) { const size_t o = off + bj * 128; f32x4 b0, b1;
;                     if (XF32) { b0 = *(const f32x4*)((const float*)base + o); b1 = *(const f32x4*)((const float*)base + o + 4); }
;                     else { const u32x4 hw = *(const u32x4*)((const bf16_t*)base + o); b0 = (f32x4){bflo(hw.x), bfhi(hw.x), bflo(hw.y), bfhi(hw.y)}; b1 = (f32x4){bflo(hw.z), bfhi(hw.z), bflo(hw.w), bfhi(hw.w)}; }
;                     const f32x4 r0 = b0 + acc[ai][bj][m][0], r1 = b1 + acc[ai][bj][m][1];
;                     u32x4 hb; hb.x = cvt_pk_bf16(r0[0], r0[1]); hb.y = cvt_pk_bf16(r0[2], r0[3]); hb.z = cvt_pk_bf16(r1[0], r1[1]); hb.w = cvt_pk_bf16(r1[2], r1[3]); *(u32x4*)(HB + o) = hb;
;                     sq += ((r0[0] * r0[0] + r0[1] * r0[1]) + (r0[2] * r0[2] + r0[3] * r0[3])) + ((r1[0] * r1[0] + r1[1] * r1[1]) + (r1[2] * r1[2] + r1[3] * r1[3])); }
;                 sq += __shfl_xor(sq, 16); sq += __shfl_xor(sq, 32);
;                 if (fq == 0) ss_add(SS + row, sq);
.LBB0_445:
	s_load_dwordx8 s[52:59], s[92:93], 0x0
	v_lshl_add_u32 v160, s24, 8, v1
	v_lshl_or_b32 v158, s26, 8, v157
	v_ashrrev_i32_e32 v161, 31, v160
	v_ashrrev_i32_e32 v159, 31, v158
	v_lshlrev_b64 v[164:165], 11, v[160:161]
	v_lshl_add_u64 v[172:173], v[164:165], 0, v[158:159]
	s_waitcnt lgkmcnt(0)
	v_lshl_add_u64 v[174:175], v[172:173], 2, s[52:53]
	v_mov_b64_e32 v[204:205], v[174:175]
	s_mov_b64 s[24:25], 0x0
	v_lshl_add_u64 v[198:199], v[204:205], 0, s[24:25]
	global_load_dwordx4 v[176:179], v[198:199], off offset:16
	global_load_dwordx4 v[180:183], v[198:199], off
	global_load_dwordx4 v[184:187], v[198:199], off offset:528
	global_load_dwordx4 v[188:191], v[198:199], off offset:512
	s_mov_b64 s[24:25], 0x20000
	v_lshl_add_u64 v[198:199], v[204:205], 0, s[24:25]
	global_load_dwordx4 v[192:195], v[198:199], off offset:16
	global_load_dwordx4 v[214:217], v[198:199], off
	global_load_dwordx4 v[218:221], v[198:199], off offset:528
	global_load_dwordx4 v[222:225], v[198:199], off offset:512
	s_mov_b64 s[24:25], 0x40000
	v_lshl_add_u64 v[198:199], v[204:205], 0, s[24:25]
	global_load_dwordx4 v[226:229], v[198:199], off offset:16
	global_load_dwordx4 v[230:233], v[198:199], off
	global_load_dwordx4 v[234:237], v[198:199], off offset:528
	global_load_dwordx4 v[238:241], v[198:199], off offset:512
	v_cmp_lt_i32_e32 vcc, v207, v202
	s_waitcnt vmcnt(10)
	s_nop 1
	v_mov_b64_e32 v[164:165], v[176:177]
	v_mov_b64_e32 v[166:167], v[178:179]
	v_mov_b64_e32 v[168:169], v[180:181]
	v_mov_b64_e32 v[170:171], v[182:183]
	v_pk_add_f32 v[126:127], v[126:127], v[164:165]
	v_lshlrev_b64 v[164:165], 1, v[172:173]
	v_pk_add_f32 v[170:171], v[124:125], v[170:171]
	v_pk_add_f32 v[168:169], v[122:123], v[168:169]
	v_pk_add_f32 v[128:129], v[128:129], v[166:167]
	v_cvt_pk_bf16_f32 v122, v168, v169
	v_cvt_pk_bf16_f32 v123, v170, v171
	v_lshl_add_u64 v[166:167], s[96:97], 0, v[164:165]
	v_cvt_pk_bf16_f32 v124, v126, v127
	v_cvt_pk_bf16_f32 v125, v128, v129
	global_store_dwordx4 v[166:167], v[122:125], off
	v_or_b32_e32 v164, 0x100, v164
	s_nop 0
	v_mul_f32_e32 v122, v169, v169
	v_mul_f32_e32 v123, v171, v171
	v_fmac_f32_e32 v122, v168, v168
	v_fmac_f32_e32 v123, v170, v170
	v_add_f32_e32 v122, v122, v123
	v_mul_f32_e32 v123, v127, v127
	v_mul_f32_e32 v124, v129, v129
	v_fmac_f32_e32 v123, v126, v126
	v_fmac_f32_e32 v124, v128, v128
	v_add_f32_e32 v123, v123, v124
	v_add_f32_e32 v148, v122, v123
	s_waitcnt vmcnt(9)
	s_nop 1
	v_mov_b64_e32 v[122:123], v[184:185]
	v_mov_b64_e32 v[124:125], v[186:187]
	v_mov_b64_e32 v[126:127], v[188:189]
	v_mov_b64_e32 v[128:129], v[190:191]
	v_pk_add_f32 v[122:123], v[114:115], v[122:123]
	v_pk_add_f32 v[120:121], v[120:121], v[128:129]
	v_pk_add_f32 v[118:119], v[118:119], v[126:127]
	v_lshl_add_u64 v[126:127], s[96:97], 0, v[164:165]
	v_cvt_pk_bf16_f32 v114, v118, v119
	v_cvt_pk_bf16_f32 v115, v120, v121
	v_pk_add_f32 v[124:125], v[116:117], v[124:125]
	v_cvt_pk_bf16_f32 v116, v122, v123
	s_nop 0
	v_cvt_pk_bf16_f32 v117, v124, v125
	global_store_dwordx4 v[126:127], v[114:117], off
	s_nop 1
	v_mul_f32_e32 v114, v119, v119
	v_mul_f32_e32 v115, v121, v121
	v_fmac_f32_e32 v114, v118, v118
	v_fmac_f32_e32 v115, v120, v120
	v_add_f32_e32 v114, v114, v115
	v_mul_f32_e32 v115, v123, v123
	v_mul_f32_e32 v116, v125, v125
	v_fmac_f32_e32 v115, v122, v122
	v_fmac_f32_e32 v116, v124, v124
	v_add_f32_e32 v115, v115, v116
	v_add_f32_e32 v114, v114, v115
	v_cndmask_b32_e32 v115, v200, v207, vcc
	v_add_f32_e32 v114, v148, v114
	v_lshlrev_b32_e32 v116, 2, v115
	ds_bpermute_b32 v115, v116, v114
	v_cmp_lt_i32_e32 vcc, v208, v202
	s_waitcnt lgkmcnt(0)
	v_add_f32_e32 v114, v114, v115
	v_cndmask_b32_e32 v115, v200, v208, vcc
	v_lshlrev_b32_e32 v117, 2, v115
	ds_bpermute_b32 v115, v117, v114
	s_and_saveexec_b64 s[24:25], s[6:7]
	s_cbranch_execz .LBB0_447
	s_waitcnt lgkmcnt(0)
	v_add_f32_e32 v114, v114, v115
	v_mul_f32_e32 v114, 0x49800000, v114
	v_trunc_f32_e32 v114, v114
	v_mul_f32_e32 v115, 0x2f800000, v114
	v_floor_f32_e32 v115, v115
	v_fmac_f32_e32 v114, 0xcf800000, v115
	v_cvt_u32_f32_e32 v114, v114
	v_cvt_u32_f32_e32 v115, v115
	v_lshl_add_u64 v[118:119], v[160:161], 3, s[2:3]
	global_atomic_add_x2 v[118:119], v[114:115], off
.LBB0_447:
	s_or_b64 exec, exec, s[24:25]
	s_mov_b64 s[24:25], 0x60000
	v_lshl_add_u64 v[198:199], v[204:205], 0, s[24:25]
	global_load_dwordx4 v[176:179], v[198:199], off offset:16
	global_load_dwordx4 v[180:183], v[198:199], off
	global_load_dwordx4 v[184:187], v[198:199], off offset:528
	global_load_dwordx4 v[188:191], v[198:199], off offset:512
	s_load_dwordx8 s[52:59], s[92:93], 0x0
	v_or_b32_e32 v114, 16, v160
	s_waitcnt lgkmcnt(0)
	v_ashrrev_i32_e32 v115, 31, v114
	v_lshlrev_b64 v[118:119], 11, v[114:115]
	v_lshl_add_u64 v[126:127], v[118:119], 0, v[158:159]
	v_lshl_add_u64 v[128:129], v[126:127], 2, s[52:53]
	s_waitcnt vmcnt(13)
	s_nop 1
	v_mov_b64_e32 v[118:119], v[192:193]
	v_mov_b64_e32 v[120:121], v[194:195]
	v_mov_b64_e32 v[122:123], v[214:215]
	v_mov_b64_e32 v[124:125], v[216:217]
	v_pk_add_f32 v[118:119], v[106:107], v[118:119]
	v_pk_add_f32 v[110:111], v[110:111], v[122:123]
	v_lshlrev_b64 v[122:123], 1, v[126:127]
	v_pk_add_f32 v[112:113], v[112:113], v[124:125]
	v_cvt_pk_bf16_f32 v106, v110, v111
	v_lshl_add_u64 v[124:125], s[96:97], 0, v[122:123]
	v_cvt_pk_bf16_f32 v107, v112, v113
	v_pk_add_f32 v[120:121], v[108:109], v[120:121]
	v_cvt_pk_bf16_f32 v108, v118, v119
	v_or_b32_e32 v122, 0x100, v122
	v_cvt_pk_bf16_f32 v109, v120, v121
	global_store_dwordx4 v[124:125], v[106:109], off
	s_nop 1
	v_mul_f32_e32 v106, v111, v111
	v_mul_f32_e32 v107, v113, v113
	v_fmac_f32_e32 v106, v110, v110
	v_fmac_f32_e32 v107, v112, v112
	v_add_f32_e32 v106, v106, v107
	v_mul_f32_e32 v107, v119, v119
	v_mul_f32_e32 v108, v121, v121
	v_fmac_f32_e32 v107, v118, v118
	v_fmac_f32_e32 v108, v120, v120
	v_add_f32_e32 v107, v107, v108
	v_add_f32_e32 v118, v106, v107
	s_waitcnt vmcnt(12)
; __device__ __forceinline__ void ss_add(ss_t* p, float v) { (void)__hip_atomic_fetch_add(p, (ss_t)(v * 1048576.0f), __ATOMIC_RELAXED, __HIP_MEMORY_SCOPE_AGENT); }
; __device__ __forceinline__ unsigned cvt_pk_bf16(float lo, float hi) { unsigned r; asm volatile("v_cvt_pk_bf16_f32 %0, %1, %2" : "=v"(r) : "v"(lo), "v"(hi)); return r; }
; __device__ __forceinline__ float bflo(unsigned w) { return __uint_as_float(w << 16); }
; __device__ __forceinline__ float bfhi(unsigned w) { return __uint_as_float(w & 0xffff0000u); }
;     __device__ __forceinline__ void operator()(const f32x4 (&acc)[2][2][4][2], const Unit& u, int wr, int wc, int fr, int fq) const {
;         const int row0 = u.pm * 256 + wr * 64 + fr, col0 = u.pn * 256 + wc * 32 + 8 * fq;
; #pragma unroll
;         for (int ai = 0; ai < 2; ++ai)
; #pragma unroll
;             for (int m = 0; m < 4; ++m) { const int row = row0 + ai * 128 + m * 16; const size_t off = (size_t)row * D + col0; float sq = 0.f;
; #pragma unroll
;                 for (int bj = 0; bj < 2; ++bj) { const size_t o = off + bj * 128; f32x4 b0, b1;
;                     if (XF32) { b0 = *(const f32x4*)((const float*)base + o); b1 = *(const f32x4*)((const float*)base + o + 4); }
;                     else { const u32x4 hw = *(const u32x4*)((const bf16_t*)base + o); b0 = (f32x4){bflo(hw.x), bfhi(hw.x), bflo(hw.y), bfhi(hw.y)}; b1 = (f32x4){bflo(hw.z), bfhi(hw.z), bflo(hw.w), bfhi(hw.w)}; }
;                     const f32x4 r0 = b0 + acc[ai][bj][m][0], r1 = b1 + acc[ai][bj][m][1];
;                     u32x4 hb; hb.x = cvt_pk_bf16(r0[0], r0[1]); hb.y = cvt_pk_bf16(r0[2], r0[3]); hb.z = cvt_pk_bf16(r1[0], r1[1]); hb.w = cvt_pk_bf16(r1[2], r1[3]); *(u32x4*)(HB + o) = hb;
;                     sq += ((r0[0] * r0[0] + r0[1] * r0[1]) + (r0[2] * r0[2] + r0[3] * r0[3])) + ((r1[0] * r1[0] + r1[1] * r1[1]) + (r1[2] * r1[2] + r1[3] * r1[3])); }
;                 sq += __shfl_xor(sq, 16); sq += __shfl_xor(sq, 32);
;                 if (fq == 0) ss_add(SS + row, sq);
	s_nop 1
	v_mov_b64_e32 v[106:107], v[218:219]
	v_mov_b64_e32 v[108:109], v[220:221]
	v_mov_b64_e32 v[110:111], v[222:223]
	v_mov_b64_e32 v[112:113], v[224:225]
	v_pk_add_f32 v[106:107], v[98:99], v[106:107]
	v_pk_add_f32 v[104:105], v[104:105], v[112:113]
	v_pk_add_f32 v[102:103], v[102:103], v[110:111]
	v_lshl_add_u64 v[110:111], s[96:97], 0, v[122:123]
	v_cvt_pk_bf16_f32 v98, v102, v103
	v_cvt_pk_bf16_f32 v99, v104, v105
	v_pk_add_f32 v[108:109], v[100:101], v[108:109]
	v_cvt_pk_bf16_f32 v100, v106, v107
	s_nop 0
	v_cvt_pk_bf16_f32 v101, v108, v109
	global_store_dwordx4 v[110:111], v[98:101], off
	s_nop 1
	v_mul_f32_e32 v98, v103, v103
	v_mul_f32_e32 v99, v105, v105
	v_fmac_f32_e32 v98, v102, v102
	v_fmac_f32_e32 v99, v104, v104
	v_add_f32_e32 v98, v98, v99
	v_mul_f32_e32 v99, v107, v107
	v_mul_f32_e32 v100, v109, v109
	v_fmac_f32_e32 v99, v106, v106
	v_fmac_f32_e32 v100, v108, v108
	v_add_f32_e32 v99, v99, v100
	v_add_f32_e32 v98, v98, v99
	v_add_f32_e32 v98, v118, v98
	ds_bpermute_b32 v99, v116, v98
	s_waitcnt lgkmcnt(0)
	v_add_f32_e32 v98, v98, v99
	ds_bpermute_b32 v99, v117, v98
	s_and_saveexec_b64 s[24:25], s[6:7]
	s_cbranch_execz .LBB0_449
	s_waitcnt lgkmcnt(0)
	v_add_f32_e32 v98, v98, v99
	v_mul_f32_e32 v98, 0x49800000, v98
	v_trunc_f32_e32 v98, v98
	v_mul_f32_e32 v99, 0x2f800000, v98
	v_floor_f32_e32 v99, v99
	v_fmac_f32_e32 v98, 0xcf800000, v99
	v_cvt_u32_f32_e32 v98, v98
	v_cvt_u32_f32_e32 v99, v99
	v_lshl_add_u64 v[100:101], v[114:115], 3, s[2:3]
	global_atomic_add_x2 v[100:101], v[98:99], off
.LBB0_449:
	s_or_b64 exec, exec, s[24:25]
	s_mov_b64 s[24:25], 0x100000
	v_lshl_add_u64 v[198:199], v[204:205], 0, s[24:25]
	global_load_dwordx4 v[192:195], v[198:199], off offset:16
	global_load_dwordx4 v[214:217], v[198:199], off
	global_load_dwordx4 v[218:221], v[198:199], off offset:528
	global_load_dwordx4 v[222:225], v[198:199], off offset:512
	s_load_dwordx8 s[52:59], s[92:93], 0x0
	v_or_b32_e32 v98, 32, v160
	s_waitcnt lgkmcnt(0)
	v_ashrrev_i32_e32 v99, 31, v98
	v_lshlrev_b64 v[100:101], 11, v[98:99]
	v_lshl_add_u64 v[108:109], v[100:101], 0, v[158:159]
	v_lshl_add_u64 v[110:111], v[108:109], 2, s[52:53]
	s_waitcnt vmcnt(16)
	s_nop 1
	v_mov_b64_e32 v[100:101], v[226:227]
	v_mov_b64_e32 v[102:103], v[228:229]
	v_mov_b64_e32 v[104:105], v[230:231]
	v_mov_b64_e32 v[106:107], v[232:233]
	v_pk_add_f32 v[100:101], v[90:91], v[100:101]
	v_pk_add_f32 v[94:95], v[94:95], v[104:105]
	v_lshlrev_b64 v[104:105], 1, v[108:109]
	v_pk_add_f32 v[96:97], v[96:97], v[106:107]
	v_cvt_pk_bf16_f32 v90, v94, v95
	v_lshl_add_u64 v[106:107], s[96:97], 0, v[104:105]
	v_cvt_pk_bf16_f32 v91, v96, v97
	v_pk_add_f32 v[102:103], v[92:93], v[102:103]
	v_cvt_pk_bf16_f32 v92, v100, v101
	v_or_b32_e32 v104, 0x100, v104
	v_cvt_pk_bf16_f32 v93, v102, v103
	global_store_dwordx4 v[106:107], v[90:93], off
	s_nop 1
	v_mul_f32_e32 v90, v95, v95
	v_mul_f32_e32 v91, v97, v97
	v_fmac_f32_e32 v90, v94, v94
	v_fmac_f32_e32 v91, v96, v96
	v_add_f32_e32 v90, v90, v91
	v_mul_f32_e32 v91, v101, v101
	v_mul_f32_e32 v92, v103, v103
	v_fmac_f32_e32 v91, v100, v100
	v_fmac_f32_e32 v92, v102, v102
	v_add_f32_e32 v91, v91, v92
	v_add_f32_e32 v100, v90, v91
	s_waitcnt vmcnt(15)
	s_nop 1
	v_mov_b64_e32 v[90:91], v[234:235]
	v_mov_b64_e32 v[92:93], v[236:237]
	v_mov_b64_e32 v[94:95], v[238:239]
	v_mov_b64_e32 v[96:97], v[240:241]
	v_pk_add_f32 v[90:91], v[82:83], v[90:91]
	v_pk_add_f32 v[88:89], v[88:89], v[96:97]
	v_pk_add_f32 v[86:87], v[86:87], v[94:95]
	v_lshl_add_u64 v[94:95], s[96:97], 0, v[104:105]
	v_cvt_pk_bf16_f32 v82, v86, v87
	v_cvt_pk_bf16_f32 v83, v88, v89
	v_pk_add_f32 v[92:93], v[84:85], v[92:93]
	v_cvt_pk_bf16_f32 v84, v90, v91
	s_nop 0
	v_cvt_pk_bf16_f32 v85, v92, v93
	global_store_dwordx4 v[94:95], v[82:85], off
	s_nop 1
	v_mul_f32_e32 v82, v87, v87
	v_mul_f32_e32 v83, v89, v89
	v_fmac_f32_e32 v82, v86, v86
	v_fmac_f32_e32 v83, v88, v88
	v_add_f32_e32 v82, v82, v83
	v_mul_f32_e32 v83, v91, v91
	v_mul_f32_e32 v84, v93, v93
	v_fmac_f32_e32 v83, v90, v90
	v_fmac_f32_e32 v84, v92, v92
	v_add_f32_e32 v83, v83, v84
	v_add_f32_e32 v82, v82, v83
	v_add_f32_e32 v82, v100, v82
	ds_bpermute_b32 v83, v116, v82
	s_waitcnt lgkmcnt(0)
	v_add_f32_e32 v82, v82, v83
	ds_bpermute_b32 v83, v117, v82
	s_and_saveexec_b64 s[24:25], s[6:7]
	s_cbranch_execz .LBB0_451
	s_waitcnt lgkmcnt(0)
	v_add_f32_e32 v82, v82, v83
	v_mul_f32_e32 v82, 0x49800000, v82
	v_trunc_f32_e32 v82, v82
	v_mul_f32_e32 v83, 0x2f800000, v82
	v_floor_f32_e32 v83, v83
	v_fmac_f32_e32 v82, 0xcf800000, v83
	v_cvt_u32_f32_e32 v82, v82
	v_cvt_u32_f32_e32 v83, v83
	v_lshl_add_u64 v[84:85], v[98:99], 3, s[2:3]
	global_atomic_add_x2 v[84:85], v[82:83], off
; __device__ __forceinline__ void ss_add(ss_t* p, float v) { (void)__hip_atomic_fetch_add(p, (ss_t)(v * 1048576.0f), __ATOMIC_RELAXED, __HIP_MEMORY_SCOPE_AGENT); }
; __device__ __forceinline__ unsigned cvt_pk_bf16(float lo, float hi) { unsigned r; asm volatile("v_cvt_pk_bf16_f32 %0, %1, %2" : "=v"(r) : "v"(lo), "v"(hi)); return r; }
; __device__ __forceinline__ float bflo(unsigned w) { return __uint_as_float(w << 16); }
; __device__ __forceinline__ float bfhi(unsigned w) { return __uint_as_float(w & 0xffff0000u); }
;     __device__ __forceinline__ void operator()(const f32x4 (&acc)[2][2][4][2], const Unit& u, int wr, int wc, int fr, int fq) const {
;         const int row0 = u.pm * 256 + wr * 64 + fr, col0 = u.pn * 256 + wc * 32 + 8 * fq;
; #pragma unroll
;         for (int ai = 0; ai < 2; ++ai)
; #pragma unroll
;             for (int m = 0; m < 4; ++m) { const int row = row0 + ai * 128 + m * 16; const size_t off = (size_t)row * D + col0; float sq = 0.f;
; #pragma unroll
;                 for (int bj = 0; bj < 2; ++bj) { const size_t o = off + bj * 128; f32x4 b0, b1;
;                     if (XF32) { b0 = *(const f32x4*)((const float*)base + o); b1 = *(const f32x4*)((const float*)base + o + 4); }
;                     else { const u32x4 hw = *(const u32x4*)((const bf16_t*)base + o); b0 = (f32x4){bflo(hw.x), bfhi(hw.x), bflo(hw.y), bfhi(hw.y)}; b1 = (f32x4){bflo(hw.z), bfhi(hw.z), bflo(hw.w), bfhi(hw.w)}; }
;                     const f32x4 r0 = b0 + acc[ai][bj][m][0], r1 = b1 + acc[ai][bj][m][1];
;                     u32x4 hb; hb.x = cvt_pk_bf16(r0[0], r0[1]); hb.y = cvt_pk_bf16(r0[2], r0[3]); hb.z = cvt_pk_bf16(r1[0], r1[1]); hb.w = cvt_pk_bf16(r1[2], r1[3]); *(u32x4*)(HB + o) = hb;
;                     sq += ((r0[0] * r0[0] + r0[1] * r0[1]) + (r0[2] * r0[2] + r0[3] * r0[3])) + ((r1[0] * r1[0] + r1[1] * r1[1]) + (r1[2] * r1[2] + r1[3] * r1[3])); }
;                 sq += __shfl_xor(sq, 16); sq += __shfl_xor(sq, 32);
;                 if (fq == 0) ss_add(SS + row, sq);
.LBB0_451:
	s_or_b64 exec, exec, s[24:25]
	s_mov_b64 s[24:25], 0x120000
	v_lshl_add_u64 v[198:199], v[204:205], 0, s[24:25]
	global_load_dwordx4 v[226:229], v[198:199], off offset:16
	global_load_dwordx4 v[230:233], v[198:199], off
	global_load_dwordx4 v[234:237], v[198:199], off offset:528
	global_load_dwordx4 v[238:241], v[198:199], off offset:512
	s_load_dwordx8 s[52:59], s[92:93], 0x0
	v_or_b32_e32 v82, 48, v160
	s_waitcnt lgkmcnt(0)
	v_ashrrev_i32_e32 v83, 31, v82
	v_lshlrev_b64 v[84:85], 11, v[82:83]
	v_lshl_add_u64 v[92:93], v[84:85], 0, v[158:159]
	v_lshl_add_u64 v[94:95], v[92:93], 2, s[52:53]
	s_waitcnt vmcnt(16)
	s_nop 1
	v_mov_b64_e32 v[84:85], v[176:177]
	v_mov_b64_e32 v[86:87], v[178:179]
	v_mov_b64_e32 v[88:89], v[180:181]
	v_mov_b64_e32 v[90:91], v[182:183]
	v_pk_add_f32 v[84:85], v[74:75], v[84:85]
	v_pk_add_f32 v[78:79], v[78:79], v[88:89]
	v_lshlrev_b64 v[88:89], 1, v[92:93]
	v_pk_add_f32 v[80:81], v[80:81], v[90:91]
	v_cvt_pk_bf16_f32 v74, v78, v79
	v_lshl_add_u64 v[90:91], s[96:97], 0, v[88:89]
	v_cvt_pk_bf16_f32 v75, v80, v81
	v_pk_add_f32 v[86:87], v[76:77], v[86:87]
	v_cvt_pk_bf16_f32 v76, v84, v85
	v_or_b32_e32 v88, 0x100, v88
	v_cvt_pk_bf16_f32 v77, v86, v87
	global_store_dwordx4 v[90:91], v[74:77], off
	s_nop 1
	v_mul_f32_e32 v74, v79, v79
	v_mul_f32_e32 v75, v81, v81
	v_fmac_f32_e32 v74, v78, v78
	v_fmac_f32_e32 v75, v80, v80
	v_add_f32_e32 v74, v74, v75
	v_mul_f32_e32 v75, v85, v85
	v_mul_f32_e32 v76, v87, v87
	v_fmac_f32_e32 v75, v84, v84
	v_fmac_f32_e32 v76, v86, v86
	v_add_f32_e32 v75, v75, v76
	v_add_f32_e32 v84, v74, v75
	s_waitcnt vmcnt(15)
	s_nop 1
	v_mov_b64_e32 v[74:75], v[184:185]
	v_mov_b64_e32 v[76:77], v[186:187]
	v_mov_b64_e32 v[78:79], v[188:189]
	v_mov_b64_e32 v[80:81], v[190:191]
	v_pk_add_f32 v[74:75], v[66:67], v[74:75]
	v_pk_add_f32 v[72:73], v[72:73], v[80:81]
	v_pk_add_f32 v[70:71], v[70:71], v[78:79]
	v_lshl_add_u64 v[78:79], s[96:97], 0, v[88:89]
	v_cvt_pk_bf16_f32 v66, v70, v71
	v_cvt_pk_bf16_f32 v67, v72, v73
	v_pk_add_f32 v[76:77], v[68:69], v[76:77]
	v_cvt_pk_bf16_f32 v68, v74, v75
	s_nop 0
	v_cvt_pk_bf16_f32 v69, v76, v77
	global_store_dwordx4 v[78:79], v[66:69], off
	s_nop 1
	v_mul_f32_e32 v66, v71, v71
	v_mul_f32_e32 v67, v73, v73
	v_fmac_f32_e32 v66, v70, v70
	v_fmac_f32_e32 v67, v72, v72
	v_add_f32_e32 v66, v66, v67
	v_mul_f32_e32 v67, v75, v75
	v_mul_f32_e32 v68, v77, v77
	v_fmac_f32_e32 v67, v74, v74
	v_fmac_f32_e32 v68, v76, v76
	v_add_f32_e32 v67, v67, v68
	v_add_f32_e32 v66, v66, v67
	v_add_f32_e32 v66, v84, v66
	ds_bpermute_b32 v67, v116, v66
	s_waitcnt lgkmcnt(0)
	v_add_f32_e32 v66, v66, v67
	ds_bpermute_b32 v67, v117, v66
	s_and_saveexec_b64 s[24:25], s[6:7]
	s_cbranch_execz .LBB0_453
	s_waitcnt lgkmcnt(0)
	v_add_f32_e32 v66, v66, v67
	v_mul_f32_e32 v66, 0x49800000, v66
	v_trunc_f32_e32 v66, v66
	v_mul_f32_e32 v67, 0x2f800000, v66
	v_floor_f32_e32 v67, v67
	v_fmac_f32_e32 v66, 0xcf800000, v67
	v_cvt_u32_f32_e32 v66, v66
	v_cvt_u32_f32_e32 v67, v67
	v_lshl_add_u64 v[68:69], v[82:83], 3, s[2:3]
	global_atomic_add_x2 v[68:69], v[66:67], off
.LBB0_453:
	s_or_b64 exec, exec, s[24:25]
	s_mov_b64 s[24:25], 0x140000
	v_lshl_add_u64 v[198:199], v[204:205], 0, s[24:25]
	global_load_dwordx4 v[176:179], v[198:199], off offset:16
	global_load_dwordx4 v[180:183], v[198:199], off
	global_load_dwordx4 v[184:187], v[198:199], off offset:528
	global_load_dwordx4 v[188:191], v[198:199], off offset:512
	s_load_dwordx8 s[52:59], s[92:93], 0x0
	v_add_u32_e32 v66, 0x80, v160
	s_waitcnt lgkmcnt(0)
	v_ashrrev_i32_e32 v67, 31, v66
	v_lshlrev_b64 v[68:69], 11, v[66:67]
	v_lshl_add_u64 v[76:77], v[68:69], 0, v[158:159]
	v_lshl_add_u64 v[78:79], v[76:77], 2, s[52:53]
	s_waitcnt vmcnt(16)
	s_nop 1
	v_mov_b64_e32 v[68:69], v[192:193]
	v_mov_b64_e32 v[70:71], v[194:195]
	v_mov_b64_e32 v[72:73], v[214:215]
	v_mov_b64_e32 v[74:75], v[216:217]
	v_pk_add_f32 v[68:69], v[58:59], v[68:69]
	v_pk_add_f32 v[62:63], v[62:63], v[72:73]
	v_lshlrev_b64 v[72:73], 1, v[76:77]
	v_pk_add_f32 v[64:65], v[64:65], v[74:75]
	v_cvt_pk_bf16_f32 v58, v62, v63
	v_lshl_add_u64 v[74:75], s[96:97], 0, v[72:73]
	v_cvt_pk_bf16_f32 v59, v64, v65
	v_pk_add_f32 v[70:71], v[60:61], v[70:71]
	v_cvt_pk_bf16_f32 v60, v68, v69
	v_or_b32_e32 v72, 0x100, v72
	v_cvt_pk_bf16_f32 v61, v70, v71
	global_store_dwordx4 v[74:75], v[58:61], off
	s_nop 1
	v_mul_f32_e32 v58, v63, v63
	v_mul_f32_e32 v59, v65, v65
	v_fmac_f32_e32 v58, v62, v62
	v_fmac_f32_e32 v59, v64, v64
	v_add_f32_e32 v58, v58, v59
	v_mul_f32_e32 v59, v69, v69
	v_mul_f32_e32 v60, v71, v71
	v_fmac_f32_e32 v59, v68, v68
	v_fmac_f32_e32 v60, v70, v70
	v_add_f32_e32 v59, v59, v60
	v_add_f32_e32 v68, v58, v59
	s_waitcnt vmcnt(15)
	s_nop 1
	v_mov_b64_e32 v[58:59], v[218:219]
	v_mov_b64_e32 v[60:61], v[220:221]
	v_mov_b64_e32 v[62:63], v[222:223]
	v_mov_b64_e32 v[64:65], v[224:225]
	v_pk_add_f32 v[58:59], v[50:51], v[58:59]
	v_pk_add_f32 v[56:57], v[56:57], v[64:65]
	v_pk_add_f32 v[54:55], v[54:55], v[62:63]
	v_lshl_add_u64 v[62:63], s[96:97], 0, v[72:73]
	v_cvt_pk_bf16_f32 v50, v54, v55
	v_cvt_pk_bf16_f32 v51, v56, v57
	v_pk_add_f32 v[60:61], v[52:53], v[60:61]
	v_cvt_pk_bf16_f32 v52, v58, v59
	s_nop 0
	v_cvt_pk_bf16_f32 v53, v60, v61
	global_store_dwordx4 v[62:63], v[50:53], off
	s_nop 1
	v_mul_f32_e32 v50, v55, v55
	v_mul_f32_e32 v51, v57, v57
	v_fmac_f32_e32 v50, v54, v54
	v_fmac_f32_e32 v51, v56, v56
	v_add_f32_e32 v50, v50, v51
	v_mul_f32_e32 v51, v59, v59
	v_mul_f32_e32 v52, v61, v61
	v_fmac_f32_e32 v51, v58, v58
	v_fmac_f32_e32 v52, v60, v60
	v_add_f32_e32 v51, v51, v52
	v_add_f32_e32 v50, v50, v51
	v_add_f32_e32 v50, v68, v50
	ds_bpermute_b32 v51, v116, v50
	s_waitcnt lgkmcnt(0)
	v_add_f32_e32 v50, v50, v51
	ds_bpermute_b32 v51, v117, v50
	s_and_saveexec_b64 s[24:25], s[6:7]
	s_cbranch_execz .LBB0_455
	s_waitcnt lgkmcnt(0)
	v_add_f32_e32 v50, v50, v51
	v_mul_f32_e32 v50, 0x49800000, v50
	v_trunc_f32_e32 v50, v50
	v_mul_f32_e32 v51, 0x2f800000, v50
	v_floor_f32_e32 v51, v51
	v_fmac_f32_e32 v50, 0xcf800000, v51
	v_cvt_u32_f32_e32 v50, v50
	v_cvt_u32_f32_e32 v51, v51
	v_lshl_add_u64 v[52:53], v[66:67], 3, s[2:3]
	global_atomic_add_x2 v[52:53], v[50:51], off
; __device__ __forceinline__ void ss_add(ss_t* p, float v) { (void)__hip_atomic_fetch_add(p, (ss_t)(v * 1048576.0f), __ATOMIC_RELAXED, __HIP_MEMORY_SCOPE_AGENT); }
; __device__ __forceinline__ unsigned cvt_pk_bf16(float lo, float hi) { unsigned r; asm volatile("v_cvt_pk_bf16_f32 %0, %1, %2" : "=v"(r) : "v"(lo), "v"(hi)); return r; }
; __device__ __forceinline__ float bflo(unsigned w) { return __uint_as_float(w << 16); }
; __device__ __forceinline__ float bfhi(unsigned w) { return __uint_as_float(w & 0xffff0000u); }
;     __device__ __forceinline__ void operator()(const f32x4 (&acc)[2][2][4][2], const Unit& u, int wr, int wc, int fr, int fq) const {
;         const int row0 = u.pm * 256 + wr * 64 + fr, col0 = u.pn * 256 + wc * 32 + 8 * fq;
; #pragma unroll
;         for (int ai = 0; ai < 2; ++ai)
; #pragma unroll
;             for (int m = 0; m < 4; ++m) { const int row = row0 + ai * 128 + m * 16; const size_t off = (size_t)row * D + col0; float sq = 0.f;
; #pragma unroll
;                 for (int bj = 0; bj < 2; ++bj) { const size_t o = off + bj * 128; f32x4 b0, b1;
;                     if (XF32) { b0 = *(const f32x4*)((const float*)base + o); b1 = *(const f32x4*)((const float*)base + o + 4); }
;                     else { const u32x4 hw = *(const u32x4*)((const bf16_t*)base + o); b0 = (f32x4){bflo(hw.x), bfhi(hw.x), bflo(hw.y), bfhi(hw.y)}; b1 = (f32x4){bflo(hw.z), bfhi(hw.z), bflo(hw.w), bfhi(hw.w)}; }
;                     const f32x4 r0 = b0 + acc[ai][bj][m][0], r1 = b1 + acc[ai][bj][m][1];
;                     u32x4 hb; hb.x = cvt_pk_bf16(r0[0], r0[1]); hb.y = cvt_pk_bf16(r0[2], r0[3]); hb.z = cvt_pk_bf16(r1[0], r1[1]); hb.w = cvt_pk_bf16(r1[2], r1[3]); *(u32x4*)(HB + o) = hb;
;                     sq += ((r0[0] * r0[0] + r0[1] * r0[1]) + (r0[2] * r0[2] + r0[3] * r0[3])) + ((r1[0] * r1[0] + r1[1] * r1[1]) + (r1[2] * r1[2] + r1[3] * r1[3])); }
;                 sq += __shfl_xor(sq, 16); sq += __shfl_xor(sq, 32);
;                 if (fq == 0) ss_add(SS + row, sq);
.LBB0_455:
	s_or_b64 exec, exec, s[24:25]
	s_mov_b64 s[24:25], 0x160000
	v_lshl_add_u64 v[198:199], v[204:205], 0, s[24:25]
	global_load_dwordx4 v[192:195], v[198:199], off offset:16
	global_load_dwordx4 v[214:217], v[198:199], off
	global_load_dwordx4 v[218:221], v[198:199], off offset:528
	global_load_dwordx4 v[222:225], v[198:199], off offset:512
	s_load_dwordx8 s[52:59], s[92:93], 0x0
	v_add_u32_e32 v50, 0x90, v160
	s_waitcnt lgkmcnt(0)
	v_ashrrev_i32_e32 v51, 31, v50
	v_lshlrev_b64 v[52:53], 11, v[50:51]
	v_lshl_add_u64 v[60:61], v[52:53], 0, v[158:159]
	v_lshl_add_u64 v[62:63], v[60:61], 2, s[52:53]
	s_waitcnt vmcnt(16)
	s_nop 1
	v_mov_b64_e32 v[52:53], v[226:227]
	v_mov_b64_e32 v[54:55], v[228:229]
	v_mov_b64_e32 v[56:57], v[230:231]
	v_mov_b64_e32 v[58:59], v[232:233]
	v_pk_add_f32 v[52:53], v[42:43], v[52:53]
	v_pk_add_f32 v[46:47], v[46:47], v[56:57]
	v_lshlrev_b64 v[56:57], 1, v[60:61]
	v_pk_add_f32 v[48:49], v[48:49], v[58:59]
	v_cvt_pk_bf16_f32 v42, v46, v47
	v_lshl_add_u64 v[58:59], s[96:97], 0, v[56:57]
	v_cvt_pk_bf16_f32 v43, v48, v49
	v_pk_add_f32 v[54:55], v[44:45], v[54:55]
	v_cvt_pk_bf16_f32 v44, v52, v53
	v_or_b32_e32 v56, 0x100, v56
	v_cvt_pk_bf16_f32 v45, v54, v55
	global_store_dwordx4 v[58:59], v[42:45], off
	s_nop 1
	v_mul_f32_e32 v42, v47, v47
	v_mul_f32_e32 v43, v49, v49
	v_fmac_f32_e32 v42, v46, v46
	v_fmac_f32_e32 v43, v48, v48
	v_add_f32_e32 v42, v42, v43
	v_mul_f32_e32 v43, v53, v53
	v_mul_f32_e32 v44, v55, v55
	v_fmac_f32_e32 v43, v52, v52
	v_fmac_f32_e32 v44, v54, v54
	v_add_f32_e32 v43, v43, v44
	v_add_f32_e32 v52, v42, v43
	s_waitcnt vmcnt(15)
	s_nop 1
	v_mov_b64_e32 v[42:43], v[234:235]
	v_mov_b64_e32 v[44:45], v[236:237]
	v_mov_b64_e32 v[46:47], v[238:239]
	v_mov_b64_e32 v[48:49], v[240:241]
	v_pk_add_f32 v[42:43], v[34:35], v[42:43]
	v_pk_add_f32 v[40:41], v[40:41], v[48:49]
	v_pk_add_f32 v[38:39], v[38:39], v[46:47]
	v_lshl_add_u64 v[46:47], s[96:97], 0, v[56:57]
	v_cvt_pk_bf16_f32 v34, v38, v39
	v_cvt_pk_bf16_f32 v35, v40, v41
	v_pk_add_f32 v[44:45], v[36:37], v[44:45]
	v_cvt_pk_bf16_f32 v36, v42, v43
	s_nop 0
	v_cvt_pk_bf16_f32 v37, v44, v45
	global_store_dwordx4 v[46:47], v[34:37], off
	s_nop 1
	v_mul_f32_e32 v34, v39, v39
	v_mul_f32_e32 v35, v41, v41
	v_fmac_f32_e32 v34, v38, v38
	v_fmac_f32_e32 v35, v40, v40
	v_add_f32_e32 v34, v34, v35
	v_mul_f32_e32 v35, v43, v43
	v_mul_f32_e32 v36, v45, v45
	v_fmac_f32_e32 v35, v42, v42
	v_fmac_f32_e32 v36, v44, v44
	v_add_f32_e32 v35, v35, v36
	v_add_f32_e32 v34, v34, v35
	v_add_f32_e32 v34, v52, v34
	ds_bpermute_b32 v35, v116, v34
	s_waitcnt lgkmcnt(0)
	v_add_f32_e32 v34, v34, v35
	ds_bpermute_b32 v35, v117, v34
	s_and_saveexec_b64 s[24:25], s[6:7]
	s_cbranch_execz .LBB0_457
	s_waitcnt lgkmcnt(0)
	v_add_f32_e32 v34, v34, v35
	v_mul_f32_e32 v34, 0x49800000, v34
	v_trunc_f32_e32 v34, v34
	v_mul_f32_e32 v35, 0x2f800000, v34
	v_floor_f32_e32 v35, v35
	v_fmac_f32_e32 v34, 0xcf800000, v35
	v_cvt_u32_f32_e32 v34, v34
	v_cvt_u32_f32_e32 v35, v35
	v_lshl_add_u64 v[36:37], v[50:51], 3, s[2:3]
	global_atomic_add_x2 v[36:37], v[34:35], off
; __device__ __forceinline__ void ss_add(ss_t* p, float v) { (void)__hip_atomic_fetch_add(p, (ss_t)(v * 1048576.0f), __ATOMIC_RELAXED, __HIP_MEMORY_SCOPE_AGENT); }
; __device__ __forceinline__ unsigned cvt_pk_bf16(float lo, float hi) { unsigned r; asm volatile("v_cvt_pk_bf16_f32 %0, %1, %2" : "=v"(r) : "v"(lo), "v"(hi)); return r; }
; __device__ __forceinline__ float bflo(unsigned w) { return __uint_as_float(w << 16); }
; __device__ __forceinline__ float bfhi(unsigned w) { return __uint_as_float(w & 0xffff0000u); }
;     __device__ __forceinline__ void operator()(const f32x4 (&acc)[2][2][4][2], const Unit& u, int wr, int wc, int fr, int fq) const {
;         const int row0 = u.pm * 256 + wr * 64 + fr, col0 = u.pn * 256 + wc * 32 + 8 * fq;
; #pragma unroll
;         for (int ai = 0; ai < 2; ++ai)
; #pragma unroll
;             for (int m = 0; m < 4; ++m) { const int row = row0 + ai * 128 + m * 16; const size_t off = (size_t)row * D + col0; float sq = 0.f;
; #pragma unroll
;                 for (int bj = 0; bj < 2; ++bj) { const size_t o = off + bj * 128; f32x4 b0, b1;
;                     if (XF32) { b0 = *(const f32x4*)((const float*)base + o); b1 = *(const f32x4*)((const float*)base + o + 4); }
;                     else { const u32x4 hw = *(const u32x4*)((const bf16_t*)base + o); b0 = (f32x4){bflo(hw.x), bfhi(hw.x), bflo(hw.y), bfhi(hw.y)}; b1 = (f32x4){bflo(hw.z), bfhi(hw.z), bflo(hw.w), bfhi(hw.w)}; }
;                     const f32x4 r0 = b0 + acc[ai][bj][m][0], r1 = b1 + acc[ai][bj][m][1];
;                     u32x4 hb; hb.x = cvt_pk_bf16(r0[0], r0[1]); hb.y = cvt_pk_bf16(r0[2], r0[3]); hb.z = cvt_pk_bf16(r1[0], r1[1]); hb.w = cvt_pk_bf16(r1[2], r1[3]); *(u32x4*)(HB + o) = hb;
;                     sq += ((r0[0] * r0[0] + r0[1] * r0[1]) + (r0[2] * r0[2] + r0[3] * r0[3])) + ((r1[0] * r1[0] + r1[1] * r1[1]) + (r1[2] * r1[2] + r1[3] * r1[3])); }
;                 sq += __shfl_xor(sq, 16); sq += __shfl_xor(sq, 32);
;                 if (fq == 0) ss_add(SS + row, sq);
.LBB0_457:
	s_or_b64 exec, exec, s[24:25]
	s_load_dwordx8 s[52:59], s[92:93], 0x0
	v_add_u32_e32 v34, 0xa0, v160
	s_waitcnt lgkmcnt(0)
	v_ashrrev_i32_e32 v35, 31, v34
	v_lshlrev_b64 v[36:37], 11, v[34:35]
	v_lshl_add_u64 v[44:45], v[36:37], 0, v[158:159]
	v_lshl_add_u64 v[46:47], v[44:45], 2, s[52:53]
	s_waitcnt vmcnt(12)
	s_nop 1
	v_mov_b64_e32 v[36:37], v[176:177]
	v_mov_b64_e32 v[38:39], v[178:179]
	v_mov_b64_e32 v[40:41], v[180:181]
	v_mov_b64_e32 v[42:43], v[182:183]
	v_pk_add_f32 v[36:37], v[26:27], v[36:37]
	v_pk_add_f32 v[30:31], v[30:31], v[40:41]
	v_lshlrev_b64 v[40:41], 1, v[44:45]
	v_pk_add_f32 v[32:33], v[32:33], v[42:43]
	v_cvt_pk_bf16_f32 v26, v30, v31
	v_lshl_add_u64 v[42:43], s[96:97], 0, v[40:41]
	v_cvt_pk_bf16_f32 v27, v32, v33
	v_pk_add_f32 v[38:39], v[28:29], v[38:39]
	v_cvt_pk_bf16_f32 v28, v36, v37
	v_or_b32_e32 v40, 0x100, v40
	v_cvt_pk_bf16_f32 v29, v38, v39
	global_store_dwordx4 v[42:43], v[26:29], off
	s_nop 1
	v_mul_f32_e32 v26, v31, v31
	v_mul_f32_e32 v27, v33, v33
	v_fmac_f32_e32 v26, v30, v30
	v_fmac_f32_e32 v27, v32, v32
	v_add_f32_e32 v26, v26, v27
	v_mul_f32_e32 v27, v37, v37
	v_mul_f32_e32 v28, v39, v39
	v_fmac_f32_e32 v27, v36, v36
	v_fmac_f32_e32 v28, v38, v38
	v_add_f32_e32 v27, v27, v28
	v_add_f32_e32 v36, v26, v27
	s_waitcnt vmcnt(11)
	s_nop 1
	v_mov_b64_e32 v[26:27], v[184:185]
	v_mov_b64_e32 v[28:29], v[186:187]
	v_mov_b64_e32 v[30:31], v[188:189]
	v_mov_b64_e32 v[32:33], v[190:191]
	v_pk_add_f32 v[26:27], v[18:19], v[26:27]
	v_pk_add_f32 v[24:25], v[24:25], v[32:33]
	v_pk_add_f32 v[22:23], v[22:23], v[30:31]
	v_lshl_add_u64 v[30:31], s[96:97], 0, v[40:41]
	v_cvt_pk_bf16_f32 v18, v22, v23
	v_cvt_pk_bf16_f32 v19, v24, v25
	v_pk_add_f32 v[28:29], v[20:21], v[28:29]
	v_cvt_pk_bf16_f32 v20, v26, v27
	s_nop 0
	v_cvt_pk_bf16_f32 v21, v28, v29
	global_store_dwordx4 v[30:31], v[18:21], off
	s_nop 1
	v_mul_f32_e32 v18, v23, v23
	v_mul_f32_e32 v19, v25, v25
	v_fmac_f32_e32 v18, v22, v22
	v_fmac_f32_e32 v19, v24, v24
	v_add_f32_e32 v18, v18, v19
	v_mul_f32_e32 v19, v27, v27
	v_mul_f32_e32 v20, v29, v29
	v_fmac_f32_e32 v19, v26, v26
	v_fmac_f32_e32 v20, v28, v28
	v_add_f32_e32 v19, v19, v20
	v_add_f32_e32 v18, v18, v19
	v_add_f32_e32 v18, v36, v18
	ds_bpermute_b32 v19, v116, v18
	s_waitcnt lgkmcnt(0)
	v_add_f32_e32 v18, v18, v19
	ds_bpermute_b32 v19, v117, v18
	s_and_saveexec_b64 s[24:25], s[6:7]
	s_cbranch_execz .LBB0_459
	s_waitcnt lgkmcnt(0)
	v_add_f32_e32 v18, v18, v19
	v_mul_f32_e32 v18, 0x49800000, v18
	v_trunc_f32_e32 v18, v18
	v_mul_f32_e32 v19, 0x2f800000, v18
	v_floor_f32_e32 v19, v19
	v_fmac_f32_e32 v18, 0xcf800000, v19
	v_cvt_u32_f32_e32 v18, v18
	v_cvt_u32_f32_e32 v19, v19
	v_lshl_add_u64 v[20:21], v[34:35], 3, s[2:3]
	global_atomic_add_x2 v[20:21], v[18:19], off
.LBB0_459:
	s_or_b64 exec, exec, s[24:25]
	s_load_dwordx8 s[52:59], s[92:93], 0x0
	v_add_u32_e32 v18, 0xb0, v160
	s_waitcnt lgkmcnt(0)
	v_ashrrev_i32_e32 v19, 31, v18
	v_lshlrev_b64 v[20:21], 11, v[18:19]
	v_lshl_add_u64 v[28:29], v[20:21], 0, v[158:159]
	v_lshl_add_u64 v[30:31], v[28:29], 2, s[52:53]
	s_waitcnt vmcnt(8)
	s_nop 1
	v_mov_b64_e32 v[20:21], v[192:193]
	v_mov_b64_e32 v[22:23], v[194:195]
	v_mov_b64_e32 v[24:25], v[214:215]
	v_mov_b64_e32 v[26:27], v[216:217]
	v_pk_add_f32 v[20:21], v[10:11], v[20:21]
	v_pk_add_f32 v[14:15], v[14:15], v[24:25]
	v_lshlrev_b64 v[24:25], 1, v[28:29]
	v_pk_add_f32 v[16:17], v[16:17], v[26:27]
	v_cvt_pk_bf16_f32 v10, v14, v15
	v_lshl_add_u64 v[26:27], s[96:97], 0, v[24:25]
	v_cvt_pk_bf16_f32 v11, v16, v17
	v_pk_add_f32 v[22:23], v[12:13], v[22:23]
	v_cvt_pk_bf16_f32 v12, v20, v21
	v_or_b32_e32 v24, 0x100, v24
	v_cvt_pk_bf16_f32 v13, v22, v23
	global_store_dwordx4 v[26:27], v[10:13], off
	s_nop 1
	v_mul_f32_e32 v10, v15, v15
	v_mul_f32_e32 v11, v17, v17
	v_fmac_f32_e32 v10, v14, v14
	v_fmac_f32_e32 v11, v16, v16
	v_add_f32_e32 v10, v10, v11
	v_mul_f32_e32 v11, v21, v21
	v_mul_f32_e32 v12, v23, v23
	v_fmac_f32_e32 v11, v20, v20
	v_fmac_f32_e32 v12, v22, v22
	v_add_f32_e32 v11, v11, v12
	v_add_f32_e32 v20, v10, v11
	s_waitcnt vmcnt(7)
	s_nop 1
	v_mov_b64_e32 v[10:11], v[218:219]
	v_mov_b64_e32 v[12:13], v[220:221]
	v_mov_b64_e32 v[14:15], v[222:223]
	v_mov_b64_e32 v[16:17], v[224:225]
	v_pk_add_f32 v[10:11], v[2:3], v[10:11]
	v_pk_add_f32 v[8:9], v[8:9], v[16:17]
	v_pk_add_f32 v[6:7], v[6:7], v[14:15]
	v_lshl_add_u64 v[14:15], s[96:97], 0, v[24:25]
	v_cvt_pk_bf16_f32 v2, v6, v7
	v_cvt_pk_bf16_f32 v3, v8, v9
	v_pk_add_f32 v[12:13], v[4:5], v[12:13]
	v_cvt_pk_bf16_f32 v4, v10, v11
	s_nop 0
	v_cvt_pk_bf16_f32 v5, v12, v13
	global_store_dwordx4 v[14:15], v[2:5], off
	s_nop 1
	v_mul_f32_e32 v2, v7, v7
	v_mul_f32_e32 v3, v9, v9
	v_fmac_f32_e32 v2, v6, v6
	v_fmac_f32_e32 v3, v8, v8
	v_add_f32_e32 v2, v2, v3
	v_mul_f32_e32 v3, v11, v11
	v_mul_f32_e32 v4, v13, v13
	v_fmac_f32_e32 v3, v10, v10
	v_fmac_f32_e32 v4, v12, v12
	v_add_f32_e32 v3, v3, v4
	v_add_f32_e32 v2, v2, v3
	v_add_f32_e32 v2, v20, v2
	ds_bpermute_b32 v3, v116, v2
	s_waitcnt lgkmcnt(0)
	v_add_f32_e32 v2, v2, v3
	ds_bpermute_b32 v3, v117, v2
	s_and_saveexec_b64 s[24:25], s[6:7]
	s_cbranch_execz .LBB0_461
	s_waitcnt lgkmcnt(0)
	v_add_f32_e32 v2, v2, v3
	v_mul_f32_e32 v2, 0x49800000, v2
	v_trunc_f32_e32 v2, v2
	v_mul_f32_e32 v3, 0x2f800000, v2
	v_floor_f32_e32 v3, v3
	v_fmac_f32_e32 v2, 0xcf800000, v3
	v_cvt_u32_f32_e32 v2, v2
	v_cvt_u32_f32_e32 v3, v3
	v_lshl_add_u64 v[4:5], v[18:19], 3, s[2:3]
	global_atomic_add_x2 v[4:5], v[2:3], off

; __device__ __forceinline__ unsigned cvt_pk_bf16(float lo, float hi) { unsigned r; asm volatile("v_cvt_pk_bf16_f32 %0, %1, %2" : "=v"(r) : "v"(lo), "v"(hi)); return r; }
; __device__ __forceinline__ float bflo(unsigned w) { return __uint_as_float(w << 16); }
; __device__ __forceinline__ float bfhi(unsigned w) { return __uint_as_float(w & 0xffff0000u); }
;     __device__ __forceinline__ void operator()(const f32x4 (&acc)[2][2][4][2], const Unit& u, int wr, int wc, int fr, int fq) const {
;         const int row0 = u.pm * 256 + wr * 64 + fr; const int chb = (u.pn >> 1) * 256 + (u.pn & 1) * 128 + wc * 32 + 4 * fq;
; #pragma unroll
;         for (int n = 0; n < 2; ++n) { const int ch = chb + 16 * n;
;             const f32x4 br4 = *(const f32x4*)(br + ch), bi4 = *(const f32x4*)(bi + ch), sp4 = *(const f32x4*)(spt + ch);
;             const bool slow = __ballot(fminf(fminf(sp4[0], sp4[1]), fminf(sp4[2], sp4[3])) <= -0.25f) != 0ull;
; #pragma unroll
;             for (int ai = 0; ai < 2; ++ai)
; #pragma unroll
;                 for (int m = 0; m < 4; ++m) { const size_t off = (size_t)(row0 + ai * 128 + m * 16) * D + ch;
;                     const u32x2 xw = *(const u32x2*)(XRC + off);
;                     const float xr[4] = {bflo(xw.x), bfhi(xw.x), bflo(xw.y), bfhi(xw.y)};
;                     f32x4 dv, bv;
; #pragma unroll
;                     for (int j = 0; j < 4; ++j) { float r, ig; sigmoid2(acc[ai][0][m][n][j] + br4[j], acc[ai][1][m][n][j] + bi4[j], r, ig);
;                         const float la = r * sp4[j]; float dd = neg_expm1_small(la); if (slow) dd = la > -0.25f ? dd : 1.0f - __expf(la);
;                         dv[j] = dd; bv[j] = __builtin_sqrtf(dd * (2.0f - dd)) * ig * xr[j]; }
;                     u32x2 dw, bw; dw.x = cvt_pk_bf16(dv[0], dv[1]); dw.y = cvt_pk_bf16(dv[2], dv[3]); bw.x = cvt_pk_bf16(bv[0], bv[1]); bw.y = cvt_pk_bf16(bv[2], bv[3]);
;                     *(u32x2*)(DD + off) = dw; *(u32x2*)(BB + off) = bw; asm volatile("" ::: "memory"); } }
.LBB0_504:
	s_load_dwordx2 s[8:9], s[92:93], 0x50
	v_lshl_or_b32 v170, s34, 7, v157
	v_ashrrev_i32_e32 v171, 31, v170
	v_lshlrev_b64 v[82:83], 2, v[170:171]
	v_lshl_add_u32 v178, s36, 8, v1
	s_waitcnt lgkmcnt(0)
	v_lshl_add_u64 v[172:173], s[8:9], 0, v[82:83]
	s_load_dwordx2 s[8:9], s[92:93], 0x60
	global_load_dwordx4 v[86:89], v[172:173], off
	v_ashrrev_i32_e32 v179, 31, v178
	v_lshlrev_b64 v[176:177], 11, v[178:179]
	v_lshl_add_u64 v[180:181], v[176:177], 0, v[170:171]
	s_waitcnt lgkmcnt(0)
	v_lshl_add_u64 v[174:175], s[8:9], 0, v[82:83]
	global_load_dwordx4 v[90:93], v[174:175], off
	v_lshl_add_u64 v[82:83], s[14:15], 0, v[82:83]
	global_load_dwordx4 v[82:85], v[82:83], off
	v_lshlrev_b64 v[180:181], 1, v[180:181]
	v_lshl_add_u64 v[184:185], s[0:1], 0, v[180:181]
	v_mov_b64_e32 v[194:195], v[184:185]
	v_mov_b64_e32 v[192:193], v[184:185]
	global_load_dwordx2 v[214:215], v[192:193], off
	global_load_dwordx2 v[230:231], v[192:193], off offset:32
	s_mov_b64 s[8:9], 0x10000
	v_lshl_add_u64 v[192:193], v[192:193], 0, s[8:9]
	global_load_dwordx2 v[216:217], v[192:193], off
	global_load_dwordx2 v[232:233], v[192:193], off offset:32
	s_mov_b64 s[8:9], 0x10000
	v_lshl_add_u64 v[192:193], v[192:193], 0, s[8:9]
	global_load_dwordx2 v[218:219], v[192:193], off
	global_load_dwordx2 v[234:235], v[192:193], off offset:32
	s_mov_b64 s[8:9], 0x10000
	v_lshl_add_u64 v[192:193], v[192:193], 0, s[8:9]
	global_load_dwordx2 v[220:221], v[192:193], off
	global_load_dwordx2 v[236:237], v[192:193], off offset:32
	s_mov_b64 s[8:9], 0x50000
	v_lshl_add_u64 v[192:193], v[192:193], 0, s[8:9]
	global_load_dwordx2 v[222:223], v[192:193], off
	global_load_dwordx2 v[238:239], v[192:193], off offset:32
	s_mov_b64 s[8:9], 0x10000
	v_lshl_add_u64 v[192:193], v[192:193], 0, s[8:9]
	global_load_dwordx2 v[224:225], v[192:193], off
	global_load_dwordx2 v[240:241], v[192:193], off offset:32
	s_mov_b64 s[8:9], 0x10000
	v_lshl_add_u64 v[192:193], v[192:193], 0, s[8:9]
	global_load_dwordx2 v[226:227], v[192:193], off
	global_load_dwordx2 v[188:189], v[192:193], off offset:32
	s_mov_b64 s[8:9], 0x10000
	v_lshl_add_u64 v[192:193], v[192:193], 0, s[8:9]
	global_load_dwordx2 v[228:229], v[192:193], off
	global_load_dwordx2 v[190:191], v[192:193], off offset:32
	s_mov_b32 s25, 0xbe800000
	s_mov_b32 s27, 0xf800000
	s_waitcnt vmcnt(15)
	v_mov_b64_e32 v[184:185], v[214:215]
	v_add_f32_e32 v134, v134, v86
	v_mul_f32_e32 v134, 0xbfb8aa3b, v134
	v_min_f32_e32 v134, 0x42700000, v134
	v_exp_f32_e32 v186, v134
	v_add_f32_e32 v130, v130, v86
	v_add_f32_e32 v138, v138, v90
	v_mul_f32_e32 v134, 0xbfb8aa3b, v138
	v_min_f32_e32 v134, 0x42700000, v134
	v_exp_f32_e32 v187, v134
	v_max_f32_e32 v148, v85, v85
	v_max_f32_e32 v149, v84, v84
	v_min_f32_e32 v148, v149, v148
	v_pk_add_f32 v[186:187], v[186:187], 1.0 op_sel_hi:[1,0]
	v_min3_f32 v148, v82, v83, v148
	v_mul_f32_e32 v134, v186, v187
	v_rcp_f32_e32 v134, v134
	v_cmp_ge_f32_e32 vcc, s25, v148
	s_cmp_eq_u64 vcc, 0
	s_cselect_b64 s[34:35], -1, 0
	v_mul_f32_e32 v138, v187, v134
	v_mul_f32_e32 v138, v82, v138
	v_fmamk_f32 v150, v138, 0x3ab60b61, v196
	v_fmaak_f32 v150, v138, v150, 0x3d2aaaab
	v_fmaak_f32 v150, v138, v150, 0x3e2aaaab
	v_fma_f32 v150, v138, v150, 0.5
	v_fma_f32 v150, v138, v150, 1.0
	v_mul_f32_e64 v150, v150, -v138
	v_cmp_lt_f32_e32 vcc, s25, v138
	v_mul_f32_e32 v138, 0x3fb8aa3b, v138
	v_exp_f32_e32 v138, v138
	s_or_b64 vcc, s[34:35], vcc
	v_lshlrev_b32_e32 v148, 16, v184
	v_and_b32_e32 v149, 0xffff0000, v184
	v_sub_f32_e32 v138, 1.0, v138
	v_cndmask_b32_e32 v138, v138, v150, vcc
	v_sub_f32_e32 v150, 2.0, v138
	v_mul_f32_e32 v150, v138, v150
	v_cmp_gt_f32_e32 vcc, s27, v150
	v_mul_f32_e32 v151, 0x4f800000, v150
	v_lshlrev_b32_e32 v184, 16, v185
	v_cndmask_b32_e32 v150, v150, v151, vcc
	v_sqrt_f32_e32 v151, v150
	v_and_b32_e32 v179, 0xffff0000, v185
	v_mul_f32_e32 v134, v186, v134
	v_add_f32_e32 v126, v126, v90
	v_add_u32_e32 v183, -1, v151
	v_fma_f32 v185, -v183, v151, v150
	v_cmp_ge_f32_e64 s[8:9], 0, v185
	v_add_u32_e32 v185, 1, v151
	v_mul_f32_e32 v130, 0xbfb8aa3b, v130
	v_cndmask_b32_e64 v183, v151, v183, s[8:9]
	v_fma_f32 v151, -v185, v151, v150
	v_cmp_lt_f32_e64 s[8:9], 0, v151
	v_mul_f32_e32 v126, 0xbfb8aa3b, v126
	v_min_f32_e32 v130, 0x42700000, v130
	v_cndmask_b32_e64 v151, v183, v185, s[8:9]
	v_mul_f32_e32 v183, 0x37800000, v151
	v_cndmask_b32_e32 v151, v151, v183, vcc
	v_cmp_class_f32_e32 vcc, v150, v197
	v_min_f32_e32 v126, 0x42700000, v126
	v_add_f32_e32 v127, v127, v91
	v_cndmask_b32_e32 v150, v151, v150, vcc
	v_mul_f32_e32 v134, v134, v150
	v_mul_f32_e32 v183, v134, v148
	v_add_f32_e32 v134, v135, v87
	v_add_f32_e32 v135, v139, v91
	v_mul_f32_e32 v134, 0xbfb8aa3b, v134
	v_mul_f32_e32 v135, 0xbfb8aa3b, v135
	v_min_f32_e32 v134, 0x42700000, v134
	v_min_f32_e32 v135, 0x42700000, v135
	v_exp_f32_e32 v134, v134
	v_exp_f32_e32 v135, v135
	v_mul_f32_e32 v127, 0xbfb8aa3b, v127
	v_min_f32_e32 v127, 0x42700000, v127
	v_exp_f32_e32 v127, v127
	v_pk_add_f32 v[134:135], v[134:135], 1.0 op_sel_hi:[1,0]
	v_add_f32_e32 v122, v122, v86
	v_mul_f32_e32 v139, v134, v135
	v_rcp_f32_e32 v139, v139
	v_add_f32_e32 v118, v118, v90
	v_mul_f32_e32 v122, 0xbfb8aa3b, v122
	v_mul_f32_e32 v118, 0xbfb8aa3b, v118
	v_mul_f32_e32 v135, v135, v139
	v_mul_f32_e32 v135, v83, v135
	v_mul_f32_e32 v134, v134, v139
	v_fmamk_f32 v139, v135, 0x3ab60b61, v196
	v_fmaak_f32 v139, v135, v139, 0x3d2aaaab
	v_fmaak_f32 v139, v135, v139, 0x3e2aaaab
	v_fma_f32 v139, v135, v139, 0.5
	v_fma_f32 v139, v135, v139, 1.0
	v_mul_f32_e64 v139, v139, -v135
	v_cmp_lt_f32_e32 vcc, s25, v135
	v_mul_f32_e32 v135, 0x3fb8aa3b, v135
	v_exp_f32_e32 v135, v135
	s_or_b64 vcc, s[34:35], vcc
; __device__ __forceinline__ unsigned cvt_pk_bf16(float lo, float hi) { unsigned r; asm volatile("v_cvt_pk_bf16_f32 %0, %1, %2" : "=v"(r) : "v"(lo), "v"(hi)); return r; }
; __device__ __forceinline__ float bflo(unsigned w) { return __uint_as_float(w << 16); }
; __device__ __forceinline__ float bfhi(unsigned w) { return __uint_as_float(w & 0xffff0000u); }
;     __device__ __forceinline__ void operator()(const f32x4 (&acc)[2][2][4][2], const Unit& u, int wr, int wc, int fr, int fq) const {
;     ...
;                 for (int m = 0; m < 4; ++m) { const size_t off = (size_t)(row0 + ai * 128 + m * 16) * D + ch;
;                     const u32x2 xw = *(const u32x2*)(XRC + off);
;                     const float xr[4] = {bflo(xw.x), bfhi(xw.x), bflo(xw.y), bfhi(xw.y)};
;                     f32x4 dv, bv;
; #pragma unroll
;                     for (int j = 0; j < 4; ++j) { float r, ig; sigmoid2(acc[ai][0][m][n][j] + br4[j], acc[ai][1][m][n][j] + bi4[j], r, ig);
;                         const float la = r * sp4[j]; float dd = neg_expm1_small(la); if (slow) dd = la > -0.25f ? dd : 1.0f - __expf(la);
;                         dv[j] = dd; bv[j] = __builtin_sqrtf(dd * (2.0f - dd)) * ig * xr[j]; }
;                     u32x2 dw, bw; dw.x = cvt_pk_bf16(dv[0], dv[1]); dw.y = cvt_pk_bf16(dv[2], dv[3]); bw.x = cvt_pk_bf16(bv[0], bv[1]); bw.y = cvt_pk_bf16(bv[2], bv[3]);
;                     *(u32x2*)(DD + off) = dw; *(u32x2*)(BB + off) = bw; asm volatile("" ::: "memory"); } }
	v_min_f32_e32 v122, 0x42700000, v122
	v_min_f32_e32 v118, 0x42700000, v118
	v_sub_f32_e32 v135, 1.0, v135
	v_cndmask_b32_e32 v139, v135, v139, vcc
	v_sub_f32_e32 v135, 2.0, v139
	v_mul_f32_e32 v135, v139, v135
	v_cmp_gt_f32_e32 vcc, s27, v135
	v_mul_f32_e32 v148, 0x4f800000, v135
	v_add_f32_e32 v119, v119, v91
	v_cndmask_b32_e32 v135, v135, v148, vcc
	v_sqrt_f32_e32 v148, v135
	v_mul_f32_e32 v119, 0xbfb8aa3b, v119
	v_min_f32_e32 v119, 0x42700000, v119
	v_exp_f32_e32 v119, v119
	v_add_u32_e32 v150, -1, v148
	v_fma_f32 v151, -v150, v148, v135
	v_cmp_ge_f32_e64 s[8:9], 0, v151
	v_add_u32_e32 v151, 1, v148
	v_add_f32_e32 v114, v114, v86
	v_cndmask_b32_e64 v150, v148, v150, s[8:9]
	v_fma_f32 v148, -v151, v148, v135
	v_cmp_lt_f32_e64 s[8:9], 0, v148
	v_add_f32_e32 v110, v110, v90
	v_mul_f32_e32 v114, 0xbfb8aa3b, v114
	v_cndmask_b32_e64 v148, v150, v151, s[8:9]
	v_mul_f32_e32 v150, 0x37800000, v148
	v_cndmask_b32_e32 v148, v148, v150, vcc
	v_cmp_class_f32_e32 vcc, v135, v197
	v_mul_f32_e32 v110, 0xbfb8aa3b, v110
	v_min_f32_e32 v114, 0x42700000, v114
	v_cndmask_b32_e32 v135, v148, v135, vcc
	v_mul_f32_e32 v134, v134, v135
	v_mul_f32_e32 v185, v134, v149
	v_add_f32_e32 v134, v136, v88
	v_add_f32_e32 v135, v140, v92
	v_mul_f32_e32 v134, 0xbfb8aa3b, v134
	v_mul_f32_e32 v135, 0xbfb8aa3b, v135
	v_min_f32_e32 v134, 0x42700000, v134
	v_min_f32_e32 v135, 0x42700000, v135
	v_exp_f32_e32 v134, v134
	v_exp_f32_e32 v135, v135
	v_min_f32_e32 v110, 0x42700000, v110
	v_add_f32_e32 v111, v111, v91
	v_mul_f32_e32 v111, 0xbfb8aa3b, v111
	v_pk_add_f32 v[134:135], v[134:135], 1.0 op_sel_hi:[1,0]
	v_min_f32_e32 v111, 0x42700000, v111
	v_mul_f32_e32 v136, v134, v135
	v_rcp_f32_e32 v136, v136
	v_exp_f32_e32 v111, v111
	v_add_f32_e32 v106, v106, v86
	v_add_f32_e32 v102, v102, v90
	v_mul_f32_e32 v135, v135, v136
	v_mul_f32_e32 v135, v84, v135
	v_mul_f32_e32 v134, v134, v136
	v_fmamk_f32 v136, v135, 0x3ab60b61, v196
	v_fmaak_f32 v136, v135, v136, 0x3d2aaaab
	v_fmaak_f32 v136, v135, v136, 0x3e2aaaab
	v_fma_f32 v136, v135, v136, 0.5
	v_fma_f32 v136, v135, v136, 1.0
	v_mul_f32_e64 v136, v136, -v135
	v_cmp_lt_f32_e32 vcc, s25, v135
	v_mul_f32_e32 v135, 0x3fb8aa3b, v135
	v_exp_f32_e32 v135, v135
	s_or_b64 vcc, s[34:35], vcc
	v_mul_f32_e32 v106, 0xbfb8aa3b, v106
	v_mul_f32_e32 v102, 0xbfb8aa3b, v102
	v_sub_f32_e32 v135, 1.0, v135
	v_cndmask_b32_e32 v136, v135, v136, vcc
	v_sub_f32_e32 v135, 2.0, v136
	v_mul_f32_e32 v135, v136, v135
	v_cmp_gt_f32_e32 vcc, s27, v135
	v_mul_f32_e32 v140, 0x4f800000, v135
	v_min_f32_e32 v106, 0x42700000, v106
	v_cndmask_b32_e32 v135, v135, v140, vcc
	v_sqrt_f32_e32 v140, v135
	v_min_f32_e32 v102, 0x42700000, v102
	v_add_f32_e32 v103, v103, v91
	v_mul_f32_e32 v103, 0xbfb8aa3b, v103
	v_add_u32_e32 v148, -1, v140
	v_fma_f32 v149, -v148, v140, v135
	v_cmp_ge_f32_e64 s[8:9], 0, v149
	v_add_u32_e32 v149, 1, v140
	v_min_f32_e32 v103, 0x42700000, v103
	v_cndmask_b32_e64 v148, v140, v148, s[8:9]
	v_fma_f32 v140, -v149, v140, v135
	v_cmp_lt_f32_e64 s[8:9], 0, v140
	v_exp_f32_e32 v103, v103
	v_add_f32_e32 v98, v98, v86
	v_cndmask_b32_e64 v140, v148, v149, s[8:9]
	v_mul_f32_e32 v148, 0x37800000, v140
	v_cndmask_b32_e32 v140, v140, v148, vcc
	v_cmp_class_f32_e32 vcc, v135, v197
	v_add_f32_e32 v94, v94, v90
	v_mul_f32_e32 v98, 0xbfb8aa3b, v98
	v_cndmask_b32_e32 v135, v140, v135, vcc
	v_mul_f32_e32 v134, v134, v135
	v_mul_f32_e32 v140, v134, v184
	v_add_f32_e32 v134, v137, v89
	v_add_f32_e32 v135, v141, v93
	v_mul_f32_e32 v134, 0xbfb8aa3b, v134
	v_mul_f32_e32 v135, 0xbfb8aa3b, v135
	v_min_f32_e32 v134, 0x42700000, v134
	v_min_f32_e32 v135, 0x42700000, v135
	v_exp_f32_e32 v134, v134
	v_exp_f32_e32 v135, v135
	v_mul_f32_e32 v94, 0xbfb8aa3b, v94
	v_min_f32_e32 v98, 0x42700000, v98
	v_min_f32_e32 v94, 0x42700000, v94
	v_pk_add_f32 v[134:135], v[134:135], 1.0 op_sel_hi:[1,0]
	v_add_f32_e32 v95, v95, v91
	v_mul_f32_e32 v137, v134, v135
	v_rcp_f32_e32 v137, v137
	v_mul_f32_e32 v95, 0xbfb8aa3b, v95
	v_min_f32_e32 v95, 0x42700000, v95
	v_exp_f32_e32 v95, v95
	v_mul_f32_e32 v135, v135, v137
	v_mul_f32_e32 v135, v85, v135
	v_mul_f32_e32 v134, v134, v137
	v_fmamk_f32 v137, v135, 0x3ab60b61, v196
	v_fmaak_f32 v137, v135, v137, 0x3d2aaaab
	v_fmaak_f32 v137, v135, v137, 0x3e2aaaab
	v_fma_f32 v137, v135, v137, 0.5
	v_fma_f32 v137, v135, v137, 1.0
	v_mul_f32_e64 v137, v137, -v135
	v_cmp_lt_f32_e32 vcc, s25, v135
	v_mul_f32_e32 v135, 0x3fb8aa3b, v135
	v_exp_f32_e32 v135, v135
	s_or_b64 vcc, s[34:35], vcc
	v_add_f32_e32 v78, v78, v86
	v_add_f32_e32 v74, v74, v90
	v_sub_f32_e32 v135, 1.0, v135
	v_cndmask_b32_e32 v135, v135, v137, vcc
	v_sub_f32_e32 v137, 2.0, v135
	v_mul_f32_e32 v137, v135, v137
	v_cmp_gt_f32_e32 vcc, s27, v137
	v_mul_f32_e32 v141, 0x4f800000, v137
	v_mul_f32_e32 v78, 0xbfb8aa3b, v78
	v_cndmask_b32_e32 v137, v137, v141, vcc
	v_sqrt_f32_e32 v141, v137
	v_mul_f32_e32 v74, 0xbfb8aa3b, v74
	v_min_f32_e32 v78, 0x42700000, v78
	v_min_f32_e32 v74, 0x42700000, v74
	v_add_u32_e32 v148, -1, v141
	v_fma_f32 v149, -v148, v141, v137
	v_cmp_ge_f32_e64 s[8:9], 0, v149
	v_add_u32_e32 v149, 1, v141
	v_add_f32_e32 v75, v75, v91
	v_cndmask_b32_e64 v148, v141, v148, s[8:9]
	v_fma_f32 v141, -v149, v141, v137
	v_cmp_lt_f32_e64 s[8:9], 0, v141
	v_mul_f32_e32 v75, 0xbfb8aa3b, v75
	v_min_f32_e32 v75, 0x42700000, v75
	v_cndmask_b32_e64 v141, v148, v149, s[8:9]
	v_mul_f32_e32 v148, 0x37800000, v141
	v_cndmask_b32_e32 v141, v141, v148, vcc
	v_cmp_class_f32_e32 vcc, v137, v197
	v_exp_f32_e32 v75, v75
	v_add_f32_e32 v70, v70, v86
	v_cndmask_b32_e32 v137, v141, v137, vcc
	v_mul_f32_e32 v134, v134, v137
	v_mul_f32_e32 v137, v134, v179
	v_cvt_pk_bf16_f32 v134, v138, v139
	v_cvt_pk_bf16_f32 v135, v136, v135
	v_lshl_add_u64 v[138:139], s[16:17], 0, v[180:181]
	v_cvt_pk_bf16_f32 v136, v183, v185
	v_cvt_pk_bf16_f32 v137, v140, v137
	global_store_dwordx2 v[138:139], v[134:135], off
	v_lshl_add_u64 v[134:135], s[18:19], 0, v[180:181]
	global_store_dwordx2 v[134:135], v[136:137], off
	v_or_b32_e32 v134, 16, v178
	v_ashrrev_i32_e32 v135, 31, v134
	v_lshlrev_b64 v[134:135], 11, v[134:135]
	v_lshl_add_u64 v[136:137], v[134:135], 0, v[170:171]
	v_lshlrev_b64 v[136:137], 1, v[136:137]
	v_lshl_add_u64 v[138:139], s[0:1], 0, v[136:137]
	v_exp_f32_e32 v140, v130
	v_exp_f32_e32 v141, v126
	v_add_f32_e32 v66, v66, v90
	v_mul_f32_e32 v70, 0xbfb8aa3b, v70
	v_mul_f32_e32 v66, 0xbfb8aa3b, v66
	v_pk_add_f32 v[140:141], v[140:141], 1.0 op_sel_hi:[1,0]
	v_min_f32_e32 v70, 0x42700000, v70
	v_mul_f32_e32 v126, v140, v141
	v_rcp_f32_e32 v126, v126
	v_min_f32_e32 v66, 0x42700000, v66
	v_add_f32_e32 v67, v67, v91
	v_mul_f32_e32 v67, 0xbfb8aa3b, v67
	v_mul_f32_e32 v130, v141, v126
	v_mul_f32_e32 v130, v82, v130
	v_cmp_lt_f32_e32 vcc, s25, v130
	s_or_b64 vcc, s[34:35], vcc
	v_mul_f32_e32 v126, v140, v126
	v_min_f32_e32 v67, 0x42700000, v67
	v_exp_f32_e32 v67, v67
	s_waitcnt vmcnt(15)
; __device__ __forceinline__ unsigned cvt_pk_bf16(float lo, float hi) { unsigned r; asm volatile("v_cvt_pk_bf16_f32 %0, %1, %2" : "=v"(r) : "v"(lo), "v"(hi)); return r; }
; __device__ __forceinline__ float bflo(unsigned w) { return __uint_as_float(w << 16); }
; __device__ __forceinline__ float bfhi(unsigned w) { return __uint_as_float(w & 0xffff0000u); }
;     __device__ __forceinline__ void operator()(const f32x4 (&acc)[2][2][4][2], const Unit& u, int wr, int wc, int fr, int fq) const {
;     ...
;                 for (int m = 0; m < 4; ++m) { const size_t off = (size_t)(row0 + ai * 128 + m * 16) * D + ch;
;                     const u32x2 xw = *(const u32x2*)(XRC + off);
;                     const float xr[4] = {bflo(xw.x), bfhi(xw.x), bflo(xw.y), bfhi(xw.y)};
;                     f32x4 dv, bv;
; #pragma unroll
;                     for (int j = 0; j < 4; ++j) { float r, ig; sigmoid2(acc[ai][0][m][n][j] + br4[j], acc[ai][1][m][n][j] + bi4[j], r, ig);
;                         const float la = r * sp4[j]; float dd = neg_expm1_small(la); if (slow) dd = la > -0.25f ? dd : 1.0f - __expf(la);
;                         dv[j] = dd; bv[j] = __builtin_sqrtf(dd * (2.0f - dd)) * ig * xr[j]; }
;                     u32x2 dw, bw; dw.x = cvt_pk_bf16(dv[0], dv[1]); dw.y = cvt_pk_bf16(dv[2], dv[3]); bw.x = cvt_pk_bf16(bv[0], bv[1]); bw.y = cvt_pk_bf16(bv[2], bv[3]);
;                     *(u32x2*)(DD + off) = dw; *(u32x2*)(BB + off) = bw; asm volatile("" ::: "memory"); } }
	v_mov_b64_e32 v[138:139], v[216:217]
	v_lshlrev_b32_e32 v148, 16, v138
	v_and_b32_e32 v149, 0xffff0000, v138
	v_lshlrev_b32_e32 v150, 16, v139
	v_and_b32_e32 v138, 0xffff0000, v139
	v_fmamk_f32 v139, v130, 0x3ab60b61, v196
	v_fmaak_f32 v139, v130, v139, 0x3d2aaaab
	v_fmaak_f32 v139, v130, v139, 0x3e2aaaab
	v_fma_f32 v139, v130, v139, 0.5
	v_fma_f32 v139, v130, v139, 1.0
	v_mul_f32_e64 v139, v139, -v130
	v_mul_f32_e32 v130, 0x3fb8aa3b, v130
	v_exp_f32_e32 v130, v130
	s_nop 0
	v_sub_f32_e32 v130, 1.0, v130
	v_cndmask_b32_e32 v130, v130, v139, vcc
	v_sub_f32_e32 v139, 2.0, v130
	v_mul_f32_e32 v139, v130, v139
	v_cmp_gt_f32_e32 vcc, s27, v139
	v_mul_f32_e32 v140, 0x4f800000, v139
	s_nop 0
	v_cndmask_b32_e32 v139, v139, v140, vcc
	v_sqrt_f32_e32 v140, v139
	s_nop 0
	v_add_u32_e32 v141, -1, v140
	v_fma_f32 v151, -v141, v140, v139
	v_cmp_ge_f32_e64 s[8:9], 0, v151
	v_add_u32_e32 v151, 1, v140
	s_nop 0
	v_cndmask_b32_e64 v141, v140, v141, s[8:9]
	v_fma_f32 v140, -v151, v140, v139
	v_cmp_lt_f32_e64 s[8:9], 0, v140
	s_nop 1
	v_cndmask_b32_e64 v140, v141, v151, s[8:9]
	v_mul_f32_e32 v141, 0x37800000, v140
	v_cndmask_b32_e32 v140, v140, v141, vcc
	v_cmp_class_f32_e32 vcc, v139, v197
	s_nop 1
	v_cndmask_b32_e32 v139, v140, v139, vcc
	v_mul_f32_e32 v126, v126, v139
	v_mul_f32_e32 v139, v126, v148
	v_add_f32_e32 v126, v131, v87
	v_mul_f32_e32 v126, 0xbfb8aa3b, v126
	v_min_f32_e32 v126, 0x42700000, v126
	v_exp_f32_e32 v126, v126
	s_nop 0
	v_pk_add_f32 v[126:127], v[126:127], 1.0 op_sel_hi:[1,0]
	s_nop 0
	v_mul_f32_e32 v131, v126, v127
	v_rcp_f32_e32 v131, v131
	s_nop 0
	v_mul_f32_e32 v127, v127, v131
	v_mul_f32_e32 v127, v83, v127
	v_mul_f32_e32 v126, v126, v131
	v_fmamk_f32 v131, v127, 0x3ab60b61, v196
	v_fmaak_f32 v131, v127, v131, 0x3d2aaaab
	v_fmaak_f32 v131, v127, v131, 0x3e2aaaab
	v_fma_f32 v131, v127, v131, 0.5
	v_fma_f32 v131, v127, v131, 1.0
	v_mul_f32_e64 v131, v131, -v127
	v_cmp_lt_f32_e32 vcc, s25, v127
	v_mul_f32_e32 v127, 0x3fb8aa3b, v127
	v_exp_f32_e32 v127, v127
	s_or_b64 vcc, s[34:35], vcc
	v_sub_f32_e32 v127, 1.0, v127
	v_cndmask_b32_e32 v131, v127, v131, vcc
	v_sub_f32_e32 v127, 2.0, v131
	v_mul_f32_e32 v127, v131, v127
	v_cmp_gt_f32_e32 vcc, s27, v127
	v_mul_f32_e32 v140, 0x4f800000, v127
	s_nop 0
	v_cndmask_b32_e32 v127, v127, v140, vcc
	v_sqrt_f32_e32 v140, v127
	s_nop 0
	v_add_u32_e32 v141, -1, v140
	v_fma_f32 v148, -v141, v140, v127
	v_cmp_ge_f32_e64 s[8:9], 0, v148
	v_add_u32_e32 v148, 1, v140
	s_nop 0
	v_cndmask_b32_e64 v141, v140, v141, s[8:9]
	v_fma_f32 v140, -v148, v140, v127
	v_cmp_lt_f32_e64 s[8:9], 0, v140
	s_nop 1
	v_cndmask_b32_e64 v140, v141, v148, s[8:9]
	v_mul_f32_e32 v141, 0x37800000, v140
	v_cndmask_b32_e32 v140, v140, v141, vcc
	v_cmp_class_f32_e32 vcc, v127, v197
	s_nop 1
	v_cndmask_b32_e32 v127, v140, v127, vcc
	v_mul_f32_e32 v126, v126, v127
	v_mul_f32_e32 v140, v126, v149
	v_add_f32_e32 v126, v132, v88
	v_add_f32_e32 v127, v128, v92
	v_mul_f32_e32 v126, 0xbfb8aa3b, v126
	v_mul_f32_e32 v127, 0xbfb8aa3b, v127
	v_min_f32_e32 v126, 0x42700000, v126
	v_min_f32_e32 v127, 0x42700000, v127
	v_exp_f32_e32 v126, v126
	v_exp_f32_e32 v127, v127
	s_nop 0
	v_pk_add_f32 v[126:127], v[126:127], 1.0 op_sel_hi:[1,0]
	s_nop 0
	v_mul_f32_e32 v128, v126, v127
	v_rcp_f32_e32 v128, v128
	s_nop 0
	v_mul_f32_e32 v127, v127, v128
	v_mul_f32_e32 v127, v84, v127
	v_mul_f32_e32 v126, v126, v128
	v_fmamk_f32 v128, v127, 0x3ab60b61, v196
	v_fmaak_f32 v128, v127, v128, 0x3d2aaaab
	v_fmaak_f32 v128, v127, v128, 0x3e2aaaab
	v_fma_f32 v128, v127, v128, 0.5
	v_fma_f32 v128, v127, v128, 1.0
	v_mul_f32_e64 v128, v128, -v127
	v_cmp_lt_f32_e32 vcc, s25, v127
	v_mul_f32_e32 v127, 0x3fb8aa3b, v127
	v_exp_f32_e32 v127, v127
	s_or_b64 vcc, s[34:35], vcc
	v_sub_f32_e32 v127, 1.0, v127
	v_cndmask_b32_e32 v128, v127, v128, vcc
	v_sub_f32_e32 v127, 2.0, v128
	v_mul_f32_e32 v127, v128, v127
	v_cmp_gt_f32_e32 vcc, s27, v127
	v_mul_f32_e32 v132, 0x4f800000, v127
	s_nop 0
	v_cndmask_b32_e32 v127, v127, v132, vcc
	v_sqrt_f32_e32 v132, v127
	s_nop 0
	v_add_u32_e32 v141, -1, v132
	v_fma_f32 v148, -v141, v132, v127
	v_cmp_ge_f32_e64 s[8:9], 0, v148
	v_add_u32_e32 v148, 1, v132
	s_nop 0
	v_cndmask_b32_e64 v141, v132, v141, s[8:9]
	v_fma_f32 v132, -v148, v132, v127
	v_cmp_lt_f32_e64 s[8:9], 0, v132
	s_nop 1
	v_cndmask_b32_e64 v132, v141, v148, s[8:9]
	v_mul_f32_e32 v141, 0x37800000, v132
	v_cndmask_b32_e32 v132, v132, v141, vcc
	v_cmp_class_f32_e32 vcc, v127, v197
	s_nop 1
	v_cndmask_b32_e32 v127, v132, v127, vcc
	v_mul_f32_e32 v126, v126, v127
	v_mul_f32_e32 v132, v126, v150
	v_add_f32_e32 v126, v133, v89
	v_add_f32_e32 v127, v129, v93
	v_mul_f32_e32 v126, 0xbfb8aa3b, v126
	v_mul_f32_e32 v127, 0xbfb8aa3b, v127
	v_min_f32_e32 v126, 0x42700000, v126
	v_min_f32_e32 v127, 0x42700000, v127
	v_exp_f32_e32 v126, v126
	v_exp_f32_e32 v127, v127
	s_nop 0
	v_pk_add_f32 v[126:127], v[126:127], 1.0 op_sel_hi:[1,0]
	s_nop 0
	v_mul_f32_e32 v129, v126, v127
	v_rcp_f32_e32 v129, v129
	s_nop 0
	v_mul_f32_e32 v127, v127, v129
	v_mul_f32_e32 v127, v85, v127
	v_mul_f32_e32 v126, v126, v129
	v_fmamk_f32 v129, v127, 0x3ab60b61, v196
	v_fmaak_f32 v129, v127, v129, 0x3d2aaaab
	v_fmaak_f32 v129, v127, v129, 0x3e2aaaab
	v_fma_f32 v129, v127, v129, 0.5
	v_fma_f32 v129, v127, v129, 1.0
	v_mul_f32_e64 v129, v129, -v127
	v_cmp_lt_f32_e32 vcc, s25, v127
	v_mul_f32_e32 v127, 0x3fb8aa3b, v127
	v_exp_f32_e32 v127, v127
	s_or_b64 vcc, s[34:35], vcc
	v_sub_f32_e32 v127, 1.0, v127
	v_cndmask_b32_e32 v127, v127, v129, vcc
	v_sub_f32_e32 v129, 2.0, v127
	v_mul_f32_e32 v129, v127, v129
	v_cmp_gt_f32_e32 vcc, s27, v129
	v_mul_f32_e32 v133, 0x4f800000, v129
	s_nop 0
	v_cndmask_b32_e32 v129, v129, v133, vcc
	v_sqrt_f32_e32 v133, v129
	s_nop 0
	v_add_u32_e32 v141, -1, v133
	v_fma_f32 v148, -v141, v133, v129
	v_cmp_ge_f32_e64 s[8:9], 0, v148
	v_add_u32_e32 v148, 1, v133
	s_nop 0
	v_cndmask_b32_e64 v141, v133, v141, s[8:9]
	v_fma_f32 v133, -v148, v133, v129
	v_cmp_lt_f32_e64 s[8:9], 0, v133
	s_nop 1
	v_cndmask_b32_e64 v133, v141, v148, s[8:9]
	v_mul_f32_e32 v141, 0x37800000, v133
	v_cndmask_b32_e32 v133, v133, v141, vcc
	v_cmp_class_f32_e32 vcc, v129, v197
	s_nop 1
	v_cndmask_b32_e32 v129, v133, v129, vcc
	v_mul_f32_e32 v126, v126, v129
	v_mul_f32_e32 v129, v126, v138
	v_cvt_pk_bf16_f32 v126, v130, v131
	v_cvt_pk_bf16_f32 v127, v128, v127
	v_lshl_add_u64 v[130:131], s[16:17], 0, v[136:137]
	v_cvt_pk_bf16_f32 v128, v139, v140
	v_cvt_pk_bf16_f32 v129, v132, v129
	global_store_dwordx2 v[130:131], v[126:127], off
	v_lshl_add_u64 v[126:127], s[18:19], 0, v[136:137]
	global_store_dwordx2 v[126:127], v[128:129], off
	v_or_b32_e32 v126, 32, v178
	v_ashrrev_i32_e32 v127, 31, v126
	v_lshlrev_b64 v[126:127], 11, v[126:127]
	v_lshl_add_u64 v[128:129], v[126:127], 0, v[170:171]
	v_lshlrev_b64 v[128:129], 1, v[128:129]
	v_lshl_add_u64 v[130:131], s[0:1], 0, v[128:129]
	v_exp_f32_e32 v132, v122
	v_exp_f32_e32 v133, v118
	s_waitcnt vmcnt(15)
; __device__ __forceinline__ unsigned cvt_pk_bf16(float lo, float hi) { unsigned r; asm volatile("v_cvt_pk_bf16_f32 %0, %1, %2" : "=v"(r) : "v"(lo), "v"(hi)); return r; }
; __device__ __forceinline__ float bflo(unsigned w) { return __uint_as_float(w << 16); }
; __device__ __forceinline__ float bfhi(unsigned w) { return __uint_as_float(w & 0xffff0000u); }
;     __device__ __forceinline__ void operator()(const f32x4 (&acc)[2][2][4][2], const Unit& u, int wr, int wc, int fr, int fq) const {
;     ...
;                 for (int m = 0; m < 4; ++m) { const size_t off = (size_t)(row0 + ai * 128 + m * 16) * D + ch;
;                     const u32x2 xw = *(const u32x2*)(XRC + off);
;                     const float xr[4] = {bflo(xw.x), bfhi(xw.x), bflo(xw.y), bfhi(xw.y)};
;                     f32x4 dv, bv;
; #pragma unroll
;                     for (int j = 0; j < 4; ++j) { float r, ig; sigmoid2(acc[ai][0][m][n][j] + br4[j], acc[ai][1][m][n][j] + bi4[j], r, ig);
;                         const float la = r * sp4[j]; float dd = neg_expm1_small(la); if (slow) dd = la > -0.25f ? dd : 1.0f - __expf(la);
;                         dv[j] = dd; bv[j] = __builtin_sqrtf(dd * (2.0f - dd)) * ig * xr[j]; }
;                     u32x2 dw, bw; dw.x = cvt_pk_bf16(dv[0], dv[1]); dw.y = cvt_pk_bf16(dv[2], dv[3]); bw.x = cvt_pk_bf16(bv[0], bv[1]); bw.y = cvt_pk_bf16(bv[2], bv[3]);
;                     *(u32x2*)(DD + off) = dw; *(u32x2*)(BB + off) = bw; asm volatile("" ::: "memory"); } }
	v_mov_b64_e32 v[130:131], v[218:219]
	v_lshlrev_b32_e32 v136, 16, v130
	v_pk_add_f32 v[132:133], v[132:133], 1.0 op_sel_hi:[1,0]
	v_and_b32_e32 v137, 0xffff0000, v130
	v_mul_f32_e32 v118, v132, v133
	v_rcp_f32_e32 v118, v118
	v_lshlrev_b32_e32 v138, 16, v131
	v_and_b32_e32 v130, 0xffff0000, v131
	v_mul_f32_e32 v122, v133, v118
	v_mul_f32_e32 v122, v82, v122
	v_fmamk_f32 v131, v122, 0x3ab60b61, v196
	v_fmaak_f32 v131, v122, v131, 0x3d2aaaab
	v_fmaak_f32 v131, v122, v131, 0x3e2aaaab
	v_fma_f32 v131, v122, v131, 0.5
	v_fma_f32 v131, v122, v131, 1.0
	v_mul_f32_e64 v131, v131, -v122
	v_cmp_lt_f32_e32 vcc, s25, v122
	v_mul_f32_e32 v122, 0x3fb8aa3b, v122
	v_exp_f32_e32 v122, v122
	s_or_b64 vcc, s[34:35], vcc
	v_mul_f32_e32 v118, v132, v118
	v_sub_f32_e32 v122, 1.0, v122
	v_cndmask_b32_e32 v122, v122, v131, vcc
	v_sub_f32_e32 v131, 2.0, v122
	v_mul_f32_e32 v131, v122, v131
	v_cmp_gt_f32_e32 vcc, s27, v131
	v_mul_f32_e32 v132, 0x4f800000, v131
	s_nop 0
	v_cndmask_b32_e32 v131, v131, v132, vcc
	v_sqrt_f32_e32 v132, v131
	s_nop 0
	v_add_u32_e32 v133, -1, v132
	v_fma_f32 v139, -v133, v132, v131
	v_cmp_ge_f32_e64 s[8:9], 0, v139
	v_add_u32_e32 v139, 1, v132
	s_nop 0
	v_cndmask_b32_e64 v133, v132, v133, s[8:9]
	v_fma_f32 v132, -v139, v132, v131
	v_cmp_lt_f32_e64 s[8:9], 0, v132
	s_nop 1
	v_cndmask_b32_e64 v132, v133, v139, s[8:9]
	v_mul_f32_e32 v133, 0x37800000, v132
	v_cndmask_b32_e32 v132, v132, v133, vcc
	v_cmp_class_f32_e32 vcc, v131, v197
	s_nop 1
	v_cndmask_b32_e32 v131, v132, v131, vcc
	v_mul_f32_e32 v118, v118, v131
	v_mul_f32_e32 v131, v118, v136
	v_add_f32_e32 v118, v123, v87
	v_mul_f32_e32 v118, 0xbfb8aa3b, v118
	v_min_f32_e32 v118, 0x42700000, v118
	v_exp_f32_e32 v118, v118
	s_nop 0
	v_pk_add_f32 v[118:119], v[118:119], 1.0 op_sel_hi:[1,0]
	s_nop 0
	v_mul_f32_e32 v123, v118, v119
	v_rcp_f32_e32 v123, v123
	s_nop 0
	v_mul_f32_e32 v119, v119, v123
	v_mul_f32_e32 v119, v83, v119
	v_mul_f32_e32 v118, v118, v123
	v_fmamk_f32 v123, v119, 0x3ab60b61, v196
	v_fmaak_f32 v123, v119, v123, 0x3d2aaaab
	v_fmaak_f32 v123, v119, v123, 0x3e2aaaab
	v_fma_f32 v123, v119, v123, 0.5
	v_fma_f32 v123, v119, v123, 1.0
	v_mul_f32_e64 v123, v123, -v119
	v_cmp_lt_f32_e32 vcc, s25, v119
	v_mul_f32_e32 v119, 0x3fb8aa3b, v119
	v_exp_f32_e32 v119, v119
	s_or_b64 vcc, s[34:35], vcc
	v_sub_f32_e32 v119, 1.0, v119
	v_cndmask_b32_e32 v123, v119, v123, vcc
	v_sub_f32_e32 v119, 2.0, v123
	v_mul_f32_e32 v119, v123, v119
	v_cmp_gt_f32_e32 vcc, s27, v119
	v_mul_f32_e32 v132, 0x4f800000, v119
	s_nop 0
	v_cndmask_b32_e32 v119, v119, v132, vcc
	v_sqrt_f32_e32 v132, v119
	s_nop 0
	v_add_u32_e32 v133, -1, v132
	v_fma_f32 v136, -v133, v132, v119
	v_cmp_ge_f32_e64 s[8:9], 0, v136
	v_add_u32_e32 v136, 1, v132
	s_nop 0
	v_cndmask_b32_e64 v133, v132, v133, s[8:9]
	v_fma_f32 v132, -v136, v132, v119
	v_cmp_lt_f32_e64 s[8:9], 0, v132
	s_nop 1
	v_cndmask_b32_e64 v132, v133, v136, s[8:9]
	v_mul_f32_e32 v133, 0x37800000, v132
	v_cndmask_b32_e32 v132, v132, v133, vcc
	v_cmp_class_f32_e32 vcc, v119, v197
	s_nop 1
	v_cndmask_b32_e32 v119, v132, v119, vcc
	v_mul_f32_e32 v118, v118, v119
	v_mul_f32_e32 v132, v118, v137
	v_add_f32_e32 v118, v124, v88
	v_add_f32_e32 v119, v120, v92
	v_mul_f32_e32 v118, 0xbfb8aa3b, v118
	v_mul_f32_e32 v119, 0xbfb8aa3b, v119
	v_min_f32_e32 v118, 0x42700000, v118
	v_min_f32_e32 v119, 0x42700000, v119
	v_exp_f32_e32 v118, v118
	v_exp_f32_e32 v119, v119
	s_nop 0
	v_pk_add_f32 v[118:119], v[118:119], 1.0 op_sel_hi:[1,0]
	s_nop 0
	v_mul_f32_e32 v120, v118, v119
	v_rcp_f32_e32 v120, v120
	s_nop 0
	v_mul_f32_e32 v119, v119, v120
	v_mul_f32_e32 v119, v84, v119
	v_mul_f32_e32 v118, v118, v120
	v_fmamk_f32 v120, v119, 0x3ab60b61, v196
	v_fmaak_f32 v120, v119, v120, 0x3d2aaaab
	v_fmaak_f32 v120, v119, v120, 0x3e2aaaab
	v_fma_f32 v120, v119, v120, 0.5
	v_fma_f32 v120, v119, v120, 1.0
	v_mul_f32_e64 v120, v120, -v119
	v_cmp_lt_f32_e32 vcc, s25, v119
	v_mul_f32_e32 v119, 0x3fb8aa3b, v119
	v_exp_f32_e32 v119, v119
	s_or_b64 vcc, s[34:35], vcc
	v_sub_f32_e32 v119, 1.0, v119
	v_cndmask_b32_e32 v120, v119, v120, vcc
	v_sub_f32_e32 v119, 2.0, v120
	v_mul_f32_e32 v119, v120, v119
	v_cmp_gt_f32_e32 vcc, s27, v119
	v_mul_f32_e32 v124, 0x4f800000, v119
	s_nop 0
	v_cndmask_b32_e32 v119, v119, v124, vcc
	v_sqrt_f32_e32 v124, v119
	s_nop 0
	v_add_u32_e32 v133, -1, v124
	v_fma_f32 v136, -v133, v124, v119
	v_cmp_ge_f32_e64 s[8:9], 0, v136
	v_add_u32_e32 v136, 1, v124
	s_nop 0
	v_cndmask_b32_e64 v133, v124, v133, s[8:9]
	v_fma_f32 v124, -v136, v124, v119
	v_cmp_lt_f32_e64 s[8:9], 0, v124
	s_nop 1
	v_cndmask_b32_e64 v124, v133, v136, s[8:9]
	v_mul_f32_e32 v133, 0x37800000, v124
	v_cndmask_b32_e32 v124, v124, v133, vcc
	v_cmp_class_f32_e32 vcc, v119, v197
	s_nop 1
	v_cndmask_b32_e32 v119, v124, v119, vcc
	v_mul_f32_e32 v118, v118, v119
	v_mul_f32_e32 v124, v118, v138
	v_add_f32_e32 v118, v125, v89
	v_add_f32_e32 v119, v121, v93
	v_mul_f32_e32 v118, 0xbfb8aa3b, v118
	v_mul_f32_e32 v119, 0xbfb8aa3b, v119
	v_min_f32_e32 v118, 0x42700000, v118
	v_min_f32_e32 v119, 0x42700000, v119
	v_exp_f32_e32 v118, v118
	v_exp_f32_e32 v119, v119
	s_nop 0
	v_pk_add_f32 v[118:119], v[118:119], 1.0 op_sel_hi:[1,0]
	s_nop 0
	v_mul_f32_e32 v121, v118, v119
	v_rcp_f32_e32 v121, v121
	s_nop 0
	v_mul_f32_e32 v119, v119, v121
	v_mul_f32_e32 v119, v85, v119
	v_mul_f32_e32 v118, v118, v121
	v_fmamk_f32 v121, v119, 0x3ab60b61, v196
	v_fmaak_f32 v121, v119, v121, 0x3d2aaaab
	v_fmaak_f32 v121, v119, v121, 0x3e2aaaab
	v_fma_f32 v121, v119, v121, 0.5
	v_fma_f32 v121, v119, v121, 1.0
	v_mul_f32_e64 v121, v121, -v119
	v_cmp_lt_f32_e32 vcc, s25, v119
	v_mul_f32_e32 v119, 0x3fb8aa3b, v119
	v_exp_f32_e32 v119, v119
	s_or_b64 vcc, s[34:35], vcc
; __device__ __forceinline__ unsigned cvt_pk_bf16(float lo, float hi) { unsigned r; asm volatile("v_cvt_pk_bf16_f32 %0, %1, %2" : "=v"(r) : "v"(lo), "v"(hi)); return r; }
; __device__ __forceinline__ float bflo(unsigned w) { return __uint_as_float(w << 16); }
; __device__ __forceinline__ float bfhi(unsigned w) { return __uint_as_float(w & 0xffff0000u); }
;     __device__ __forceinline__ void operator()(const f32x4 (&acc)[2][2][4][2], const Unit& u, int wr, int wc, int fr, int fq) const {
;     ...
;                 for (int m = 0; m < 4; ++m) { const size_t off = (size_t)(row0 + ai * 128 + m * 16) * D + ch;
;                     const u32x2 xw = *(const u32x2*)(XRC + off);
;                     const float xr[4] = {bflo(xw.x), bfhi(xw.x), bflo(xw.y), bfhi(xw.y)};
;                     f32x4 dv, bv;
; #pragma unroll
;                     for (int j = 0; j < 4; ++j) { float r, ig; sigmoid2(acc[ai][0][m][n][j] + br4[j], acc[ai][1][m][n][j] + bi4[j], r, ig);
;                         const float la = r * sp4[j]; float dd = neg_expm1_small(la); if (slow) dd = la > -0.25f ? dd : 1.0f - __expf(la);
;                         dv[j] = dd; bv[j] = __builtin_sqrtf(dd * (2.0f - dd)) * ig * xr[j]; }
;                     u32x2 dw, bw; dw.x = cvt_pk_bf16(dv[0], dv[1]); dw.y = cvt_pk_bf16(dv[2], dv[3]); bw.x = cvt_pk_bf16(bv[0], bv[1]); bw.y = cvt_pk_bf16(bv[2], bv[3]);
;                     *(u32x2*)(DD + off) = dw; *(u32x2*)(BB + off) = bw; asm volatile("" ::: "memory"); } }
	v_sub_f32_e32 v119, 1.0, v119
	v_cndmask_b32_e32 v119, v119, v121, vcc
	v_sub_f32_e32 v121, 2.0, v119
	v_mul_f32_e32 v121, v119, v121
	v_cmp_gt_f32_e32 vcc, s27, v121
	v_mul_f32_e32 v125, 0x4f800000, v121
	s_nop 0
	v_cndmask_b32_e32 v121, v121, v125, vcc
	v_sqrt_f32_e32 v125, v121
	s_nop 0
	v_add_u32_e32 v133, -1, v125
	v_fma_f32 v136, -v133, v125, v121
	v_cmp_ge_f32_e64 s[8:9], 0, v136
	v_add_u32_e32 v136, 1, v125
	s_nop 0
	v_cndmask_b32_e64 v133, v125, v133, s[8:9]
	v_fma_f32 v125, -v136, v125, v121
	v_cmp_lt_f32_e64 s[8:9], 0, v125
	s_nop 1
	v_cndmask_b32_e64 v125, v133, v136, s[8:9]
	v_mul_f32_e32 v133, 0x37800000, v125
	v_cndmask_b32_e32 v125, v125, v133, vcc
	v_cmp_class_f32_e32 vcc, v121, v197
	s_nop 1
	v_cndmask_b32_e32 v121, v125, v121, vcc
	v_mul_f32_e32 v118, v118, v121
	v_mul_f32_e32 v121, v118, v130
	v_cvt_pk_bf16_f32 v118, v122, v123
	v_cvt_pk_bf16_f32 v119, v120, v119
	v_lshl_add_u64 v[122:123], s[16:17], 0, v[128:129]
	v_cvt_pk_bf16_f32 v120, v131, v132
	v_cvt_pk_bf16_f32 v121, v124, v121
	global_store_dwordx2 v[122:123], v[118:119], off
	v_lshl_add_u64 v[118:119], s[18:19], 0, v[128:129]
	global_store_dwordx2 v[118:119], v[120:121], off
	v_or_b32_e32 v118, 48, v178
	v_ashrrev_i32_e32 v119, 31, v118
	v_lshlrev_b64 v[118:119], 11, v[118:119]
	v_lshl_add_u64 v[120:121], v[118:119], 0, v[170:171]
	v_lshlrev_b64 v[120:121], 1, v[120:121]
	v_lshl_add_u64 v[122:123], s[0:1], 0, v[120:121]
	v_exp_f32_e32 v124, v114
	v_exp_f32_e32 v125, v110
	s_waitcnt vmcnt(15)
	v_mov_b64_e32 v[122:123], v[220:221]
	v_lshlrev_b32_e32 v128, 16, v122
	v_pk_add_f32 v[124:125], v[124:125], 1.0 op_sel_hi:[1,0]
	v_and_b32_e32 v129, 0xffff0000, v122
	v_mul_f32_e32 v110, v124, v125
	v_rcp_f32_e32 v110, v110
	v_lshlrev_b32_e32 v130, 16, v123
	v_and_b32_e32 v122, 0xffff0000, v123
	v_mul_f32_e32 v114, v125, v110
	v_mul_f32_e32 v114, v82, v114
	v_fmamk_f32 v123, v114, 0x3ab60b61, v196
	v_fmaak_f32 v123, v114, v123, 0x3d2aaaab
	v_fmaak_f32 v123, v114, v123, 0x3e2aaaab
	v_fma_f32 v123, v114, v123, 0.5
	v_fma_f32 v123, v114, v123, 1.0
	v_mul_f32_e64 v123, v123, -v114
	v_cmp_lt_f32_e32 vcc, s25, v114
	v_mul_f32_e32 v114, 0x3fb8aa3b, v114
	v_exp_f32_e32 v114, v114
	s_or_b64 vcc, s[34:35], vcc
	v_mul_f32_e32 v110, v124, v110
	v_sub_f32_e32 v114, 1.0, v114
	v_cndmask_b32_e32 v114, v114, v123, vcc
	v_sub_f32_e32 v123, 2.0, v114
	v_mul_f32_e32 v123, v114, v123
	v_cmp_gt_f32_e32 vcc, s27, v123
	v_mul_f32_e32 v124, 0x4f800000, v123
	s_nop 0
	v_cndmask_b32_e32 v123, v123, v124, vcc
	v_sqrt_f32_e32 v124, v123
	s_nop 0
	v_add_u32_e32 v125, -1, v124
	v_fma_f32 v131, -v125, v124, v123
	v_cmp_ge_f32_e64 s[8:9], 0, v131
	v_add_u32_e32 v131, 1, v124
	s_nop 0
	v_cndmask_b32_e64 v125, v124, v125, s[8:9]
	v_fma_f32 v124, -v131, v124, v123
	v_cmp_lt_f32_e64 s[8:9], 0, v124
	s_nop 1
	v_cndmask_b32_e64 v124, v125, v131, s[8:9]
	v_mul_f32_e32 v125, 0x37800000, v124
	v_cndmask_b32_e32 v124, v124, v125, vcc
	v_cmp_class_f32_e32 vcc, v123, v197
	s_nop 1
	v_cndmask_b32_e32 v123, v124, v123, vcc
	v_mul_f32_e32 v110, v110, v123
	v_mul_f32_e32 v123, v110, v128
	v_add_f32_e32 v110, v115, v87
	v_mul_f32_e32 v110, 0xbfb8aa3b, v110
	v_min_f32_e32 v110, 0x42700000, v110
	v_exp_f32_e32 v110, v110
	s_nop 0
	v_pk_add_f32 v[110:111], v[110:111], 1.0 op_sel_hi:[1,0]
	s_nop 0
	v_mul_f32_e32 v115, v110, v111
	v_rcp_f32_e32 v115, v115
	s_nop 0
	v_mul_f32_e32 v111, v111, v115
	v_mul_f32_e32 v111, v83, v111
	v_mul_f32_e32 v110, v110, v115
	v_fmamk_f32 v115, v111, 0x3ab60b61, v196
	v_fmaak_f32 v115, v111, v115, 0x3d2aaaab
	v_fmaak_f32 v115, v111, v115, 0x3e2aaaab
	v_fma_f32 v115, v111, v115, 0.5
	v_fma_f32 v115, v111, v115, 1.0
	v_mul_f32_e64 v115, v115, -v111
	v_cmp_lt_f32_e32 vcc, s25, v111
	v_mul_f32_e32 v111, 0x3fb8aa3b, v111
	v_exp_f32_e32 v111, v111
	s_or_b64 vcc, s[34:35], vcc
	v_sub_f32_e32 v111, 1.0, v111
	v_cndmask_b32_e32 v115, v111, v115, vcc
	v_sub_f32_e32 v111, 2.0, v115
	v_mul_f32_e32 v111, v115, v111
	v_cmp_gt_f32_e32 vcc, s27, v111
	v_mul_f32_e32 v124, 0x4f800000, v111
	s_nop 0
	v_cndmask_b32_e32 v111, v111, v124, vcc
	v_sqrt_f32_e32 v124, v111
	s_nop 0
	v_add_u32_e32 v125, -1, v124
	v_fma_f32 v128, -v125, v124, v111
	v_cmp_ge_f32_e64 s[8:9], 0, v128
	v_add_u32_e32 v128, 1, v124
	s_nop 0
	v_cndmask_b32_e64 v125, v124, v125, s[8:9]
	v_fma_f32 v124, -v128, v124, v111
	v_cmp_lt_f32_e64 s[8:9], 0, v124
	s_nop 1
	v_cndmask_b32_e64 v124, v125, v128, s[8:9]
	v_mul_f32_e32 v125, 0x37800000, v124
	v_cndmask_b32_e32 v124, v124, v125, vcc
	v_cmp_class_f32_e32 vcc, v111, v197
	s_nop 1
	v_cndmask_b32_e32 v111, v124, v111, vcc
	v_mul_f32_e32 v110, v110, v111
	v_mul_f32_e32 v124, v110, v129
	v_add_f32_e32 v110, v116, v88
	v_add_f32_e32 v111, v112, v92
	v_mul_f32_e32 v110, 0xbfb8aa3b, v110
	v_mul_f32_e32 v111, 0xbfb8aa3b, v111
	v_min_f32_e32 v110, 0x42700000, v110
	v_min_f32_e32 v111, 0x42700000, v111
	v_exp_f32_e32 v110, v110
	v_exp_f32_e32 v111, v111
	s_nop 0
	v_pk_add_f32 v[110:111], v[110:111], 1.0 op_sel_hi:[1,0]
	s_nop 0
	v_mul_f32_e32 v112, v110, v111
	v_rcp_f32_e32 v112, v112
	s_nop 0
	v_mul_f32_e32 v111, v111, v112
	v_mul_f32_e32 v111, v84, v111
	v_mul_f32_e32 v110, v110, v112
	v_fmamk_f32 v112, v111, 0x3ab60b61, v196
	v_fmaak_f32 v112, v111, v112, 0x3d2aaaab
	v_fmaak_f32 v112, v111, v112, 0x3e2aaaab
	v_fma_f32 v112, v111, v112, 0.5
	v_fma_f32 v112, v111, v112, 1.0
	v_mul_f32_e64 v112, v112, -v111
	v_cmp_lt_f32_e32 vcc, s25, v111
	v_mul_f32_e32 v111, 0x3fb8aa3b, v111
	v_exp_f32_e32 v111, v111
	s_or_b64 vcc, s[34:35], vcc
	v_sub_f32_e32 v111, 1.0, v111
	v_cndmask_b32_e32 v112, v111, v112, vcc
	v_sub_f32_e32 v111, 2.0, v112
	v_mul_f32_e32 v111, v112, v111
	v_cmp_gt_f32_e32 vcc, s27, v111
; __device__ __forceinline__ unsigned cvt_pk_bf16(float lo, float hi) { unsigned r; asm volatile("v_cvt_pk_bf16_f32 %0, %1, %2" : "=v"(r) : "v"(lo), "v"(hi)); return r; }
; __device__ __forceinline__ float bflo(unsigned w) { return __uint_as_float(w << 16); }
; __device__ __forceinline__ float bfhi(unsigned w) { return __uint_as_float(w & 0xffff0000u); }
;     __device__ __forceinline__ void operator()(const f32x4 (&acc)[2][2][4][2], const Unit& u, int wr, int wc, int fr, int fq) const {
;     ...
;                 for (int m = 0; m < 4; ++m) { const size_t off = (size_t)(row0 + ai * 128 + m * 16) * D + ch;
;                     const u32x2 xw = *(const u32x2*)(XRC + off);
;                     const float xr[4] = {bflo(xw.x), bfhi(xw.x), bflo(xw.y), bfhi(xw.y)};
;                     f32x4 dv, bv;
; #pragma unroll
;                     for (int j = 0; j < 4; ++j) { float r, ig; sigmoid2(acc[ai][0][m][n][j] + br4[j], acc[ai][1][m][n][j] + bi4[j], r, ig);
;                         const float la = r * sp4[j]; float dd = neg_expm1_small(la); if (slow) dd = la > -0.25f ? dd : 1.0f - __expf(la);
;                         dv[j] = dd; bv[j] = __builtin_sqrtf(dd * (2.0f - dd)) * ig * xr[j]; }
;                     u32x2 dw, bw; dw.x = cvt_pk_bf16(dv[0], dv[1]); dw.y = cvt_pk_bf16(dv[2], dv[3]); bw.x = cvt_pk_bf16(bv[0], bv[1]); bw.y = cvt_pk_bf16(bv[2], bv[3]);
;                     *(u32x2*)(DD + off) = dw; *(u32x2*)(BB + off) = bw; asm volatile("" ::: "memory"); } }
	v_mul_f32_e32 v116, 0x4f800000, v111
	s_nop 0
	v_cndmask_b32_e32 v111, v111, v116, vcc
	v_sqrt_f32_e32 v116, v111
	s_nop 0
	v_add_u32_e32 v125, -1, v116
	v_fma_f32 v128, -v125, v116, v111
	v_cmp_ge_f32_e64 s[8:9], 0, v128
	v_add_u32_e32 v128, 1, v116
	s_nop 0
	v_cndmask_b32_e64 v125, v116, v125, s[8:9]
	v_fma_f32 v116, -v128, v116, v111
	v_cmp_lt_f32_e64 s[8:9], 0, v116
	s_nop 1
	v_cndmask_b32_e64 v116, v125, v128, s[8:9]
	v_mul_f32_e32 v125, 0x37800000, v116
	v_cndmask_b32_e32 v116, v116, v125, vcc
	v_cmp_class_f32_e32 vcc, v111, v197
	s_nop 1
	v_cndmask_b32_e32 v111, v116, v111, vcc
	v_mul_f32_e32 v110, v110, v111
	v_mul_f32_e32 v116, v110, v130
	v_add_f32_e32 v110, v117, v89
	v_add_f32_e32 v111, v113, v93
	v_mul_f32_e32 v110, 0xbfb8aa3b, v110
	v_mul_f32_e32 v111, 0xbfb8aa3b, v111
	v_min_f32_e32 v110, 0x42700000, v110
	v_min_f32_e32 v111, 0x42700000, v111
	v_exp_f32_e32 v110, v110
	v_exp_f32_e32 v111, v111
	s_nop 0
	v_pk_add_f32 v[110:111], v[110:111], 1.0 op_sel_hi:[1,0]
	s_nop 0
	v_mul_f32_e32 v113, v110, v111
	v_rcp_f32_e32 v113, v113
	s_nop 0
	v_mul_f32_e32 v111, v111, v113
	v_mul_f32_e32 v111, v85, v111
	v_mul_f32_e32 v110, v110, v113
	v_fmamk_f32 v113, v111, 0x3ab60b61, v196
	v_fmaak_f32 v113, v111, v113, 0x3d2aaaab
	v_fmaak_f32 v113, v111, v113, 0x3e2aaaab
	v_fma_f32 v113, v111, v113, 0.5
	v_fma_f32 v113, v111, v113, 1.0
	v_mul_f32_e64 v113, v113, -v111
	v_cmp_lt_f32_e32 vcc, s25, v111
	v_mul_f32_e32 v111, 0x3fb8aa3b, v111
	v_exp_f32_e32 v111, v111
	s_or_b64 vcc, s[34:35], vcc
	v_sub_f32_e32 v111, 1.0, v111
	v_cndmask_b32_e32 v111, v111, v113, vcc
	v_sub_f32_e32 v113, 2.0, v111
	v_mul_f32_e32 v113, v111, v113
	v_cmp_gt_f32_e32 vcc, s27, v113
	v_mul_f32_e32 v117, 0x4f800000, v113
	s_nop 0
	v_cndmask_b32_e32 v113, v113, v117, vcc
	v_sqrt_f32_e32 v117, v113
	s_nop 0
	v_add_u32_e32 v125, -1, v117
	v_fma_f32 v128, -v125, v117, v113
	v_cmp_ge_f32_e64 s[8:9], 0, v128
	v_add_u32_e32 v128, 1, v117
	s_nop 0
	v_cndmask_b32_e64 v125, v117, v125, s[8:9]
	v_fma_f32 v117, -v128, v117, v113
	v_cmp_lt_f32_e64 s[8:9], 0, v117
	s_nop 1
	v_cndmask_b32_e64 v117, v125, v128, s[8:9]
	v_mul_f32_e32 v125, 0x37800000, v117
	v_cndmask_b32_e32 v117, v117, v125, vcc
	v_cmp_class_f32_e32 vcc, v113, v197
	s_mov_b64 s[8:9], 0x40000
	s_nop 0
	v_cndmask_b32_e32 v113, v117, v113, vcc
	v_mul_f32_e32 v110, v110, v113
	v_mul_f32_e32 v113, v110, v122
	v_cvt_pk_bf16_f32 v110, v114, v115
	v_cvt_pk_bf16_f32 v111, v112, v111
	v_lshl_add_u64 v[114:115], s[16:17], 0, v[120:121]
	v_cvt_pk_bf16_f32 v112, v123, v124
	v_cvt_pk_bf16_f32 v113, v116, v113
	global_store_dwordx2 v[114:115], v[110:111], off
	v_lshl_add_u64 v[110:111], s[18:19], 0, v[120:121]
	global_store_dwordx2 v[110:111], v[112:113], off
	v_lshl_add_u64 v[110:111], v[176:177], 0, s[8:9]
	v_lshl_add_u64 v[112:113], v[110:111], 0, v[170:171]
	v_lshlrev_b64 v[112:113], 1, v[112:113]
	v_lshl_add_u64 v[114:115], s[0:1], 0, v[112:113]
	v_exp_f32_e32 v116, v106
	v_exp_f32_e32 v117, v102
	s_waitcnt vmcnt(15)
	v_mov_b64_e32 v[114:115], v[222:223]
	v_lshlrev_b32_e32 v120, 16, v114
	v_pk_add_f32 v[116:117], v[116:117], 1.0 op_sel_hi:[1,0]
	v_and_b32_e32 v121, 0xffff0000, v114
	v_mul_f32_e32 v102, v116, v117
	v_rcp_f32_e32 v102, v102
	v_lshlrev_b32_e32 v122, 16, v115
	v_and_b32_e32 v114, 0xffff0000, v115
	v_mul_f32_e32 v106, v117, v102
	v_mul_f32_e32 v106, v82, v106
	v_fmamk_f32 v115, v106, 0x3ab60b61, v196
	v_fmaak_f32 v115, v106, v115, 0x3d2aaaab
	v_fmaak_f32 v115, v106, v115, 0x3e2aaaab
	v_fma_f32 v115, v106, v115, 0.5
	v_fma_f32 v115, v106, v115, 1.0
	v_mul_f32_e64 v115, v115, -v106
	v_cmp_lt_f32_e32 vcc, s25, v106
	v_mul_f32_e32 v106, 0x3fb8aa3b, v106
	v_exp_f32_e32 v106, v106
	s_or_b64 vcc, s[34:35], vcc
	v_mul_f32_e32 v102, v116, v102
	v_sub_f32_e32 v106, 1.0, v106
	v_cndmask_b32_e32 v106, v106, v115, vcc
	v_sub_f32_e32 v115, 2.0, v106
	v_mul_f32_e32 v115, v106, v115
	v_cmp_gt_f32_e32 vcc, s27, v115
	v_mul_f32_e32 v116, 0x4f800000, v115
	s_nop 0
	v_cndmask_b32_e32 v115, v115, v116, vcc
	v_sqrt_f32_e32 v116, v115
	s_nop 0
	v_add_u32_e32 v117, -1, v116
	v_fma_f32 v123, -v117, v116, v115
	v_cmp_ge_f32_e64 s[8:9], 0, v123
	v_add_u32_e32 v123, 1, v116
	s_nop 0
	v_cndmask_b32_e64 v117, v116, v117, s[8:9]
	v_fma_f32 v116, -v123, v116, v115
	v_cmp_lt_f32_e64 s[8:9], 0, v116
	s_nop 1
	v_cndmask_b32_e64 v116, v117, v123, s[8:9]
	v_mul_f32_e32 v117, 0x37800000, v116
	v_cndmask_b32_e32 v116, v116, v117, vcc
	v_cmp_class_f32_e32 vcc, v115, v197
	s_nop 1
	v_cndmask_b32_e32 v115, v116, v115, vcc
	v_mul_f32_e32 v102, v102, v115
	v_mul_f32_e32 v115, v102, v120
	v_add_f32_e32 v102, v107, v87
	v_mul_f32_e32 v102, 0xbfb8aa3b, v102
	v_min_f32_e32 v102, 0x42700000, v102
	v_exp_f32_e32 v102, v102
	s_nop 0
	v_pk_add_f32 v[102:103], v[102:103], 1.0 op_sel_hi:[1,0]
	s_nop 0
	v_mul_f32_e32 v107, v102, v103
	v_rcp_f32_e32 v107, v107
	s_nop 0
	v_mul_f32_e32 v103, v103, v107
	v_mul_f32_e32 v103, v83, v103
	v_mul_f32_e32 v102, v102, v107
	v_fmamk_f32 v107, v103, 0x3ab60b61, v196
	v_fmaak_f32 v107, v103, v107, 0x3d2aaaab
	v_fmaak_f32 v107, v103, v107, 0x3e2aaaab
	v_fma_f32 v107, v103, v107, 0.5
	v_fma_f32 v107, v103, v107, 1.0
	v_mul_f32_e64 v107, v107, -v103
	v_cmp_lt_f32_e32 vcc, s25, v103
	v_mul_f32_e32 v103, 0x3fb8aa3b, v103
	v_exp_f32_e32 v103, v103
	s_or_b64 vcc, s[34:35], vcc
	v_sub_f32_e32 v103, 1.0, v103
	v_cndmask_b32_e32 v107, v103, v107, vcc
	v_sub_f32_e32 v103, 2.0, v107
	v_mul_f32_e32 v103, v107, v103
	v_cmp_gt_f32_e32 vcc, s27, v103
	v_mul_f32_e32 v116, 0x4f800000, v103
	s_nop 0
	v_cndmask_b32_e32 v103, v103, v116, vcc
	v_sqrt_f32_e32 v116, v103
	s_nop 0
	v_add_u32_e32 v117, -1, v116
	v_fma_f32 v120, -v117, v116, v103
; __device__ __forceinline__ unsigned cvt_pk_bf16(float lo, float hi) { unsigned r; asm volatile("v_cvt_pk_bf16_f32 %0, %1, %2" : "=v"(r) : "v"(lo), "v"(hi)); return r; }
; __device__ __forceinline__ float bflo(unsigned w) { return __uint_as_float(w << 16); }
; __device__ __forceinline__ float bfhi(unsigned w) { return __uint_as_float(w & 0xffff0000u); }
;     __device__ __forceinline__ void operator()(const f32x4 (&acc)[2][2][4][2], const Unit& u, int wr, int wc, int fr, int fq) const {
;     ...
;                 for (int m = 0; m < 4; ++m) { const size_t off = (size_t)(row0 + ai * 128 + m * 16) * D + ch;
;                     const u32x2 xw = *(const u32x2*)(XRC + off);
;                     const float xr[4] = {bflo(xw.x), bfhi(xw.x), bflo(xw.y), bfhi(xw.y)};
;                     f32x4 dv, bv;
; #pragma unroll
;                     for (int j = 0; j < 4; ++j) { float r, ig; sigmoid2(acc[ai][0][m][n][j] + br4[j], acc[ai][1][m][n][j] + bi4[j], r, ig);
;                         const float la = r * sp4[j]; float dd = neg_expm1_small(la); if (slow) dd = la > -0.25f ? dd : 1.0f - __expf(la);
;                         dv[j] = dd; bv[j] = __builtin_sqrtf(dd * (2.0f - dd)) * ig * xr[j]; }
;                     u32x2 dw, bw; dw.x = cvt_pk_bf16(dv[0], dv[1]); dw.y = cvt_pk_bf16(dv[2], dv[3]); bw.x = cvt_pk_bf16(bv[0], bv[1]); bw.y = cvt_pk_bf16(bv[2], bv[3]);
;                     *(u32x2*)(DD + off) = dw; *(u32x2*)(BB + off) = bw; asm volatile("" ::: "memory"); } }
	v_cmp_ge_f32_e64 s[8:9], 0, v120
	v_add_u32_e32 v120, 1, v116
	s_nop 0
	v_cndmask_b32_e64 v117, v116, v117, s[8:9]
	v_fma_f32 v116, -v120, v116, v103
	v_cmp_lt_f32_e64 s[8:9], 0, v116
	s_nop 1
	v_cndmask_b32_e64 v116, v117, v120, s[8:9]
	v_mul_f32_e32 v117, 0x37800000, v116
	v_cndmask_b32_e32 v116, v116, v117, vcc
	v_cmp_class_f32_e32 vcc, v103, v197
	s_nop 1
	v_cndmask_b32_e32 v103, v116, v103, vcc
	v_mul_f32_e32 v102, v102, v103
	v_mul_f32_e32 v116, v102, v121
	v_add_f32_e32 v102, v108, v88
	v_add_f32_e32 v103, v104, v92
	v_mul_f32_e32 v102, 0xbfb8aa3b, v102
	v_mul_f32_e32 v103, 0xbfb8aa3b, v103
	v_min_f32_e32 v102, 0x42700000, v102
	v_min_f32_e32 v103, 0x42700000, v103
	v_exp_f32_e32 v102, v102
	v_exp_f32_e32 v103, v103
	s_nop 0
	v_pk_add_f32 v[102:103], v[102:103], 1.0 op_sel_hi:[1,0]
	s_nop 0
	v_mul_f32_e32 v104, v102, v103
	v_rcp_f32_e32 v104, v104
	s_nop 0
	v_mul_f32_e32 v103, v103, v104
	v_mul_f32_e32 v103, v84, v103
	v_mul_f32_e32 v102, v102, v104
	v_fmamk_f32 v104, v103, 0x3ab60b61, v196
	v_fmaak_f32 v104, v103, v104, 0x3d2aaaab
	v_fmaak_f32 v104, v103, v104, 0x3e2aaaab
	v_fma_f32 v104, v103, v104, 0.5
	v_fma_f32 v104, v103, v104, 1.0
	v_mul_f32_e64 v104, v104, -v103
	v_cmp_lt_f32_e32 vcc, s25, v103
	v_mul_f32_e32 v103, 0x3fb8aa3b, v103
	v_exp_f32_e32 v103, v103
	s_or_b64 vcc, s[34:35], vcc
	v_sub_f32_e32 v103, 1.0, v103
	v_cndmask_b32_e32 v104, v103, v104, vcc
	v_sub_f32_e32 v103, 2.0, v104
	v_mul_f32_e32 v103, v104, v103
	v_cmp_gt_f32_e32 vcc, s27, v103
	v_mul_f32_e32 v108, 0x4f800000, v103
	s_nop 0
	v_cndmask_b32_e32 v103, v103, v108, vcc
	v_sqrt_f32_e32 v108, v103
	s_nop 0
	v_add_u32_e32 v117, -1, v108
	v_fma_f32 v120, -v117, v108, v103
	v_cmp_ge_f32_e64 s[8:9], 0, v120
	v_add_u32_e32 v120, 1, v108
	s_nop 0
	v_cndmask_b32_e64 v117, v108, v117, s[8:9]
	v_fma_f32 v108, -v120, v108, v103
	v_cmp_lt_f32_e64 s[8:9], 0, v108
	s_nop 1
	v_cndmask_b32_e64 v108, v117, v120, s[8:9]
	v_mul_f32_e32 v117, 0x37800000, v108
	v_cndmask_b32_e32 v108, v108, v117, vcc
	v_cmp_class_f32_e32 vcc, v103, v197
	s_nop 1
	v_cndmask_b32_e32 v103, v108, v103, vcc
	v_mul_f32_e32 v102, v102, v103
	v_mul_f32_e32 v108, v102, v122
	v_add_f32_e32 v102, v109, v89
	v_add_f32_e32 v103, v105, v93
	v_mul_f32_e32 v102, 0xbfb8aa3b, v102
	v_mul_f32_e32 v103, 0xbfb8aa3b, v103
	v_min_f32_e32 v102, 0x42700000, v102
	v_min_f32_e32 v103, 0x42700000, v103
	v_exp_f32_e32 v102, v102
	v_exp_f32_e32 v103, v103
	s_nop 0
	v_pk_add_f32 v[102:103], v[102:103], 1.0 op_sel_hi:[1,0]
	s_nop 0
	v_mul_f32_e32 v105, v102, v103
	v_rcp_f32_e32 v105, v105
	s_nop 0
	v_mul_f32_e32 v103, v103, v105
	v_mul_f32_e32 v103, v85, v103
	v_mul_f32_e32 v102, v102, v105
	v_fmamk_f32 v105, v103, 0x3ab60b61, v196
	v_fmaak_f32 v105, v103, v105, 0x3d2aaaab
	v_fmaak_f32 v105, v103, v105, 0x3e2aaaab
	v_fma_f32 v105, v103, v105, 0.5
	v_fma_f32 v105, v103, v105, 1.0
	v_mul_f32_e64 v105, v105, -v103
	v_cmp_lt_f32_e32 vcc, s25, v103
	v_mul_f32_e32 v103, 0x3fb8aa3b, v103
	v_exp_f32_e32 v103, v103
	s_or_b64 vcc, s[34:35], vcc
	v_sub_f32_e32 v103, 1.0, v103
	v_cndmask_b32_e32 v103, v103, v105, vcc
	v_sub_f32_e32 v105, 2.0, v103
	v_mul_f32_e32 v105, v103, v105
	v_cmp_gt_f32_e32 vcc, s27, v105
	v_mul_f32_e32 v109, 0x4f800000, v105
	s_nop 0
	v_cndmask_b32_e32 v105, v105, v109, vcc
	v_sqrt_f32_e32 v109, v105
	s_nop 0
	v_add_u32_e32 v117, -1, v109
	v_fma_f32 v120, -v117, v109, v105
	v_cmp_ge_f32_e64 s[8:9], 0, v120
	v_add_u32_e32 v120, 1, v109
	s_nop 0
	v_cndmask_b32_e64 v117, v109, v117, s[8:9]
	v_fma_f32 v109, -v120, v109, v105
	v_cmp_lt_f32_e64 s[8:9], 0, v109
	s_nop 1
	v_cndmask_b32_e64 v109, v117, v120, s[8:9]
	v_mul_f32_e32 v117, 0x37800000, v109
	v_cndmask_b32_e32 v109, v109, v117, vcc
	v_cmp_class_f32_e32 vcc, v105, v197
	s_mov_b64 s[8:9], 0x48000
	s_nop 0
	v_cndmask_b32_e32 v105, v109, v105, vcc
	v_mul_f32_e32 v102, v102, v105
	v_mul_f32_e32 v105, v102, v114
	v_cvt_pk_bf16_f32 v102, v106, v107
	v_cvt_pk_bf16_f32 v103, v104, v103
	v_lshl_add_u64 v[106:107], s[16:17], 0, v[112:113]
	v_cvt_pk_bf16_f32 v104, v115, v116
	v_cvt_pk_bf16_f32 v105, v108, v105
	global_store_dwordx2 v[106:107], v[102:103], off
	v_lshl_add_u64 v[102:103], s[18:19], 0, v[112:113]
	global_store_dwordx2 v[102:103], v[104:105], off
	v_lshl_add_u64 v[102:103], v[176:177], 0, s[8:9]
	v_lshl_add_u64 v[104:105], v[102:103], 0, v[170:171]
	v_lshlrev_b64 v[104:105], 1, v[104:105]
	v_lshl_add_u64 v[106:107], s[0:1], 0, v[104:105]
	v_exp_f32_e32 v108, v98
	v_exp_f32_e32 v109, v94
	s_waitcnt vmcnt(15)
; __device__ __forceinline__ unsigned cvt_pk_bf16(float lo, float hi) { unsigned r; asm volatile("v_cvt_pk_bf16_f32 %0, %1, %2" : "=v"(r) : "v"(lo), "v"(hi)); return r; }
; __device__ __forceinline__ float bflo(unsigned w) { return __uint_as_float(w << 16); }
; __device__ __forceinline__ float bfhi(unsigned w) { return __uint_as_float(w & 0xffff0000u); }
;     __device__ __forceinline__ void operator()(const f32x4 (&acc)[2][2][4][2], const Unit& u, int wr, int wc, int fr, int fq) const {
;     ...
;                 for (int m = 0; m < 4; ++m) { const size_t off = (size_t)(row0 + ai * 128 + m * 16) * D + ch;
;                     const u32x2 xw = *(const u32x2*)(XRC + off);
;                     const float xr[4] = {bflo(xw.x), bfhi(xw.x), bflo(xw.y), bfhi(xw.y)};
;                     f32x4 dv, bv;
; #pragma unroll
;                     for (int j = 0; j < 4; ++j) { float r, ig; sigmoid2(acc[ai][0][m][n][j] + br4[j], acc[ai][1][m][n][j] + bi4[j], r, ig);
;                         const float la = r * sp4[j]; float dd = neg_expm1_small(la); if (slow) dd = la > -0.25f ? dd : 1.0f - __expf(la);
;                         dv[j] = dd; bv[j] = __builtin_sqrtf(dd * (2.0f - dd)) * ig * xr[j]; }
;                     u32x2 dw, bw; dw.x = cvt_pk_bf16(dv[0], dv[1]); dw.y = cvt_pk_bf16(dv[2], dv[3]); bw.x = cvt_pk_bf16(bv[0], bv[1]); bw.y = cvt_pk_bf16(bv[2], bv[3]);
;                     *(u32x2*)(DD + off) = dw; *(u32x2*)(BB + off) = bw; asm volatile("" ::: "memory"); } }
	v_mov_b64_e32 v[106:107], v[224:225]
	v_lshlrev_b32_e32 v112, 16, v106
	v_pk_add_f32 v[108:109], v[108:109], 1.0 op_sel_hi:[1,0]
	v_and_b32_e32 v113, 0xffff0000, v106
	v_mul_f32_e32 v94, v108, v109
	v_rcp_f32_e32 v94, v94
	v_lshlrev_b32_e32 v114, 16, v107
	v_and_b32_e32 v106, 0xffff0000, v107
	v_mul_f32_e32 v98, v109, v94
	v_mul_f32_e32 v98, v82, v98
	v_fmamk_f32 v107, v98, 0x3ab60b61, v196
	v_fmaak_f32 v107, v98, v107, 0x3d2aaaab
	v_fmaak_f32 v107, v98, v107, 0x3e2aaaab
	v_fma_f32 v107, v98, v107, 0.5
	v_fma_f32 v107, v98, v107, 1.0
	v_mul_f32_e64 v107, v107, -v98
	v_cmp_lt_f32_e32 vcc, s25, v98
	v_mul_f32_e32 v98, 0x3fb8aa3b, v98
	v_exp_f32_e32 v98, v98
	s_or_b64 vcc, s[34:35], vcc
	v_mul_f32_e32 v94, v108, v94
	v_sub_f32_e32 v98, 1.0, v98
	v_cndmask_b32_e32 v98, v98, v107, vcc
	v_sub_f32_e32 v107, 2.0, v98
	v_mul_f32_e32 v107, v98, v107
	v_cmp_gt_f32_e32 vcc, s27, v107
	v_mul_f32_e32 v108, 0x4f800000, v107
	s_nop 0
	v_cndmask_b32_e32 v107, v107, v108, vcc
	v_sqrt_f32_e32 v108, v107
	s_nop 0
	v_add_u32_e32 v109, -1, v108
	v_fma_f32 v115, -v109, v108, v107
	v_cmp_ge_f32_e64 s[8:9], 0, v115
	v_add_u32_e32 v115, 1, v108
	s_nop 0
	v_cndmask_b32_e64 v109, v108, v109, s[8:9]
	v_fma_f32 v108, -v115, v108, v107
	v_cmp_lt_f32_e64 s[8:9], 0, v108
	s_nop 1
	v_cndmask_b32_e64 v108, v109, v115, s[8:9]
	v_mul_f32_e32 v109, 0x37800000, v108
	v_cndmask_b32_e32 v108, v108, v109, vcc
	v_cmp_class_f32_e32 vcc, v107, v197
	s_nop 1
	v_cndmask_b32_e32 v107, v108, v107, vcc
	v_mul_f32_e32 v94, v94, v107
	v_mul_f32_e32 v107, v94, v112
	v_add_f32_e32 v94, v99, v87
	v_mul_f32_e32 v94, 0xbfb8aa3b, v94
	v_min_f32_e32 v94, 0x42700000, v94
	v_exp_f32_e32 v94, v94
	s_nop 0
	v_pk_add_f32 v[94:95], v[94:95], 1.0 op_sel_hi:[1,0]
	s_nop 0
	v_mul_f32_e32 v99, v94, v95
	v_rcp_f32_e32 v99, v99
	s_nop 0
	v_mul_f32_e32 v95, v95, v99
	v_mul_f32_e32 v95, v83, v95
	v_mul_f32_e32 v94, v94, v99
	v_fmamk_f32 v99, v95, 0x3ab60b61, v196
	v_fmaak_f32 v99, v95, v99, 0x3d2aaaab
	v_fmaak_f32 v99, v95, v99, 0x3e2aaaab
	v_fma_f32 v99, v95, v99, 0.5
	v_fma_f32 v99, v95, v99, 1.0
	v_mul_f32_e64 v99, v99, -v95
	v_cmp_lt_f32_e32 vcc, s25, v95
	v_mul_f32_e32 v95, 0x3fb8aa3b, v95
	v_exp_f32_e32 v95, v95
	s_or_b64 vcc, s[34:35], vcc
	v_sub_f32_e32 v95, 1.0, v95
	v_cndmask_b32_e32 v99, v95, v99, vcc
	v_sub_f32_e32 v95, 2.0, v99
	v_mul_f32_e32 v95, v99, v95
	v_cmp_gt_f32_e32 vcc, s27, v95
	v_mul_f32_e32 v108, 0x4f800000, v95
	s_nop 0
	v_cndmask_b32_e32 v95, v95, v108, vcc
	v_sqrt_f32_e32 v108, v95
	s_nop 0
	v_add_u32_e32 v109, -1, v108
	v_fma_f32 v112, -v109, v108, v95
	v_cmp_ge_f32_e64 s[8:9], 0, v112
	v_add_u32_e32 v112, 1, v108
	s_nop 0
	v_cndmask_b32_e64 v109, v108, v109, s[8:9]
	v_fma_f32 v108, -v112, v108, v95
	v_cmp_lt_f32_e64 s[8:9], 0, v108
	s_nop 1
	v_cndmask_b32_e64 v108, v109, v112, s[8:9]
	v_mul_f32_e32 v109, 0x37800000, v108
	v_cndmask_b32_e32 v108, v108, v109, vcc
	v_cmp_class_f32_e32 vcc, v95, v197
	s_nop 1
	v_cndmask_b32_e32 v95, v108, v95, vcc
	v_mul_f32_e32 v94, v94, v95
	v_mul_f32_e32 v108, v94, v113
	v_add_f32_e32 v94, v100, v88
	v_add_f32_e32 v95, v96, v92
	v_mul_f32_e32 v94, 0xbfb8aa3b, v94
	v_mul_f32_e32 v95, 0xbfb8aa3b, v95
	v_min_f32_e32 v94, 0x42700000, v94
	v_min_f32_e32 v95, 0x42700000, v95
	v_exp_f32_e32 v94, v94
	v_exp_f32_e32 v95, v95
	s_nop 0
	v_pk_add_f32 v[94:95], v[94:95], 1.0 op_sel_hi:[1,0]
	s_nop 0
	v_mul_f32_e32 v96, v94, v95
	v_rcp_f32_e32 v96, v96
	s_nop 0
	v_mul_f32_e32 v95, v95, v96
	v_mul_f32_e32 v95, v84, v95
	v_mul_f32_e32 v94, v94, v96
	v_fmamk_f32 v96, v95, 0x3ab60b61, v196
	v_fmaak_f32 v96, v95, v96, 0x3d2aaaab
	v_fmaak_f32 v96, v95, v96, 0x3e2aaaab
	v_fma_f32 v96, v95, v96, 0.5
	v_fma_f32 v96, v95, v96, 1.0
	v_mul_f32_e64 v96, v96, -v95
	v_cmp_lt_f32_e32 vcc, s25, v95
	v_mul_f32_e32 v95, 0x3fb8aa3b, v95
	v_exp_f32_e32 v95, v95
	s_or_b64 vcc, s[34:35], vcc
	v_sub_f32_e32 v95, 1.0, v95
	v_cndmask_b32_e32 v96, v95, v96, vcc
	v_sub_f32_e32 v95, 2.0, v96
	v_mul_f32_e32 v95, v96, v95
	v_cmp_gt_f32_e32 vcc, s27, v95
	v_mul_f32_e32 v100, 0x4f800000, v95
	s_nop 0
	v_cndmask_b32_e32 v95, v95, v100, vcc
	v_sqrt_f32_e32 v100, v95
	s_nop 0
	v_add_u32_e32 v109, -1, v100
	v_fma_f32 v112, -v109, v100, v95
	v_cmp_ge_f32_e64 s[8:9], 0, v112
	v_add_u32_e32 v112, 1, v100
	s_nop 0
	v_cndmask_b32_e64 v109, v100, v109, s[8:9]
	v_fma_f32 v100, -v112, v100, v95
	v_cmp_lt_f32_e64 s[8:9], 0, v100
	s_nop 1
	v_cndmask_b32_e64 v100, v109, v112, s[8:9]
	v_mul_f32_e32 v109, 0x37800000, v100
	v_cndmask_b32_e32 v100, v100, v109, vcc
	v_cmp_class_f32_e32 vcc, v95, v197
	s_nop 1
	v_cndmask_b32_e32 v95, v100, v95, vcc
	v_mul_f32_e32 v94, v94, v95
	v_mul_f32_e32 v100, v94, v114
	v_add_f32_e32 v94, v101, v89
	v_add_f32_e32 v95, v97, v93
	v_mul_f32_e32 v94, 0xbfb8aa3b, v94
	v_mul_f32_e32 v95, 0xbfb8aa3b, v95
	v_min_f32_e32 v94, 0x42700000, v94
	v_min_f32_e32 v95, 0x42700000, v95
	v_exp_f32_e32 v94, v94
	v_exp_f32_e32 v95, v95
	s_nop 0
	v_pk_add_f32 v[94:95], v[94:95], 1.0 op_sel_hi:[1,0]
	s_nop 0
	v_mul_f32_e32 v97, v94, v95
	v_rcp_f32_e32 v97, v97
	s_nop 0
	v_mul_f32_e32 v95, v95, v97
	v_mul_f32_e32 v95, v85, v95
	v_mul_f32_e32 v94, v94, v97
	v_fmamk_f32 v97, v95, 0x3ab60b61, v196
	v_fmaak_f32 v97, v95, v97, 0x3d2aaaab
	v_fmaak_f32 v97, v95, v97, 0x3e2aaaab
	v_fma_f32 v97, v95, v97, 0.5
	v_fma_f32 v97, v95, v97, 1.0
	v_mul_f32_e64 v97, v97, -v95
	v_cmp_lt_f32_e32 vcc, s25, v95
	v_mul_f32_e32 v95, 0x3fb8aa3b, v95
	v_exp_f32_e32 v95, v95
	s_or_b64 vcc, s[34:35], vcc
	v_sub_f32_e32 v95, 1.0, v95
	v_cndmask_b32_e32 v95, v95, v97, vcc
	v_sub_f32_e32 v97, 2.0, v95
	v_mul_f32_e32 v97, v95, v97
	v_cmp_gt_f32_e32 vcc, s27, v97
	v_mul_f32_e32 v101, 0x4f800000, v97
	s_nop 0
	v_cndmask_b32_e32 v97, v97, v101, vcc
	v_sqrt_f32_e32 v101, v97
	s_nop 0
	v_add_u32_e32 v109, -1, v101
	v_fma_f32 v112, -v109, v101, v97
	v_cmp_ge_f32_e64 s[8:9], 0, v112
	v_add_u32_e32 v112, 1, v101
	s_nop 0
	v_cndmask_b32_e64 v109, v101, v109, s[8:9]
	v_fma_f32 v101, -v112, v101, v97
	v_cmp_lt_f32_e64 s[8:9], 0, v101
	s_nop 1
	v_cndmask_b32_e64 v101, v109, v112, s[8:9]
	v_mul_f32_e32 v109, 0x37800000, v101
	v_cndmask_b32_e32 v101, v101, v109, vcc
	v_cmp_class_f32_e32 vcc, v97, v197
	s_mov_b64 s[8:9], 0x50000
	s_nop 0
	v_cndmask_b32_e32 v97, v101, v97, vcc
	v_mul_f32_e32 v94, v94, v97
	v_mul_f32_e32 v97, v94, v106
	v_cvt_pk_bf16_f32 v94, v98, v99
	v_cvt_pk_bf16_f32 v95, v96, v95
	v_lshl_add_u64 v[98:99], s[16:17], 0, v[104:105]
	v_cvt_pk_bf16_f32 v96, v107, v108
	v_cvt_pk_bf16_f32 v97, v100, v97
	global_store_dwordx2 v[98:99], v[94:95], off
	v_lshl_add_u64 v[94:95], s[18:19], 0, v[104:105]
	global_store_dwordx2 v[94:95], v[96:97], off
	v_lshl_add_u64 v[94:95], v[176:177], 0, s[8:9]
	v_lshl_add_u64 v[96:97], v[94:95], 0, v[170:171]
	v_lshlrev_b64 v[96:97], 1, v[96:97]
	v_lshl_add_u64 v[98:99], s[0:1], 0, v[96:97]
	v_exp_f32_e32 v100, v78
	v_exp_f32_e32 v101, v74
	s_waitcnt vmcnt(15)
; __device__ __forceinline__ unsigned cvt_pk_bf16(float lo, float hi) { unsigned r; asm volatile("v_cvt_pk_bf16_f32 %0, %1, %2" : "=v"(r) : "v"(lo), "v"(hi)); return r; }
; __device__ __forceinline__ float bflo(unsigned w) { return __uint_as_float(w << 16); }
; __device__ __forceinline__ float bfhi(unsigned w) { return __uint_as_float(w & 0xffff0000u); }
;     __device__ __forceinline__ void operator()(const f32x4 (&acc)[2][2][4][2], const Unit& u, int wr, int wc, int fr, int fq) const {
;     ...
;                 for (int m = 0; m < 4; ++m) { const size_t off = (size_t)(row0 + ai * 128 + m * 16) * D + ch;
;                     const u32x2 xw = *(const u32x2*)(XRC + off);
;                     const float xr[4] = {bflo(xw.x), bfhi(xw.x), bflo(xw.y), bfhi(xw.y)};
;                     f32x4 dv, bv;
; #pragma unroll
;                     for (int j = 0; j < 4; ++j) { float r, ig; sigmoid2(acc[ai][0][m][n][j] + br4[j], acc[ai][1][m][n][j] + bi4[j], r, ig);
;                         const float la = r * sp4[j]; float dd = neg_expm1_small(la); if (slow) dd = la > -0.25f ? dd : 1.0f - __expf(la);
;                         dv[j] = dd; bv[j] = __builtin_sqrtf(dd * (2.0f - dd)) * ig * xr[j]; }
;                     u32x2 dw, bw; dw.x = cvt_pk_bf16(dv[0], dv[1]); dw.y = cvt_pk_bf16(dv[2], dv[3]); bw.x = cvt_pk_bf16(bv[0], bv[1]); bw.y = cvt_pk_bf16(bv[2], bv[3]);
;                     *(u32x2*)(DD + off) = dw; *(u32x2*)(BB + off) = bw; asm volatile("" ::: "memory"); } }
	v_mov_b64_e32 v[98:99], v[226:227]
	v_lshlrev_b32_e32 v104, 16, v98
	v_pk_add_f32 v[100:101], v[100:101], 1.0 op_sel_hi:[1,0]
	v_and_b32_e32 v105, 0xffff0000, v98
	v_mul_f32_e32 v74, v100, v101
	v_rcp_f32_e32 v74, v74
	v_lshlrev_b32_e32 v106, 16, v99
	v_and_b32_e32 v98, 0xffff0000, v99
	v_mul_f32_e32 v78, v101, v74
	v_mul_f32_e32 v78, v82, v78
	v_fmamk_f32 v99, v78, 0x3ab60b61, v196
	v_fmaak_f32 v99, v78, v99, 0x3d2aaaab
	v_fmaak_f32 v99, v78, v99, 0x3e2aaaab
	v_fma_f32 v99, v78, v99, 0.5
	v_fma_f32 v99, v78, v99, 1.0
	v_mul_f32_e64 v99, v99, -v78
	v_cmp_lt_f32_e32 vcc, s25, v78
	v_mul_f32_e32 v78, 0x3fb8aa3b, v78
	v_exp_f32_e32 v78, v78
	s_or_b64 vcc, s[34:35], vcc
	v_mul_f32_e32 v74, v100, v74
	v_sub_f32_e32 v78, 1.0, v78
	v_cndmask_b32_e32 v78, v78, v99, vcc
	v_sub_f32_e32 v99, 2.0, v78
	v_mul_f32_e32 v99, v78, v99
	v_cmp_gt_f32_e32 vcc, s27, v99
	v_mul_f32_e32 v100, 0x4f800000, v99
	s_nop 0
	v_cndmask_b32_e32 v99, v99, v100, vcc
	v_sqrt_f32_e32 v100, v99
	s_nop 0
	v_add_u32_e32 v101, -1, v100
	v_fma_f32 v107, -v101, v100, v99
	v_cmp_ge_f32_e64 s[8:9], 0, v107
	v_add_u32_e32 v107, 1, v100
	s_nop 0
	v_cndmask_b32_e64 v101, v100, v101, s[8:9]
	v_fma_f32 v100, -v107, v100, v99
	v_cmp_lt_f32_e64 s[8:9], 0, v100
	s_nop 1
	v_cndmask_b32_e64 v100, v101, v107, s[8:9]
	v_mul_f32_e32 v101, 0x37800000, v100
	v_cndmask_b32_e32 v100, v100, v101, vcc
	v_cmp_class_f32_e32 vcc, v99, v197
	s_nop 1
	v_cndmask_b32_e32 v99, v100, v99, vcc
	v_mul_f32_e32 v74, v74, v99
	v_mul_f32_e32 v99, v74, v104
	v_add_f32_e32 v74, v79, v87
	v_mul_f32_e32 v74, 0xbfb8aa3b, v74
	v_min_f32_e32 v74, 0x42700000, v74
	v_exp_f32_e32 v74, v74
	s_nop 0
	v_pk_add_f32 v[74:75], v[74:75], 1.0 op_sel_hi:[1,0]
	s_nop 0
	v_mul_f32_e32 v79, v74, v75
	v_rcp_f32_e32 v79, v79
	s_nop 0
	v_mul_f32_e32 v75, v75, v79
	v_mul_f32_e32 v75, v83, v75
	v_mul_f32_e32 v74, v74, v79
	v_fmamk_f32 v79, v75, 0x3ab60b61, v196
	v_fmaak_f32 v79, v75, v79, 0x3d2aaaab
	v_fmaak_f32 v79, v75, v79, 0x3e2aaaab
	v_fma_f32 v79, v75, v79, 0.5
	v_fma_f32 v79, v75, v79, 1.0
	v_mul_f32_e64 v79, v79, -v75
	v_cmp_lt_f32_e32 vcc, s25, v75
	v_mul_f32_e32 v75, 0x3fb8aa3b, v75
	v_exp_f32_e32 v75, v75
	s_or_b64 vcc, s[34:35], vcc
	v_sub_f32_e32 v75, 1.0, v75
	v_cndmask_b32_e32 v79, v75, v79, vcc
	v_sub_f32_e32 v75, 2.0, v79
	v_mul_f32_e32 v75, v79, v75
	v_cmp_gt_f32_e32 vcc, s27, v75
	v_mul_f32_e32 v100, 0x4f800000, v75
	s_nop 0
	v_cndmask_b32_e32 v75, v75, v100, vcc
	v_sqrt_f32_e32 v100, v75
	s_nop 0
	v_add_u32_e32 v101, -1, v100
	v_fma_f32 v104, -v101, v100, v75
	v_cmp_ge_f32_e64 s[8:9], 0, v104
	v_add_u32_e32 v104, 1, v100
	s_nop 0
	v_cndmask_b32_e64 v101, v100, v101, s[8:9]
	v_fma_f32 v100, -v104, v100, v75
	v_cmp_lt_f32_e64 s[8:9], 0, v100
	s_nop 1
	v_cndmask_b32_e64 v100, v101, v104, s[8:9]
	v_mul_f32_e32 v101, 0x37800000, v100
	v_cndmask_b32_e32 v100, v100, v101, vcc
	v_cmp_class_f32_e32 vcc, v75, v197
	s_nop 1
	v_cndmask_b32_e32 v75, v100, v75, vcc
	v_mul_f32_e32 v74, v74, v75
	v_mul_f32_e32 v100, v74, v105
	v_add_f32_e32 v74, v80, v88
	v_add_f32_e32 v75, v76, v92
	v_mul_f32_e32 v74, 0xbfb8aa3b, v74
	v_mul_f32_e32 v75, 0xbfb8aa3b, v75
	v_min_f32_e32 v74, 0x42700000, v74
	v_min_f32_e32 v75, 0x42700000, v75
	v_exp_f32_e32 v74, v74
	v_exp_f32_e32 v75, v75
	s_nop 0
	v_pk_add_f32 v[74:75], v[74:75], 1.0 op_sel_hi:[1,0]
	s_nop 0
	v_mul_f32_e32 v76, v74, v75
	v_rcp_f32_e32 v76, v76
	s_nop 0
	v_mul_f32_e32 v75, v75, v76
	v_mul_f32_e32 v75, v84, v75
	v_mul_f32_e32 v74, v74, v76
	v_fmamk_f32 v76, v75, 0x3ab60b61, v196
	v_fmaak_f32 v76, v75, v76, 0x3d2aaaab
	v_fmaak_f32 v76, v75, v76, 0x3e2aaaab
	v_fma_f32 v76, v75, v76, 0.5
	v_fma_f32 v76, v75, v76, 1.0
	v_mul_f32_e64 v76, v76, -v75
	v_cmp_lt_f32_e32 vcc, s25, v75
	v_mul_f32_e32 v75, 0x3fb8aa3b, v75
	v_exp_f32_e32 v75, v75
	s_or_b64 vcc, s[34:35], vcc
	v_sub_f32_e32 v75, 1.0, v75
	v_cndmask_b32_e32 v76, v75, v76, vcc
	v_sub_f32_e32 v75, 2.0, v76
	v_mul_f32_e32 v75, v76, v75
	v_cmp_gt_f32_e32 vcc, s27, v75
	v_mul_f32_e32 v80, 0x4f800000, v75
	s_nop 0
	v_cndmask_b32_e32 v75, v75, v80, vcc
	v_sqrt_f32_e32 v80, v75
	s_nop 0
	v_add_u32_e32 v101, -1, v80
	v_fma_f32 v104, -v101, v80, v75
	v_cmp_ge_f32_e64 s[8:9], 0, v104
	v_add_u32_e32 v104, 1, v80
	s_nop 0
	v_cndmask_b32_e64 v101, v80, v101, s[8:9]
	v_fma_f32 v80, -v104, v80, v75
	v_cmp_lt_f32_e64 s[8:9], 0, v80
	s_nop 1
	v_cndmask_b32_e64 v80, v101, v104, s[8:9]
	v_mul_f32_e32 v101, 0x37800000, v80
	v_cndmask_b32_e32 v80, v80, v101, vcc
	v_cmp_class_f32_e32 vcc, v75, v197
	s_nop 1
	v_cndmask_b32_e32 v75, v80, v75, vcc
	v_mul_f32_e32 v74, v74, v75
	v_mul_f32_e32 v80, v74, v106
	v_add_f32_e32 v74, v81, v89
	v_add_f32_e32 v75, v77, v93
	v_mul_f32_e32 v74, 0xbfb8aa3b, v74
	v_mul_f32_e32 v75, 0xbfb8aa3b, v75
	v_min_f32_e32 v74, 0x42700000, v74
	v_min_f32_e32 v75, 0x42700000, v75
	v_exp_f32_e32 v74, v74
	v_exp_f32_e32 v75, v75
	s_nop 0
	v_pk_add_f32 v[74:75], v[74:75], 1.0 op_sel_hi:[1,0]
	s_nop 0
	v_mul_f32_e32 v77, v74, v75
	v_rcp_f32_e32 v77, v77
	s_nop 0
	v_mul_f32_e32 v75, v75, v77
	v_mul_f32_e32 v75, v85, v75
	v_mul_f32_e32 v74, v74, v77
	v_fmamk_f32 v77, v75, 0x3ab60b61, v196
	v_fmaak_f32 v77, v75, v77, 0x3d2aaaab
	v_fmaak_f32 v77, v75, v77, 0x3e2aaaab
	v_fma_f32 v77, v75, v77, 0.5
	v_fma_f32 v77, v75, v77, 1.0
	v_mul_f32_e64 v77, v77, -v75
	v_cmp_lt_f32_e32 vcc, s25, v75
	v_mul_f32_e32 v75, 0x3fb8aa3b, v75
	v_exp_f32_e32 v75, v75
	s_or_b64 vcc, s[34:35], vcc
	v_sub_f32_e32 v75, 1.0, v75
	v_cndmask_b32_e32 v75, v75, v77, vcc
	v_sub_f32_e32 v77, 2.0, v75
	v_mul_f32_e32 v77, v75, v77
	v_cmp_gt_f32_e32 vcc, s27, v77
	v_mul_f32_e32 v81, 0x4f800000, v77
	s_nop 0
	v_cndmask_b32_e32 v77, v77, v81, vcc
	v_sqrt_f32_e32 v81, v77
	s_nop 0
	v_add_u32_e32 v101, -1, v81
	v_fma_f32 v104, -v101, v81, v77
	v_cmp_ge_f32_e64 s[8:9], 0, v104
	v_add_u32_e32 v104, 1, v81
	s_nop 0
	v_cndmask_b32_e64 v101, v81, v101, s[8:9]
	v_fma_f32 v81, -v104, v81, v77
	v_cmp_lt_f32_e64 s[8:9], 0, v81
	s_nop 1
	v_cndmask_b32_e64 v81, v101, v104, s[8:9]
	v_mul_f32_e32 v101, 0x37800000, v81
	v_cndmask_b32_e32 v81, v81, v101, vcc
	v_cmp_class_f32_e32 vcc, v77, v197
	s_mov_b64 s[8:9], 0x58000
	s_nop 0
	v_cndmask_b32_e32 v77, v81, v77, vcc
	v_mul_f32_e32 v74, v74, v77
	v_mul_f32_e32 v77, v74, v98
	v_cvt_pk_bf16_f32 v74, v78, v79
	v_cvt_pk_bf16_f32 v75, v76, v75
	v_lshl_add_u64 v[78:79], s[16:17], 0, v[96:97]
	v_cvt_pk_bf16_f32 v76, v99, v100
	v_cvt_pk_bf16_f32 v77, v80, v77
	global_store_dwordx2 v[78:79], v[74:75], off
	v_lshl_add_u64 v[74:75], s[18:19], 0, v[96:97]
	v_lshl_add_u64 v[78:79], v[176:177], 0, s[8:9]
	global_store_dwordx2 v[74:75], v[76:77], off
	v_lshl_add_u64 v[74:75], v[78:79], 0, v[170:171]
	v_lshlrev_b64 v[74:75], 1, v[74:75]
	v_lshl_add_u64 v[76:77], s[0:1], 0, v[74:75]
	v_exp_f32_e32 v80, v70
	v_exp_f32_e32 v81, v66
	s_waitcnt vmcnt(15)
; __device__ __forceinline__ unsigned cvt_pk_bf16(float lo, float hi) { unsigned r; asm volatile("v_cvt_pk_bf16_f32 %0, %1, %2" : "=v"(r) : "v"(lo), "v"(hi)); return r; }
; __device__ __forceinline__ float bflo(unsigned w) { return __uint_as_float(w << 16); }
; __device__ __forceinline__ float bfhi(unsigned w) { return __uint_as_float(w & 0xffff0000u); }
;     __device__ __forceinline__ void operator()(const f32x4 (&acc)[2][2][4][2], const Unit& u, int wr, int wc, int fr, int fq) const {
;     ...
;         for (int n = 0; n < 2; ++n) { const int ch = chb + 16 * n;
;             const f32x4 br4 = *(const f32x4*)(br + ch), bi4 = *(const f32x4*)(bi + ch), sp4 = *(const f32x4*)(spt + ch);
;             const bool slow = __ballot(fminf(fminf(sp4[0], sp4[1]), fminf(sp4[2], sp4[3])) <= -0.25f) != 0ull;
;     ...
;                 for (int m = 0; m < 4; ++m) { const size_t off = (size_t)(row0 + ai * 128 + m * 16) * D + ch;
;                     const u32x2 xw = *(const u32x2*)(XRC + off);
;                     const float xr[4] = {bflo(xw.x), bfhi(xw.x), bflo(xw.y), bfhi(xw.y)};
;                     f32x4 dv, bv;
; #pragma unroll
;                     for (int j = 0; j < 4; ++j) { float r, ig; sigmoid2(acc[ai][0][m][n][j] + br4[j], acc[ai][1][m][n][j] + bi4[j], r, ig);
;                         const float la = r * sp4[j]; float dd = neg_expm1_small(la); if (slow) dd = la > -0.25f ? dd : 1.0f - __expf(la);
;                         dv[j] = dd; bv[j] = __builtin_sqrtf(dd * (2.0f - dd)) * ig * xr[j]; }
;                     u32x2 dw, bw; dw.x = cvt_pk_bf16(dv[0], dv[1]); dw.y = cvt_pk_bf16(dv[2], dv[3]); bw.x = cvt_pk_bf16(bv[0], bv[1]); bw.y = cvt_pk_bf16(bv[2], bv[3]);
;                     *(u32x2*)(DD + off) = dw; *(u32x2*)(BB + off) = bw; asm volatile("" ::: "memory"); } }
	v_mov_b64_e32 v[76:77], v[228:229]
	v_lshlrev_b32_e32 v96, 16, v76
	v_pk_add_f32 v[80:81], v[80:81], 1.0 op_sel_hi:[1,0]
	v_and_b32_e32 v97, 0xffff0000, v76
	v_mul_f32_e32 v66, v80, v81
	v_rcp_f32_e32 v66, v66
	v_lshlrev_b32_e32 v98, 16, v77
	v_and_b32_e32 v76, 0xffff0000, v77
	v_mul_f32_e32 v70, v81, v66
	v_mul_f32_e32 v70, v82, v70
	v_fmamk_f32 v77, v70, 0x3ab60b61, v196
	v_fmaak_f32 v77, v70, v77, 0x3d2aaaab
	v_fmaak_f32 v77, v70, v77, 0x3e2aaaab
	v_fma_f32 v77, v70, v77, 0.5
	v_fma_f32 v77, v70, v77, 1.0
	v_mul_f32_e64 v77, v77, -v70
	v_cmp_lt_f32_e32 vcc, s25, v70
	v_mul_f32_e32 v70, 0x3fb8aa3b, v70
	v_exp_f32_e32 v70, v70
	s_or_b64 vcc, s[34:35], vcc
	v_mul_f32_e32 v66, v80, v66
	v_sub_f32_e32 v70, 1.0, v70
	v_cndmask_b32_e32 v70, v70, v77, vcc
	v_sub_f32_e32 v77, 2.0, v70
	v_mul_f32_e32 v77, v70, v77
	v_cmp_gt_f32_e32 vcc, s27, v77
	v_mul_f32_e32 v80, 0x4f800000, v77
	s_nop 0
	v_cndmask_b32_e32 v77, v77, v80, vcc
	v_sqrt_f32_e32 v80, v77
	s_nop 0
	v_add_u32_e32 v81, -1, v80
	v_fma_f32 v82, -v81, v80, v77
	v_cmp_ge_f32_e64 s[8:9], 0, v82
	v_add_u32_e32 v82, 1, v80
	s_nop 0
	v_cndmask_b32_e64 v81, v80, v81, s[8:9]
	v_fma_f32 v80, -v82, v80, v77
	v_cmp_lt_f32_e64 s[8:9], 0, v80
	s_nop 1
	v_cndmask_b32_e64 v80, v81, v82, s[8:9]
	v_mul_f32_e32 v81, 0x37800000, v80
	v_cndmask_b32_e32 v80, v80, v81, vcc
	v_cmp_class_f32_e32 vcc, v77, v197
	s_nop 1
	v_cndmask_b32_e32 v77, v80, v77, vcc
	v_mul_f32_e32 v66, v66, v77
	v_mul_f32_e32 v77, v66, v96
	v_add_f32_e32 v66, v71, v87
	v_mul_f32_e32 v66, 0xbfb8aa3b, v66
	v_min_f32_e32 v66, 0x42700000, v66
	v_exp_f32_e32 v66, v66
	s_nop 0
	v_pk_add_f32 v[66:67], v[66:67], 1.0 op_sel_hi:[1,0]
	s_nop 0
	v_mul_f32_e32 v71, v66, v67
	v_rcp_f32_e32 v71, v71
	s_nop 0
	v_mul_f32_e32 v67, v67, v71
	v_mul_f32_e32 v67, v83, v67
	v_mul_f32_e32 v66, v66, v71
	v_fmamk_f32 v71, v67, 0x3ab60b61, v196
	v_fmaak_f32 v71, v67, v71, 0x3d2aaaab
	v_fmaak_f32 v71, v67, v71, 0x3e2aaaab
	v_fma_f32 v71, v67, v71, 0.5
	v_fma_f32 v71, v67, v71, 1.0
	v_mul_f32_e64 v71, v71, -v67
	v_cmp_lt_f32_e32 vcc, s25, v67
	v_mul_f32_e32 v67, 0x3fb8aa3b, v67
	v_exp_f32_e32 v67, v67
	s_or_b64 vcc, s[34:35], vcc
	v_sub_f32_e32 v67, 1.0, v67
	v_cndmask_b32_e32 v71, v67, v71, vcc
	v_sub_f32_e32 v67, 2.0, v71
	v_mul_f32_e32 v67, v71, v67
	v_cmp_gt_f32_e32 vcc, s27, v67
	v_mul_f32_e32 v80, 0x4f800000, v67
	s_nop 0
	v_cndmask_b32_e32 v67, v67, v80, vcc
	v_sqrt_f32_e32 v80, v67
	s_nop 0
	v_add_u32_e32 v81, -1, v80
	v_fma_f32 v82, -v81, v80, v67
	v_cmp_ge_f32_e64 s[8:9], 0, v82
	v_add_u32_e32 v82, 1, v80
	s_nop 0
	v_cndmask_b32_e64 v81, v80, v81, s[8:9]
	v_fma_f32 v80, -v82, v80, v67
	v_cmp_lt_f32_e64 s[8:9], 0, v80
	s_nop 1
	v_cndmask_b32_e64 v80, v81, v82, s[8:9]
	v_mul_f32_e32 v81, 0x37800000, v80
	v_cndmask_b32_e32 v80, v80, v81, vcc
	v_cmp_class_f32_e32 vcc, v67, v197
	s_nop 1
	v_cndmask_b32_e32 v67, v80, v67, vcc
	v_mul_f32_e32 v66, v66, v67
	v_mul_f32_e32 v80, v66, v97
	v_add_f32_e32 v66, v72, v88
	v_add_f32_e32 v67, v68, v92
	v_mul_f32_e32 v66, 0xbfb8aa3b, v66
	v_mul_f32_e32 v67, 0xbfb8aa3b, v67
	v_min_f32_e32 v66, 0x42700000, v66
	v_min_f32_e32 v67, 0x42700000, v67
	v_exp_f32_e32 v66, v66
	v_exp_f32_e32 v67, v67
	s_nop 0
	v_pk_add_f32 v[66:67], v[66:67], 1.0 op_sel_hi:[1,0]
	s_nop 0
	v_mul_f32_e32 v68, v66, v67
	v_rcp_f32_e32 v68, v68
	s_nop 0
	v_mul_f32_e32 v67, v67, v68
	v_mul_f32_e32 v67, v84, v67
	v_mul_f32_e32 v66, v66, v68
	v_fmamk_f32 v68, v67, 0x3ab60b61, v196
	v_fmaak_f32 v68, v67, v68, 0x3d2aaaab
	v_fmaak_f32 v68, v67, v68, 0x3e2aaaab
	v_fma_f32 v68, v67, v68, 0.5
	v_fma_f32 v68, v67, v68, 1.0
	v_mul_f32_e64 v68, v68, -v67
	v_cmp_lt_f32_e32 vcc, s25, v67
	v_mul_f32_e32 v67, 0x3fb8aa3b, v67
	v_exp_f32_e32 v67, v67
	s_or_b64 vcc, s[34:35], vcc
	v_sub_f32_e32 v67, 1.0, v67
	v_cndmask_b32_e32 v68, v67, v68, vcc
	v_sub_f32_e32 v67, 2.0, v68
	v_mul_f32_e32 v67, v68, v67
	v_cmp_gt_f32_e32 vcc, s27, v67
	v_mul_f32_e32 v72, 0x4f800000, v67
	s_nop 0
	v_cndmask_b32_e32 v67, v67, v72, vcc
	v_sqrt_f32_e32 v72, v67
	s_nop 0
	v_add_u32_e32 v81, -1, v72
	v_fma_f32 v82, -v81, v72, v67
	v_cmp_ge_f32_e64 s[8:9], 0, v82
	v_add_u32_e32 v82, 1, v72
	s_nop 0
	v_cndmask_b32_e64 v81, v72, v81, s[8:9]
	v_fma_f32 v72, -v82, v72, v67
	v_cmp_lt_f32_e64 s[8:9], 0, v72
	s_nop 1
	v_cndmask_b32_e64 v72, v81, v82, s[8:9]
	v_mul_f32_e32 v81, 0x37800000, v72
	v_cndmask_b32_e32 v72, v72, v81, vcc
	v_cmp_class_f32_e32 vcc, v67, v197
	s_nop 1
	v_cndmask_b32_e32 v67, v72, v67, vcc
	v_mul_f32_e32 v66, v66, v67
	v_mul_f32_e32 v72, v66, v98
	v_add_f32_e32 v66, v73, v89
	v_add_f32_e32 v67, v69, v93
	v_mul_f32_e32 v66, 0xbfb8aa3b, v66
	v_mul_f32_e32 v67, 0xbfb8aa3b, v67
	v_min_f32_e32 v66, 0x42700000, v66
	v_min_f32_e32 v67, 0x42700000, v67
	v_exp_f32_e32 v66, v66
	v_exp_f32_e32 v67, v67
	s_nop 0
	v_pk_add_f32 v[66:67], v[66:67], 1.0 op_sel_hi:[1,0]
	s_nop 0
	v_mul_f32_e32 v69, v66, v67
	v_rcp_f32_e32 v69, v69
	s_nop 0
	v_mul_f32_e32 v67, v67, v69
	v_mul_f32_e32 v67, v85, v67
	v_mul_f32_e32 v66, v66, v69
	v_fmamk_f32 v69, v67, 0x3ab60b61, v196
	v_fmaak_f32 v69, v67, v69, 0x3d2aaaab
	v_fmaak_f32 v69, v67, v69, 0x3e2aaaab
	v_fma_f32 v69, v67, v69, 0.5
	v_fma_f32 v69, v67, v69, 1.0
	v_mul_f32_e64 v69, v69, -v67
	v_cmp_lt_f32_e32 vcc, s25, v67
	v_mul_f32_e32 v67, 0x3fb8aa3b, v67
	v_exp_f32_e32 v67, v67
	s_or_b64 vcc, s[34:35], vcc
	v_sub_f32_e32 v67, 1.0, v67
	v_cndmask_b32_e32 v67, v67, v69, vcc
	v_sub_f32_e32 v69, 2.0, v67
	v_mul_f32_e32 v69, v67, v69
	v_cmp_gt_f32_e32 vcc, s27, v69
	v_mul_f32_e32 v73, 0x4f800000, v69
	s_nop 0
	v_cndmask_b32_e32 v69, v69, v73, vcc
	v_sqrt_f32_e32 v73, v69
	s_nop 0
	v_add_u32_e32 v81, -1, v73
	v_fma_f32 v82, -v81, v73, v69
	v_cmp_ge_f32_e64 s[8:9], 0, v82
	v_add_u32_e32 v82, 1, v73
	s_nop 0
	v_cndmask_b32_e64 v81, v73, v81, s[8:9]
	v_fma_f32 v73, -v82, v73, v69
	v_cmp_lt_f32_e64 s[8:9], 0, v73
	s_nop 1
	v_cndmask_b32_e64 v73, v81, v82, s[8:9]
	v_mul_f32_e32 v81, 0x37800000, v73
	v_cndmask_b32_e32 v73, v73, v81, vcc
	v_cmp_class_f32_e32 vcc, v69, v197
	s_nop 1
	v_cndmask_b32_e32 v69, v73, v69, vcc
	v_mul_f32_e32 v66, v66, v69
	v_mul_f32_e32 v69, v66, v76
	v_cvt_pk_bf16_f32 v66, v70, v71
	v_cvt_pk_bf16_f32 v67, v68, v67
	v_lshl_add_u64 v[70:71], s[16:17], 0, v[74:75]
	v_cvt_pk_bf16_f32 v68, v77, v80
	v_cvt_pk_bf16_f32 v69, v72, v69
	global_store_dwordx2 v[70:71], v[66:67], off
	v_lshl_add_u64 v[66:67], s[18:19], 0, v[74:75]
	v_or_b32_e32 v80, 16, v170
	global_store_dwordx2 v[66:67], v[68:69], off
	v_ashrrev_i32_e32 v81, 31, v80
	v_lshl_add_u64 v[66:67], v[80:81], 2, s[14:15]
	global_load_dwordx4 v[70:73], v[172:173], off offset:64
	global_load_dwordx4 v[74:77], v[174:175], off offset:64
	s_waitcnt vmcnt(1)
; __device__ __forceinline__ unsigned cvt_pk_bf16(float lo, float hi) { unsigned r; asm volatile("v_cvt_pk_bf16_f32 %0, %1, %2" : "=v"(r) : "v"(lo), "v"(hi)); return r; }
; __device__ __forceinline__ float bflo(unsigned w) { return __uint_as_float(w << 16); }
; __device__ __forceinline__ float bfhi(unsigned w) { return __uint_as_float(w & 0xffff0000u); }
;     __device__ __forceinline__ void operator()(const f32x4 (&acc)[2][2][4][2], const Unit& u, int wr, int wc, int fr, int fq) const {
;     ...
;         for (int n = 0; n < 2; ++n) { const int ch = chb + 16 * n;
;             const f32x4 br4 = *(const f32x4*)(br + ch), bi4 = *(const f32x4*)(bi + ch), sp4 = *(const f32x4*)(spt + ch);
;             const bool slow = __ballot(fminf(fminf(sp4[0], sp4[1]), fminf(sp4[2], sp4[3])) <= -0.25f) != 0ull;
; #pragma unroll
;             for (int ai = 0; ai < 2; ++ai)
; #pragma unroll
;                 for (int m = 0; m < 4; ++m) { const size_t off = (size_t)(row0 + ai * 128 + m * 16) * D + ch;
;                     const u32x2 xw = *(const u32x2*)(XRC + off);
;                     const float xr[4] = {bflo(xw.x), bfhi(xw.x), bflo(xw.y), bfhi(xw.y)};
;                     f32x4 dv, bv;
; #pragma unroll
;                     for (int j = 0; j < 4; ++j) { float r, ig; sigmoid2(acc[ai][0][m][n][j] + br4[j], acc[ai][1][m][n][j] + bi4[j], r, ig);
;                         const float la = r * sp4[j]; float dd = neg_expm1_small(la); if (slow) dd = la > -0.25f ? dd : 1.0f - __expf(la);
;                         dv[j] = dd; bv[j] = __builtin_sqrtf(dd * (2.0f - dd)) * ig * xr[j]; }
;                     u32x2 dw, bw; dw.x = cvt_pk_bf16(dv[0], dv[1]); dw.y = cvt_pk_bf16(dv[2], dv[3]); bw.x = cvt_pk_bf16(bv[0], bv[1]); bw.y = cvt_pk_bf16(bv[2], bv[3]);
;                     *(u32x2*)(DD + off) = dw; *(u32x2*)(BB + off) = bw; asm volatile("" ::: "memory"); } }
	v_add_f32_e32 v62, v62, v70
	global_load_dwordx4 v[66:69], v[66:67], off
	s_waitcnt vmcnt(1)
	v_add_f32_e32 v58, v58, v74
	v_mul_f32_e32 v62, 0xbfb8aa3b, v62
	v_mul_f32_e32 v58, 0xbfb8aa3b, v58
	v_min_f32_e32 v62, 0x42700000, v62
	v_min_f32_e32 v58, 0x42700000, v58
	v_exp_f32_e32 v86, v62
	v_exp_f32_e32 v87, v58
	v_add_f32_e32 v59, v59, v75
	v_mul_f32_e32 v59, 0xbfb8aa3b, v59
	v_min_f32_e32 v59, 0x42700000, v59
	v_pk_add_f32 v[86:87], v[86:87], 1.0 op_sel_hi:[1,0]
	v_exp_f32_e32 v59, v59
	v_mul_f32_e32 v58, v86, v87
	v_rcp_f32_e32 v58, v58
	v_add_f32_e32 v54, v54, v70
	v_add_f32_e32 v50, v50, v74
	v_mul_f32_e32 v54, 0xbfb8aa3b, v54
	v_mul_f32_e32 v62, v87, v58
	v_mul_f32_e32 v58, v86, v58
	v_mul_f32_e32 v50, 0xbfb8aa3b, v50
	v_min_f32_e32 v54, 0x42700000, v54
	v_min_f32_e32 v50, 0x42700000, v50
	v_add_f32_e32 v51, v51, v75
	v_mul_f32_e32 v51, 0xbfb8aa3b, v51
	v_min_f32_e32 v51, 0x42700000, v51
	v_exp_f32_e32 v51, v51
	v_add_f32_e32 v46, v46, v70
	v_add_f32_e32 v42, v42, v74
	v_mul_f32_e32 v46, 0xbfb8aa3b, v46
	v_mul_f32_e32 v42, 0xbfb8aa3b, v42
	v_min_f32_e32 v46, 0x42700000, v46
	v_min_f32_e32 v42, 0x42700000, v42
	v_add_f32_e32 v43, v43, v75
	v_mul_f32_e32 v43, 0xbfb8aa3b, v43
	v_min_f32_e32 v43, 0x42700000, v43
	v_exp_f32_e32 v43, v43
	v_add_f32_e32 v38, v38, v70
	v_add_f32_e32 v34, v34, v74
	v_mul_f32_e32 v38, 0xbfb8aa3b, v38
	v_mul_f32_e32 v34, 0xbfb8aa3b, v34
	v_min_f32_e32 v38, 0x42700000, v38
	v_min_f32_e32 v34, 0x42700000, v34
	v_add_f32_e32 v35, v35, v75
	v_mul_f32_e32 v35, 0xbfb8aa3b, v35
	v_min_f32_e32 v35, 0x42700000, v35
	v_exp_f32_e32 v35, v35
	v_add_f32_e32 v30, v30, v70
	v_add_f32_e32 v26, v26, v74
	v_mul_f32_e32 v30, 0xbfb8aa3b, v30
	v_mul_f32_e32 v26, 0xbfb8aa3b, v26
	v_min_f32_e32 v30, 0x42700000, v30
	v_min_f32_e32 v26, 0x42700000, v26
	v_add_f32_e32 v27, v27, v75
	v_mul_f32_e32 v27, 0xbfb8aa3b, v27
	v_min_f32_e32 v27, 0x42700000, v27
	v_exp_f32_e32 v27, v27
	v_add_f32_e32 v22, v22, v70
	v_add_f32_e32 v18, v18, v74
	v_mul_f32_e32 v22, 0xbfb8aa3b, v22
	v_mul_f32_e32 v18, 0xbfb8aa3b, v18
	v_min_f32_e32 v22, 0x42700000, v22
	v_min_f32_e32 v18, 0x42700000, v18
	v_add_f32_e32 v19, v19, v75
	v_mul_f32_e32 v19, 0xbfb8aa3b, v19
	v_min_f32_e32 v19, 0x42700000, v19
	v_exp_f32_e32 v19, v19
	v_add_f32_e32 v14, v14, v70
	v_add_f32_e32 v10, v10, v74
	v_mul_f32_e32 v14, 0xbfb8aa3b, v14
	v_mul_f32_e32 v10, 0xbfb8aa3b, v10
	v_min_f32_e32 v14, 0x42700000, v14
	v_min_f32_e32 v10, 0x42700000, v10
	v_add_f32_e32 v11, v11, v75
	v_mul_f32_e32 v11, 0xbfb8aa3b, v11
	v_min_f32_e32 v11, 0x42700000, v11
	v_exp_f32_e32 v11, v11
	v_add_f32_e32 v6, v6, v70
	v_add_f32_e32 v2, v2, v74
	v_mul_f32_e32 v6, 0xbfb8aa3b, v6
	s_waitcnt vmcnt(0)
	v_max_f32_e32 v82, v69, v69
	v_max_f32_e32 v83, v68, v68
	v_min_f32_e32 v82, v83, v82
	v_min3_f32 v82, v66, v67, v82
	v_cmp_ge_f32_e32 vcc, s25, v82
	v_lshl_add_u64 v[82:83], v[176:177], 0, v[80:81]
	v_lshlrev_b64 v[82:83], 1, v[82:83]
	v_lshl_add_u64 v[84:85], s[0:1], 0, v[82:83]
	v_mul_f32_e32 v62, v66, v62
	s_cmp_eq_u64 vcc, 0
	v_cmp_lt_f32_e32 vcc, s25, v62
	s_cselect_b64 s[34:35], -1, 0
	s_or_b64 vcc, s[34:35], vcc
	v_mul_f32_e32 v2, 0xbfb8aa3b, v2
	v_min_f32_e32 v6, 0x42700000, v6
	v_min_f32_e32 v2, 0x42700000, v2
	v_add_f32_e32 v3, v3, v75
	v_mul_f32_e32 v3, 0xbfb8aa3b, v3
	v_min_f32_e32 v3, 0x42700000, v3
	v_add_f32_e32 v4, v4, v76
	v_add_f32_e32 v5, v5, v77
	v_mov_b64_e32 v[84:85], v[230:231]
	v_lshlrev_b32_e32 v88, 16, v84
	v_and_b32_e32 v89, 0xffff0000, v84
	v_lshlrev_b32_e32 v90, 16, v85
	v_and_b32_e32 v84, 0xffff0000, v85
	v_fmamk_f32 v85, v62, 0x3ab60b61, v196
	v_fmaak_f32 v85, v62, v85, 0x3d2aaaab
	v_fmaak_f32 v85, v62, v85, 0x3e2aaaab
	v_fma_f32 v85, v62, v85, 0.5
	v_fma_f32 v85, v62, v85, 1.0
	v_mul_f32_e64 v85, v85, -v62
	v_mul_f32_e32 v62, 0x3fb8aa3b, v62
	v_exp_f32_e32 v62, v62
	s_nop 0
	v_sub_f32_e32 v62, 1.0, v62
	v_cndmask_b32_e32 v62, v62, v85, vcc
	v_sub_f32_e32 v85, 2.0, v62
	v_mul_f32_e32 v85, v62, v85
	v_cmp_gt_f32_e32 vcc, s27, v85
	v_mul_f32_e32 v86, 0x4f800000, v85
	s_nop 0
	v_cndmask_b32_e32 v85, v85, v86, vcc
	v_sqrt_f32_e32 v86, v85
	s_nop 0
	v_add_u32_e32 v87, -1, v86
	v_fma_f32 v91, -v87, v86, v85
	v_cmp_ge_f32_e64 s[8:9], 0, v91
	v_add_u32_e32 v91, 1, v86
	s_nop 0
	v_cndmask_b32_e64 v87, v86, v87, s[8:9]
	v_fma_f32 v86, -v91, v86, v85
	v_cmp_lt_f32_e64 s[8:9], 0, v86
	s_nop 1
	v_cndmask_b32_e64 v86, v87, v91, s[8:9]
	v_mul_f32_e32 v87, 0x37800000, v86
	v_cndmask_b32_e32 v86, v86, v87, vcc
	v_cmp_class_f32_e32 vcc, v85, v197
	s_nop 1
	v_cndmask_b32_e32 v85, v86, v85, vcc
	v_mul_f32_e32 v58, v58, v85
	v_mul_f32_e32 v85, v58, v88
	v_add_f32_e32 v58, v63, v71
	v_mul_f32_e32 v58, 0xbfb8aa3b, v58
	v_min_f32_e32 v58, 0x42700000, v58
	v_exp_f32_e32 v58, v58
	s_nop 0
	v_pk_add_f32 v[58:59], v[58:59], 1.0 op_sel_hi:[1,0]
	s_nop 0
	v_mul_f32_e32 v63, v58, v59
	v_rcp_f32_e32 v63, v63
	s_nop 0
	v_mul_f32_e32 v59, v59, v63
	v_mul_f32_e32 v59, v67, v59
	v_mul_f32_e32 v58, v58, v63
	v_fmamk_f32 v63, v59, 0x3ab60b61, v196
	v_fmaak_f32 v63, v59, v63, 0x3d2aaaab
	v_fmaak_f32 v63, v59, v63, 0x3e2aaaab
	v_fma_f32 v63, v59, v63, 0.5
	v_fma_f32 v63, v59, v63, 1.0
	v_mul_f32_e64 v63, v63, -v59
	v_cmp_lt_f32_e32 vcc, s25, v59
	v_mul_f32_e32 v59, 0x3fb8aa3b, v59
	v_exp_f32_e32 v59, v59
	s_or_b64 vcc, s[34:35], vcc
	v_sub_f32_e32 v59, 1.0, v59
	v_cndmask_b32_e32 v63, v59, v63, vcc
	v_sub_f32_e32 v59, 2.0, v63
	v_mul_f32_e32 v59, v63, v59
	v_cmp_gt_f32_e32 vcc, s27, v59
	v_mul_f32_e32 v86, 0x4f800000, v59
	s_nop 0
	v_cndmask_b32_e32 v59, v59, v86, vcc
	v_sqrt_f32_e32 v86, v59
	s_nop 0
	v_add_u32_e32 v87, -1, v86
	v_fma_f32 v88, -v87, v86, v59
	v_cmp_ge_f32_e64 s[8:9], 0, v88
	v_add_u32_e32 v88, 1, v86
; __device__ __forceinline__ unsigned cvt_pk_bf16(float lo, float hi) { unsigned r; asm volatile("v_cvt_pk_bf16_f32 %0, %1, %2" : "=v"(r) : "v"(lo), "v"(hi)); return r; }
; __device__ __forceinline__ float bflo(unsigned w) { return __uint_as_float(w << 16); }
; __device__ __forceinline__ float bfhi(unsigned w) { return __uint_as_float(w & 0xffff0000u); }
; __device__ __forceinline__ float fsigmoid(float x) { return __builtin_amdgcn_rcpf(1.0f + __expf(-x)); }
; __device__ __forceinline__ void sigmoid2(float x0, float x1, float& s0, float& s1) {
;     const float d0 = 1.0f + __builtin_amdgcn_exp2f(fminf(x0 * -1.4426950408889634f, 60.f)), d1 = 1.0f + __builtin_amdgcn_exp2f(fminf(x1 * -1.4426950408889634f, 60.f));
;     const float rp = __builtin_amdgcn_rcpf(d0 * d1); s0 = rp * d1; s1 = rp * d0; }
; __device__ __forceinline__ f32x4 sigmoid4(f32x4 x) { float a, b, c, d; sigmoid2(x[0], x[1], a, b); sigmoid2(x[2], x[3], c, d); return (f32x4){a, b, c, d}; }
; __device__ __forceinline__ f32x4 gelu_tanh4(f32x4 v) { const f32x4 z = (v * v * 0.044715f + 1.0f) * v * 1.5957691216057308f; return v * sigmoid4(z); }
; __device__ __forceinline__ float fgelu_tanh(float v) { return v * fsigmoid(1.5957691216057308f * (v + 0.044715f * v * v * v)); }
; __device__ __forceinline__ float fsoftplus(float x) { return x > 20.f ? x : __logf(1.0f + __expf(x)); }
;     __device__ __forceinline__ void operator()(const f32x4 (&acc)[2][2][4][2], const Unit& u, int wr, int wc, int fr, int fq) const {
;     ...
;                     const u32x2 xw = *(const u32x2*)(XRC + off);
;                     const float xr[4] = {bflo(xw.x), bfhi(xw.x), bflo(xw.y), bfhi(xw.y)};
;                     f32x4 dv, bv;
; #pragma unroll
;                     for (int j = 0; j < 4; ++j) { float r, ig; sigmoid2(acc[ai][0][m][n][j] + br4[j], acc[ai][1][m][n][j] + bi4[j], r, ig);
;                         const float la = r * sp4[j]; float dd = neg_expm1_small(la); if (slow) dd = la > -0.25f ? dd : 1.0f - __expf(la);
;                         dv[j] = dd; bv[j] = __builtin_sqrtf(dd * (2.0f - dd)) * ig * xr[j]; }
;                     u32x2 dw, bw; dw.x = cvt_pk_bf16(dv[0], dv[1]); dw.y = cvt_pk_bf16(dv[2], dv[3]); bw.x = cvt_pk_bf16(bv[0], bv[1]); bw.y = cvt_pk_bf16(bv[2], bv[3]);
;                     *(u32x2*)(DD + off) = dw; *(u32x2*)(BB + off) = bw; asm volatile("" ::: "memory"); } }
	s_nop 0
	v_cndmask_b32_e64 v87, v86, v87, s[8:9]
	v_fma_f32 v86, -v88, v86, v59
	v_cmp_lt_f32_e64 s[8:9], 0, v86
	s_nop 1
	v_cndmask_b32_e64 v86, v87, v88, s[8:9]
	v_mul_f32_e32 v87, 0x37800000, v86
	v_cndmask_b32_e32 v86, v86, v87, vcc
	v_cmp_class_f32_e32 vcc, v59, v197
	s_nop 1
	v_cndmask_b32_e32 v59, v86, v59, vcc
	v_mul_f32_e32 v58, v58, v59
	v_mul_f32_e32 v86, v58, v89
	v_add_f32_e32 v58, v64, v72
	v_add_f32_e32 v59, v60, v76
	v_mul_f32_e32 v58, 0xbfb8aa3b, v58
	v_mul_f32_e32 v59, 0xbfb8aa3b, v59
	v_min_f32_e32 v58, 0x42700000, v58
	v_min_f32_e32 v59, 0x42700000, v59
	v_exp_f32_e32 v58, v58
	v_exp_f32_e32 v59, v59
	s_nop 0
	v_pk_add_f32 v[58:59], v[58:59], 1.0 op_sel_hi:[1,0]
	s_nop 0
	v_mul_f32_e32 v60, v58, v59
	v_rcp_f32_e32 v60, v60
	s_nop 0
	v_mul_f32_e32 v59, v59, v60
	v_mul_f32_e32 v59, v68, v59
	v_mul_f32_e32 v58, v58, v60
	v_fmamk_f32 v60, v59, 0x3ab60b61, v196
	v_fmaak_f32 v60, v59, v60, 0x3d2aaaab
	v_fmaak_f32 v60, v59, v60, 0x3e2aaaab
	v_fma_f32 v60, v59, v60, 0.5
	v_fma_f32 v60, v59, v60, 1.0
	v_mul_f32_e64 v60, v60, -v59
	v_cmp_lt_f32_e32 vcc, s25, v59
	v_mul_f32_e32 v59, 0x3fb8aa3b, v59
	v_exp_f32_e32 v59, v59
	s_or_b64 vcc, s[34:35], vcc
	v_sub_f32_e32 v59, 1.0, v59
	v_cndmask_b32_e32 v60, v59, v60, vcc
	v_sub_f32_e32 v59, 2.0, v60
	v_mul_f32_e32 v59, v60, v59
	v_cmp_gt_f32_e32 vcc, s27, v59
	v_mul_f32_e32 v64, 0x4f800000, v59
	s_nop 0
	v_cndmask_b32_e32 v59, v59, v64, vcc
	v_sqrt_f32_e32 v64, v59
	s_nop 0
	v_add_u32_e32 v87, -1, v64
	v_fma_f32 v88, -v87, v64, v59
	v_cmp_ge_f32_e64 s[8:9], 0, v88
	v_add_u32_e32 v88, 1, v64
	s_nop 0
	v_cndmask_b32_e64 v87, v64, v87, s[8:9]
	v_fma_f32 v64, -v88, v64, v59
	v_cmp_lt_f32_e64 s[8:9], 0, v64
	s_nop 1
	v_cndmask_b32_e64 v64, v87, v88, s[8:9]
	v_mul_f32_e32 v87, 0x37800000, v64
	v_cndmask_b32_e32 v64, v64, v87, vcc
	v_cmp_class_f32_e32 vcc, v59, v197
	s_nop 1
	v_cndmask_b32_e32 v59, v64, v59, vcc
	v_mul_f32_e32 v58, v58, v59
	v_mul_f32_e32 v64, v58, v90
	v_add_f32_e32 v58, v65, v73
	v_add_f32_e32 v59, v61, v77
	v_mul_f32_e32 v58, 0xbfb8aa3b, v58
	v_mul_f32_e32 v59, 0xbfb8aa3b, v59
	v_min_f32_e32 v58, 0x42700000, v58
	v_min_f32_e32 v59, 0x42700000, v59
	v_exp_f32_e32 v58, v58
	v_exp_f32_e32 v59, v59
	s_nop 0
	v_pk_add_f32 v[58:59], v[58:59], 1.0 op_sel_hi:[1,0]
	s_nop 0
	v_mul_f32_e32 v61, v58, v59
	v_rcp_f32_e32 v61, v61
	s_nop 0
	v_mul_f32_e32 v59, v59, v61
	v_mul_f32_e32 v59, v69, v59
	v_mul_f32_e32 v58, v58, v61
	v_fmamk_f32 v61, v59, 0x3ab60b61, v196
	v_fmaak_f32 v61, v59, v61, 0x3d2aaaab
	v_fmaak_f32 v61, v59, v61, 0x3e2aaaab
	v_fma_f32 v61, v59, v61, 0.5
	v_fma_f32 v61, v59, v61, 1.0
	v_mul_f32_e64 v61, v61, -v59
	v_cmp_lt_f32_e32 vcc, s25, v59
	v_mul_f32_e32 v59, 0x3fb8aa3b, v59
	v_exp_f32_e32 v59, v59
	s_or_b64 vcc, s[34:35], vcc
	v_sub_f32_e32 v59, 1.0, v59
	v_cndmask_b32_e32 v59, v59, v61, vcc
	v_sub_f32_e32 v61, 2.0, v59
	v_mul_f32_e32 v61, v59, v61
	v_cmp_gt_f32_e32 vcc, s27, v61
	v_mul_f32_e32 v65, 0x4f800000, v61
	s_nop 0
	v_cndmask_b32_e32 v61, v61, v65, vcc
	v_sqrt_f32_e32 v65, v61
	s_nop 0
	v_add_u32_e32 v87, -1, v65
	v_fma_f32 v88, -v87, v65, v61
	v_cmp_ge_f32_e64 s[8:9], 0, v88
	v_add_u32_e32 v88, 1, v65
	s_nop 0
	v_cndmask_b32_e64 v87, v65, v87, s[8:9]
	v_fma_f32 v65, -v88, v65, v61
	v_cmp_lt_f32_e64 s[8:9], 0, v65
	s_nop 1
	v_cndmask_b32_e64 v65, v87, v88, s[8:9]
	v_mul_f32_e32 v87, 0x37800000, v65
	v_cndmask_b32_e32 v65, v65, v87, vcc
	v_cmp_class_f32_e32 vcc, v61, v197
	s_nop 1
	v_cndmask_b32_e32 v61, v65, v61, vcc
	v_mul_f32_e32 v58, v58, v61
	v_mul_f32_e32 v61, v58, v84
	v_cvt_pk_bf16_f32 v58, v62, v63
	v_cvt_pk_bf16_f32 v59, v60, v59
	v_lshl_add_u64 v[62:63], s[16:17], 0, v[82:83]
	v_cvt_pk_bf16_f32 v60, v85, v86
	v_cvt_pk_bf16_f32 v61, v64, v61
	global_store_dwordx2 v[62:63], v[58:59], off
	v_lshl_add_u64 v[58:59], s[18:19], 0, v[82:83]
	global_store_dwordx2 v[58:59], v[60:61], off
	v_lshl_add_u64 v[58:59], v[134:135], 0, v[80:81]
	v_lshlrev_b64 v[58:59], 1, v[58:59]
	v_lshl_add_u64 v[60:61], s[0:1], 0, v[58:59]
	v_exp_f32_e32 v62, v54
	v_exp_f32_e32 v63, v50
	v_mov_b64_e32 v[60:61], v[232:233]
	v_lshlrev_b32_e32 v64, 16, v60
	v_pk_add_f32 v[62:63], v[62:63], 1.0 op_sel_hi:[1,0]
	v_and_b32_e32 v65, 0xffff0000, v60
	v_mul_f32_e32 v50, v62, v63
	v_rcp_f32_e32 v50, v50
	v_lshlrev_b32_e32 v82, 16, v61
	v_and_b32_e32 v60, 0xffff0000, v61
	v_mul_f32_e32 v54, v63, v50
	v_mul_f32_e32 v54, v66, v54
	v_fmamk_f32 v61, v54, 0x3ab60b61, v196
	v_fmaak_f32 v61, v54, v61, 0x3d2aaaab
	v_fmaak_f32 v61, v54, v61, 0x3e2aaaab
	v_fma_f32 v61, v54, v61, 0.5
	v_fma_f32 v61, v54, v61, 1.0
	v_mul_f32_e64 v61, v61, -v54
	v_cmp_lt_f32_e32 vcc, s25, v54
	v_mul_f32_e32 v54, 0x3fb8aa3b, v54
	v_exp_f32_e32 v54, v54
	s_or_b64 vcc, s[34:35], vcc
	v_mul_f32_e32 v50, v62, v50
	v_sub_f32_e32 v54, 1.0, v54
	v_cndmask_b32_e32 v54, v54, v61, vcc
	v_sub_f32_e32 v61, 2.0, v54
	v_mul_f32_e32 v61, v54, v61
	v_cmp_gt_f32_e32 vcc, s27, v61
	v_mul_f32_e32 v62, 0x4f800000, v61
	s_nop 0
	v_cndmask_b32_e32 v61, v61, v62, vcc
	v_sqrt_f32_e32 v62, v61
	s_nop 0
	v_add_u32_e32 v63, -1, v62
	v_fma_f32 v83, -v63, v62, v61
	v_cmp_ge_f32_e64 s[8:9], 0, v83
	v_add_u32_e32 v83, 1, v62
	s_nop 0
	v_cndmask_b32_e64 v63, v62, v63, s[8:9]
	v_fma_f32 v62, -v83, v62, v61
	v_cmp_lt_f32_e64 s[8:9], 0, v62
	s_nop 1
	v_cndmask_b32_e64 v62, v63, v83, s[8:9]
	v_mul_f32_e32 v63, 0x37800000, v62
	v_cndmask_b32_e32 v62, v62, v63, vcc
	v_cmp_class_f32_e32 vcc, v61, v197
	s_nop 1
	v_cndmask_b32_e32 v61, v62, v61, vcc
	v_mul_f32_e32 v50, v50, v61
	v_mul_f32_e32 v61, v50, v64
	v_add_f32_e32 v50, v55, v71
	v_mul_f32_e32 v50, 0xbfb8aa3b, v50
	v_min_f32_e32 v50, 0x42700000, v50
	v_exp_f32_e32 v50, v50
	s_nop 0
; __device__ __forceinline__ unsigned cvt_pk_bf16(float lo, float hi) { unsigned r; asm volatile("v_cvt_pk_bf16_f32 %0, %1, %2" : "=v"(r) : "v"(lo), "v"(hi)); return r; }
; __device__ __forceinline__ float bflo(unsigned w) { return __uint_as_float(w << 16); }
; __device__ __forceinline__ float bfhi(unsigned w) { return __uint_as_float(w & 0xffff0000u); }
; __device__ __forceinline__ float fsigmoid(float x) { return __builtin_amdgcn_rcpf(1.0f + __expf(-x)); }
; __device__ __forceinline__ void sigmoid2(float x0, float x1, float& s0, float& s1) {
;     const float d0 = 1.0f + __builtin_amdgcn_exp2f(fminf(x0 * -1.4426950408889634f, 60.f)), d1 = 1.0f + __builtin_amdgcn_exp2f(fminf(x1 * -1.4426950408889634f, 60.f));
;     const float rp = __builtin_amdgcn_rcpf(d0 * d1); s0 = rp * d1; s1 = rp * d0; }
; __device__ __forceinline__ f32x4 sigmoid4(f32x4 x) { float a, b, c, d; sigmoid2(x[0], x[1], a, b); sigmoid2(x[2], x[3], c, d); return (f32x4){a, b, c, d}; }
; __device__ __forceinline__ f32x4 gelu_tanh4(f32x4 v) { const f32x4 z = (v * v * 0.044715f + 1.0f) * v * 1.5957691216057308f; return v * sigmoid4(z); }
; __device__ __forceinline__ float fgelu_tanh(float v) { return v * fsigmoid(1.5957691216057308f * (v + 0.044715f * v * v * v)); }
; __device__ __forceinline__ float fsoftplus(float x) { return x > 20.f ? x : __logf(1.0f + __expf(x)); }
;     __device__ __forceinline__ void operator()(const f32x4 (&acc)[2][2][4][2], const Unit& u, int wr, int wc, int fr, int fq) const {
;     ...
;                     const u32x2 xw = *(const u32x2*)(XRC + off);
;                     const float xr[4] = {bflo(xw.x), bfhi(xw.x), bflo(xw.y), bfhi(xw.y)};
;                     f32x4 dv, bv;
; #pragma unroll
;                     for (int j = 0; j < 4; ++j) { float r, ig; sigmoid2(acc[ai][0][m][n][j] + br4[j], acc[ai][1][m][n][j] + bi4[j], r, ig);
;                         const float la = r * sp4[j]; float dd = neg_expm1_small(la); if (slow) dd = la > -0.25f ? dd : 1.0f - __expf(la);
;                         dv[j] = dd; bv[j] = __builtin_sqrtf(dd * (2.0f - dd)) * ig * xr[j]; }
;                     u32x2 dw, bw; dw.x = cvt_pk_bf16(dv[0], dv[1]); dw.y = cvt_pk_bf16(dv[2], dv[3]); bw.x = cvt_pk_bf16(bv[0], bv[1]); bw.y = cvt_pk_bf16(bv[2], bv[3]);
;                     *(u32x2*)(DD + off) = dw; *(u32x2*)(BB + off) = bw; asm volatile("" ::: "memory"); } }
	v_pk_add_f32 v[50:51], v[50:51], 1.0 op_sel_hi:[1,0]
	s_nop 0
	v_mul_f32_e32 v55, v50, v51
	v_rcp_f32_e32 v55, v55
	s_nop 0
	v_mul_f32_e32 v51, v51, v55
	v_mul_f32_e32 v51, v67, v51
	v_mul_f32_e32 v50, v50, v55
	v_fmamk_f32 v55, v51, 0x3ab60b61, v196
	v_fmaak_f32 v55, v51, v55, 0x3d2aaaab
	v_fmaak_f32 v55, v51, v55, 0x3e2aaaab
	v_fma_f32 v55, v51, v55, 0.5
	v_fma_f32 v55, v51, v55, 1.0
	v_mul_f32_e64 v55, v55, -v51
	v_cmp_lt_f32_e32 vcc, s25, v51
	v_mul_f32_e32 v51, 0x3fb8aa3b, v51
	v_exp_f32_e32 v51, v51
	s_or_b64 vcc, s[34:35], vcc
	v_sub_f32_e32 v51, 1.0, v51
	v_cndmask_b32_e32 v55, v51, v55, vcc
	v_sub_f32_e32 v51, 2.0, v55
	v_mul_f32_e32 v51, v55, v51
	v_cmp_gt_f32_e32 vcc, s27, v51
	v_mul_f32_e32 v62, 0x4f800000, v51
	s_nop 0
	v_cndmask_b32_e32 v51, v51, v62, vcc
	v_sqrt_f32_e32 v62, v51
	s_nop 0
	v_add_u32_e32 v63, -1, v62
	v_fma_f32 v64, -v63, v62, v51
	v_cmp_ge_f32_e64 s[8:9], 0, v64
	v_add_u32_e32 v64, 1, v62
	s_nop 0
	v_cndmask_b32_e64 v63, v62, v63, s[8:9]
	v_fma_f32 v62, -v64, v62, v51
	v_cmp_lt_f32_e64 s[8:9], 0, v62
	s_nop 1
	v_cndmask_b32_e64 v62, v63, v64, s[8:9]
	v_mul_f32_e32 v63, 0x37800000, v62
	v_cndmask_b32_e32 v62, v62, v63, vcc
	v_cmp_class_f32_e32 vcc, v51, v197
	s_nop 1
	v_cndmask_b32_e32 v51, v62, v51, vcc
	v_mul_f32_e32 v50, v50, v51
	v_mul_f32_e32 v62, v50, v65
	v_add_f32_e32 v50, v56, v72
	v_add_f32_e32 v51, v52, v76
	v_mul_f32_e32 v50, 0xbfb8aa3b, v50
	v_mul_f32_e32 v51, 0xbfb8aa3b, v51
	v_min_f32_e32 v50, 0x42700000, v50
	v_min_f32_e32 v51, 0x42700000, v51
	v_exp_f32_e32 v50, v50
	v_exp_f32_e32 v51, v51
	s_nop 0
	v_pk_add_f32 v[50:51], v[50:51], 1.0 op_sel_hi:[1,0]
	s_nop 0
	v_mul_f32_e32 v52, v50, v51
	v_rcp_f32_e32 v52, v52
	s_nop 0
	v_mul_f32_e32 v51, v51, v52
	v_mul_f32_e32 v51, v68, v51
	v_mul_f32_e32 v50, v50, v52
	v_fmamk_f32 v52, v51, 0x3ab60b61, v196
	v_fmaak_f32 v52, v51, v52, 0x3d2aaaab
	v_fmaak_f32 v52, v51, v52, 0x3e2aaaab
	v_fma_f32 v52, v51, v52, 0.5
	v_fma_f32 v52, v51, v52, 1.0
	v_mul_f32_e64 v52, v52, -v51
	v_cmp_lt_f32_e32 vcc, s25, v51
	v_mul_f32_e32 v51, 0x3fb8aa3b, v51
	v_exp_f32_e32 v51, v51
	s_or_b64 vcc, s[34:35], vcc
	v_sub_f32_e32 v51, 1.0, v51
	v_cndmask_b32_e32 v52, v51, v52, vcc
	v_sub_f32_e32 v51, 2.0, v52
	v_mul_f32_e32 v51, v52, v51
	v_cmp_gt_f32_e32 vcc, s27, v51
	v_mul_f32_e32 v56, 0x4f800000, v51
	s_nop 0
	v_cndmask_b32_e32 v51, v51, v56, vcc
	v_sqrt_f32_e32 v56, v51
	s_nop 0
	v_add_u32_e32 v63, -1, v56
	v_fma_f32 v64, -v63, v56, v51
	v_cmp_ge_f32_e64 s[8:9], 0, v64
	v_add_u32_e32 v64, 1, v56
	s_nop 0
	v_cndmask_b32_e64 v63, v56, v63, s[8:9]
	v_fma_f32 v56, -v64, v56, v51
	v_cmp_lt_f32_e64 s[8:9], 0, v56
	s_nop 1
	v_cndmask_b32_e64 v56, v63, v64, s[8:9]
	v_mul_f32_e32 v63, 0x37800000, v56
	v_cndmask_b32_e32 v56, v56, v63, vcc
	v_cmp_class_f32_e32 vcc, v51, v197
	s_nop 1
	v_cndmask_b32_e32 v51, v56, v51, vcc
	v_mul_f32_e32 v50, v50, v51
	v_mul_f32_e32 v56, v50, v82
	v_add_f32_e32 v50, v57, v73
	v_add_f32_e32 v51, v53, v77
	v_mul_f32_e32 v50, 0xbfb8aa3b, v50
	v_mul_f32_e32 v51, 0xbfb8aa3b, v51
	v_min_f32_e32 v50, 0x42700000, v50
	v_min_f32_e32 v51, 0x42700000, v51
	v_exp_f32_e32 v50, v50
	v_exp_f32_e32 v51, v51
	s_nop 0
	v_pk_add_f32 v[50:51], v[50:51], 1.0 op_sel_hi:[1,0]
	s_nop 0
	v_mul_f32_e32 v53, v50, v51
	v_rcp_f32_e32 v53, v53
	s_nop 0
	v_mul_f32_e32 v51, v51, v53
	v_mul_f32_e32 v51, v69, v51
	v_mul_f32_e32 v50, v50, v53
	v_fmamk_f32 v53, v51, 0x3ab60b61, v196
	v_fmaak_f32 v53, v51, v53, 0x3d2aaaab
	v_fmaak_f32 v53, v51, v53, 0x3e2aaaab
	v_fma_f32 v53, v51, v53, 0.5
	v_fma_f32 v53, v51, v53, 1.0
	v_mul_f32_e64 v53, v53, -v51
	v_cmp_lt_f32_e32 vcc, s25, v51
	v_mul_f32_e32 v51, 0x3fb8aa3b, v51
	v_exp_f32_e32 v51, v51
	s_or_b64 vcc, s[34:35], vcc
	v_sub_f32_e32 v51, 1.0, v51
	v_cndmask_b32_e32 v51, v51, v53, vcc
	v_sub_f32_e32 v53, 2.0, v51
	v_mul_f32_e32 v53, v51, v53
	v_cmp_gt_f32_e32 vcc, s27, v53
	v_mul_f32_e32 v57, 0x4f800000, v53
	s_nop 0
	v_cndmask_b32_e32 v53, v53, v57, vcc
	v_sqrt_f32_e32 v57, v53
	s_nop 0
	v_add_u32_e32 v63, -1, v57
	v_fma_f32 v64, -v63, v57, v53
	v_cmp_ge_f32_e64 s[8:9], 0, v64
	v_add_u32_e32 v64, 1, v57
	s_nop 0
	v_cndmask_b32_e64 v63, v57, v63, s[8:9]
	v_fma_f32 v57, -v64, v57, v53
	v_cmp_lt_f32_e64 s[8:9], 0, v57
	s_nop 1
	v_cndmask_b32_e64 v57, v63, v64, s[8:9]
	v_mul_f32_e32 v63, 0x37800000, v57
	v_cndmask_b32_e32 v57, v57, v63, vcc
	v_cmp_class_f32_e32 vcc, v53, v197
	s_nop 1
	v_cndmask_b32_e32 v53, v57, v53, vcc
	v_mul_f32_e32 v50, v50, v53
	v_mul_f32_e32 v53, v50, v60
	v_cvt_pk_bf16_f32 v50, v54, v55
	v_cvt_pk_bf16_f32 v51, v52, v51
	v_lshl_add_u64 v[54:55], s[16:17], 0, v[58:59]
	v_cvt_pk_bf16_f32 v52, v61, v62
	v_cvt_pk_bf16_f32 v53, v56, v53
	global_store_dwordx2 v[54:55], v[50:51], off
	v_lshl_add_u64 v[50:51], s[18:19], 0, v[58:59]
	global_store_dwordx2 v[50:51], v[52:53], off
	v_lshl_add_u64 v[50:51], v[126:127], 0, v[80:81]
	v_lshlrev_b64 v[50:51], 1, v[50:51]
	v_lshl_add_u64 v[52:53], s[0:1], 0, v[50:51]
	v_exp_f32_e32 v54, v46
	v_exp_f32_e32 v55, v42
	v_mov_b64_e32 v[52:53], v[234:235]
	v_lshlrev_b32_e32 v56, 16, v52
	v_pk_add_f32 v[54:55], v[54:55], 1.0 op_sel_hi:[1,0]
	v_and_b32_e32 v57, 0xffff0000, v52
	v_mul_f32_e32 v42, v54, v55
	v_rcp_f32_e32 v42, v42
	v_lshlrev_b32_e32 v58, 16, v53
	v_and_b32_e32 v52, 0xffff0000, v53
	v_mul_f32_e32 v46, v55, v42
	v_mul_f32_e32 v46, v66, v46
	v_fmamk_f32 v53, v46, 0x3ab60b61, v196
	v_fmaak_f32 v53, v46, v53, 0x3d2aaaab
	v_fmaak_f32 v53, v46, v53, 0x3e2aaaab
	v_fma_f32 v53, v46, v53, 0.5
	v_fma_f32 v53, v46, v53, 1.0
	v_mul_f32_e64 v53, v53, -v46
	v_cmp_lt_f32_e32 vcc, s25, v46
	v_mul_f32_e32 v46, 0x3fb8aa3b, v46
	v_exp_f32_e32 v46, v46
	s_or_b64 vcc, s[34:35], vcc
	v_mul_f32_e32 v42, v54, v42
; __device__ __forceinline__ unsigned cvt_pk_bf16(float lo, float hi) { unsigned r; asm volatile("v_cvt_pk_bf16_f32 %0, %1, %2" : "=v"(r) : "v"(lo), "v"(hi)); return r; }
; __device__ __forceinline__ float fsigmoid(float x) { return __builtin_amdgcn_rcpf(1.0f + __expf(-x)); }
; __device__ __forceinline__ void sigmoid2(float x0, float x1, float& s0, float& s1) {
;     const float d0 = 1.0f + __builtin_amdgcn_exp2f(fminf(x0 * -1.4426950408889634f, 60.f)), d1 = 1.0f + __builtin_amdgcn_exp2f(fminf(x1 * -1.4426950408889634f, 60.f));
;     const float rp = __builtin_amdgcn_rcpf(d0 * d1); s0 = rp * d1; s1 = rp * d0; }
; __device__ __forceinline__ f32x4 sigmoid4(f32x4 x) { float a, b, c, d; sigmoid2(x[0], x[1], a, b); sigmoid2(x[2], x[3], c, d); return (f32x4){a, b, c, d}; }
; __device__ __forceinline__ f32x4 gelu_tanh4(f32x4 v) { const f32x4 z = (v * v * 0.044715f + 1.0f) * v * 1.5957691216057308f; return v * sigmoid4(z); }
; __device__ __forceinline__ float fgelu_tanh(float v) { return v * fsigmoid(1.5957691216057308f * (v + 0.044715f * v * v * v)); }
; __device__ __forceinline__ float fsoftplus(float x) { return x > 20.f ? x : __logf(1.0f + __expf(x)); }
;     __device__ __forceinline__ void operator()(const f32x4 (&acc)[2][2][4][2], const Unit& u, int wr, int wc, int fr, int fq) const {
;     ...
;                     for (int j = 0; j < 4; ++j) { float r, ig; sigmoid2(acc[ai][0][m][n][j] + br4[j], acc[ai][1][m][n][j] + bi4[j], r, ig);
;                         const float la = r * sp4[j]; float dd = neg_expm1_small(la); if (slow) dd = la > -0.25f ? dd : 1.0f - __expf(la);
;                         dv[j] = dd; bv[j] = __builtin_sqrtf(dd * (2.0f - dd)) * ig * xr[j]; }
;                     u32x2 dw, bw; dw.x = cvt_pk_bf16(dv[0], dv[1]); dw.y = cvt_pk_bf16(dv[2], dv[3]); bw.x = cvt_pk_bf16(bv[0], bv[1]); bw.y = cvt_pk_bf16(bv[2], bv[3]);
;                     *(u32x2*)(DD + off) = dw; *(u32x2*)(BB + off) = bw; asm volatile("" ::: "memory"); } }
	v_sub_f32_e32 v46, 1.0, v46
	v_cndmask_b32_e32 v46, v46, v53, vcc
	v_sub_f32_e32 v53, 2.0, v46
	v_mul_f32_e32 v53, v46, v53
	v_cmp_gt_f32_e32 vcc, s27, v53
	v_mul_f32_e32 v54, 0x4f800000, v53
	s_nop 0
	v_cndmask_b32_e32 v53, v53, v54, vcc
	v_sqrt_f32_e32 v54, v53
	s_nop 0
	v_add_u32_e32 v55, -1, v54
	v_fma_f32 v59, -v55, v54, v53
	v_cmp_ge_f32_e64 s[8:9], 0, v59
	v_add_u32_e32 v59, 1, v54
	s_nop 0
	v_cndmask_b32_e64 v55, v54, v55, s[8:9]
	v_fma_f32 v54, -v59, v54, v53
	v_cmp_lt_f32_e64 s[8:9], 0, v54
	s_nop 1
	v_cndmask_b32_e64 v54, v55, v59, s[8:9]
	v_mul_f32_e32 v55, 0x37800000, v54
	v_cndmask_b32_e32 v54, v54, v55, vcc
	v_cmp_class_f32_e32 vcc, v53, v197
	s_nop 1
	v_cndmask_b32_e32 v53, v54, v53, vcc
	v_mul_f32_e32 v42, v42, v53
	v_mul_f32_e32 v53, v42, v56
	v_add_f32_e32 v42, v47, v71
	v_mul_f32_e32 v42, 0xbfb8aa3b, v42
	v_min_f32_e32 v42, 0x42700000, v42
	v_exp_f32_e32 v42, v42
	s_nop 0
	v_pk_add_f32 v[42:43], v[42:43], 1.0 op_sel_hi:[1,0]
	s_nop 0
	v_mul_f32_e32 v47, v42, v43
	v_rcp_f32_e32 v47, v47
	s_nop 0
	v_mul_f32_e32 v43, v43, v47
	v_mul_f32_e32 v43, v67, v43
	v_mul_f32_e32 v42, v42, v47
	v_fmamk_f32 v47, v43, 0x3ab60b61, v196
	v_fmaak_f32 v47, v43, v47, 0x3d2aaaab
	v_fmaak_f32 v47, v43, v47, 0x3e2aaaab
	v_fma_f32 v47, v43, v47, 0.5
	v_fma_f32 v47, v43, v47, 1.0
	v_mul_f32_e64 v47, v47, -v43
	v_cmp_lt_f32_e32 vcc, s25, v43
	v_mul_f32_e32 v43, 0x3fb8aa3b, v43
	v_exp_f32_e32 v43, v43
	s_or_b64 vcc, s[34:35], vcc
	v_sub_f32_e32 v43, 1.0, v43
	v_cndmask_b32_e32 v47, v43, v47, vcc
	v_sub_f32_e32 v43, 2.0, v47
	v_mul_f32_e32 v43, v47, v43
	v_cmp_gt_f32_e32 vcc, s27, v43
	v_mul_f32_e32 v54, 0x4f800000, v43
	s_nop 0
	v_cndmask_b32_e32 v43, v43, v54, vcc
	v_sqrt_f32_e32 v54, v43
	s_nop 0
	v_add_u32_e32 v55, -1, v54
	v_fma_f32 v56, -v55, v54, v43
	v_cmp_ge_f32_e64 s[8:9], 0, v56
	v_add_u32_e32 v56, 1, v54
	s_nop 0
	v_cndmask_b32_e64 v55, v54, v55, s[8:9]
	v_fma_f32 v54, -v56, v54, v43
	v_cmp_lt_f32_e64 s[8:9], 0, v54
	s_nop 1
	v_cndmask_b32_e64 v54, v55, v56, s[8:9]
	v_mul_f32_e32 v55, 0x37800000, v54
	v_cndmask_b32_e32 v54, v54, v55, vcc
	v_cmp_class_f32_e32 vcc, v43, v197
	s_nop 1
	v_cndmask_b32_e32 v43, v54, v43, vcc
	v_mul_f32_e32 v42, v42, v43
	v_mul_f32_e32 v54, v42, v57
	v_add_f32_e32 v42, v48, v72
	v_add_f32_e32 v43, v44, v76
	v_mul_f32_e32 v42, 0xbfb8aa3b, v42
	v_mul_f32_e32 v43, 0xbfb8aa3b, v43
	v_min_f32_e32 v42, 0x42700000, v42
	v_min_f32_e32 v43, 0x42700000, v43
	v_exp_f32_e32 v42, v42
	v_exp_f32_e32 v43, v43
	s_nop 0
	v_pk_add_f32 v[42:43], v[42:43], 1.0 op_sel_hi:[1,0]
	s_nop 0
	v_mul_f32_e32 v44, v42, v43
	v_rcp_f32_e32 v44, v44
	s_nop 0
	v_mul_f32_e32 v43, v43, v44
	v_mul_f32_e32 v43, v68, v43
	v_mul_f32_e32 v42, v42, v44
	v_fmamk_f32 v44, v43, 0x3ab60b61, v196
	v_fmaak_f32 v44, v43, v44, 0x3d2aaaab
	v_fmaak_f32 v44, v43, v44, 0x3e2aaaab
	v_fma_f32 v44, v43, v44, 0.5
	v_fma_f32 v44, v43, v44, 1.0
	v_mul_f32_e64 v44, v44, -v43
	v_cmp_lt_f32_e32 vcc, s25, v43
	v_mul_f32_e32 v43, 0x3fb8aa3b, v43
	v_exp_f32_e32 v43, v43
	s_or_b64 vcc, s[34:35], vcc
	v_sub_f32_e32 v43, 1.0, v43
	v_cndmask_b32_e32 v44, v43, v44, vcc
	v_sub_f32_e32 v43, 2.0, v44
	v_mul_f32_e32 v43, v44, v43
	v_cmp_gt_f32_e32 vcc, s27, v43
	v_mul_f32_e32 v48, 0x4f800000, v43
	s_nop 0
	v_cndmask_b32_e32 v43, v43, v48, vcc
	v_sqrt_f32_e32 v48, v43
	s_nop 0
	v_add_u32_e32 v55, -1, v48
	v_fma_f32 v56, -v55, v48, v43
	v_cmp_ge_f32_e64 s[8:9], 0, v56
	v_add_u32_e32 v56, 1, v48
	s_nop 0
	v_cndmask_b32_e64 v55, v48, v55, s[8:9]
	v_fma_f32 v48, -v56, v48, v43
	v_cmp_lt_f32_e64 s[8:9], 0, v48
	s_nop 1
	v_cndmask_b32_e64 v48, v55, v56, s[8:9]
	v_mul_f32_e32 v55, 0x37800000, v48
	v_cndmask_b32_e32 v48, v48, v55, vcc
	v_cmp_class_f32_e32 vcc, v43, v197
	s_nop 1
	v_cndmask_b32_e32 v43, v48, v43, vcc
	v_mul_f32_e32 v42, v42, v43
	v_mul_f32_e32 v48, v42, v58
	v_add_f32_e32 v42, v49, v73
	v_add_f32_e32 v43, v45, v77
	v_mul_f32_e32 v42, 0xbfb8aa3b, v42
	v_mul_f32_e32 v43, 0xbfb8aa3b, v43
	v_min_f32_e32 v42, 0x42700000, v42
	v_min_f32_e32 v43, 0x42700000, v43
	v_exp_f32_e32 v42, v42
	v_exp_f32_e32 v43, v43
	s_nop 0
	v_pk_add_f32 v[42:43], v[42:43], 1.0 op_sel_hi:[1,0]
	s_nop 0
	v_mul_f32_e32 v45, v42, v43
	v_rcp_f32_e32 v45, v45
	s_nop 0
	v_mul_f32_e32 v43, v43, v45
	v_mul_f32_e32 v43, v69, v43
	v_mul_f32_e32 v42, v42, v45
	v_fmamk_f32 v45, v43, 0x3ab60b61, v196
	v_fmaak_f32 v45, v43, v45, 0x3d2aaaab
	v_fmaak_f32 v45, v43, v45, 0x3e2aaaab
	v_fma_f32 v45, v43, v45, 0.5
	v_fma_f32 v45, v43, v45, 1.0
	v_mul_f32_e64 v45, v45, -v43
	v_cmp_lt_f32_e32 vcc, s25, v43
	v_mul_f32_e32 v43, 0x3fb8aa3b, v43
	v_exp_f32_e32 v43, v43
	s_or_b64 vcc, s[34:35], vcc
	v_sub_f32_e32 v43, 1.0, v43
	v_cndmask_b32_e32 v43, v43, v45, vcc
	v_sub_f32_e32 v45, 2.0, v43
	v_mul_f32_e32 v45, v43, v45
	v_cmp_gt_f32_e32 vcc, s27, v45
	v_mul_f32_e32 v49, 0x4f800000, v45
	s_nop 0
	v_cndmask_b32_e32 v45, v45, v49, vcc
	v_sqrt_f32_e32 v49, v45
	s_nop 0
	v_add_u32_e32 v55, -1, v49
	v_fma_f32 v56, -v55, v49, v45
	v_cmp_ge_f32_e64 s[8:9], 0, v56
	v_add_u32_e32 v56, 1, v49
	s_nop 0
	v_cndmask_b32_e64 v55, v49, v55, s[8:9]
	v_fma_f32 v49, -v56, v49, v45
	v_cmp_lt_f32_e64 s[8:9], 0, v49
	s_nop 1
	v_cndmask_b32_e64 v49, v55, v56, s[8:9]
	v_mul_f32_e32 v55, 0x37800000, v49
	v_cndmask_b32_e32 v49, v49, v55, vcc
	v_cmp_class_f32_e32 vcc, v45, v197
	s_nop 1
	v_cndmask_b32_e32 v45, v49, v45, vcc
	v_mul_f32_e32 v42, v42, v45
	v_mul_f32_e32 v45, v42, v52
	v_cvt_pk_bf16_f32 v42, v46, v47
	v_cvt_pk_bf16_f32 v43, v44, v43
	v_lshl_add_u64 v[46:47], s[16:17], 0, v[50:51]
	v_cvt_pk_bf16_f32 v44, v53, v54
	v_cvt_pk_bf16_f32 v45, v48, v45
	global_store_dwordx2 v[46:47], v[42:43], off
	v_lshl_add_u64 v[42:43], s[18:19], 0, v[50:51]
; __device__ __forceinline__ unsigned cvt_pk_bf16(float lo, float hi) { unsigned r; asm volatile("v_cvt_pk_bf16_f32 %0, %1, %2" : "=v"(r) : "v"(lo), "v"(hi)); return r; }
; __device__ __forceinline__ float bflo(unsigned w) { return __uint_as_float(w << 16); }
; __device__ __forceinline__ float bfhi(unsigned w) { return __uint_as_float(w & 0xffff0000u); }
; __device__ __forceinline__ float fsigmoid(float x) { return __builtin_amdgcn_rcpf(1.0f + __expf(-x)); }
; __device__ __forceinline__ void sigmoid2(float x0, float x1, float& s0, float& s1) {
;     const float d0 = 1.0f + __builtin_amdgcn_exp2f(fminf(x0 * -1.4426950408889634f, 60.f)), d1 = 1.0f + __builtin_amdgcn_exp2f(fminf(x1 * -1.4426950408889634f, 60.f));
;     const float rp = __builtin_amdgcn_rcpf(d0 * d1); s0 = rp * d1; s1 = rp * d0; }
; __device__ __forceinline__ f32x4 sigmoid4(f32x4 x) { float a, b, c, d; sigmoid2(x[0], x[1], a, b); sigmoid2(x[2], x[3], c, d); return (f32x4){a, b, c, d}; }
; __device__ __forceinline__ f32x4 gelu_tanh4(f32x4 v) { const f32x4 z = (v * v * 0.044715f + 1.0f) * v * 1.5957691216057308f; return v * sigmoid4(z); }
; __device__ __forceinline__ float fgelu_tanh(float v) { return v * fsigmoid(1.5957691216057308f * (v + 0.044715f * v * v * v)); }
; __device__ __forceinline__ float fsoftplus(float x) { return x > 20.f ? x : __logf(1.0f + __expf(x)); }
;     __device__ __forceinline__ void operator()(const f32x4 (&acc)[2][2][4][2], const Unit& u, int wr, int wc, int fr, int fq) const {
;     ...
;                     const u32x2 xw = *(const u32x2*)(XRC + off);
;                     const float xr[4] = {bflo(xw.x), bfhi(xw.x), bflo(xw.y), bfhi(xw.y)};
;                     f32x4 dv, bv;
; #pragma unroll
;                     for (int j = 0; j < 4; ++j) { float r, ig; sigmoid2(acc[ai][0][m][n][j] + br4[j], acc[ai][1][m][n][j] + bi4[j], r, ig);
;                         const float la = r * sp4[j]; float dd = neg_expm1_small(la); if (slow) dd = la > -0.25f ? dd : 1.0f - __expf(la);
;                         dv[j] = dd; bv[j] = __builtin_sqrtf(dd * (2.0f - dd)) * ig * xr[j]; }
;                     u32x2 dw, bw; dw.x = cvt_pk_bf16(dv[0], dv[1]); dw.y = cvt_pk_bf16(dv[2], dv[3]); bw.x = cvt_pk_bf16(bv[0], bv[1]); bw.y = cvt_pk_bf16(bv[2], bv[3]);
;                     *(u32x2*)(DD + off) = dw; *(u32x2*)(BB + off) = bw; asm volatile("" ::: "memory"); } }
	global_store_dwordx2 v[42:43], v[44:45], off
	v_lshl_add_u64 v[42:43], v[118:119], 0, v[80:81]
	v_lshlrev_b64 v[42:43], 1, v[42:43]
	v_lshl_add_u64 v[44:45], s[0:1], 0, v[42:43]
	v_exp_f32_e32 v46, v38
	v_exp_f32_e32 v47, v34
	v_mov_b64_e32 v[44:45], v[236:237]
	v_lshlrev_b32_e32 v48, 16, v44
	v_pk_add_f32 v[46:47], v[46:47], 1.0 op_sel_hi:[1,0]
	v_and_b32_e32 v49, 0xffff0000, v44
	v_mul_f32_e32 v34, v46, v47
	v_rcp_f32_e32 v34, v34
	v_lshlrev_b32_e32 v50, 16, v45
	v_and_b32_e32 v44, 0xffff0000, v45
	v_mul_f32_e32 v38, v47, v34
	v_mul_f32_e32 v38, v66, v38
	v_fmamk_f32 v45, v38, 0x3ab60b61, v196
	v_fmaak_f32 v45, v38, v45, 0x3d2aaaab
	v_fmaak_f32 v45, v38, v45, 0x3e2aaaab
	v_fma_f32 v45, v38, v45, 0.5
	v_fma_f32 v45, v38, v45, 1.0
	v_mul_f32_e64 v45, v45, -v38
	v_cmp_lt_f32_e32 vcc, s25, v38
	v_mul_f32_e32 v38, 0x3fb8aa3b, v38
	v_exp_f32_e32 v38, v38
	s_or_b64 vcc, s[34:35], vcc
	v_mul_f32_e32 v34, v46, v34
	v_sub_f32_e32 v38, 1.0, v38
	v_cndmask_b32_e32 v38, v38, v45, vcc
	v_sub_f32_e32 v45, 2.0, v38
	v_mul_f32_e32 v45, v38, v45
	v_cmp_gt_f32_e32 vcc, s27, v45
	v_mul_f32_e32 v46, 0x4f800000, v45
	s_nop 0
	v_cndmask_b32_e32 v45, v45, v46, vcc
	v_sqrt_f32_e32 v46, v45
	s_nop 0
	v_add_u32_e32 v47, -1, v46
	v_fma_f32 v51, -v47, v46, v45
	v_cmp_ge_f32_e64 s[8:9], 0, v51
	v_add_u32_e32 v51, 1, v46
	s_nop 0
	v_cndmask_b32_e64 v47, v46, v47, s[8:9]
	v_fma_f32 v46, -v51, v46, v45
	v_cmp_lt_f32_e64 s[8:9], 0, v46
	s_nop 1
	v_cndmask_b32_e64 v46, v47, v51, s[8:9]
	v_mul_f32_e32 v47, 0x37800000, v46
	v_cndmask_b32_e32 v46, v46, v47, vcc
	v_cmp_class_f32_e32 vcc, v45, v197
	s_nop 1
	v_cndmask_b32_e32 v45, v46, v45, vcc
	v_mul_f32_e32 v34, v34, v45
	v_mul_f32_e32 v45, v34, v48
	v_add_f32_e32 v34, v39, v71
	v_mul_f32_e32 v34, 0xbfb8aa3b, v34
	v_min_f32_e32 v34, 0x42700000, v34
	v_exp_f32_e32 v34, v34
	s_nop 0
	v_pk_add_f32 v[34:35], v[34:35], 1.0 op_sel_hi:[1,0]
	s_nop 0
	v_mul_f32_e32 v39, v34, v35
	v_rcp_f32_e32 v39, v39
	s_nop 0
	v_mul_f32_e32 v35, v35, v39
	v_mul_f32_e32 v35, v67, v35
	v_mul_f32_e32 v34, v34, v39
	v_fmamk_f32 v39, v35, 0x3ab60b61, v196
	v_fmaak_f32 v39, v35, v39, 0x3d2aaaab
	v_fmaak_f32 v39, v35, v39, 0x3e2aaaab
	v_fma_f32 v39, v35, v39, 0.5
	v_fma_f32 v39, v35, v39, 1.0
	v_mul_f32_e64 v39, v39, -v35
	v_cmp_lt_f32_e32 vcc, s25, v35
	v_mul_f32_e32 v35, 0x3fb8aa3b, v35
	v_exp_f32_e32 v35, v35
	s_or_b64 vcc, s[34:35], vcc
	v_sub_f32_e32 v35, 1.0, v35
	v_cndmask_b32_e32 v39, v35, v39, vcc
	v_sub_f32_e32 v35, 2.0, v39
	v_mul_f32_e32 v35, v39, v35
	v_cmp_gt_f32_e32 vcc, s27, v35
	v_mul_f32_e32 v46, 0x4f800000, v35
	s_nop 0
	v_cndmask_b32_e32 v35, v35, v46, vcc
	v_sqrt_f32_e32 v46, v35
	s_nop 0
	v_add_u32_e32 v47, -1, v46
	v_fma_f32 v48, -v47, v46, v35
	v_cmp_ge_f32_e64 s[8:9], 0, v48
	v_add_u32_e32 v48, 1, v46
	s_nop 0
	v_cndmask_b32_e64 v47, v46, v47, s[8:9]
	v_fma_f32 v46, -v48, v46, v35
	v_cmp_lt_f32_e64 s[8:9], 0, v46
	s_nop 1
	v_cndmask_b32_e64 v46, v47, v48, s[8:9]
	v_mul_f32_e32 v47, 0x37800000, v46
	v_cndmask_b32_e32 v46, v46, v47, vcc
	v_cmp_class_f32_e32 vcc, v35, v197
	s_nop 1
	v_cndmask_b32_e32 v35, v46, v35, vcc
	v_mul_f32_e32 v34, v34, v35
	v_mul_f32_e32 v46, v34, v49
	v_add_f32_e32 v34, v40, v72
	v_add_f32_e32 v35, v36, v76
	v_mul_f32_e32 v34, 0xbfb8aa3b, v34
	v_mul_f32_e32 v35, 0xbfb8aa3b, v35
	v_min_f32_e32 v34, 0x42700000, v34
	v_min_f32_e32 v35, 0x42700000, v35
	v_exp_f32_e32 v34, v34
	v_exp_f32_e32 v35, v35
	s_nop 0
	v_pk_add_f32 v[34:35], v[34:35], 1.0 op_sel_hi:[1,0]
	s_nop 0
	v_mul_f32_e32 v36, v34, v35
	v_rcp_f32_e32 v36, v36
	s_nop 0
	v_mul_f32_e32 v35, v35, v36
	v_mul_f32_e32 v35, v68, v35
	v_mul_f32_e32 v34, v34, v36
	v_fmamk_f32 v36, v35, 0x3ab60b61, v196
	v_fmaak_f32 v36, v35, v36, 0x3d2aaaab
	v_fmaak_f32 v36, v35, v36, 0x3e2aaaab
	v_fma_f32 v36, v35, v36, 0.5
	v_fma_f32 v36, v35, v36, 1.0
	v_mul_f32_e64 v36, v36, -v35
	v_cmp_lt_f32_e32 vcc, s25, v35
	v_mul_f32_e32 v35, 0x3fb8aa3b, v35
	v_exp_f32_e32 v35, v35
	s_or_b64 vcc, s[34:35], vcc
	v_sub_f32_e32 v35, 1.0, v35
	v_cndmask_b32_e32 v36, v35, v36, vcc
	v_sub_f32_e32 v35, 2.0, v36
	v_mul_f32_e32 v35, v36, v35
	v_cmp_gt_f32_e32 vcc, s27, v35
	v_mul_f32_e32 v40, 0x4f800000, v35
	s_nop 0
	v_cndmask_b32_e32 v35, v35, v40, vcc
	v_sqrt_f32_e32 v40, v35
	s_nop 0
	v_add_u32_e32 v47, -1, v40
	v_fma_f32 v48, -v47, v40, v35
	v_cmp_ge_f32_e64 s[8:9], 0, v48
	v_add_u32_e32 v48, 1, v40
	s_nop 0
	v_cndmask_b32_e64 v47, v40, v47, s[8:9]
	v_fma_f32 v40, -v48, v40, v35
	v_cmp_lt_f32_e64 s[8:9], 0, v40
	s_nop 1
	v_cndmask_b32_e64 v40, v47, v48, s[8:9]
	v_mul_f32_e32 v47, 0x37800000, v40
	v_cndmask_b32_e32 v40, v40, v47, vcc
	v_cmp_class_f32_e32 vcc, v35, v197
	s_nop 1
	v_cndmask_b32_e32 v35, v40, v35, vcc
	v_mul_f32_e32 v34, v34, v35
	v_mul_f32_e32 v40, v34, v50
	v_add_f32_e32 v34, v41, v73
	v_add_f32_e32 v35, v37, v77
	v_mul_f32_e32 v34, 0xbfb8aa3b, v34
	v_mul_f32_e32 v35, 0xbfb8aa3b, v35
	v_min_f32_e32 v34, 0x42700000, v34
	v_min_f32_e32 v35, 0x42700000, v35
	v_exp_f32_e32 v34, v34
	v_exp_f32_e32 v35, v35
	s_nop 0
	v_pk_add_f32 v[34:35], v[34:35], 1.0 op_sel_hi:[1,0]
	s_nop 0
	v_mul_f32_e32 v37, v34, v35
	v_rcp_f32_e32 v37, v37
	s_nop 0
	v_mul_f32_e32 v35, v35, v37
	v_mul_f32_e32 v35, v69, v35
	v_mul_f32_e32 v34, v34, v37
	v_fmamk_f32 v37, v35, 0x3ab60b61, v196
	v_fmaak_f32 v37, v35, v37, 0x3d2aaaab
	v_fmaak_f32 v37, v35, v37, 0x3e2aaaab
	v_fma_f32 v37, v35, v37, 0.5
	v_fma_f32 v37, v35, v37, 1.0
	v_mul_f32_e64 v37, v37, -v35
	v_cmp_lt_f32_e32 vcc, s25, v35
	v_mul_f32_e32 v35, 0x3fb8aa3b, v35
	v_exp_f32_e32 v35, v35
	s_or_b64 vcc, s[34:35], vcc
	v_sub_f32_e32 v35, 1.0, v35
	v_cndmask_b32_e32 v35, v35, v37, vcc
	v_sub_f32_e32 v37, 2.0, v35
	v_mul_f32_e32 v37, v35, v37
; __device__ __forceinline__ unsigned cvt_pk_bf16(float lo, float hi) { unsigned r; asm volatile("v_cvt_pk_bf16_f32 %0, %1, %2" : "=v"(r) : "v"(lo), "v"(hi)); return r; }
; __device__ __forceinline__ float bflo(unsigned w) { return __uint_as_float(w << 16); }
; __device__ __forceinline__ float bfhi(unsigned w) { return __uint_as_float(w & 0xffff0000u); }
; __device__ __forceinline__ float fsigmoid(float x) { return __builtin_amdgcn_rcpf(1.0f + __expf(-x)); }
; __device__ __forceinline__ void sigmoid2(float x0, float x1, float& s0, float& s1) {
;     const float d0 = 1.0f + __builtin_amdgcn_exp2f(fminf(x0 * -1.4426950408889634f, 60.f)), d1 = 1.0f + __builtin_amdgcn_exp2f(fminf(x1 * -1.4426950408889634f, 60.f));
;     const float rp = __builtin_amdgcn_rcpf(d0 * d1); s0 = rp * d1; s1 = rp * d0; }
; __device__ __forceinline__ f32x4 sigmoid4(f32x4 x) { float a, b, c, d; sigmoid2(x[0], x[1], a, b); sigmoid2(x[2], x[3], c, d); return (f32x4){a, b, c, d}; }
; __device__ __forceinline__ f32x4 gelu_tanh4(f32x4 v) { const f32x4 z = (v * v * 0.044715f + 1.0f) * v * 1.5957691216057308f; return v * sigmoid4(z); }
; __device__ __forceinline__ float fgelu_tanh(float v) { return v * fsigmoid(1.5957691216057308f * (v + 0.044715f * v * v * v)); }
; __device__ __forceinline__ float fsoftplus(float x) { return x > 20.f ? x : __logf(1.0f + __expf(x)); }
;     __device__ __forceinline__ void operator()(const f32x4 (&acc)[2][2][4][2], const Unit& u, int wr, int wc, int fr, int fq) const {
;     ...
;                     const u32x2 xw = *(const u32x2*)(XRC + off);
;                     const float xr[4] = {bflo(xw.x), bfhi(xw.x), bflo(xw.y), bfhi(xw.y)};
;                     f32x4 dv, bv;
; #pragma unroll
;                     for (int j = 0; j < 4; ++j) { float r, ig; sigmoid2(acc[ai][0][m][n][j] + br4[j], acc[ai][1][m][n][j] + bi4[j], r, ig);
;                         const float la = r * sp4[j]; float dd = neg_expm1_small(la); if (slow) dd = la > -0.25f ? dd : 1.0f - __expf(la);
;                         dv[j] = dd; bv[j] = __builtin_sqrtf(dd * (2.0f - dd)) * ig * xr[j]; }
;                     u32x2 dw, bw; dw.x = cvt_pk_bf16(dv[0], dv[1]); dw.y = cvt_pk_bf16(dv[2], dv[3]); bw.x = cvt_pk_bf16(bv[0], bv[1]); bw.y = cvt_pk_bf16(bv[2], bv[3]);
;                     *(u32x2*)(DD + off) = dw; *(u32x2*)(BB + off) = bw; asm volatile("" ::: "memory"); } }
	v_cmp_gt_f32_e32 vcc, s27, v37
	v_mul_f32_e32 v41, 0x4f800000, v37
	s_nop 0
	v_cndmask_b32_e32 v37, v37, v41, vcc
	v_sqrt_f32_e32 v41, v37
	s_nop 0
	v_add_u32_e32 v47, -1, v41
	v_fma_f32 v48, -v47, v41, v37
	v_cmp_ge_f32_e64 s[8:9], 0, v48
	v_add_u32_e32 v48, 1, v41
	s_nop 0
	v_cndmask_b32_e64 v47, v41, v47, s[8:9]
	v_fma_f32 v41, -v48, v41, v37
	v_cmp_lt_f32_e64 s[8:9], 0, v41
	s_nop 1
	v_cndmask_b32_e64 v41, v47, v48, s[8:9]
	v_mul_f32_e32 v47, 0x37800000, v41
	v_cndmask_b32_e32 v41, v41, v47, vcc
	v_cmp_class_f32_e32 vcc, v37, v197
	s_nop 1
	v_cndmask_b32_e32 v37, v41, v37, vcc
	v_mul_f32_e32 v34, v34, v37
	v_mul_f32_e32 v37, v34, v44
	v_cvt_pk_bf16_f32 v34, v38, v39
	v_cvt_pk_bf16_f32 v35, v36, v35
	v_lshl_add_u64 v[38:39], s[16:17], 0, v[42:43]
	v_cvt_pk_bf16_f32 v36, v45, v46
	v_cvt_pk_bf16_f32 v37, v40, v37
	global_store_dwordx2 v[38:39], v[34:35], off
	v_lshl_add_u64 v[34:35], s[18:19], 0, v[42:43]
	global_store_dwordx2 v[34:35], v[36:37], off
	v_lshl_add_u64 v[34:35], v[110:111], 0, v[80:81]
	v_lshlrev_b64 v[34:35], 1, v[34:35]
	v_lshl_add_u64 v[36:37], s[0:1], 0, v[34:35]
	v_exp_f32_e32 v38, v30
	v_exp_f32_e32 v39, v26
	v_mov_b64_e32 v[36:37], v[238:239]
	v_lshlrev_b32_e32 v40, 16, v36
	v_pk_add_f32 v[38:39], v[38:39], 1.0 op_sel_hi:[1,0]
	v_and_b32_e32 v41, 0xffff0000, v36
	v_mul_f32_e32 v26, v38, v39
	v_rcp_f32_e32 v26, v26
	v_lshlrev_b32_e32 v42, 16, v37
	v_and_b32_e32 v36, 0xffff0000, v37
	v_mul_f32_e32 v30, v39, v26
	v_mul_f32_e32 v30, v66, v30
	v_fmamk_f32 v37, v30, 0x3ab60b61, v196
	v_fmaak_f32 v37, v30, v37, 0x3d2aaaab
	v_fmaak_f32 v37, v30, v37, 0x3e2aaaab
	v_fma_f32 v37, v30, v37, 0.5
	v_fma_f32 v37, v30, v37, 1.0
	v_mul_f32_e64 v37, v37, -v30
	v_cmp_lt_f32_e32 vcc, s25, v30
	v_mul_f32_e32 v30, 0x3fb8aa3b, v30
	v_exp_f32_e32 v30, v30
	s_or_b64 vcc, s[34:35], vcc
	v_mul_f32_e32 v26, v38, v26
	v_sub_f32_e32 v30, 1.0, v30
	v_cndmask_b32_e32 v30, v30, v37, vcc
	v_sub_f32_e32 v37, 2.0, v30
	v_mul_f32_e32 v37, v30, v37
	v_cmp_gt_f32_e32 vcc, s27, v37
	v_mul_f32_e32 v38, 0x4f800000, v37
	s_nop 0
	v_cndmask_b32_e32 v37, v37, v38, vcc
	v_sqrt_f32_e32 v38, v37
	s_nop 0
	v_add_u32_e32 v39, -1, v38
	v_fma_f32 v43, -v39, v38, v37
	v_cmp_ge_f32_e64 s[8:9], 0, v43
	v_add_u32_e32 v43, 1, v38
	s_nop 0
	v_cndmask_b32_e64 v39, v38, v39, s[8:9]
	v_fma_f32 v38, -v43, v38, v37
	v_cmp_lt_f32_e64 s[8:9], 0, v38
	s_nop 1
	v_cndmask_b32_e64 v38, v39, v43, s[8:9]
	v_mul_f32_e32 v39, 0x37800000, v38
	v_cndmask_b32_e32 v38, v38, v39, vcc
	v_cmp_class_f32_e32 vcc, v37, v197
	s_nop 1
	v_cndmask_b32_e32 v37, v38, v37, vcc
	v_mul_f32_e32 v26, v26, v37
	v_mul_f32_e32 v37, v26, v40
	v_add_f32_e32 v26, v31, v71
	v_mul_f32_e32 v26, 0xbfb8aa3b, v26
	v_min_f32_e32 v26, 0x42700000, v26
	v_exp_f32_e32 v26, v26
	s_nop 0
	v_pk_add_f32 v[26:27], v[26:27], 1.0 op_sel_hi:[1,0]
	s_nop 0
	v_mul_f32_e32 v31, v26, v27
	v_rcp_f32_e32 v31, v31
	s_nop 0
	v_mul_f32_e32 v27, v27, v31
	v_mul_f32_e32 v27, v67, v27
	v_mul_f32_e32 v26, v26, v31
	v_fmamk_f32 v31, v27, 0x3ab60b61, v196
	v_fmaak_f32 v31, v27, v31, 0x3d2aaaab
	v_fmaak_f32 v31, v27, v31, 0x3e2aaaab
	v_fma_f32 v31, v27, v31, 0.5
	v_fma_f32 v31, v27, v31, 1.0
	v_mul_f32_e64 v31, v31, -v27
	v_cmp_lt_f32_e32 vcc, s25, v27
	v_mul_f32_e32 v27, 0x3fb8aa3b, v27
	v_exp_f32_e32 v27, v27
	s_or_b64 vcc, s[34:35], vcc
	v_sub_f32_e32 v27, 1.0, v27
	v_cndmask_b32_e32 v31, v27, v31, vcc
	v_sub_f32_e32 v27, 2.0, v31
	v_mul_f32_e32 v27, v31, v27
	v_cmp_gt_f32_e32 vcc, s27, v27
	v_mul_f32_e32 v38, 0x4f800000, v27
	s_nop 0
	v_cndmask_b32_e32 v27, v27, v38, vcc
	v_sqrt_f32_e32 v38, v27
	s_nop 0
	v_add_u32_e32 v39, -1, v38
	v_fma_f32 v40, -v39, v38, v27
	v_cmp_ge_f32_e64 s[8:9], 0, v40
	v_add_u32_e32 v40, 1, v38
	s_nop 0
	v_cndmask_b32_e64 v39, v38, v39, s[8:9]
	v_fma_f32 v38, -v40, v38, v27
	v_cmp_lt_f32_e64 s[8:9], 0, v38
	s_nop 1
	v_cndmask_b32_e64 v38, v39, v40, s[8:9]
	v_mul_f32_e32 v39, 0x37800000, v38
	v_cndmask_b32_e32 v38, v38, v39, vcc
	v_cmp_class_f32_e32 vcc, v27, v197
	s_nop 1
	v_cndmask_b32_e32 v27, v38, v27, vcc
	v_mul_f32_e32 v26, v26, v27
	v_mul_f32_e32 v38, v26, v41
	v_add_f32_e32 v26, v32, v72
	v_add_f32_e32 v27, v28, v76
	v_mul_f32_e32 v26, 0xbfb8aa3b, v26
	v_mul_f32_e32 v27, 0xbfb8aa3b, v27
	v_min_f32_e32 v26, 0x42700000, v26
	v_min_f32_e32 v27, 0x42700000, v27
	v_exp_f32_e32 v26, v26
	v_exp_f32_e32 v27, v27
	s_nop 0
	v_pk_add_f32 v[26:27], v[26:27], 1.0 op_sel_hi:[1,0]
	s_nop 0
	v_mul_f32_e32 v28, v26, v27
	v_rcp_f32_e32 v28, v28
	s_nop 0
	v_mul_f32_e32 v27, v27, v28
	v_mul_f32_e32 v27, v68, v27
	v_mul_f32_e32 v26, v26, v28
	v_fmamk_f32 v28, v27, 0x3ab60b61, v196
	v_fmaak_f32 v28, v27, v28, 0x3d2aaaab
	v_fmaak_f32 v28, v27, v28, 0x3e2aaaab
	v_fma_f32 v28, v27, v28, 0.5
	v_fma_f32 v28, v27, v28, 1.0
	v_mul_f32_e64 v28, v28, -v27
	v_cmp_lt_f32_e32 vcc, s25, v27
	v_mul_f32_e32 v27, 0x3fb8aa3b, v27
	v_exp_f32_e32 v27, v27
	s_or_b64 vcc, s[34:35], vcc
	v_sub_f32_e32 v27, 1.0, v27
	v_cndmask_b32_e32 v28, v27, v28, vcc
	v_sub_f32_e32 v27, 2.0, v28
	v_mul_f32_e32 v27, v28, v27
	v_cmp_gt_f32_e32 vcc, s27, v27
	v_mul_f32_e32 v32, 0x4f800000, v27
	s_nop 0
	v_cndmask_b32_e32 v27, v27, v32, vcc
	v_sqrt_f32_e32 v32, v27
	s_nop 0
	v_add_u32_e32 v39, -1, v32
	v_fma_f32 v40, -v39, v32, v27
	v_cmp_ge_f32_e64 s[8:9], 0, v40
	v_add_u32_e32 v40, 1, v32
	s_nop 0
	v_cndmask_b32_e64 v39, v32, v39, s[8:9]
	v_fma_f32 v32, -v40, v32, v27
	v_cmp_lt_f32_e64 s[8:9], 0, v32
	s_nop 1
	v_cndmask_b32_e64 v32, v39, v40, s[8:9]
	v_mul_f32_e32 v39, 0x37800000, v32
	v_cndmask_b32_e32 v32, v32, v39, vcc
	v_cmp_class_f32_e32 vcc, v27, v197
	s_nop 1
	v_cndmask_b32_e32 v27, v32, v27, vcc
	v_mul_f32_e32 v26, v26, v27
	v_mul_f32_e32 v32, v26, v42
; __device__ __forceinline__ unsigned cvt_pk_bf16(float lo, float hi) { unsigned r; asm volatile("v_cvt_pk_bf16_f32 %0, %1, %2" : "=v"(r) : "v"(lo), "v"(hi)); return r; }
; __device__ __forceinline__ float bflo(unsigned w) { return __uint_as_float(w << 16); }
; __device__ __forceinline__ float bfhi(unsigned w) { return __uint_as_float(w & 0xffff0000u); }
; __device__ __forceinline__ float fsigmoid(float x) { return __builtin_amdgcn_rcpf(1.0f + __expf(-x)); }
; __device__ __forceinline__ void sigmoid2(float x0, float x1, float& s0, float& s1) {
;     const float d0 = 1.0f + __builtin_amdgcn_exp2f(fminf(x0 * -1.4426950408889634f, 60.f)), d1 = 1.0f + __builtin_amdgcn_exp2f(fminf(x1 * -1.4426950408889634f, 60.f));
;     const float rp = __builtin_amdgcn_rcpf(d0 * d1); s0 = rp * d1; s1 = rp * d0; }
; __device__ __forceinline__ f32x4 sigmoid4(f32x4 x) { float a, b, c, d; sigmoid2(x[0], x[1], a, b); sigmoid2(x[2], x[3], c, d); return (f32x4){a, b, c, d}; }
; __device__ __forceinline__ f32x4 gelu_tanh4(f32x4 v) { const f32x4 z = (v * v * 0.044715f + 1.0f) * v * 1.5957691216057308f; return v * sigmoid4(z); }
; __device__ __forceinline__ float fgelu_tanh(float v) { return v * fsigmoid(1.5957691216057308f * (v + 0.044715f * v * v * v)); }
; __device__ __forceinline__ float fsoftplus(float x) { return x > 20.f ? x : __logf(1.0f + __expf(x)); }
;     __device__ __forceinline__ void operator()(const f32x4 (&acc)[2][2][4][2], const Unit& u, int wr, int wc, int fr, int fq) const {
;     ...
;                     const u32x2 xw = *(const u32x2*)(XRC + off);
;                     const float xr[4] = {bflo(xw.x), bfhi(xw.x), bflo(xw.y), bfhi(xw.y)};
;                     f32x4 dv, bv;
; #pragma unroll
;                     for (int j = 0; j < 4; ++j) { float r, ig; sigmoid2(acc[ai][0][m][n][j] + br4[j], acc[ai][1][m][n][j] + bi4[j], r, ig);
;                         const float la = r * sp4[j]; float dd = neg_expm1_small(la); if (slow) dd = la > -0.25f ? dd : 1.0f - __expf(la);
;                         dv[j] = dd; bv[j] = __builtin_sqrtf(dd * (2.0f - dd)) * ig * xr[j]; }
;                     u32x2 dw, bw; dw.x = cvt_pk_bf16(dv[0], dv[1]); dw.y = cvt_pk_bf16(dv[2], dv[3]); bw.x = cvt_pk_bf16(bv[0], bv[1]); bw.y = cvt_pk_bf16(bv[2], bv[3]);
;                     *(u32x2*)(DD + off) = dw; *(u32x2*)(BB + off) = bw; asm volatile("" ::: "memory"); } }
	v_add_f32_e32 v26, v33, v73
	v_add_f32_e32 v27, v29, v77
	v_mul_f32_e32 v26, 0xbfb8aa3b, v26
	v_mul_f32_e32 v27, 0xbfb8aa3b, v27
	v_min_f32_e32 v26, 0x42700000, v26
	v_min_f32_e32 v27, 0x42700000, v27
	v_exp_f32_e32 v26, v26
	v_exp_f32_e32 v27, v27
	s_nop 0
	v_pk_add_f32 v[26:27], v[26:27], 1.0 op_sel_hi:[1,0]
	s_nop 0
	v_mul_f32_e32 v29, v26, v27
	v_rcp_f32_e32 v29, v29
	s_nop 0
	v_mul_f32_e32 v27, v27, v29
	v_mul_f32_e32 v27, v69, v27
	v_mul_f32_e32 v26, v26, v29
	v_fmamk_f32 v29, v27, 0x3ab60b61, v196
	v_fmaak_f32 v29, v27, v29, 0x3d2aaaab
	v_fmaak_f32 v29, v27, v29, 0x3e2aaaab
	v_fma_f32 v29, v27, v29, 0.5
	v_fma_f32 v29, v27, v29, 1.0
	v_mul_f32_e64 v29, v29, -v27
	v_cmp_lt_f32_e32 vcc, s25, v27
	v_mul_f32_e32 v27, 0x3fb8aa3b, v27
	v_exp_f32_e32 v27, v27
	s_or_b64 vcc, s[34:35], vcc
	v_sub_f32_e32 v27, 1.0, v27
	v_cndmask_b32_e32 v27, v27, v29, vcc
	v_sub_f32_e32 v29, 2.0, v27
	v_mul_f32_e32 v29, v27, v29
	v_cmp_gt_f32_e32 vcc, s27, v29
	v_mul_f32_e32 v33, 0x4f800000, v29
	s_nop 0
	v_cndmask_b32_e32 v29, v29, v33, vcc
	v_sqrt_f32_e32 v33, v29
	s_nop 0
	v_add_u32_e32 v39, -1, v33
	v_fma_f32 v40, -v39, v33, v29
	v_cmp_ge_f32_e64 s[8:9], 0, v40
	v_add_u32_e32 v40, 1, v33
	s_nop 0
	v_cndmask_b32_e64 v39, v33, v39, s[8:9]
	v_fma_f32 v33, -v40, v33, v29
	v_cmp_lt_f32_e64 s[8:9], 0, v33
	s_nop 1
	v_cndmask_b32_e64 v33, v39, v40, s[8:9]
	v_mul_f32_e32 v39, 0x37800000, v33
	v_cndmask_b32_e32 v33, v33, v39, vcc
	v_cmp_class_f32_e32 vcc, v29, v197
	s_nop 1
	v_cndmask_b32_e32 v29, v33, v29, vcc
	v_mul_f32_e32 v26, v26, v29
	v_mul_f32_e32 v29, v26, v36
	v_cvt_pk_bf16_f32 v26, v30, v31
	v_cvt_pk_bf16_f32 v27, v28, v27
	v_lshl_add_u64 v[30:31], s[16:17], 0, v[34:35]
	v_cvt_pk_bf16_f32 v28, v37, v38
	v_cvt_pk_bf16_f32 v29, v32, v29
	global_store_dwordx2 v[30:31], v[26:27], off
	v_lshl_add_u64 v[26:27], s[18:19], 0, v[34:35]
	global_store_dwordx2 v[26:27], v[28:29], off
	v_lshl_add_u64 v[26:27], v[102:103], 0, v[80:81]
	v_lshlrev_b64 v[26:27], 1, v[26:27]
	v_lshl_add_u64 v[28:29], s[0:1], 0, v[26:27]
	v_exp_f32_e32 v30, v22
	v_exp_f32_e32 v31, v18
	v_mov_b64_e32 v[28:29], v[240:241]
	v_lshlrev_b32_e32 v32, 16, v28
	v_pk_add_f32 v[30:31], v[30:31], 1.0 op_sel_hi:[1,0]
	v_and_b32_e32 v33, 0xffff0000, v28
	v_mul_f32_e32 v18, v30, v31
	v_rcp_f32_e32 v18, v18
	v_lshlrev_b32_e32 v34, 16, v29
	v_and_b32_e32 v28, 0xffff0000, v29
	v_mul_f32_e32 v22, v31, v18
	v_mul_f32_e32 v22, v66, v22
	v_fmamk_f32 v29, v22, 0x3ab60b61, v196
	v_fmaak_f32 v29, v22, v29, 0x3d2aaaab
	v_fmaak_f32 v29, v22, v29, 0x3e2aaaab
	v_fma_f32 v29, v22, v29, 0.5
	v_fma_f32 v29, v22, v29, 1.0
	v_mul_f32_e64 v29, v29, -v22
	v_cmp_lt_f32_e32 vcc, s25, v22
	v_mul_f32_e32 v22, 0x3fb8aa3b, v22
	v_exp_f32_e32 v22, v22
	s_or_b64 vcc, s[34:35], vcc
	v_mul_f32_e32 v18, v30, v18
	v_sub_f32_e32 v22, 1.0, v22
	v_cndmask_b32_e32 v22, v22, v29, vcc
	v_sub_f32_e32 v29, 2.0, v22
	v_mul_f32_e32 v29, v22, v29
	v_cmp_gt_f32_e32 vcc, s27, v29
	v_mul_f32_e32 v30, 0x4f800000, v29
	s_nop 0
	v_cndmask_b32_e32 v29, v29, v30, vcc
	v_sqrt_f32_e32 v30, v29
	s_nop 0
	v_add_u32_e32 v31, -1, v30
	v_fma_f32 v35, -v31, v30, v29
	v_cmp_ge_f32_e64 s[8:9], 0, v35
	v_add_u32_e32 v35, 1, v30
	s_nop 0
	v_cndmask_b32_e64 v31, v30, v31, s[8:9]
	v_fma_f32 v30, -v35, v30, v29
	v_cmp_lt_f32_e64 s[8:9], 0, v30
	s_nop 1
	v_cndmask_b32_e64 v30, v31, v35, s[8:9]
	v_mul_f32_e32 v31, 0x37800000, v30
	v_cndmask_b32_e32 v30, v30, v31, vcc
	v_cmp_class_f32_e32 vcc, v29, v197
	s_nop 1
	v_cndmask_b32_e32 v29, v30, v29, vcc
	v_mul_f32_e32 v18, v18, v29
	v_mul_f32_e32 v29, v18, v32
	v_add_f32_e32 v18, v23, v71
	v_mul_f32_e32 v18, 0xbfb8aa3b, v18
	v_min_f32_e32 v18, 0x42700000, v18
	v_exp_f32_e32 v18, v18
	s_nop 0
	v_pk_add_f32 v[18:19], v[18:19], 1.0 op_sel_hi:[1,0]
	s_nop 0
	v_mul_f32_e32 v23, v18, v19
	v_rcp_f32_e32 v23, v23
	s_nop 0
	v_mul_f32_e32 v19, v19, v23
	v_mul_f32_e32 v19, v67, v19
	v_mul_f32_e32 v18, v18, v23
	v_fmamk_f32 v23, v19, 0x3ab60b61, v196
	v_fmaak_f32 v23, v19, v23, 0x3d2aaaab
	v_fmaak_f32 v23, v19, v23, 0x3e2aaaab
	v_fma_f32 v23, v19, v23, 0.5
	v_fma_f32 v23, v19, v23, 1.0
	v_mul_f32_e64 v23, v23, -v19
	v_cmp_lt_f32_e32 vcc, s25, v19
	v_mul_f32_e32 v19, 0x3fb8aa3b, v19
	v_exp_f32_e32 v19, v19
	s_or_b64 vcc, s[34:35], vcc
	v_sub_f32_e32 v19, 1.0, v19
	v_cndmask_b32_e32 v23, v19, v23, vcc
	v_sub_f32_e32 v19, 2.0, v23
	v_mul_f32_e32 v19, v23, v19
	v_cmp_gt_f32_e32 vcc, s27, v19
	v_mul_f32_e32 v30, 0x4f800000, v19
	s_nop 0
	v_cndmask_b32_e32 v19, v19, v30, vcc
	v_sqrt_f32_e32 v30, v19
	s_nop 0
	v_add_u32_e32 v31, -1, v30
	v_fma_f32 v32, -v31, v30, v19
	v_cmp_ge_f32_e64 s[8:9], 0, v32
	v_add_u32_e32 v32, 1, v30
	s_nop 0
	v_cndmask_b32_e64 v31, v30, v31, s[8:9]
	v_fma_f32 v30, -v32, v30, v19
	v_cmp_lt_f32_e64 s[8:9], 0, v30
	s_nop 1
	v_cndmask_b32_e64 v30, v31, v32, s[8:9]
	v_mul_f32_e32 v31, 0x37800000, v30
	v_cndmask_b32_e32 v30, v30, v31, vcc
	v_cmp_class_f32_e32 vcc, v19, v197
	s_nop 1
	v_cndmask_b32_e32 v19, v30, v19, vcc
	v_mul_f32_e32 v18, v18, v19
	v_mul_f32_e32 v30, v18, v33
	v_add_f32_e32 v18, v24, v72
	v_add_f32_e32 v19, v20, v76
	v_mul_f32_e32 v18, 0xbfb8aa3b, v18
	v_mul_f32_e32 v19, 0xbfb8aa3b, v19
	v_min_f32_e32 v18, 0x42700000, v18
	v_min_f32_e32 v19, 0x42700000, v19
	v_exp_f32_e32 v18, v18
	v_exp_f32_e32 v19, v19
	s_nop 0
	v_pk_add_f32 v[18:19], v[18:19], 1.0 op_sel_hi:[1,0]
	s_nop 0
	v_mul_f32_e32 v20, v18, v19
	v_rcp_f32_e32 v20, v20
	s_nop 0
	v_mul_f32_e32 v19, v19, v20
	v_mul_f32_e32 v19, v68, v19
	v_mul_f32_e32 v18, v18, v20
	v_fmamk_f32 v20, v19, 0x3ab60b61, v196
	v_fmaak_f32 v20, v19, v20, 0x3d2aaaab
	v_fmaak_f32 v20, v19, v20, 0x3e2aaaab
	v_fma_f32 v20, v19, v20, 0.5
	v_fma_f32 v20, v19, v20, 1.0
; __device__ __forceinline__ unsigned cvt_pk_bf16(float lo, float hi) { unsigned r; asm volatile("v_cvt_pk_bf16_f32 %0, %1, %2" : "=v"(r) : "v"(lo), "v"(hi)); return r; }
; __device__ __forceinline__ float bflo(unsigned w) { return __uint_as_float(w << 16); }
; __device__ __forceinline__ float bfhi(unsigned w) { return __uint_as_float(w & 0xffff0000u); }
; __device__ __forceinline__ float fsigmoid(float x) { return __builtin_amdgcn_rcpf(1.0f + __expf(-x)); }
; __device__ __forceinline__ void sigmoid2(float x0, float x1, float& s0, float& s1) {
;     const float d0 = 1.0f + __builtin_amdgcn_exp2f(fminf(x0 * -1.4426950408889634f, 60.f)), d1 = 1.0f + __builtin_amdgcn_exp2f(fminf(x1 * -1.4426950408889634f, 60.f));
;     const float rp = __builtin_amdgcn_rcpf(d0 * d1); s0 = rp * d1; s1 = rp * d0; }
; __device__ __forceinline__ f32x4 sigmoid4(f32x4 x) { float a, b, c, d; sigmoid2(x[0], x[1], a, b); sigmoid2(x[2], x[3], c, d); return (f32x4){a, b, c, d}; }
; __device__ __forceinline__ f32x4 gelu_tanh4(f32x4 v) { const f32x4 z = (v * v * 0.044715f + 1.0f) * v * 1.5957691216057308f; return v * sigmoid4(z); }
; __device__ __forceinline__ float fgelu_tanh(float v) { return v * fsigmoid(1.5957691216057308f * (v + 0.044715f * v * v * v)); }
; __device__ __forceinline__ float fsoftplus(float x) { return x > 20.f ? x : __logf(1.0f + __expf(x)); }
;     __device__ __forceinline__ void operator()(const f32x4 (&acc)[2][2][4][2], const Unit& u, int wr, int wc, int fr, int fq) const {
;     ...
;                     const u32x2 xw = *(const u32x2*)(XRC + off);
;                     const float xr[4] = {bflo(xw.x), bfhi(xw.x), bflo(xw.y), bfhi(xw.y)};
;                     f32x4 dv, bv;
; #pragma unroll
;                     for (int j = 0; j < 4; ++j) { float r, ig; sigmoid2(acc[ai][0][m][n][j] + br4[j], acc[ai][1][m][n][j] + bi4[j], r, ig);
;                         const float la = r * sp4[j]; float dd = neg_expm1_small(la); if (slow) dd = la > -0.25f ? dd : 1.0f - __expf(la);
;                         dv[j] = dd; bv[j] = __builtin_sqrtf(dd * (2.0f - dd)) * ig * xr[j]; }
;                     u32x2 dw, bw; dw.x = cvt_pk_bf16(dv[0], dv[1]); dw.y = cvt_pk_bf16(dv[2], dv[3]); bw.x = cvt_pk_bf16(bv[0], bv[1]); bw.y = cvt_pk_bf16(bv[2], bv[3]);
;                     *(u32x2*)(DD + off) = dw; *(u32x2*)(BB + off) = bw; asm volatile("" ::: "memory"); } }
	v_mul_f32_e64 v20, v20, -v19
	v_cmp_lt_f32_e32 vcc, s25, v19
	v_mul_f32_e32 v19, 0x3fb8aa3b, v19
	v_exp_f32_e32 v19, v19
	s_or_b64 vcc, s[34:35], vcc
	v_sub_f32_e32 v19, 1.0, v19
	v_cndmask_b32_e32 v20, v19, v20, vcc
	v_sub_f32_e32 v19, 2.0, v20
	v_mul_f32_e32 v19, v20, v19
	v_cmp_gt_f32_e32 vcc, s27, v19
	v_mul_f32_e32 v24, 0x4f800000, v19
	s_nop 0
	v_cndmask_b32_e32 v19, v19, v24, vcc
	v_sqrt_f32_e32 v24, v19
	s_nop 0
	v_add_u32_e32 v31, -1, v24
	v_fma_f32 v32, -v31, v24, v19
	v_cmp_ge_f32_e64 s[8:9], 0, v32
	v_add_u32_e32 v32, 1, v24
	s_nop 0
	v_cndmask_b32_e64 v31, v24, v31, s[8:9]
	v_fma_f32 v24, -v32, v24, v19
	v_cmp_lt_f32_e64 s[8:9], 0, v24
	s_nop 1
	v_cndmask_b32_e64 v24, v31, v32, s[8:9]
	v_mul_f32_e32 v31, 0x37800000, v24
	v_cndmask_b32_e32 v24, v24, v31, vcc
	v_cmp_class_f32_e32 vcc, v19, v197
	s_nop 1
	v_cndmask_b32_e32 v19, v24, v19, vcc
	v_mul_f32_e32 v18, v18, v19
	v_mul_f32_e32 v24, v18, v34
	v_add_f32_e32 v18, v25, v73
	v_add_f32_e32 v19, v21, v77
	v_mul_f32_e32 v18, 0xbfb8aa3b, v18
	v_mul_f32_e32 v19, 0xbfb8aa3b, v19
	v_min_f32_e32 v18, 0x42700000, v18
	v_min_f32_e32 v19, 0x42700000, v19
	v_exp_f32_e32 v18, v18
	v_exp_f32_e32 v19, v19
	s_nop 0
	v_pk_add_f32 v[18:19], v[18:19], 1.0 op_sel_hi:[1,0]
	s_nop 0
	v_mul_f32_e32 v21, v18, v19
	v_rcp_f32_e32 v21, v21
	s_nop 0
	v_mul_f32_e32 v19, v19, v21
	v_mul_f32_e32 v19, v69, v19
	v_mul_f32_e32 v18, v18, v21
	v_fmamk_f32 v21, v19, 0x3ab60b61, v196
	v_fmaak_f32 v21, v19, v21, 0x3d2aaaab
	v_fmaak_f32 v21, v19, v21, 0x3e2aaaab
	v_fma_f32 v21, v19, v21, 0.5
	v_fma_f32 v21, v19, v21, 1.0
	v_mul_f32_e64 v21, v21, -v19
	v_cmp_lt_f32_e32 vcc, s25, v19
	v_mul_f32_e32 v19, 0x3fb8aa3b, v19
	v_exp_f32_e32 v19, v19
	s_or_b64 vcc, s[34:35], vcc
	v_sub_f32_e32 v19, 1.0, v19
	v_cndmask_b32_e32 v19, v19, v21, vcc
	v_sub_f32_e32 v21, 2.0, v19
	v_mul_f32_e32 v21, v19, v21
	v_cmp_gt_f32_e32 vcc, s27, v21
	v_mul_f32_e32 v25, 0x4f800000, v21
	s_nop 0
	v_cndmask_b32_e32 v21, v21, v25, vcc
	v_sqrt_f32_e32 v25, v21
	s_nop 0
	v_add_u32_e32 v31, -1, v25
	v_fma_f32 v32, -v31, v25, v21
	v_cmp_ge_f32_e64 s[8:9], 0, v32
	v_add_u32_e32 v32, 1, v25
	s_nop 0
	v_cndmask_b32_e64 v31, v25, v31, s[8:9]
	v_fma_f32 v25, -v32, v25, v21
	v_cmp_lt_f32_e64 s[8:9], 0, v25
	s_nop 1
	v_cndmask_b32_e64 v25, v31, v32, s[8:9]
	v_mul_f32_e32 v31, 0x37800000, v25
	v_cndmask_b32_e32 v25, v25, v31, vcc
	v_cmp_class_f32_e32 vcc, v21, v197
	s_nop 1
	v_cndmask_b32_e32 v21, v25, v21, vcc
	v_mul_f32_e32 v18, v18, v21
	v_mul_f32_e32 v21, v18, v28
	v_cvt_pk_bf16_f32 v18, v22, v23
	v_cvt_pk_bf16_f32 v19, v20, v19
	v_lshl_add_u64 v[22:23], s[16:17], 0, v[26:27]
	v_cvt_pk_bf16_f32 v20, v29, v30
	v_cvt_pk_bf16_f32 v21, v24, v21
	global_store_dwordx2 v[22:23], v[18:19], off
	v_lshl_add_u64 v[18:19], s[18:19], 0, v[26:27]
	global_store_dwordx2 v[18:19], v[20:21], off
	v_lshl_add_u64 v[18:19], v[94:95], 0, v[80:81]
	v_lshlrev_b64 v[18:19], 1, v[18:19]
	v_lshl_add_u64 v[20:21], s[0:1], 0, v[18:19]
	v_exp_f32_e32 v22, v14
	v_exp_f32_e32 v23, v10
	v_mov_b64_e32 v[20:21], v[188:189]
	v_lshlrev_b32_e32 v24, 16, v20
	v_pk_add_f32 v[22:23], v[22:23], 1.0 op_sel_hi:[1,0]
	v_and_b32_e32 v25, 0xffff0000, v20
	v_mul_f32_e32 v10, v22, v23
	v_rcp_f32_e32 v10, v10
	v_lshlrev_b32_e32 v26, 16, v21
	v_and_b32_e32 v20, 0xffff0000, v21
	v_mul_f32_e32 v14, v23, v10
	v_mul_f32_e32 v14, v66, v14
	v_fmamk_f32 v21, v14, 0x3ab60b61, v196
	v_fmaak_f32 v21, v14, v21, 0x3d2aaaab
	v_fmaak_f32 v21, v14, v21, 0x3e2aaaab
	v_fma_f32 v21, v14, v21, 0.5
	v_fma_f32 v21, v14, v21, 1.0
	v_mul_f32_e64 v21, v21, -v14
	v_cmp_lt_f32_e32 vcc, s25, v14
	v_mul_f32_e32 v14, 0x3fb8aa3b, v14
	v_exp_f32_e32 v14, v14
	s_or_b64 vcc, s[34:35], vcc
	v_mul_f32_e32 v10, v22, v10
	v_sub_f32_e32 v14, 1.0, v14
	v_cndmask_b32_e32 v14, v14, v21, vcc
	v_sub_f32_e32 v21, 2.0, v14
	v_mul_f32_e32 v21, v14, v21
	v_cmp_gt_f32_e32 vcc, s27, v21
	v_mul_f32_e32 v22, 0x4f800000, v21
	s_nop 0
	v_cndmask_b32_e32 v21, v21, v22, vcc
	v_sqrt_f32_e32 v22, v21
	s_nop 0
	v_add_u32_e32 v23, -1, v22
	v_fma_f32 v27, -v23, v22, v21
	v_cmp_ge_f32_e64 s[8:9], 0, v27
	v_add_u32_e32 v27, 1, v22
	s_nop 0
	v_cndmask_b32_e64 v23, v22, v23, s[8:9]
	v_fma_f32 v22, -v27, v22, v21
	v_cmp_lt_f32_e64 s[8:9], 0, v22
	s_nop 1
	v_cndmask_b32_e64 v22, v23, v27, s[8:9]
	v_mul_f32_e32 v23, 0x37800000, v22
	v_cndmask_b32_e32 v22, v22, v23, vcc
	v_cmp_class_f32_e32 vcc, v21, v197
	s_nop 1
	v_cndmask_b32_e32 v21, v22, v21, vcc
	v_mul_f32_e32 v10, v10, v21
	v_mul_f32_e32 v21, v10, v24
	v_add_f32_e32 v10, v15, v71
	v_mul_f32_e32 v10, 0xbfb8aa3b, v10
	v_min_f32_e32 v10, 0x42700000, v10
	v_exp_f32_e32 v10, v10
	s_nop 0
	v_pk_add_f32 v[10:11], v[10:11], 1.0 op_sel_hi:[1,0]
	s_nop 0
	v_mul_f32_e32 v15, v10, v11
	v_rcp_f32_e32 v15, v15
	s_nop 0
	v_mul_f32_e32 v11, v11, v15
	v_mul_f32_e32 v11, v67, v11
	v_mul_f32_e32 v10, v10, v15
	v_fmamk_f32 v15, v11, 0x3ab60b61, v196
	v_fmaak_f32 v15, v11, v15, 0x3d2aaaab
	v_fmaak_f32 v15, v11, v15, 0x3e2aaaab
	v_fma_f32 v15, v11, v15, 0.5
	v_fma_f32 v15, v11, v15, 1.0
	v_mul_f32_e64 v15, v15, -v11
	v_cmp_lt_f32_e32 vcc, s25, v11
	v_mul_f32_e32 v11, 0x3fb8aa3b, v11
	v_exp_f32_e32 v11, v11
	s_or_b64 vcc, s[34:35], vcc
	v_sub_f32_e32 v11, 1.0, v11
	v_cndmask_b32_e32 v15, v11, v15, vcc
	v_sub_f32_e32 v11, 2.0, v15
	v_mul_f32_e32 v11, v15, v11
	v_cmp_gt_f32_e32 vcc, s27, v11
	v_mul_f32_e32 v22, 0x4f800000, v11
	s_nop 0
	v_cndmask_b32_e32 v11, v11, v22, vcc
	v_sqrt_f32_e32 v22, v11
	s_nop 0
	v_add_u32_e32 v23, -1, v22
	v_fma_f32 v24, -v23, v22, v11
	v_cmp_ge_f32_e64 s[8:9], 0, v24
	v_add_u32_e32 v24, 1, v22
	s_nop 0
	v_cndmask_b32_e64 v23, v22, v23, s[8:9]
	v_fma_f32 v22, -v24, v22, v11
	v_cmp_lt_f32_e64 s[8:9], 0, v22
; __device__ __forceinline__ unsigned cvt_pk_bf16(float lo, float hi) { unsigned r; asm volatile("v_cvt_pk_bf16_f32 %0, %1, %2" : "=v"(r) : "v"(lo), "v"(hi)); return r; }
; __device__ __forceinline__ float bflo(unsigned w) { return __uint_as_float(w << 16); }
; __device__ __forceinline__ float bfhi(unsigned w) { return __uint_as_float(w & 0xffff0000u); }
; __device__ __forceinline__ float fsigmoid(float x) { return __builtin_amdgcn_rcpf(1.0f + __expf(-x)); }
; __device__ __forceinline__ void sigmoid2(float x0, float x1, float& s0, float& s1) {
;     const float d0 = 1.0f + __builtin_amdgcn_exp2f(fminf(x0 * -1.4426950408889634f, 60.f)), d1 = 1.0f + __builtin_amdgcn_exp2f(fminf(x1 * -1.4426950408889634f, 60.f));
;     const float rp = __builtin_amdgcn_rcpf(d0 * d1); s0 = rp * d1; s1 = rp * d0; }
; __device__ __forceinline__ f32x4 sigmoid4(f32x4 x) { float a, b, c, d; sigmoid2(x[0], x[1], a, b); sigmoid2(x[2], x[3], c, d); return (f32x4){a, b, c, d}; }
; __device__ __forceinline__ f32x4 gelu_tanh4(f32x4 v) { const f32x4 z = (v * v * 0.044715f + 1.0f) * v * 1.5957691216057308f; return v * sigmoid4(z); }
; __device__ __forceinline__ float fgelu_tanh(float v) { return v * fsigmoid(1.5957691216057308f * (v + 0.044715f * v * v * v)); }
; __device__ __forceinline__ float fsoftplus(float x) { return x > 20.f ? x : __logf(1.0f + __expf(x)); }
;     __device__ __forceinline__ void operator()(const f32x4 (&acc)[2][2][4][2], const Unit& u, int wr, int wc, int fr, int fq) const {
;     ...
;                     const u32x2 xw = *(const u32x2*)(XRC + off);
;                     const float xr[4] = {bflo(xw.x), bfhi(xw.x), bflo(xw.y), bfhi(xw.y)};
;                     f32x4 dv, bv;
; #pragma unroll
;                     for (int j = 0; j < 4; ++j) { float r, ig; sigmoid2(acc[ai][0][m][n][j] + br4[j], acc[ai][1][m][n][j] + bi4[j], r, ig);
;                         const float la = r * sp4[j]; float dd = neg_expm1_small(la); if (slow) dd = la > -0.25f ? dd : 1.0f - __expf(la);
;                         dv[j] = dd; bv[j] = __builtin_sqrtf(dd * (2.0f - dd)) * ig * xr[j]; }
;                     u32x2 dw, bw; dw.x = cvt_pk_bf16(dv[0], dv[1]); dw.y = cvt_pk_bf16(dv[2], dv[3]); bw.x = cvt_pk_bf16(bv[0], bv[1]); bw.y = cvt_pk_bf16(bv[2], bv[3]);
;                     *(u32x2*)(DD + off) = dw; *(u32x2*)(BB + off) = bw; asm volatile("" ::: "memory"); } }
	s_nop 1
	v_cndmask_b32_e64 v22, v23, v24, s[8:9]
	v_mul_f32_e32 v23, 0x37800000, v22
	v_cndmask_b32_e32 v22, v22, v23, vcc
	v_cmp_class_f32_e32 vcc, v11, v197
	s_nop 1
	v_cndmask_b32_e32 v11, v22, v11, vcc
	v_mul_f32_e32 v10, v10, v11
	v_mul_f32_e32 v22, v10, v25
	v_add_f32_e32 v10, v16, v72
	v_add_f32_e32 v11, v12, v76
	v_mul_f32_e32 v10, 0xbfb8aa3b, v10
	v_mul_f32_e32 v11, 0xbfb8aa3b, v11
	v_min_f32_e32 v10, 0x42700000, v10
	v_min_f32_e32 v11, 0x42700000, v11
	v_exp_f32_e32 v10, v10
	v_exp_f32_e32 v11, v11
	s_nop 0
	v_pk_add_f32 v[10:11], v[10:11], 1.0 op_sel_hi:[1,0]
	s_nop 0
	v_mul_f32_e32 v12, v10, v11
	v_rcp_f32_e32 v12, v12
	s_nop 0
	v_mul_f32_e32 v11, v11, v12
	v_mul_f32_e32 v11, v68, v11
	v_mul_f32_e32 v10, v10, v12
	v_fmamk_f32 v12, v11, 0x3ab60b61, v196
	v_fmaak_f32 v12, v11, v12, 0x3d2aaaab
	v_fmaak_f32 v12, v11, v12, 0x3e2aaaab
	v_fma_f32 v12, v11, v12, 0.5
	v_fma_f32 v12, v11, v12, 1.0
	v_mul_f32_e64 v12, v12, -v11
	v_cmp_lt_f32_e32 vcc, s25, v11
	v_mul_f32_e32 v11, 0x3fb8aa3b, v11
	v_exp_f32_e32 v11, v11
	s_or_b64 vcc, s[34:35], vcc
	v_sub_f32_e32 v11, 1.0, v11
	v_cndmask_b32_e32 v12, v11, v12, vcc
	v_sub_f32_e32 v11, 2.0, v12
	v_mul_f32_e32 v11, v12, v11
	v_cmp_gt_f32_e32 vcc, s27, v11
	v_mul_f32_e32 v16, 0x4f800000, v11
	s_nop 0
	v_cndmask_b32_e32 v11, v11, v16, vcc
	v_sqrt_f32_e32 v16, v11
	s_nop 0
	v_add_u32_e32 v23, -1, v16
	v_fma_f32 v24, -v23, v16, v11
	v_cmp_ge_f32_e64 s[8:9], 0, v24
	v_add_u32_e32 v24, 1, v16
	s_nop 0
	v_cndmask_b32_e64 v23, v16, v23, s[8:9]
	v_fma_f32 v16, -v24, v16, v11
	v_cmp_lt_f32_e64 s[8:9], 0, v16
	s_nop 1
	v_cndmask_b32_e64 v16, v23, v24, s[8:9]
	v_mul_f32_e32 v23, 0x37800000, v16
	v_cndmask_b32_e32 v16, v16, v23, vcc
	v_cmp_class_f32_e32 vcc, v11, v197
	s_nop 1
	v_cndmask_b32_e32 v11, v16, v11, vcc
	v_mul_f32_e32 v10, v10, v11
	v_mul_f32_e32 v16, v10, v26
	v_add_f32_e32 v10, v17, v73
	v_add_f32_e32 v11, v13, v77
	v_mul_f32_e32 v10, 0xbfb8aa3b, v10
	v_mul_f32_e32 v11, 0xbfb8aa3b, v11
	v_min_f32_e32 v10, 0x42700000, v10
	v_min_f32_e32 v11, 0x42700000, v11
	v_exp_f32_e32 v10, v10
	v_exp_f32_e32 v11, v11
	s_nop 0
	v_pk_add_f32 v[10:11], v[10:11], 1.0 op_sel_hi:[1,0]
	s_nop 0
	v_mul_f32_e32 v13, v10, v11
	v_rcp_f32_e32 v13, v13
	s_nop 0
	v_mul_f32_e32 v11, v11, v13
	v_mul_f32_e32 v11, v69, v11
	v_mul_f32_e32 v10, v10, v13
	v_fmamk_f32 v13, v11, 0x3ab60b61, v196
	v_fmaak_f32 v13, v11, v13, 0x3d2aaaab
	v_fmaak_f32 v13, v11, v13, 0x3e2aaaab
	v_fma_f32 v13, v11, v13, 0.5
	v_fma_f32 v13, v11, v13, 1.0
	v_mul_f32_e64 v13, v13, -v11
	v_cmp_lt_f32_e32 vcc, s25, v11
	v_mul_f32_e32 v11, 0x3fb8aa3b, v11
	v_exp_f32_e32 v11, v11
	s_or_b64 vcc, s[34:35], vcc
	v_sub_f32_e32 v11, 1.0, v11
	v_cndmask_b32_e32 v11, v11, v13, vcc
	v_sub_f32_e32 v13, 2.0, v11
	v_mul_f32_e32 v13, v11, v13
	v_cmp_gt_f32_e32 vcc, s27, v13
	v_mul_f32_e32 v17, 0x4f800000, v13
	s_nop 0
	v_cndmask_b32_e32 v13, v13, v17, vcc
	v_sqrt_f32_e32 v17, v13
	s_nop 0
	v_add_u32_e32 v23, -1, v17
	v_fma_f32 v24, -v23, v17, v13
	v_cmp_ge_f32_e64 s[8:9], 0, v24
	v_add_u32_e32 v24, 1, v17
	s_nop 0
	v_cndmask_b32_e64 v23, v17, v23, s[8:9]
	v_fma_f32 v17, -v24, v17, v13
	v_cmp_lt_f32_e64 s[8:9], 0, v17
	s_nop 1
	v_cndmask_b32_e64 v17, v23, v24, s[8:9]
	v_mul_f32_e32 v23, 0x37800000, v17
	v_cndmask_b32_e32 v17, v17, v23, vcc
	v_cmp_class_f32_e32 vcc, v13, v197
	s_nop 1
	v_cndmask_b32_e32 v13, v17, v13, vcc
	v_mul_f32_e32 v10, v10, v13
	v_mul_f32_e32 v13, v10, v20
	v_cvt_pk_bf16_f32 v10, v14, v15
	v_cvt_pk_bf16_f32 v11, v12, v11
	v_lshl_add_u64 v[14:15], s[16:17], 0, v[18:19]
	v_cvt_pk_bf16_f32 v12, v21, v22
	v_cvt_pk_bf16_f32 v13, v16, v13
	global_store_dwordx2 v[14:15], v[10:11], off
	v_lshl_add_u64 v[10:11], s[18:19], 0, v[18:19]
	global_store_dwordx2 v[10:11], v[12:13], off
	v_lshl_add_u64 v[10:11], v[78:79], 0, v[80:81]
	v_lshlrev_b64 v[10:11], 1, v[10:11]
	v_lshl_add_u64 v[12:13], s[0:1], 0, v[10:11]
	v_exp_f32_e32 v14, v6
	v_exp_f32_e32 v15, v2
	v_mov_b64_e32 v[12:13], v[190:191]
	v_lshlrev_b32_e32 v16, 16, v12
	v_pk_add_f32 v[14:15], v[14:15], 1.0 op_sel_hi:[1,0]
	v_and_b32_e32 v17, 0xffff0000, v12
	v_mul_f32_e32 v2, v14, v15
	v_rcp_f32_e32 v2, v2
	v_lshlrev_b32_e32 v18, 16, v13
	v_and_b32_e32 v12, 0xffff0000, v13
	v_mul_f32_e32 v6, v15, v2
	v_mul_f32_e32 v13, v14, v2
	v_mul_f32_e32 v2, v66, v6
	v_fmamk_f32 v6, v2, 0x3ab60b61, v196
	v_fmaak_f32 v6, v2, v6, 0x3d2aaaab
	v_fmaak_f32 v6, v2, v6, 0x3e2aaaab
	v_fma_f32 v6, v2, v6, 0.5
	v_fma_f32 v6, v2, v6, 1.0
	v_mul_f32_e64 v6, v6, -v2
	v_cmp_lt_f32_e32 vcc, s25, v2
	v_mul_f32_e32 v2, 0x3fb8aa3b, v2
	v_exp_f32_e32 v2, v2
	s_or_b64 vcc, s[34:35], vcc
	v_sub_f32_e32 v2, 1.0, v2
	v_cndmask_b32_e32 v2, v2, v6, vcc
	v_sub_f32_e32 v6, 2.0, v2
	v_mul_f32_e32 v6, v2, v6
	v_cmp_gt_f32_e32 vcc, s27, v6
	v_mul_f32_e32 v14, 0x4f800000, v6
	s_nop 0
	v_cndmask_b32_e32 v6, v6, v14, vcc
	v_sqrt_f32_e32 v14, v6
	s_nop 0
	v_add_u32_e32 v15, -1, v14
	v_fma_f32 v19, -v15, v14, v6
	v_cmp_ge_f32_e64 s[8:9], 0, v19
	v_add_u32_e32 v19, 1, v14
	s_nop 0
	v_cndmask_b32_e64 v15, v14, v15, s[8:9]
	v_fma_f32 v14, -v19, v14, v6
; __device__ __forceinline__ unsigned cvt_pk_bf16(float lo, float hi) { unsigned r; asm volatile("v_cvt_pk_bf16_f32 %0, %1, %2" : "=v"(r) : "v"(lo), "v"(hi)); return r; }
; #define PG8_BAR __builtin_amdgcn_s_barrier()
; template <class Epi>
; __device__ __forceinline__ void gemm_phase(LAS unsigned char* lds, const Gemm g, const StaticOrder& S, const Epi& E, const int tid) {
;     ...
;         if (wr == 0) PG8_BAR;
;         E(acc, cur, wr, wc, fr, fq);
;         if (!has_next) break;
; #pragma unroll
;         for (int a = 0; a < 2; ++a)
; #pragma unroll
;             for (int b = 0; b < 2; ++b)
; #pragma unroll
;                 for (int m = 0; m < 4; ++m)
; #pragma unroll
;                     for (int n = 0; n < 2; ++n) acc[a][b][m][n] = (f32x4){0.f, 0.f, 0.f, 0.f};
;         cur = nxt; cA = nA; cB = nB; ++ui;
;         if (wr == 1) PG8_BAR;
;     }
;     __device__ __forceinline__ void operator()(const f32x4 (&acc)[2][2][4][2], const Unit& u, int wr, int wc, int fr, int fq) const {
;     ...
;                     for (int j = 0; j < 4; ++j) { float r, ig; sigmoid2(acc[ai][0][m][n][j] + br4[j], acc[ai][1][m][n][j] + bi4[j], r, ig);
;                         const float la = r * sp4[j]; float dd = neg_expm1_small(la); if (slow) dd = la > -0.25f ? dd : 1.0f - __expf(la);
;                         dv[j] = dd; bv[j] = __builtin_sqrtf(dd * (2.0f - dd)) * ig * xr[j]; }
;                     u32x2 dw, bw; dw.x = cvt_pk_bf16(dv[0], dv[1]); dw.y = cvt_pk_bf16(dv[2], dv[3]); bw.x = cvt_pk_bf16(bv[0], bv[1]); bw.y = cvt_pk_bf16(bv[2], bv[3]);
;                     *(u32x2*)(DD + off) = dw; *(u32x2*)(BB + off) = bw; asm volatile("" ::: "memory"); } }
	v_cmp_lt_f32_e64 s[8:9], 0, v14
	s_nop 1
	v_cndmask_b32_e64 v14, v15, v19, s[8:9]
	v_mul_f32_e32 v15, 0x37800000, v14
	v_cndmask_b32_e32 v14, v14, v15, vcc
	v_cmp_class_f32_e32 vcc, v6, v197
	s_nop 1
	v_cndmask_b32_e32 v6, v14, v6, vcc
	v_mul_f32_e32 v6, v13, v6
	v_mul_f32_e32 v13, v6, v16
	v_add_f32_e32 v6, v7, v71
	v_mul_f32_e32 v6, 0xbfb8aa3b, v6
	v_min_f32_e32 v6, 0x42700000, v6
	v_exp_f32_e32 v6, v6
	v_exp_f32_e32 v7, v3
	s_nop 0
	v_pk_add_f32 v[6:7], v[6:7], 1.0 op_sel_hi:[1,0]
	s_nop 0
	v_mul_f32_e32 v3, v6, v7
	v_rcp_f32_e32 v3, v3
	s_nop 0
	v_mul_f32_e32 v7, v7, v3
	v_mul_f32_e32 v3, v6, v3
	v_mul_f32_e32 v6, v67, v7
	v_fmamk_f32 v7, v6, 0x3ab60b61, v196
	v_fmaak_f32 v7, v6, v7, 0x3d2aaaab
	v_fmaak_f32 v7, v6, v7, 0x3e2aaaab
	v_fma_f32 v7, v6, v7, 0.5
	v_fma_f32 v7, v6, v7, 1.0
	v_mul_f32_e64 v7, v7, -v6
	v_cmp_lt_f32_e32 vcc, s25, v6
	v_mul_f32_e32 v6, 0x3fb8aa3b, v6
	v_exp_f32_e32 v6, v6
	s_or_b64 vcc, s[34:35], vcc
	v_sub_f32_e32 v6, 1.0, v6
	v_cndmask_b32_e32 v14, v6, v7, vcc
	v_sub_f32_e32 v6, 2.0, v14
	v_mul_f32_e32 v6, v14, v6
	v_cmp_gt_f32_e32 vcc, s27, v6
	v_mul_f32_e32 v7, 0x4f800000, v6
	v_cvt_pk_bf16_f32 v2, v2, v14
	s_nop 0
	v_cndmask_b32_e32 v6, v6, v7, vcc
	v_sqrt_f32_e32 v7, v6
	s_nop 0
	v_add_u32_e32 v15, -1, v7
	v_fma_f32 v16, -v15, v7, v6
	v_cmp_ge_f32_e64 s[8:9], 0, v16
	v_add_u32_e32 v16, 1, v7
	s_nop 0
	v_cndmask_b32_e64 v15, v7, v15, s[8:9]
	v_fma_f32 v7, -v16, v7, v6
	v_cmp_lt_f32_e64 s[8:9], 0, v7
	s_nop 1
	v_cndmask_b32_e64 v7, v15, v16, s[8:9]
	v_mul_f32_e32 v15, 0x37800000, v7
	v_cndmask_b32_e32 v7, v7, v15, vcc
	v_cmp_class_f32_e32 vcc, v6, v197
	s_nop 1
	v_cndmask_b32_e32 v6, v7, v6, vcc
	v_mul_f32_e32 v3, v3, v6
	v_mul_f32_e32 v15, v3, v17
	v_add_f32_e32 v3, v8, v72
	v_mul_f32_e32 v3, 0xbfb8aa3b, v3
	v_min_f32_e32 v3, 0x42700000, v3
	v_exp_f32_e32 v6, v3
	v_mul_f32_e32 v3, 0xbfb8aa3b, v4
	v_min_f32_e32 v3, 0x42700000, v3
	v_exp_f32_e32 v7, v3
	s_nop 0
	v_pk_add_f32 v[6:7], v[6:7], 1.0 op_sel_hi:[1,0]
	s_nop 0
	v_mul_f32_e32 v3, v6, v7
	v_rcp_f32_e32 v3, v3
	s_nop 0
	v_mul_f32_e32 v4, v7, v3
	v_mul_f32_e32 v4, v68, v4
	v_mul_f32_e32 v3, v6, v3
	v_fmamk_f32 v6, v4, 0x3ab60b61, v196
	v_fmaak_f32 v6, v4, v6, 0x3d2aaaab
	v_fmaak_f32 v6, v4, v6, 0x3e2aaaab
	v_fma_f32 v6, v4, v6, 0.5
	v_fma_f32 v6, v4, v6, 1.0
	v_mul_f32_e64 v6, v6, -v4
	v_cmp_lt_f32_e32 vcc, s25, v4
	v_mul_f32_e32 v4, 0x3fb8aa3b, v4
	v_exp_f32_e32 v4, v4
	s_or_b64 vcc, s[34:35], vcc
	v_sub_f32_e32 v4, 1.0, v4
	v_cndmask_b32_e32 v6, v4, v6, vcc
	v_sub_f32_e32 v4, 2.0, v6
	v_mul_f32_e32 v4, v6, v4
	v_cmp_gt_f32_e32 vcc, s27, v4
	v_mul_f32_e32 v7, 0x4f800000, v4
	s_nop 0
	v_cndmask_b32_e32 v4, v4, v7, vcc
	v_sqrt_f32_e32 v7, v4
	s_nop 0
	v_add_u32_e32 v8, -1, v7
	v_fma_f32 v16, -v8, v7, v4
	v_cmp_ge_f32_e64 s[8:9], 0, v16
	v_add_u32_e32 v16, 1, v7
	s_nop 0
	v_cndmask_b32_e64 v8, v7, v8, s[8:9]
	v_fma_f32 v7, -v16, v7, v4
	v_cmp_lt_f32_e64 s[8:9], 0, v7
	s_nop 1
	v_cndmask_b32_e64 v7, v8, v16, s[8:9]
	v_mul_f32_e32 v8, 0x37800000, v7
	v_cndmask_b32_e32 v7, v7, v8, vcc
	v_cmp_class_f32_e32 vcc, v4, v197
	s_nop 1
	v_cndmask_b32_e32 v4, v7, v4, vcc
	v_mul_f32_e32 v3, v3, v4
	v_mul_f32_e32 v7, v3, v18
	v_add_f32_e32 v3, v9, v73
	v_mul_f32_e32 v3, 0xbfb8aa3b, v3
	v_min_f32_e32 v3, 0x42700000, v3
	v_exp_f32_e32 v4, v3
	v_mul_f32_e32 v3, 0xbfb8aa3b, v5
	v_min_f32_e32 v3, 0x42700000, v3
	v_exp_f32_e32 v5, v3
	s_nop 0
	v_pk_add_f32 v[4:5], v[4:5], 1.0 op_sel_hi:[1,0]
	s_nop 0
	v_mul_f32_e32 v3, v4, v5
	v_rcp_f32_e32 v3, v3
	s_nop 0
	v_mul_f32_e32 v5, v5, v3
	v_mul_f32_e32 v3, v4, v3
	v_mul_f32_e32 v4, v69, v5
	v_fmamk_f32 v5, v4, 0x3ab60b61, v196
	v_fmaak_f32 v5, v4, v5, 0x3d2aaaab
	v_fmaak_f32 v5, v4, v5, 0x3e2aaaab
	v_fma_f32 v5, v4, v5, 0.5
	v_fma_f32 v5, v4, v5, 1.0
	v_mul_f32_e64 v5, v5, -v4
	v_cmp_lt_f32_e32 vcc, s25, v4
	v_mul_f32_e32 v4, 0x3fb8aa3b, v4
	v_exp_f32_e32 v4, v4
	s_or_b64 vcc, s[34:35], vcc
	v_sub_f32_e32 v4, 1.0, v4
	v_cndmask_b32_e32 v4, v4, v5, vcc
	v_sub_f32_e32 v5, 2.0, v4
	v_mul_f32_e32 v5, v4, v5
	v_cmp_gt_f32_e32 vcc, s27, v5
	v_mul_f32_e32 v8, 0x4f800000, v5
	s_nop 0
	v_cndmask_b32_e32 v5, v5, v8, vcc
	v_sqrt_f32_e32 v8, v5
	s_nop 0
	v_add_u32_e32 v9, -1, v8
	v_fma_f32 v16, -v9, v8, v5
	v_cmp_ge_f32_e64 s[8:9], 0, v16
	v_add_u32_e32 v16, 1, v8
	s_nop 0
	v_cndmask_b32_e64 v9, v8, v9, s[8:9]
	v_fma_f32 v8, -v16, v8, v5
	v_cmp_lt_f32_e64 s[8:9], 0, v8
	s_nop 1
	v_cndmask_b32_e64 v8, v9, v16, s[8:9]
	v_mul_f32_e32 v9, 0x37800000, v8
	v_cndmask_b32_e32 v8, v8, v9, vcc
	v_cmp_class_f32_e32 vcc, v5, v197
	s_mov_b64 s[8:9], -1
	s_nop 0
	v_cndmask_b32_e32 v5, v8, v5, vcc
	v_mul_f32_e32 v3, v3, v5
	v_mul_f32_e32 v5, v3, v12
	v_cvt_pk_bf16_f32 v3, v6, v4
	v_cvt_pk_bf16_f32 v4, v13, v15
	v_cvt_pk_bf16_f32 v5, v7, v5
	v_lshl_add_u64 v[6:7], s[16:17], 0, v[10:11]
	global_store_dwordx2 v[6:7], v[2:3], off
	v_lshl_add_u64 v[2:3], s[18:19], 0, v[10:11]
	global_store_dwordx2 v[2:3], v[4:5], off
	s_and_b64 vcc, exec, s[6:7]
	s_cbranch_vccnz .LBB0_490
	s_andn2_b64 vcc, exec, s[10:11]
	s_cbranch_vccnz .LBB0_489
	s_barrier
	s_branch .LBB0_489
